# gather dot phase: padding nops after the packed partial-sum adds replaced by the next pair's independent readlanes (84 fewer issue slots per token)
# baseline (speedup 1.0000x reference)
; __device__ void peer_gather_phase(const Params& P, int l, bool do_store) {
;     ...
;       for (int pr = 0; pr < 4; ++pr) {
;         const int ea = __builtin_amdgcn_readlane(evs, kb + 2 * pr), eb = __builtin_amdgcn_readlane(evs, kb + 2 * pr + 1);
;         const uint2* up = (const uint2*)(U + (size_t)(uphi ? eb : ea) * 768);
;         u6[3 * pr] = up[0]; u6[3 * pr + 1] = up[1]; u6[3 * pr + 2] = up[2];
;     ...
;       for (int pr = 0; pr < 4; ++pr) {
;         v6u_t qv; qv[0] = u6[3 * pr].x; qv[1] = u6[3 * pr].y; qv[2] = u6[3 * pr + 1].x; qv[3] = u6[3 * pr + 1].y; qv[4] = u6[3 * pr + 2].x; qv[5] = u6[3 * pr + 2].y;
;         const v32f_t wv = __builtin_amdgcn_cvt_scalef32_pk32_f32_fp6(qv, 1.0f);
;         f32x2 a2 = f32x2{0.f, 0.f};
; #pragma unroll
;         for (int i = 0; i < 16; ++i) a2 += f32x2{wv[2 * i], wv[2 * i + 1]} * xu[i];
;         float hs = a2.x + a2.y;
;         hs += dpp_row_shr(hs, 1); hs += dpp_row_shr(hs, 2); hs += dpp_row_shr(hs, 4); hs += dpp_row_shr(hs, 8);
;         hs += __builtin_bit_cast(float, __builtin_amdgcn_update_dpp(0, __builtin_bit_cast(int, hs), 0x142, 0xa, 0xf, false));
;         const float da = __builtin_bit_cast(float, __builtin_amdgcn_readlane(__builtin_bit_cast(int, hs), 31));
;         const float db = __builtin_bit_cast(float, __builtin_amdgcn_readlane(__builtin_bit_cast(int, hs), 63));
.LBB0_22:
	v_readlane_b32 s54, v92, 16
	v_readlane_b32 s55, v92, 17
	s_mul_i32 s0, s54, 0x300
	s_mul_i32 s1, s55, 0x300
	v_add_u32_e32 v167, s0, v195
	s_and_saveexec_b64 s[98:99], s[40:41]
	v_add_u32_e32 v167, s1, v195
	s_mov_b64 exec, s[98:99]
	s_waitcnt vmcnt(32)
	v_cvt_scalef32_pk32_f32_fp6 v[0:31], v[50:55], 1.0
	global_load_dwordx2 v[54:55], v167, s[62:63] offset:16
	global_load_dwordx4 v[50:53], v167, s[62:63]
	v_pk_mul_f32 v[246:247], v[0:1], v[96:97]
	v_pk_mul_f32 v[254:255], v[2:3], v[98:99]
	v_pk_mul_f32 v[160:161], v[4:5], v[100:101]
	v_pk_fma_f32 v[246:247], v[6:7], v[102:103], v[246:247]
	v_pk_fma_f32 v[254:255], v[8:9], v[104:105], v[254:255]
	v_pk_fma_f32 v[160:161], v[10:11], v[106:107], v[160:161]
	v_pk_fma_f32 v[246:247], v[12:13], v[108:109], v[246:247]
	v_pk_fma_f32 v[254:255], v[14:15], v[110:111], v[254:255]
	v_pk_fma_f32 v[160:161], v[16:17], v[112:113], v[160:161]
	v_pk_fma_f32 v[246:247], v[18:19], v[114:115], v[246:247]
	v_pk_fma_f32 v[254:255], v[20:21], v[116:117], v[254:255]
	v_pk_fma_f32 v[160:161], v[22:23], v[118:119], v[160:161]
	v_pk_fma_f32 v[246:247], v[24:25], v[120:121], v[246:247]
	v_pk_fma_f32 v[254:255], v[26:27], v[122:123], v[254:255]
	v_pk_fma_f32 v[160:161], v[28:29], v[124:125], v[160:161]
	v_pk_fma_f32 v[246:247], v[30:31], v[126:127], v[246:247]
	v_pk_add_f32 v[254:255], v[254:255], v[160:161]
	v_readlane_b32 s54, v92, 18
	v_pk_add_f32 v[246:247], v[246:247], v[254:255]
	v_readlane_b32 s55, v92, 19
	v_add_f32_e32 v162, v246, v247
	s_mul_i32 s0, s54, 0x300
	s_mul_i32 s1, s55, 0x300
	v_add_u32_e32 v167, s0, v195
	s_and_saveexec_b64 s[98:99], s[40:41]
	v_add_u32_e32 v167, s1, v195
	s_mov_b64 exec, s[98:99]
	s_waitcnt vmcnt(32)
	v_cvt_scalef32_pk32_f32_fp6 v[0:31], v[44:49], 1.0
	global_load_dwordx2 v[48:49], v167, s[62:63] offset:16
	global_load_dwordx4 v[44:47], v167, s[62:63]
	v_pk_mul_f32 v[246:247], v[0:1], v[96:97]
	v_pk_mul_f32 v[254:255], v[2:3], v[98:99]
	v_pk_mul_f32 v[160:161], v[4:5], v[100:101]
	v_pk_fma_f32 v[246:247], v[6:7], v[102:103], v[246:247]
	v_pk_fma_f32 v[254:255], v[8:9], v[104:105], v[254:255]
	v_pk_fma_f32 v[160:161], v[10:11], v[106:107], v[160:161]
	v_pk_fma_f32 v[246:247], v[12:13], v[108:109], v[246:247]
	v_pk_fma_f32 v[254:255], v[14:15], v[110:111], v[254:255]
	v_pk_fma_f32 v[160:161], v[16:17], v[112:113], v[160:161]
	v_pk_fma_f32 v[246:247], v[18:19], v[114:115], v[246:247]
	v_pk_fma_f32 v[254:255], v[20:21], v[116:117], v[254:255]
	v_pk_fma_f32 v[160:161], v[22:23], v[118:119], v[160:161]
	v_pk_fma_f32 v[246:247], v[24:25], v[120:121], v[246:247]
	v_pk_fma_f32 v[254:255], v[26:27], v[122:123], v[254:255]
	v_pk_fma_f32 v[160:161], v[28:29], v[124:125], v[160:161]
	v_pk_fma_f32 v[246:247], v[30:31], v[126:127], v[246:247]
	v_pk_add_f32 v[254:255], v[254:255], v[160:161]
	v_readlane_b32 s54, v92, 20
	v_pk_add_f32 v[246:247], v[246:247], v[254:255]
	v_readlane_b32 s55, v92, 21
	v_add_f32_e32 v163, v246, v247
	s_mul_i32 s0, s54, 0x300
	s_mul_i32 s1, s55, 0x300
	v_add_u32_e32 v167, s0, v195
	s_and_saveexec_b64 s[98:99], s[40:41]
	v_add_u32_e32 v167, s1, v195
	s_mov_b64 exec, s[98:99]
	s_waitcnt vmcnt(32)
	v_cvt_scalef32_pk32_f32_fp6 v[0:31], v[38:43], 1.0
	global_load_dwordx2 v[42:43], v167, s[62:63] offset:16
	global_load_dwordx4 v[38:41], v167, s[62:63]
	v_pk_mul_f32 v[246:247], v[0:1], v[96:97]
	v_pk_mul_f32 v[254:255], v[2:3], v[98:99]
	v_pk_mul_f32 v[160:161], v[4:5], v[100:101]
	v_pk_fma_f32 v[246:247], v[6:7], v[102:103], v[246:247]
	v_pk_fma_f32 v[254:255], v[8:9], v[104:105], v[254:255]
	v_pk_fma_f32 v[160:161], v[10:11], v[106:107], v[160:161]
	v_pk_fma_f32 v[246:247], v[12:13], v[108:109], v[246:247]
	v_pk_fma_f32 v[254:255], v[14:15], v[110:111], v[254:255]
	v_pk_fma_f32 v[160:161], v[16:17], v[112:113], v[160:161]
	v_pk_fma_f32 v[246:247], v[18:19], v[114:115], v[246:247]
	v_pk_fma_f32 v[254:255], v[20:21], v[116:117], v[254:255]
	v_pk_fma_f32 v[160:161], v[22:23], v[118:119], v[160:161]
	v_pk_fma_f32 v[246:247], v[24:25], v[120:121], v[246:247]
	v_pk_fma_f32 v[254:255], v[26:27], v[122:123], v[254:255]
	v_pk_fma_f32 v[160:161], v[28:29], v[124:125], v[160:161]
	v_pk_fma_f32 v[246:247], v[30:31], v[126:127], v[246:247]
	v_pk_add_f32 v[254:255], v[254:255], v[160:161]
	v_readlane_b32 s54, v92, 22
	v_pk_add_f32 v[246:247], v[246:247], v[254:255]
	v_readlane_b32 s55, v92, 23
	v_add_f32_e32 v164, v246, v247
	s_mul_i32 s0, s54, 0x300
	s_mul_i32 s1, s55, 0x300
	v_add_u32_e32 v167, s0, v195
	s_and_saveexec_b64 s[98:99], s[40:41]
	v_add_u32_e32 v167, s1, v195
	s_mov_b64 exec, s[98:99]
	s_waitcnt vmcnt(32)
; __device__ void peer_gather_phase(const Params& P, int l, bool do_store) {
;     ...
;       for (int pr = 0; pr < 4; ++pr) {
;         v6u_t qv; qv[0] = u6[3 * pr].x; qv[1] = u6[3 * pr].y; qv[2] = u6[3 * pr + 1].x; qv[3] = u6[3 * pr + 1].y; qv[4] = u6[3 * pr + 2].x; qv[5] = u6[3 * pr + 2].y;
;         const v32f_t wv = __builtin_amdgcn_cvt_scalef32_pk32_f32_fp6(qv, 1.0f);
;         f32x2 a2 = f32x2{0.f, 0.f};
; #pragma unroll
;         for (int i = 0; i < 16; ++i) a2 += f32x2{wv[2 * i], wv[2 * i + 1]} * xu[i];
;         float hs = a2.x + a2.y;
;         hs += dpp_row_shr(hs, 1); hs += dpp_row_shr(hs, 2); hs += dpp_row_shr(hs, 4); hs += dpp_row_shr(hs, 8);
;         hs += __builtin_bit_cast(float, __builtin_amdgcn_update_dpp(0, __builtin_bit_cast(int, hs), 0x142, 0xa, 0xf, false));
;         const float da = __builtin_bit_cast(float, __builtin_amdgcn_readlane(__builtin_bit_cast(int, hs), 31));
;         const float db = __builtin_bit_cast(float, __builtin_amdgcn_readlane(__builtin_bit_cast(int, hs), 63));
;         dvec = (lane == kb + 2 * pr) ? da : dvec;
;         dvec = (lane == kb + 2 * pr + 1) ? db : dvec;
	v_cvt_scalef32_pk32_f32_fp6 v[0:31], v[32:37], 1.0
	global_load_dwordx2 v[36:37], v167, s[62:63] offset:16
	global_load_dwordx4 v[32:35], v167, s[62:63]
	v_pk_mul_f32 v[246:247], v[0:1], v[96:97]
	v_pk_mul_f32 v[254:255], v[2:3], v[98:99]
	v_pk_mul_f32 v[160:161], v[4:5], v[100:101]
	v_pk_fma_f32 v[246:247], v[6:7], v[102:103], v[246:247]
	v_pk_fma_f32 v[254:255], v[8:9], v[104:105], v[254:255]
	v_pk_fma_f32 v[160:161], v[10:11], v[106:107], v[160:161]
	v_pk_fma_f32 v[246:247], v[12:13], v[108:109], v[246:247]
	v_pk_fma_f32 v[254:255], v[14:15], v[110:111], v[254:255]
	v_pk_fma_f32 v[160:161], v[16:17], v[112:113], v[160:161]
	v_pk_fma_f32 v[246:247], v[18:19], v[114:115], v[246:247]
	v_pk_fma_f32 v[254:255], v[20:21], v[116:117], v[254:255]
	v_pk_fma_f32 v[160:161], v[22:23], v[118:119], v[160:161]
	v_pk_fma_f32 v[246:247], v[24:25], v[120:121], v[246:247]
	v_pk_fma_f32 v[254:255], v[26:27], v[122:123], v[254:255]
	v_pk_fma_f32 v[160:161], v[28:29], v[124:125], v[160:161]
	v_pk_fma_f32 v[246:247], v[30:31], v[126:127], v[246:247]
	v_pk_add_f32 v[254:255], v[254:255], v[160:161]
	s_nop 0
	v_pk_add_f32 v[246:247], v[246:247], v[254:255]
	s_nop 0
	v_add_f32_e32 v165, v246, v247
	v_add_f32_dpp v162, v162, v162 row_shr:1 row_mask:0xf bank_mask:0xf bound_ctrl:1
	v_add_f32_dpp v163, v163, v163 row_shr:1 row_mask:0xf bank_mask:0xf bound_ctrl:1
	v_add_f32_dpp v164, v164, v164 row_shr:1 row_mask:0xf bank_mask:0xf bound_ctrl:1
	v_add_f32_dpp v165, v165, v165 row_shr:1 row_mask:0xf bank_mask:0xf bound_ctrl:1
	v_add_f32_dpp v162, v162, v162 row_shr:2 row_mask:0xf bank_mask:0xf bound_ctrl:1
	v_add_f32_dpp v163, v163, v163 row_shr:2 row_mask:0xf bank_mask:0xf bound_ctrl:1
	v_add_f32_dpp v164, v164, v164 row_shr:2 row_mask:0xf bank_mask:0xf bound_ctrl:1
	v_add_f32_dpp v165, v165, v165 row_shr:2 row_mask:0xf bank_mask:0xf bound_ctrl:1
	v_add_f32_dpp v162, v162, v162 row_shr:4 row_mask:0xf bank_mask:0xf bound_ctrl:1
	v_add_f32_dpp v163, v163, v163 row_shr:4 row_mask:0xf bank_mask:0xf bound_ctrl:1
	v_add_f32_dpp v164, v164, v164 row_shr:4 row_mask:0xf bank_mask:0xf bound_ctrl:1
	v_add_f32_dpp v165, v165, v165 row_shr:4 row_mask:0xf bank_mask:0xf bound_ctrl:1
	v_add_f32_dpp v162, v162, v162 row_shr:8 row_mask:0xf bank_mask:0xf bound_ctrl:1
	v_add_f32_dpp v163, v163, v163 row_shr:8 row_mask:0xf bank_mask:0xf bound_ctrl:1
	v_add_f32_dpp v164, v164, v164 row_shr:8 row_mask:0xf bank_mask:0xf bound_ctrl:1
	v_add_f32_dpp v165, v165, v165 row_shr:8 row_mask:0xf bank_mask:0xf bound_ctrl:1
	v_add_f32_dpp v162, v162, v162 row_bcast:15 row_mask:0xa bank_mask:0xf
	v_add_f32_dpp v163, v163, v163 row_bcast:15 row_mask:0xa bank_mask:0xf
	v_add_f32_dpp v164, v164, v164 row_bcast:15 row_mask:0xa bank_mask:0xf
	v_add_f32_dpp v165, v165, v165 row_bcast:15 row_mask:0xa bank_mask:0xf
	s_nop 1
	v_readlane_b32 s46, v162, 31
	v_readlane_b32 s47, v162, 63
	v_readlane_b32 s48, v163, 31
	v_readlane_b32 s49, v163, 63
	v_readlane_b32 s50, v164, 31
	v_readlane_b32 s51, v164, 63
	v_readlane_b32 s52, v165, 31
	v_readlane_b32 s53, v165, 63
	v_writelane_b32 v166, s46, 0
	s_nop 1
	v_writelane_b32 v166, s47, 1
	v_writelane_b32 v166, s48, 2
	v_writelane_b32 v166, s49, 3
	v_writelane_b32 v166, s50, 4
	v_writelane_b32 v166, s51, 5
	v_writelane_b32 v166, s52, 6
	v_writelane_b32 v166, s53, 7
	v_readlane_b32 s54, v92, 24
	v_readlane_b32 s55, v92, 25
	s_mul_i32 s0, s54, 0x300
	s_mul_i32 s1, s55, 0x300
	v_add_u32_e32 v167, s0, v195
	s_and_saveexec_b64 s[98:99], s[40:41]
	v_add_u32_e32 v167, s1, v195
	s_mov_b64 exec, s[98:99]
	s_waitcnt vmcnt(32)
	v_cvt_scalef32_pk32_f32_fp6 v[0:31], v[196:201], 1.0
	global_load_dwordx2 v[200:201], v167, s[62:63] offset:16
	global_load_dwordx4 v[196:199], v167, s[62:63]
	v_pk_mul_f32 v[246:247], v[0:1], v[96:97]
	v_pk_mul_f32 v[254:255], v[2:3], v[98:99]
	v_pk_mul_f32 v[160:161], v[4:5], v[100:101]
	v_pk_fma_f32 v[246:247], v[6:7], v[102:103], v[246:247]
	v_pk_fma_f32 v[254:255], v[8:9], v[104:105], v[254:255]
	v_pk_fma_f32 v[160:161], v[10:11], v[106:107], v[160:161]
	v_pk_fma_f32 v[246:247], v[12:13], v[108:109], v[246:247]
	v_pk_fma_f32 v[254:255], v[14:15], v[110:111], v[254:255]
	v_pk_fma_f32 v[160:161], v[16:17], v[112:113], v[160:161]
	v_pk_fma_f32 v[246:247], v[18:19], v[114:115], v[246:247]
	v_pk_fma_f32 v[254:255], v[20:21], v[116:117], v[254:255]
	v_pk_fma_f32 v[160:161], v[22:23], v[118:119], v[160:161]
	v_pk_fma_f32 v[246:247], v[24:25], v[120:121], v[246:247]
	v_pk_fma_f32 v[254:255], v[26:27], v[122:123], v[254:255]
	v_pk_fma_f32 v[160:161], v[28:29], v[124:125], v[160:161]
	v_pk_fma_f32 v[246:247], v[30:31], v[126:127], v[246:247]
	v_pk_add_f32 v[254:255], v[254:255], v[160:161]
	v_readlane_b32 s54, v92, 26
	v_pk_add_f32 v[246:247], v[246:247], v[254:255]
	v_readlane_b32 s55, v92, 27
	v_add_f32_e32 v162, v246, v247
	s_mul_i32 s0, s54, 0x300
	s_mul_i32 s1, s55, 0x300
	v_add_u32_e32 v167, s0, v195
	s_and_saveexec_b64 s[98:99], s[40:41]
	v_add_u32_e32 v167, s1, v195
	s_mov_b64 exec, s[98:99]
	s_waitcnt vmcnt(32)
; __device__ void peer_gather_phase(const Params& P, int l, bool do_store) {
;     ...
;       for (int pr = 0; pr < 4; ++pr) {
;         v6u_t qv; qv[0] = u6[3 * pr].x; qv[1] = u6[3 * pr].y; qv[2] = u6[3 * pr + 1].x; qv[3] = u6[3 * pr + 1].y; qv[4] = u6[3 * pr + 2].x; qv[5] = u6[3 * pr + 2].y;
;         const v32f_t wv = __builtin_amdgcn_cvt_scalef32_pk32_f32_fp6(qv, 1.0f);
;         f32x2 a2 = f32x2{0.f, 0.f};
; #pragma unroll
;         for (int i = 0; i < 16; ++i) a2 += f32x2{wv[2 * i], wv[2 * i + 1]} * xu[i];
;         float hs = a2.x + a2.y;
;         hs += dpp_row_shr(hs, 1); hs += dpp_row_shr(hs, 2); hs += dpp_row_shr(hs, 4); hs += dpp_row_shr(hs, 8);
;         hs += __builtin_bit_cast(float, __builtin_amdgcn_update_dpp(0, __builtin_bit_cast(int, hs), 0x142, 0xa, 0xf, false));
;         const float da = __builtin_bit_cast(float, __builtin_amdgcn_readlane(__builtin_bit_cast(int, hs), 31));
;         const float db = __builtin_bit_cast(float, __builtin_amdgcn_readlane(__builtin_bit_cast(int, hs), 63));
;         dvec = (lane == kb + 2 * pr) ? da : dvec;
;         dvec = (lane == kb + 2 * pr + 1) ? db : dvec;
	v_cvt_scalef32_pk32_f32_fp6 v[0:31], v[228:233], 1.0
	global_load_dwordx2 v[232:233], v167, s[62:63] offset:16
	global_load_dwordx4 v[228:231], v167, s[62:63]
	v_pk_mul_f32 v[246:247], v[0:1], v[96:97]
	v_pk_mul_f32 v[254:255], v[2:3], v[98:99]
	v_pk_mul_f32 v[160:161], v[4:5], v[100:101]
	v_pk_fma_f32 v[246:247], v[6:7], v[102:103], v[246:247]
	v_pk_fma_f32 v[254:255], v[8:9], v[104:105], v[254:255]
	v_pk_fma_f32 v[160:161], v[10:11], v[106:107], v[160:161]
	v_pk_fma_f32 v[246:247], v[12:13], v[108:109], v[246:247]
	v_pk_fma_f32 v[254:255], v[14:15], v[110:111], v[254:255]
	v_pk_fma_f32 v[160:161], v[16:17], v[112:113], v[160:161]
	v_pk_fma_f32 v[246:247], v[18:19], v[114:115], v[246:247]
	v_pk_fma_f32 v[254:255], v[20:21], v[116:117], v[254:255]
	v_pk_fma_f32 v[160:161], v[22:23], v[118:119], v[160:161]
	v_pk_fma_f32 v[246:247], v[24:25], v[120:121], v[246:247]
	v_pk_fma_f32 v[254:255], v[26:27], v[122:123], v[254:255]
	v_pk_fma_f32 v[160:161], v[28:29], v[124:125], v[160:161]
	v_pk_fma_f32 v[246:247], v[30:31], v[126:127], v[246:247]
	v_pk_add_f32 v[254:255], v[254:255], v[160:161]
	v_readlane_b32 s54, v92, 28
	v_pk_add_f32 v[246:247], v[246:247], v[254:255]
	v_readlane_b32 s55, v92, 29
	v_add_f32_e32 v163, v246, v247
	s_mul_i32 s0, s54, 0x300
	s_mul_i32 s1, s55, 0x300
	v_add_u32_e32 v167, s0, v195
	s_and_saveexec_b64 s[98:99], s[40:41]
	v_add_u32_e32 v167, s1, v195
	s_mov_b64 exec, s[98:99]
	s_waitcnt vmcnt(32)
	v_cvt_scalef32_pk32_f32_fp6 v[0:31], v[234:239], 1.0
	global_load_dwordx2 v[238:239], v167, s[62:63] offset:16
	global_load_dwordx4 v[234:237], v167, s[62:63]
	v_pk_mul_f32 v[246:247], v[0:1], v[96:97]
	v_pk_mul_f32 v[254:255], v[2:3], v[98:99]
	v_pk_mul_f32 v[160:161], v[4:5], v[100:101]
	v_pk_fma_f32 v[246:247], v[6:7], v[102:103], v[246:247]
	v_pk_fma_f32 v[254:255], v[8:9], v[104:105], v[254:255]
	v_pk_fma_f32 v[160:161], v[10:11], v[106:107], v[160:161]
	v_pk_fma_f32 v[246:247], v[12:13], v[108:109], v[246:247]
	v_pk_fma_f32 v[254:255], v[14:15], v[110:111], v[254:255]
	v_pk_fma_f32 v[160:161], v[16:17], v[112:113], v[160:161]
	v_pk_fma_f32 v[246:247], v[18:19], v[114:115], v[246:247]
	v_pk_fma_f32 v[254:255], v[20:21], v[116:117], v[254:255]
	v_pk_fma_f32 v[160:161], v[22:23], v[118:119], v[160:161]
	v_pk_fma_f32 v[246:247], v[24:25], v[120:121], v[246:247]
	v_pk_fma_f32 v[254:255], v[26:27], v[122:123], v[254:255]
	v_pk_fma_f32 v[160:161], v[28:29], v[124:125], v[160:161]
	v_pk_fma_f32 v[246:247], v[30:31], v[126:127], v[246:247]
	v_pk_add_f32 v[254:255], v[254:255], v[160:161]
	v_readlane_b32 s54, v92, 30
	v_pk_add_f32 v[246:247], v[246:247], v[254:255]
	v_readlane_b32 s55, v92, 31
	v_add_f32_e32 v164, v246, v247
	s_mul_i32 s0, s54, 0x300
	s_mul_i32 s1, s55, 0x300
	v_add_u32_e32 v167, s0, v195
	s_and_saveexec_b64 s[98:99], s[40:41]
	v_add_u32_e32 v167, s1, v195
	s_mov_b64 exec, s[98:99]
	s_waitcnt vmcnt(32)
	v_cvt_scalef32_pk32_f32_fp6 v[0:31], v[240:245], 1.0
	global_load_dwordx2 v[244:245], v167, s[62:63] offset:16
	global_load_dwordx4 v[240:243], v167, s[62:63]
	v_pk_mul_f32 v[246:247], v[0:1], v[96:97]
	v_pk_mul_f32 v[254:255], v[2:3], v[98:99]
	v_pk_mul_f32 v[160:161], v[4:5], v[100:101]
	v_pk_fma_f32 v[246:247], v[6:7], v[102:103], v[246:247]
	v_pk_fma_f32 v[254:255], v[8:9], v[104:105], v[254:255]
	v_pk_fma_f32 v[160:161], v[10:11], v[106:107], v[160:161]
	v_pk_fma_f32 v[246:247], v[12:13], v[108:109], v[246:247]
	v_pk_fma_f32 v[254:255], v[14:15], v[110:111], v[254:255]
	v_pk_fma_f32 v[160:161], v[16:17], v[112:113], v[160:161]
	v_pk_fma_f32 v[246:247], v[18:19], v[114:115], v[246:247]
	v_pk_fma_f32 v[254:255], v[20:21], v[116:117], v[254:255]
	v_pk_fma_f32 v[160:161], v[22:23], v[118:119], v[160:161]
	v_pk_fma_f32 v[246:247], v[24:25], v[120:121], v[246:247]
	v_pk_fma_f32 v[254:255], v[26:27], v[122:123], v[254:255]
	v_pk_fma_f32 v[160:161], v[28:29], v[124:125], v[160:161]
	v_pk_fma_f32 v[246:247], v[30:31], v[126:127], v[246:247]
	v_pk_add_f32 v[254:255], v[254:255], v[160:161]
	s_nop 0
	v_pk_add_f32 v[246:247], v[246:247], v[254:255]
	s_nop 0
	v_add_f32_e32 v165, v246, v247
	v_add_f32_dpp v162, v162, v162 row_shr:1 row_mask:0xf bank_mask:0xf bound_ctrl:1
	v_add_f32_dpp v163, v163, v163 row_shr:1 row_mask:0xf bank_mask:0xf bound_ctrl:1
	v_add_f32_dpp v164, v164, v164 row_shr:1 row_mask:0xf bank_mask:0xf bound_ctrl:1
	v_add_f32_dpp v165, v165, v165 row_shr:1 row_mask:0xf bank_mask:0xf bound_ctrl:1
	v_add_f32_dpp v162, v162, v162 row_shr:2 row_mask:0xf bank_mask:0xf bound_ctrl:1
	v_add_f32_dpp v163, v163, v163 row_shr:2 row_mask:0xf bank_mask:0xf bound_ctrl:1
	v_add_f32_dpp v164, v164, v164 row_shr:2 row_mask:0xf bank_mask:0xf bound_ctrl:1
	v_add_f32_dpp v165, v165, v165 row_shr:2 row_mask:0xf bank_mask:0xf bound_ctrl:1
	v_add_f32_dpp v162, v162, v162 row_shr:4 row_mask:0xf bank_mask:0xf bound_ctrl:1
	v_add_f32_dpp v163, v163, v163 row_shr:4 row_mask:0xf bank_mask:0xf bound_ctrl:1
	v_add_f32_dpp v164, v164, v164 row_shr:4 row_mask:0xf bank_mask:0xf bound_ctrl:1
	v_add_f32_dpp v165, v165, v165 row_shr:4 row_mask:0xf bank_mask:0xf bound_ctrl:1
	v_add_f32_dpp v162, v162, v162 row_shr:8 row_mask:0xf bank_mask:0xf bound_ctrl:1
	v_add_f32_dpp v163, v163, v163 row_shr:8 row_mask:0xf bank_mask:0xf bound_ctrl:1
	v_add_f32_dpp v164, v164, v164 row_shr:8 row_mask:0xf bank_mask:0xf bound_ctrl:1
	v_add_f32_dpp v165, v165, v165 row_shr:8 row_mask:0xf bank_mask:0xf bound_ctrl:1
	v_add_f32_dpp v162, v162, v162 row_bcast:15 row_mask:0xa bank_mask:0xf
	v_add_f32_dpp v163, v163, v163 row_bcast:15 row_mask:0xa bank_mask:0xf
	v_add_f32_dpp v164, v164, v164 row_bcast:15 row_mask:0xa bank_mask:0xf
	v_add_f32_dpp v165, v165, v165 row_bcast:15 row_mask:0xa bank_mask:0xf
	s_nop 1
	v_readlane_b32 s46, v162, 31
	v_readlane_b32 s47, v162, 63
	v_readlane_b32 s48, v163, 31
	v_readlane_b32 s49, v163, 63
	v_readlane_b32 s50, v164, 31
	v_readlane_b32 s51, v164, 63
	v_readlane_b32 s52, v165, 31
	v_readlane_b32 s53, v165, 63
	v_writelane_b32 v166, s46, 8
	s_nop 1
	v_writelane_b32 v166, s47, 9
	v_writelane_b32 v166, s48, 10
	v_writelane_b32 v166, s49, 11
	v_writelane_b32 v166, s50, 12
	v_writelane_b32 v166, s51, 13
	v_writelane_b32 v166, s52, 14
	v_writelane_b32 v166, s53, 15
	v_readlane_b32 s54, v92, 32
	v_readlane_b32 s55, v92, 33
	s_mul_i32 s0, s54, 0x300
	s_mul_i32 s1, s55, 0x300
	v_add_u32_e32 v167, s0, v195
	s_and_saveexec_b64 s[98:99], s[40:41]
	v_add_u32_e32 v167, s1, v195
	s_mov_b64 exec, s[98:99]
	s_waitcnt vmcnt(14)
; __device__ void peer_gather_phase(const Params& P, int l, bool do_store) {
;     ...
;         const int ea = __builtin_amdgcn_readlane(evs, kb + 2 * pr), eb = __builtin_amdgcn_readlane(evs, kb + 2 * pr + 1);
;         const uint2* up = (const uint2*)(U + (size_t)(uphi ? eb : ea) * 768);
;         u6[3 * pr] = up[0]; u6[3 * pr + 1] = up[1]; u6[3 * pr + 2] = up[2];
;     ...
;         v6u_t qv; qv[0] = u6[3 * pr].x; qv[1] = u6[3 * pr].y; qv[2] = u6[3 * pr + 1].x; qv[3] = u6[3 * pr + 1].y; qv[4] = u6[3 * pr + 2].x; qv[5] = u6[3 * pr + 2].y;
;         const v32f_t wv = __builtin_amdgcn_cvt_scalef32_pk32_f32_fp6(qv, 1.0f);
;         f32x2 a2 = f32x2{0.f, 0.f};
; #pragma unroll
;         for (int i = 0; i < 16; ++i) a2 += f32x2{wv[2 * i], wv[2 * i + 1]} * xu[i];
;         float hs = a2.x + a2.y;
	v_cvt_scalef32_pk32_f32_fp6 v[0:31], v[50:55], 1.0
	global_load_dwordx2 v[54:55], v167, s[62:63] offset:16
	global_load_dwordx4 v[50:53], v167, s[62:63]
	v_pk_mul_f32 v[246:247], v[0:1], v[96:97]
	v_pk_mul_f32 v[254:255], v[2:3], v[98:99]
	v_pk_mul_f32 v[160:161], v[4:5], v[100:101]
	v_pk_fma_f32 v[246:247], v[6:7], v[102:103], v[246:247]
	v_pk_fma_f32 v[254:255], v[8:9], v[104:105], v[254:255]
	v_pk_fma_f32 v[160:161], v[10:11], v[106:107], v[160:161]
	v_pk_fma_f32 v[246:247], v[12:13], v[108:109], v[246:247]
	v_pk_fma_f32 v[254:255], v[14:15], v[110:111], v[254:255]
	v_pk_fma_f32 v[160:161], v[16:17], v[112:113], v[160:161]
	v_pk_fma_f32 v[246:247], v[18:19], v[114:115], v[246:247]
	v_pk_fma_f32 v[254:255], v[20:21], v[116:117], v[254:255]
	v_pk_fma_f32 v[160:161], v[22:23], v[118:119], v[160:161]
	v_pk_fma_f32 v[246:247], v[24:25], v[120:121], v[246:247]
	v_pk_fma_f32 v[254:255], v[26:27], v[122:123], v[254:255]
	v_pk_fma_f32 v[160:161], v[28:29], v[124:125], v[160:161]
	v_pk_fma_f32 v[246:247], v[30:31], v[126:127], v[246:247]
	v_pk_add_f32 v[254:255], v[254:255], v[160:161]
	v_readlane_b32 s54, v92, 34
	v_pk_add_f32 v[246:247], v[246:247], v[254:255]
	v_readlane_b32 s55, v92, 35
	v_add_f32_e32 v162, v246, v247
	s_mul_i32 s0, s54, 0x300
	s_mul_i32 s1, s55, 0x300
	v_add_u32_e32 v167, s0, v195
	s_and_saveexec_b64 s[98:99], s[40:41]
	v_add_u32_e32 v167, s1, v195
	s_mov_b64 exec, s[98:99]
	s_waitcnt vmcnt(14)
	v_cvt_scalef32_pk32_f32_fp6 v[0:31], v[44:49], 1.0
	global_load_dwordx2 v[48:49], v167, s[62:63] offset:16
	global_load_dwordx4 v[44:47], v167, s[62:63]
	v_pk_mul_f32 v[246:247], v[0:1], v[96:97]
	v_pk_mul_f32 v[254:255], v[2:3], v[98:99]
	v_pk_mul_f32 v[160:161], v[4:5], v[100:101]
	v_pk_fma_f32 v[246:247], v[6:7], v[102:103], v[246:247]
	v_pk_fma_f32 v[254:255], v[8:9], v[104:105], v[254:255]
	v_pk_fma_f32 v[160:161], v[10:11], v[106:107], v[160:161]
	v_pk_fma_f32 v[246:247], v[12:13], v[108:109], v[246:247]
	v_pk_fma_f32 v[254:255], v[14:15], v[110:111], v[254:255]
	v_pk_fma_f32 v[160:161], v[16:17], v[112:113], v[160:161]
	v_pk_fma_f32 v[246:247], v[18:19], v[114:115], v[246:247]
	v_pk_fma_f32 v[254:255], v[20:21], v[116:117], v[254:255]
	v_pk_fma_f32 v[160:161], v[22:23], v[118:119], v[160:161]
	v_pk_fma_f32 v[246:247], v[24:25], v[120:121], v[246:247]
	v_pk_fma_f32 v[254:255], v[26:27], v[122:123], v[254:255]
	v_pk_fma_f32 v[160:161], v[28:29], v[124:125], v[160:161]
	v_pk_fma_f32 v[246:247], v[30:31], v[126:127], v[246:247]
	v_pk_add_f32 v[254:255], v[254:255], v[160:161]
	v_readlane_b32 s54, v92, 36
	v_pk_add_f32 v[246:247], v[246:247], v[254:255]
	v_readlane_b32 s55, v92, 37
	v_add_f32_e32 v163, v246, v247
	s_mul_i32 s0, s54, 0x300
	s_mul_i32 s1, s55, 0x300
	v_add_u32_e32 v167, s0, v195
	s_and_saveexec_b64 s[98:99], s[40:41]
	v_add_u32_e32 v167, s1, v195
	s_mov_b64 exec, s[98:99]
	s_waitcnt vmcnt(14)
	v_cvt_scalef32_pk32_f32_fp6 v[0:31], v[38:43], 1.0
	global_load_dwordx2 v[42:43], v167, s[62:63] offset:16
	global_load_dwordx4 v[38:41], v167, s[62:63]
	v_pk_mul_f32 v[246:247], v[0:1], v[96:97]
	v_pk_mul_f32 v[254:255], v[2:3], v[98:99]
	v_pk_mul_f32 v[160:161], v[4:5], v[100:101]
	v_pk_fma_f32 v[246:247], v[6:7], v[102:103], v[246:247]
	v_pk_fma_f32 v[254:255], v[8:9], v[104:105], v[254:255]
	v_pk_fma_f32 v[160:161], v[10:11], v[106:107], v[160:161]
	v_pk_fma_f32 v[246:247], v[12:13], v[108:109], v[246:247]
	v_pk_fma_f32 v[254:255], v[14:15], v[110:111], v[254:255]
	v_pk_fma_f32 v[160:161], v[16:17], v[112:113], v[160:161]
	v_pk_fma_f32 v[246:247], v[18:19], v[114:115], v[246:247]
	v_pk_fma_f32 v[254:255], v[20:21], v[116:117], v[254:255]
	v_pk_fma_f32 v[160:161], v[22:23], v[118:119], v[160:161]
	v_pk_fma_f32 v[246:247], v[24:25], v[120:121], v[246:247]
	v_pk_fma_f32 v[254:255], v[26:27], v[122:123], v[254:255]
	v_pk_fma_f32 v[160:161], v[28:29], v[124:125], v[160:161]
	v_pk_fma_f32 v[246:247], v[30:31], v[126:127], v[246:247]
	v_pk_add_f32 v[254:255], v[254:255], v[160:161]
	v_readlane_b32 s54, v92, 38
	v_pk_add_f32 v[246:247], v[246:247], v[254:255]
	v_readlane_b32 s55, v92, 39
	v_add_f32_e32 v164, v246, v247
	s_mul_i32 s0, s54, 0x300
	s_mul_i32 s1, s55, 0x300
	v_add_u32_e32 v167, s0, v195
	s_and_saveexec_b64 s[98:99], s[40:41]
	v_add_u32_e32 v167, s1, v195
	s_mov_b64 exec, s[98:99]
	s_waitcnt vmcnt(14)
; __device__ void peer_gather_phase(const Params& P, int l, bool do_store) {
;     ...
;         const int ea = __builtin_amdgcn_readlane(evs, kb + 2 * pr), eb = __builtin_amdgcn_readlane(evs, kb + 2 * pr + 1);
;         const uint2* up = (const uint2*)(U + (size_t)(uphi ? eb : ea) * 768);
;         u6[3 * pr] = up[0]; u6[3 * pr + 1] = up[1]; u6[3 * pr + 2] = up[2];
;     ...
;         v6u_t qv; qv[0] = u6[3 * pr].x; qv[1] = u6[3 * pr].y; qv[2] = u6[3 * pr + 1].x; qv[3] = u6[3 * pr + 1].y; qv[4] = u6[3 * pr + 2].x; qv[5] = u6[3 * pr + 2].y;
;         const v32f_t wv = __builtin_amdgcn_cvt_scalef32_pk32_f32_fp6(qv, 1.0f);
;         f32x2 a2 = f32x2{0.f, 0.f};
; #pragma unroll
;         for (int i = 0; i < 16; ++i) a2 += f32x2{wv[2 * i], wv[2 * i + 1]} * xu[i];
;         float hs = a2.x + a2.y;
;         hs += dpp_row_shr(hs, 1); hs += dpp_row_shr(hs, 2); hs += dpp_row_shr(hs, 4); hs += dpp_row_shr(hs, 8);
;         hs += __builtin_bit_cast(float, __builtin_amdgcn_update_dpp(0, __builtin_bit_cast(int, hs), 0x142, 0xa, 0xf, false));
;         const float da = __builtin_bit_cast(float, __builtin_amdgcn_readlane(__builtin_bit_cast(int, hs), 31));
;         const float db = __builtin_bit_cast(float, __builtin_amdgcn_readlane(__builtin_bit_cast(int, hs), 63));
;         dvec = (lane == kb + 2 * pr) ? da : dvec;
;         dvec = (lane == kb + 2 * pr + 1) ? db : dvec;
	v_cvt_scalef32_pk32_f32_fp6 v[0:31], v[32:37], 1.0
	global_load_dwordx2 v[36:37], v167, s[62:63] offset:16
	global_load_dwordx4 v[32:35], v167, s[62:63]
	v_pk_mul_f32 v[246:247], v[0:1], v[96:97]
	v_pk_mul_f32 v[254:255], v[2:3], v[98:99]
	v_pk_mul_f32 v[160:161], v[4:5], v[100:101]
	v_pk_fma_f32 v[246:247], v[6:7], v[102:103], v[246:247]
	v_pk_fma_f32 v[254:255], v[8:9], v[104:105], v[254:255]
	v_pk_fma_f32 v[160:161], v[10:11], v[106:107], v[160:161]
	v_pk_fma_f32 v[246:247], v[12:13], v[108:109], v[246:247]
	v_pk_fma_f32 v[254:255], v[14:15], v[110:111], v[254:255]
	v_pk_fma_f32 v[160:161], v[16:17], v[112:113], v[160:161]
	v_pk_fma_f32 v[246:247], v[18:19], v[114:115], v[246:247]
	v_pk_fma_f32 v[254:255], v[20:21], v[116:117], v[254:255]
	v_pk_fma_f32 v[160:161], v[22:23], v[118:119], v[160:161]
	v_pk_fma_f32 v[246:247], v[24:25], v[120:121], v[246:247]
	v_pk_fma_f32 v[254:255], v[26:27], v[122:123], v[254:255]
	v_pk_fma_f32 v[160:161], v[28:29], v[124:125], v[160:161]
	v_pk_fma_f32 v[246:247], v[30:31], v[126:127], v[246:247]
	v_pk_add_f32 v[254:255], v[254:255], v[160:161]
	s_nop 0
	v_pk_add_f32 v[246:247], v[246:247], v[254:255]
	s_nop 0
	v_add_f32_e32 v165, v246, v247
	v_add_f32_dpp v162, v162, v162 row_shr:1 row_mask:0xf bank_mask:0xf bound_ctrl:1
	v_add_f32_dpp v163, v163, v163 row_shr:1 row_mask:0xf bank_mask:0xf bound_ctrl:1
	v_add_f32_dpp v164, v164, v164 row_shr:1 row_mask:0xf bank_mask:0xf bound_ctrl:1
	v_add_f32_dpp v165, v165, v165 row_shr:1 row_mask:0xf bank_mask:0xf bound_ctrl:1
	v_add_f32_dpp v162, v162, v162 row_shr:2 row_mask:0xf bank_mask:0xf bound_ctrl:1
	v_add_f32_dpp v163, v163, v163 row_shr:2 row_mask:0xf bank_mask:0xf bound_ctrl:1
	v_add_f32_dpp v164, v164, v164 row_shr:2 row_mask:0xf bank_mask:0xf bound_ctrl:1
	v_add_f32_dpp v165, v165, v165 row_shr:2 row_mask:0xf bank_mask:0xf bound_ctrl:1
	v_add_f32_dpp v162, v162, v162 row_shr:4 row_mask:0xf bank_mask:0xf bound_ctrl:1
	v_add_f32_dpp v163, v163, v163 row_shr:4 row_mask:0xf bank_mask:0xf bound_ctrl:1
	v_add_f32_dpp v164, v164, v164 row_shr:4 row_mask:0xf bank_mask:0xf bound_ctrl:1
	v_add_f32_dpp v165, v165, v165 row_shr:4 row_mask:0xf bank_mask:0xf bound_ctrl:1
	v_add_f32_dpp v162, v162, v162 row_shr:8 row_mask:0xf bank_mask:0xf bound_ctrl:1
	v_add_f32_dpp v163, v163, v163 row_shr:8 row_mask:0xf bank_mask:0xf bound_ctrl:1
	v_add_f32_dpp v164, v164, v164 row_shr:8 row_mask:0xf bank_mask:0xf bound_ctrl:1
	v_add_f32_dpp v165, v165, v165 row_shr:8 row_mask:0xf bank_mask:0xf bound_ctrl:1
	v_add_f32_dpp v162, v162, v162 row_bcast:15 row_mask:0xa bank_mask:0xf
	v_add_f32_dpp v163, v163, v163 row_bcast:15 row_mask:0xa bank_mask:0xf
	v_add_f32_dpp v164, v164, v164 row_bcast:15 row_mask:0xa bank_mask:0xf
	v_add_f32_dpp v165, v165, v165 row_bcast:15 row_mask:0xa bank_mask:0xf
	s_nop 1
	v_readlane_b32 s46, v162, 31
	v_readlane_b32 s47, v162, 63
	v_readlane_b32 s48, v163, 31
	v_readlane_b32 s49, v163, 63
	v_readlane_b32 s50, v164, 31
	v_readlane_b32 s51, v164, 63
	v_readlane_b32 s52, v165, 31
	v_readlane_b32 s53, v165, 63
	v_writelane_b32 v166, s46, 16
	s_nop 1
	v_writelane_b32 v166, s47, 17
	v_writelane_b32 v166, s48, 18
	v_writelane_b32 v166, s49, 19
	v_writelane_b32 v166, s50, 20
	v_writelane_b32 v166, s51, 21
	v_writelane_b32 v166, s52, 22
	v_writelane_b32 v166, s53, 23
	v_readlane_b32 s54, v92, 40
	v_readlane_b32 s55, v92, 41
	s_mul_i32 s0, s54, 0x300
	s_mul_i32 s1, s55, 0x300
	v_add_u32_e32 v167, s0, v195
	s_and_saveexec_b64 s[98:99], s[40:41]
	v_add_u32_e32 v167, s1, v195
	s_mov_b64 exec, s[98:99]
	s_waitcnt vmcnt(14)
	v_cvt_scalef32_pk32_f32_fp6 v[0:31], v[196:201], 1.0
	global_load_dwordx2 v[200:201], v167, s[62:63] offset:16
	global_load_dwordx4 v[196:199], v167, s[62:63]
	v_pk_mul_f32 v[246:247], v[0:1], v[96:97]
	v_pk_mul_f32 v[254:255], v[2:3], v[98:99]
	v_pk_mul_f32 v[160:161], v[4:5], v[100:101]
	v_pk_fma_f32 v[246:247], v[6:7], v[102:103], v[246:247]
	v_pk_fma_f32 v[254:255], v[8:9], v[104:105], v[254:255]
	v_pk_fma_f32 v[160:161], v[10:11], v[106:107], v[160:161]
	v_pk_fma_f32 v[246:247], v[12:13], v[108:109], v[246:247]
	v_pk_fma_f32 v[254:255], v[14:15], v[110:111], v[254:255]
	v_pk_fma_f32 v[160:161], v[16:17], v[112:113], v[160:161]
	v_pk_fma_f32 v[246:247], v[18:19], v[114:115], v[246:247]
	v_pk_fma_f32 v[254:255], v[20:21], v[116:117], v[254:255]
	v_pk_fma_f32 v[160:161], v[22:23], v[118:119], v[160:161]
	v_pk_fma_f32 v[246:247], v[24:25], v[120:121], v[246:247]
	v_pk_fma_f32 v[254:255], v[26:27], v[122:123], v[254:255]
	v_pk_fma_f32 v[160:161], v[28:29], v[124:125], v[160:161]
	v_pk_fma_f32 v[246:247], v[30:31], v[126:127], v[246:247]
	v_pk_add_f32 v[254:255], v[254:255], v[160:161]
	v_readlane_b32 s54, v92, 42
	v_pk_add_f32 v[246:247], v[246:247], v[254:255]
	v_readlane_b32 s55, v92, 43
	v_add_f32_e32 v162, v246, v247
	s_mul_i32 s0, s54, 0x300
	s_mul_i32 s1, s55, 0x300
	v_add_u32_e32 v167, s0, v195
	s_and_saveexec_b64 s[98:99], s[40:41]
	v_add_u32_e32 v167, s1, v195
	s_mov_b64 exec, s[98:99]
	s_waitcnt vmcnt(14)
; __device__ void peer_gather_phase(const Params& P, int l, bool do_store) {
;     ...
;         const int ea = __builtin_amdgcn_readlane(evs, kb + 2 * pr), eb = __builtin_amdgcn_readlane(evs, kb + 2 * pr + 1);
;         const uint2* up = (const uint2*)(U + (size_t)(uphi ? eb : ea) * 768);
;         u6[3 * pr] = up[0]; u6[3 * pr + 1] = up[1]; u6[3 * pr + 2] = up[2];
;     ...
;         v6u_t qv; qv[0] = u6[3 * pr].x; qv[1] = u6[3 * pr].y; qv[2] = u6[3 * pr + 1].x; qv[3] = u6[3 * pr + 1].y; qv[4] = u6[3 * pr + 2].x; qv[5] = u6[3 * pr + 2].y;
;         const v32f_t wv = __builtin_amdgcn_cvt_scalef32_pk32_f32_fp6(qv, 1.0f);
;         f32x2 a2 = f32x2{0.f, 0.f};
; #pragma unroll
;         for (int i = 0; i < 16; ++i) a2 += f32x2{wv[2 * i], wv[2 * i + 1]} * xu[i];
;         float hs = a2.x + a2.y;
;         hs += dpp_row_shr(hs, 1); hs += dpp_row_shr(hs, 2); hs += dpp_row_shr(hs, 4); hs += dpp_row_shr(hs, 8);
;         hs += __builtin_bit_cast(float, __builtin_amdgcn_update_dpp(0, __builtin_bit_cast(int, hs), 0x142, 0xa, 0xf, false));
;         const float da = __builtin_bit_cast(float, __builtin_amdgcn_readlane(__builtin_bit_cast(int, hs), 31));
;         const float db = __builtin_bit_cast(float, __builtin_amdgcn_readlane(__builtin_bit_cast(int, hs), 63));
;         dvec = (lane == kb + 2 * pr) ? da : dvec;
;         dvec = (lane == kb + 2 * pr + 1) ? db : dvec;
	v_cvt_scalef32_pk32_f32_fp6 v[0:31], v[228:233], 1.0
	global_load_dwordx2 v[232:233], v167, s[62:63] offset:16
	global_load_dwordx4 v[228:231], v167, s[62:63]
	v_pk_mul_f32 v[246:247], v[0:1], v[96:97]
	v_pk_mul_f32 v[254:255], v[2:3], v[98:99]
	v_pk_mul_f32 v[160:161], v[4:5], v[100:101]
	v_pk_fma_f32 v[246:247], v[6:7], v[102:103], v[246:247]
	v_pk_fma_f32 v[254:255], v[8:9], v[104:105], v[254:255]
	v_pk_fma_f32 v[160:161], v[10:11], v[106:107], v[160:161]
	v_pk_fma_f32 v[246:247], v[12:13], v[108:109], v[246:247]
	v_pk_fma_f32 v[254:255], v[14:15], v[110:111], v[254:255]
	v_pk_fma_f32 v[160:161], v[16:17], v[112:113], v[160:161]
	v_pk_fma_f32 v[246:247], v[18:19], v[114:115], v[246:247]
	v_pk_fma_f32 v[254:255], v[20:21], v[116:117], v[254:255]
	v_pk_fma_f32 v[160:161], v[22:23], v[118:119], v[160:161]
	v_pk_fma_f32 v[246:247], v[24:25], v[120:121], v[246:247]
	v_pk_fma_f32 v[254:255], v[26:27], v[122:123], v[254:255]
	v_pk_fma_f32 v[160:161], v[28:29], v[124:125], v[160:161]
	v_pk_fma_f32 v[246:247], v[30:31], v[126:127], v[246:247]
	v_pk_add_f32 v[254:255], v[254:255], v[160:161]
	v_readlane_b32 s54, v92, 44
	v_pk_add_f32 v[246:247], v[246:247], v[254:255]
	v_readlane_b32 s55, v92, 45
	v_add_f32_e32 v163, v246, v247
	s_mul_i32 s0, s54, 0x300
	s_mul_i32 s1, s55, 0x300
	v_add_u32_e32 v167, s0, v195
	s_and_saveexec_b64 s[98:99], s[40:41]
	v_add_u32_e32 v167, s1, v195
	s_mov_b64 exec, s[98:99]
	s_waitcnt vmcnt(14)
	v_cvt_scalef32_pk32_f32_fp6 v[0:31], v[234:239], 1.0
	global_load_dwordx2 v[238:239], v167, s[62:63] offset:16
	global_load_dwordx4 v[234:237], v167, s[62:63]
	v_pk_mul_f32 v[246:247], v[0:1], v[96:97]
	v_pk_mul_f32 v[254:255], v[2:3], v[98:99]
	v_pk_mul_f32 v[160:161], v[4:5], v[100:101]
	v_pk_fma_f32 v[246:247], v[6:7], v[102:103], v[246:247]
	v_pk_fma_f32 v[254:255], v[8:9], v[104:105], v[254:255]
	v_pk_fma_f32 v[160:161], v[10:11], v[106:107], v[160:161]
	v_pk_fma_f32 v[246:247], v[12:13], v[108:109], v[246:247]
	v_pk_fma_f32 v[254:255], v[14:15], v[110:111], v[254:255]
	v_pk_fma_f32 v[160:161], v[16:17], v[112:113], v[160:161]
	v_pk_fma_f32 v[246:247], v[18:19], v[114:115], v[246:247]
	v_pk_fma_f32 v[254:255], v[20:21], v[116:117], v[254:255]
	v_pk_fma_f32 v[160:161], v[22:23], v[118:119], v[160:161]
	v_pk_fma_f32 v[246:247], v[24:25], v[120:121], v[246:247]
	v_pk_fma_f32 v[254:255], v[26:27], v[122:123], v[254:255]
	v_pk_fma_f32 v[160:161], v[28:29], v[124:125], v[160:161]
	v_pk_fma_f32 v[246:247], v[30:31], v[126:127], v[246:247]
	v_pk_add_f32 v[254:255], v[254:255], v[160:161]
	v_readlane_b32 s54, v92, 46
	v_pk_add_f32 v[246:247], v[246:247], v[254:255]
	v_readlane_b32 s55, v92, 47
	v_add_f32_e32 v164, v246, v247
	s_mul_i32 s0, s54, 0x300
	s_mul_i32 s1, s55, 0x300
	v_add_u32_e32 v167, s0, v195
	s_and_saveexec_b64 s[98:99], s[40:41]
	v_add_u32_e32 v167, s1, v195
	s_mov_b64 exec, s[98:99]
	s_waitcnt vmcnt(14)
	v_cvt_scalef32_pk32_f32_fp6 v[0:31], v[240:245], 1.0
	global_load_dwordx2 v[244:245], v167, s[62:63] offset:16
	global_load_dwordx4 v[240:243], v167, s[62:63]
	v_pk_mul_f32 v[246:247], v[0:1], v[96:97]
	v_pk_mul_f32 v[254:255], v[2:3], v[98:99]
	v_pk_mul_f32 v[160:161], v[4:5], v[100:101]
	v_pk_fma_f32 v[246:247], v[6:7], v[102:103], v[246:247]
	v_pk_fma_f32 v[254:255], v[8:9], v[104:105], v[254:255]
	v_pk_fma_f32 v[160:161], v[10:11], v[106:107], v[160:161]
	v_pk_fma_f32 v[246:247], v[12:13], v[108:109], v[246:247]
	v_pk_fma_f32 v[254:255], v[14:15], v[110:111], v[254:255]
	v_pk_fma_f32 v[160:161], v[16:17], v[112:113], v[160:161]
	v_pk_fma_f32 v[246:247], v[18:19], v[114:115], v[246:247]
	v_pk_fma_f32 v[254:255], v[20:21], v[116:117], v[254:255]
	v_pk_fma_f32 v[160:161], v[22:23], v[118:119], v[160:161]
	v_pk_fma_f32 v[246:247], v[24:25], v[120:121], v[246:247]
	v_pk_fma_f32 v[254:255], v[26:27], v[122:123], v[254:255]
	v_pk_fma_f32 v[160:161], v[28:29], v[124:125], v[160:161]
	v_pk_fma_f32 v[246:247], v[30:31], v[126:127], v[246:247]
	v_pk_add_f32 v[254:255], v[254:255], v[160:161]
	s_nop 0
	v_pk_add_f32 v[246:247], v[246:247], v[254:255]
	s_nop 0
	v_add_f32_e32 v165, v246, v247
	v_add_f32_dpp v162, v162, v162 row_shr:1 row_mask:0xf bank_mask:0xf bound_ctrl:1
	v_add_f32_dpp v163, v163, v163 row_shr:1 row_mask:0xf bank_mask:0xf bound_ctrl:1
	v_add_f32_dpp v164, v164, v164 row_shr:1 row_mask:0xf bank_mask:0xf bound_ctrl:1
	v_add_f32_dpp v165, v165, v165 row_shr:1 row_mask:0xf bank_mask:0xf bound_ctrl:1
	v_add_f32_dpp v162, v162, v162 row_shr:2 row_mask:0xf bank_mask:0xf bound_ctrl:1
	v_add_f32_dpp v163, v163, v163 row_shr:2 row_mask:0xf bank_mask:0xf bound_ctrl:1
	v_add_f32_dpp v164, v164, v164 row_shr:2 row_mask:0xf bank_mask:0xf bound_ctrl:1
	v_add_f32_dpp v165, v165, v165 row_shr:2 row_mask:0xf bank_mask:0xf bound_ctrl:1
	v_add_f32_dpp v162, v162, v162 row_shr:4 row_mask:0xf bank_mask:0xf bound_ctrl:1
	v_add_f32_dpp v163, v163, v163 row_shr:4 row_mask:0xf bank_mask:0xf bound_ctrl:1
	v_add_f32_dpp v164, v164, v164 row_shr:4 row_mask:0xf bank_mask:0xf bound_ctrl:1
	v_add_f32_dpp v165, v165, v165 row_shr:4 row_mask:0xf bank_mask:0xf bound_ctrl:1
	v_add_f32_dpp v162, v162, v162 row_shr:8 row_mask:0xf bank_mask:0xf bound_ctrl:1
	v_add_f32_dpp v163, v163, v163 row_shr:8 row_mask:0xf bank_mask:0xf bound_ctrl:1
	v_add_f32_dpp v164, v164, v164 row_shr:8 row_mask:0xf bank_mask:0xf bound_ctrl:1
	v_add_f32_dpp v165, v165, v165 row_shr:8 row_mask:0xf bank_mask:0xf bound_ctrl:1
	v_add_f32_dpp v162, v162, v162 row_bcast:15 row_mask:0xa bank_mask:0xf
	v_add_f32_dpp v163, v163, v163 row_bcast:15 row_mask:0xa bank_mask:0xf
	v_add_f32_dpp v164, v164, v164 row_bcast:15 row_mask:0xa bank_mask:0xf
	v_add_f32_dpp v165, v165, v165 row_bcast:15 row_mask:0xa bank_mask:0xf
	s_nop 1
	v_readlane_b32 s46, v162, 31
	v_readlane_b32 s47, v162, 63
	v_readlane_b32 s48, v163, 31
	v_readlane_b32 s49, v163, 63
	v_readlane_b32 s50, v164, 31
	v_readlane_b32 s51, v164, 63
	v_readlane_b32 s52, v165, 31
	v_readlane_b32 s53, v165, 63
	v_writelane_b32 v166, s46, 24
	s_nop 1
	v_writelane_b32 v166, s47, 25
	v_writelane_b32 v166, s48, 26
	v_writelane_b32 v166, s49, 27
	v_writelane_b32 v166, s50, 28
	v_writelane_b32 v166, s51, 29
	v_writelane_b32 v166, s52, 30
	v_writelane_b32 v166, s53, 31
	v_readlane_b32 s54, v92, 48
	v_readlane_b32 s55, v92, 49
	s_mul_i32 s0, s54, 0x300
	s_mul_i32 s1, s55, 0x300
	v_add_u32_e32 v167, s0, v195
	s_and_saveexec_b64 s[98:99], s[40:41]
	v_add_u32_e32 v167, s1, v195
	s_mov_b64 exec, s[98:99]
	s_waitcnt vmcnt(14)
; __device__ void peer_gather_phase(const Params& P, int l, bool do_store) {
;     ...
;         const int ea = __builtin_amdgcn_readlane(evs, kb + 2 * pr), eb = __builtin_amdgcn_readlane(evs, kb + 2 * pr + 1);
;         const uint2* up = (const uint2*)(U + (size_t)(uphi ? eb : ea) * 768);
;         u6[3 * pr] = up[0]; u6[3 * pr + 1] = up[1]; u6[3 * pr + 2] = up[2];
;     ...
;         v6u_t qv; qv[0] = u6[3 * pr].x; qv[1] = u6[3 * pr].y; qv[2] = u6[3 * pr + 1].x; qv[3] = u6[3 * pr + 1].y; qv[4] = u6[3 * pr + 2].x; qv[5] = u6[3 * pr + 2].y;
;         const v32f_t wv = __builtin_amdgcn_cvt_scalef32_pk32_f32_fp6(qv, 1.0f);
;         f32x2 a2 = f32x2{0.f, 0.f};
; #pragma unroll
;         for (int i = 0; i < 16; ++i) a2 += f32x2{wv[2 * i], wv[2 * i + 1]} * xu[i];
;         float hs = a2.x + a2.y;
	v_cvt_scalef32_pk32_f32_fp6 v[0:31], v[50:55], 1.0
	global_load_dwordx2 v[54:55], v167, s[62:63] offset:16
	global_load_dwordx4 v[50:53], v167, s[62:63]
	v_pk_mul_f32 v[246:247], v[0:1], v[96:97]
	v_pk_mul_f32 v[254:255], v[2:3], v[98:99]
	v_pk_mul_f32 v[160:161], v[4:5], v[100:101]
	v_pk_fma_f32 v[246:247], v[6:7], v[102:103], v[246:247]
	v_pk_fma_f32 v[254:255], v[8:9], v[104:105], v[254:255]
	v_pk_fma_f32 v[160:161], v[10:11], v[106:107], v[160:161]
	v_pk_fma_f32 v[246:247], v[12:13], v[108:109], v[246:247]
	v_pk_fma_f32 v[254:255], v[14:15], v[110:111], v[254:255]
	v_pk_fma_f32 v[160:161], v[16:17], v[112:113], v[160:161]
	v_pk_fma_f32 v[246:247], v[18:19], v[114:115], v[246:247]
	v_pk_fma_f32 v[254:255], v[20:21], v[116:117], v[254:255]
	v_pk_fma_f32 v[160:161], v[22:23], v[118:119], v[160:161]
	v_pk_fma_f32 v[246:247], v[24:25], v[120:121], v[246:247]
	v_pk_fma_f32 v[254:255], v[26:27], v[122:123], v[254:255]
	v_pk_fma_f32 v[160:161], v[28:29], v[124:125], v[160:161]
	v_pk_fma_f32 v[246:247], v[30:31], v[126:127], v[246:247]
	v_pk_add_f32 v[254:255], v[254:255], v[160:161]
	v_readlane_b32 s54, v92, 50
	v_pk_add_f32 v[246:247], v[246:247], v[254:255]
	v_readlane_b32 s55, v92, 51
	v_add_f32_e32 v162, v246, v247
	s_mul_i32 s0, s54, 0x300
	s_mul_i32 s1, s55, 0x300
	v_add_u32_e32 v167, s0, v195
	s_and_saveexec_b64 s[98:99], s[40:41]
	v_add_u32_e32 v167, s1, v195
	s_mov_b64 exec, s[98:99]
	s_waitcnt vmcnt(14)
	v_cvt_scalef32_pk32_f32_fp6 v[0:31], v[44:49], 1.0
	global_load_dwordx2 v[48:49], v167, s[62:63] offset:16
	global_load_dwordx4 v[44:47], v167, s[62:63]
	v_pk_mul_f32 v[246:247], v[0:1], v[96:97]
	v_pk_mul_f32 v[254:255], v[2:3], v[98:99]
	v_pk_mul_f32 v[160:161], v[4:5], v[100:101]
	v_pk_fma_f32 v[246:247], v[6:7], v[102:103], v[246:247]
	v_pk_fma_f32 v[254:255], v[8:9], v[104:105], v[254:255]
	v_pk_fma_f32 v[160:161], v[10:11], v[106:107], v[160:161]
	v_pk_fma_f32 v[246:247], v[12:13], v[108:109], v[246:247]
	v_pk_fma_f32 v[254:255], v[14:15], v[110:111], v[254:255]
	v_pk_fma_f32 v[160:161], v[16:17], v[112:113], v[160:161]
	v_pk_fma_f32 v[246:247], v[18:19], v[114:115], v[246:247]
	v_pk_fma_f32 v[254:255], v[20:21], v[116:117], v[254:255]
	v_pk_fma_f32 v[160:161], v[22:23], v[118:119], v[160:161]
	v_pk_fma_f32 v[246:247], v[24:25], v[120:121], v[246:247]
	v_pk_fma_f32 v[254:255], v[26:27], v[122:123], v[254:255]
	v_pk_fma_f32 v[160:161], v[28:29], v[124:125], v[160:161]
	v_pk_fma_f32 v[246:247], v[30:31], v[126:127], v[246:247]
	v_pk_add_f32 v[254:255], v[254:255], v[160:161]
	v_readlane_b32 s54, v92, 52
	v_pk_add_f32 v[246:247], v[246:247], v[254:255]
	v_readlane_b32 s55, v92, 53
	v_add_f32_e32 v163, v246, v247
	s_mul_i32 s0, s54, 0x300
	s_mul_i32 s1, s55, 0x300
	v_add_u32_e32 v167, s0, v195
	s_and_saveexec_b64 s[98:99], s[40:41]
	v_add_u32_e32 v167, s1, v195
	s_mov_b64 exec, s[98:99]
	s_waitcnt vmcnt(14)
	v_cvt_scalef32_pk32_f32_fp6 v[0:31], v[38:43], 1.0
	global_load_dwordx2 v[42:43], v167, s[62:63] offset:16
	global_load_dwordx4 v[38:41], v167, s[62:63]
	v_pk_mul_f32 v[246:247], v[0:1], v[96:97]
	v_pk_mul_f32 v[254:255], v[2:3], v[98:99]
	v_pk_mul_f32 v[160:161], v[4:5], v[100:101]
	v_pk_fma_f32 v[246:247], v[6:7], v[102:103], v[246:247]
	v_pk_fma_f32 v[254:255], v[8:9], v[104:105], v[254:255]
	v_pk_fma_f32 v[160:161], v[10:11], v[106:107], v[160:161]
	v_pk_fma_f32 v[246:247], v[12:13], v[108:109], v[246:247]
	v_pk_fma_f32 v[254:255], v[14:15], v[110:111], v[254:255]
	v_pk_fma_f32 v[160:161], v[16:17], v[112:113], v[160:161]
	v_pk_fma_f32 v[246:247], v[18:19], v[114:115], v[246:247]
	v_pk_fma_f32 v[254:255], v[20:21], v[116:117], v[254:255]
	v_pk_fma_f32 v[160:161], v[22:23], v[118:119], v[160:161]
	v_pk_fma_f32 v[246:247], v[24:25], v[120:121], v[246:247]
	v_pk_fma_f32 v[254:255], v[26:27], v[122:123], v[254:255]
	v_pk_fma_f32 v[160:161], v[28:29], v[124:125], v[160:161]
	v_pk_fma_f32 v[246:247], v[30:31], v[126:127], v[246:247]
	v_pk_add_f32 v[254:255], v[254:255], v[160:161]
	v_readlane_b32 s54, v92, 54
	v_pk_add_f32 v[246:247], v[246:247], v[254:255]
	v_readlane_b32 s55, v92, 55
	v_add_f32_e32 v164, v246, v247
	s_mul_i32 s0, s54, 0x300
	s_mul_i32 s1, s55, 0x300
	v_add_u32_e32 v167, s0, v195
	s_and_saveexec_b64 s[98:99], s[40:41]
	v_add_u32_e32 v167, s1, v195
	s_mov_b64 exec, s[98:99]
	s_waitcnt vmcnt(14)
; __device__ void peer_gather_phase(const Params& P, int l, bool do_store) {
;     ...
;         const int ea = __builtin_amdgcn_readlane(evs, kb + 2 * pr), eb = __builtin_amdgcn_readlane(evs, kb + 2 * pr + 1);
;         const uint2* up = (const uint2*)(U + (size_t)(uphi ? eb : ea) * 768);
;         u6[3 * pr] = up[0]; u6[3 * pr + 1] = up[1]; u6[3 * pr + 2] = up[2];
;     ...
;         v6u_t qv; qv[0] = u6[3 * pr].x; qv[1] = u6[3 * pr].y; qv[2] = u6[3 * pr + 1].x; qv[3] = u6[3 * pr + 1].y; qv[4] = u6[3 * pr + 2].x; qv[5] = u6[3 * pr + 2].y;
;         const v32f_t wv = __builtin_amdgcn_cvt_scalef32_pk32_f32_fp6(qv, 1.0f);
;         f32x2 a2 = f32x2{0.f, 0.f};
; #pragma unroll
;         for (int i = 0; i < 16; ++i) a2 += f32x2{wv[2 * i], wv[2 * i + 1]} * xu[i];
;         float hs = a2.x + a2.y;
;         hs += dpp_row_shr(hs, 1); hs += dpp_row_shr(hs, 2); hs += dpp_row_shr(hs, 4); hs += dpp_row_shr(hs, 8);
;         hs += __builtin_bit_cast(float, __builtin_amdgcn_update_dpp(0, __builtin_bit_cast(int, hs), 0x142, 0xa, 0xf, false));
;         const float da = __builtin_bit_cast(float, __builtin_amdgcn_readlane(__builtin_bit_cast(int, hs), 31));
;         const float db = __builtin_bit_cast(float, __builtin_amdgcn_readlane(__builtin_bit_cast(int, hs), 63));
;         dvec = (lane == kb + 2 * pr) ? da : dvec;
;         dvec = (lane == kb + 2 * pr + 1) ? db : dvec;
	v_cvt_scalef32_pk32_f32_fp6 v[0:31], v[32:37], 1.0
	global_load_dwordx2 v[36:37], v167, s[62:63] offset:16
	global_load_dwordx4 v[32:35], v167, s[62:63]
	v_pk_mul_f32 v[246:247], v[0:1], v[96:97]
	v_pk_mul_f32 v[254:255], v[2:3], v[98:99]
	v_pk_mul_f32 v[160:161], v[4:5], v[100:101]
	v_pk_fma_f32 v[246:247], v[6:7], v[102:103], v[246:247]
	v_pk_fma_f32 v[254:255], v[8:9], v[104:105], v[254:255]
	v_pk_fma_f32 v[160:161], v[10:11], v[106:107], v[160:161]
	v_pk_fma_f32 v[246:247], v[12:13], v[108:109], v[246:247]
	v_pk_fma_f32 v[254:255], v[14:15], v[110:111], v[254:255]
	v_pk_fma_f32 v[160:161], v[16:17], v[112:113], v[160:161]
	v_pk_fma_f32 v[246:247], v[18:19], v[114:115], v[246:247]
	v_pk_fma_f32 v[254:255], v[20:21], v[116:117], v[254:255]
	v_pk_fma_f32 v[160:161], v[22:23], v[118:119], v[160:161]
	v_pk_fma_f32 v[246:247], v[24:25], v[120:121], v[246:247]
	v_pk_fma_f32 v[254:255], v[26:27], v[122:123], v[254:255]
	v_pk_fma_f32 v[160:161], v[28:29], v[124:125], v[160:161]
	v_pk_fma_f32 v[246:247], v[30:31], v[126:127], v[246:247]
	v_pk_add_f32 v[254:255], v[254:255], v[160:161]
	s_nop 0
	v_pk_add_f32 v[246:247], v[246:247], v[254:255]
	s_nop 0
	v_add_f32_e32 v165, v246, v247
	v_add_f32_dpp v162, v162, v162 row_shr:1 row_mask:0xf bank_mask:0xf bound_ctrl:1
	v_add_f32_dpp v163, v163, v163 row_shr:1 row_mask:0xf bank_mask:0xf bound_ctrl:1
	v_add_f32_dpp v164, v164, v164 row_shr:1 row_mask:0xf bank_mask:0xf bound_ctrl:1
	v_add_f32_dpp v165, v165, v165 row_shr:1 row_mask:0xf bank_mask:0xf bound_ctrl:1
	v_add_f32_dpp v162, v162, v162 row_shr:2 row_mask:0xf bank_mask:0xf bound_ctrl:1
	v_add_f32_dpp v163, v163, v163 row_shr:2 row_mask:0xf bank_mask:0xf bound_ctrl:1
	v_add_f32_dpp v164, v164, v164 row_shr:2 row_mask:0xf bank_mask:0xf bound_ctrl:1
	v_add_f32_dpp v165, v165, v165 row_shr:2 row_mask:0xf bank_mask:0xf bound_ctrl:1
	v_add_f32_dpp v162, v162, v162 row_shr:4 row_mask:0xf bank_mask:0xf bound_ctrl:1
	v_add_f32_dpp v163, v163, v163 row_shr:4 row_mask:0xf bank_mask:0xf bound_ctrl:1
	v_add_f32_dpp v164, v164, v164 row_shr:4 row_mask:0xf bank_mask:0xf bound_ctrl:1
	v_add_f32_dpp v165, v165, v165 row_shr:4 row_mask:0xf bank_mask:0xf bound_ctrl:1
	v_add_f32_dpp v162, v162, v162 row_shr:8 row_mask:0xf bank_mask:0xf bound_ctrl:1
	v_add_f32_dpp v163, v163, v163 row_shr:8 row_mask:0xf bank_mask:0xf bound_ctrl:1
	v_add_f32_dpp v164, v164, v164 row_shr:8 row_mask:0xf bank_mask:0xf bound_ctrl:1
	v_add_f32_dpp v165, v165, v165 row_shr:8 row_mask:0xf bank_mask:0xf bound_ctrl:1
	v_add_f32_dpp v162, v162, v162 row_bcast:15 row_mask:0xa bank_mask:0xf
	v_add_f32_dpp v163, v163, v163 row_bcast:15 row_mask:0xa bank_mask:0xf
	v_add_f32_dpp v164, v164, v164 row_bcast:15 row_mask:0xa bank_mask:0xf
	v_add_f32_dpp v165, v165, v165 row_bcast:15 row_mask:0xa bank_mask:0xf
	s_nop 1
	v_readlane_b32 s46, v162, 31
	v_readlane_b32 s47, v162, 63
	v_readlane_b32 s48, v163, 31
	v_readlane_b32 s49, v163, 63
	v_readlane_b32 s50, v164, 31
	v_readlane_b32 s51, v164, 63
	v_readlane_b32 s52, v165, 31
	v_readlane_b32 s53, v165, 63
	v_writelane_b32 v166, s46, 32
	s_nop 1
	v_writelane_b32 v166, s47, 33
	v_writelane_b32 v166, s48, 34
	v_writelane_b32 v166, s49, 35
	v_writelane_b32 v166, s50, 36
	v_writelane_b32 v166, s51, 37
	v_writelane_b32 v166, s52, 38
	v_writelane_b32 v166, s53, 39
	v_readlane_b32 s54, v92, 56
	v_readlane_b32 s55, v92, 57
	s_mul_i32 s0, s54, 0x300
	s_mul_i32 s1, s55, 0x300
	v_add_u32_e32 v167, s0, v195
	s_and_saveexec_b64 s[98:99], s[40:41]
	v_add_u32_e32 v167, s1, v195
	s_mov_b64 exec, s[98:99]
	s_waitcnt vmcnt(14)
	v_cvt_scalef32_pk32_f32_fp6 v[0:31], v[196:201], 1.0
	global_load_dwordx2 v[200:201], v167, s[62:63] offset:16
	global_load_dwordx4 v[196:199], v167, s[62:63]
	v_pk_mul_f32 v[246:247], v[0:1], v[96:97]
	v_pk_mul_f32 v[254:255], v[2:3], v[98:99]
	v_pk_mul_f32 v[160:161], v[4:5], v[100:101]
	v_pk_fma_f32 v[246:247], v[6:7], v[102:103], v[246:247]
	v_pk_fma_f32 v[254:255], v[8:9], v[104:105], v[254:255]
	v_pk_fma_f32 v[160:161], v[10:11], v[106:107], v[160:161]
	v_pk_fma_f32 v[246:247], v[12:13], v[108:109], v[246:247]
	v_pk_fma_f32 v[254:255], v[14:15], v[110:111], v[254:255]
	v_pk_fma_f32 v[160:161], v[16:17], v[112:113], v[160:161]
	v_pk_fma_f32 v[246:247], v[18:19], v[114:115], v[246:247]
	v_pk_fma_f32 v[254:255], v[20:21], v[116:117], v[254:255]
	v_pk_fma_f32 v[160:161], v[22:23], v[118:119], v[160:161]
	v_pk_fma_f32 v[246:247], v[24:25], v[120:121], v[246:247]
	v_pk_fma_f32 v[254:255], v[26:27], v[122:123], v[254:255]
	v_pk_fma_f32 v[160:161], v[28:29], v[124:125], v[160:161]
	v_pk_fma_f32 v[246:247], v[30:31], v[126:127], v[246:247]
	v_pk_add_f32 v[254:255], v[254:255], v[160:161]
	v_readlane_b32 s54, v92, 58
	v_pk_add_f32 v[246:247], v[246:247], v[254:255]
	v_readlane_b32 s55, v92, 59
	v_add_f32_e32 v162, v246, v247
	s_mul_i32 s0, s54, 0x300
	s_mul_i32 s1, s55, 0x300
	v_add_u32_e32 v167, s0, v195
	s_and_saveexec_b64 s[98:99], s[40:41]
	v_add_u32_e32 v167, s1, v195
	s_mov_b64 exec, s[98:99]
	s_waitcnt vmcnt(14)
; __device__ void peer_gather_phase(const Params& P, int l, bool do_store) {
;     ...
;         const int ea = __builtin_amdgcn_readlane(evs, kb + 2 * pr), eb = __builtin_amdgcn_readlane(evs, kb + 2 * pr + 1);
;         const uint2* up = (const uint2*)(U + (size_t)(uphi ? eb : ea) * 768);
;         u6[3 * pr] = up[0]; u6[3 * pr + 1] = up[1]; u6[3 * pr + 2] = up[2];
;     ...
;         v6u_t qv; qv[0] = u6[3 * pr].x; qv[1] = u6[3 * pr].y; qv[2] = u6[3 * pr + 1].x; qv[3] = u6[3 * pr + 1].y; qv[4] = u6[3 * pr + 2].x; qv[5] = u6[3 * pr + 2].y;
;         const v32f_t wv = __builtin_amdgcn_cvt_scalef32_pk32_f32_fp6(qv, 1.0f);
;         f32x2 a2 = f32x2{0.f, 0.f};
; #pragma unroll
;         for (int i = 0; i < 16; ++i) a2 += f32x2{wv[2 * i], wv[2 * i + 1]} * xu[i];
;         float hs = a2.x + a2.y;
;         hs += dpp_row_shr(hs, 1); hs += dpp_row_shr(hs, 2); hs += dpp_row_shr(hs, 4); hs += dpp_row_shr(hs, 8);
;         hs += __builtin_bit_cast(float, __builtin_amdgcn_update_dpp(0, __builtin_bit_cast(int, hs), 0x142, 0xa, 0xf, false));
;         const float da = __builtin_bit_cast(float, __builtin_amdgcn_readlane(__builtin_bit_cast(int, hs), 31));
;         const float db = __builtin_bit_cast(float, __builtin_amdgcn_readlane(__builtin_bit_cast(int, hs), 63));
;         dvec = (lane == kb + 2 * pr) ? da : dvec;
;         dvec = (lane == kb + 2 * pr + 1) ? db : dvec;
	v_cvt_scalef32_pk32_f32_fp6 v[0:31], v[228:233], 1.0
	global_load_dwordx2 v[232:233], v167, s[62:63] offset:16
	global_load_dwordx4 v[228:231], v167, s[62:63]
	v_pk_mul_f32 v[246:247], v[0:1], v[96:97]
	v_pk_mul_f32 v[254:255], v[2:3], v[98:99]
	v_pk_mul_f32 v[160:161], v[4:5], v[100:101]
	v_pk_fma_f32 v[246:247], v[6:7], v[102:103], v[246:247]
	v_pk_fma_f32 v[254:255], v[8:9], v[104:105], v[254:255]
	v_pk_fma_f32 v[160:161], v[10:11], v[106:107], v[160:161]
	v_pk_fma_f32 v[246:247], v[12:13], v[108:109], v[246:247]
	v_pk_fma_f32 v[254:255], v[14:15], v[110:111], v[254:255]
	v_pk_fma_f32 v[160:161], v[16:17], v[112:113], v[160:161]
	v_pk_fma_f32 v[246:247], v[18:19], v[114:115], v[246:247]
	v_pk_fma_f32 v[254:255], v[20:21], v[116:117], v[254:255]
	v_pk_fma_f32 v[160:161], v[22:23], v[118:119], v[160:161]
	v_pk_fma_f32 v[246:247], v[24:25], v[120:121], v[246:247]
	v_pk_fma_f32 v[254:255], v[26:27], v[122:123], v[254:255]
	v_pk_fma_f32 v[160:161], v[28:29], v[124:125], v[160:161]
	v_pk_fma_f32 v[246:247], v[30:31], v[126:127], v[246:247]
	v_pk_add_f32 v[254:255], v[254:255], v[160:161]
	v_readlane_b32 s54, v92, 60
	v_pk_add_f32 v[246:247], v[246:247], v[254:255]
	v_readlane_b32 s55, v92, 61
	v_add_f32_e32 v163, v246, v247
	s_mul_i32 s0, s54, 0x300
	s_mul_i32 s1, s55, 0x300
	v_add_u32_e32 v167, s0, v195
	s_and_saveexec_b64 s[98:99], s[40:41]
	v_add_u32_e32 v167, s1, v195
	s_mov_b64 exec, s[98:99]
	s_waitcnt vmcnt(14)
	v_cvt_scalef32_pk32_f32_fp6 v[0:31], v[234:239], 1.0
	global_load_dwordx2 v[238:239], v167, s[62:63] offset:16
	global_load_dwordx4 v[234:237], v167, s[62:63]
	v_pk_mul_f32 v[246:247], v[0:1], v[96:97]
	v_pk_mul_f32 v[254:255], v[2:3], v[98:99]
	v_pk_mul_f32 v[160:161], v[4:5], v[100:101]
	v_pk_fma_f32 v[246:247], v[6:7], v[102:103], v[246:247]
	v_pk_fma_f32 v[254:255], v[8:9], v[104:105], v[254:255]
	v_pk_fma_f32 v[160:161], v[10:11], v[106:107], v[160:161]
	v_pk_fma_f32 v[246:247], v[12:13], v[108:109], v[246:247]
	v_pk_fma_f32 v[254:255], v[14:15], v[110:111], v[254:255]
	v_pk_fma_f32 v[160:161], v[16:17], v[112:113], v[160:161]
	v_pk_fma_f32 v[246:247], v[18:19], v[114:115], v[246:247]
	v_pk_fma_f32 v[254:255], v[20:21], v[116:117], v[254:255]
	v_pk_fma_f32 v[160:161], v[22:23], v[118:119], v[160:161]
	v_pk_fma_f32 v[246:247], v[24:25], v[120:121], v[246:247]
	v_pk_fma_f32 v[254:255], v[26:27], v[122:123], v[254:255]
	v_pk_fma_f32 v[160:161], v[28:29], v[124:125], v[160:161]
	v_pk_fma_f32 v[246:247], v[30:31], v[126:127], v[246:247]
	v_pk_add_f32 v[254:255], v[254:255], v[160:161]
	v_readlane_b32 s54, v92, 62
	v_pk_add_f32 v[246:247], v[246:247], v[254:255]
	v_readlane_b32 s55, v92, 63
	v_add_f32_e32 v164, v246, v247
	s_mul_i32 s0, s54, 0x300
	s_mul_i32 s1, s55, 0x300
	v_add_u32_e32 v167, s0, v195
	s_and_saveexec_b64 s[98:99], s[40:41]
	v_add_u32_e32 v167, s1, v195
	s_mov_b64 exec, s[98:99]
	s_waitcnt vmcnt(14)
	v_cvt_scalef32_pk32_f32_fp6 v[0:31], v[240:245], 1.0
	global_load_dwordx2 v[244:245], v167, s[62:63] offset:16
	global_load_dwordx4 v[240:243], v167, s[62:63]
	v_pk_mul_f32 v[246:247], v[0:1], v[96:97]
	v_pk_mul_f32 v[254:255], v[2:3], v[98:99]
	v_pk_mul_f32 v[160:161], v[4:5], v[100:101]
	v_pk_fma_f32 v[246:247], v[6:7], v[102:103], v[246:247]
	v_pk_fma_f32 v[254:255], v[8:9], v[104:105], v[254:255]
	v_pk_fma_f32 v[160:161], v[10:11], v[106:107], v[160:161]
	v_pk_fma_f32 v[246:247], v[12:13], v[108:109], v[246:247]
	v_pk_fma_f32 v[254:255], v[14:15], v[110:111], v[254:255]
	v_pk_fma_f32 v[160:161], v[16:17], v[112:113], v[160:161]
	v_pk_fma_f32 v[246:247], v[18:19], v[114:115], v[246:247]
	v_pk_fma_f32 v[254:255], v[20:21], v[116:117], v[254:255]
	v_pk_fma_f32 v[160:161], v[22:23], v[118:119], v[160:161]
	v_pk_fma_f32 v[246:247], v[24:25], v[120:121], v[246:247]
	v_pk_fma_f32 v[254:255], v[26:27], v[122:123], v[254:255]
	v_pk_fma_f32 v[160:161], v[28:29], v[124:125], v[160:161]
	v_pk_fma_f32 v[246:247], v[30:31], v[126:127], v[246:247]
	v_pk_add_f32 v[254:255], v[254:255], v[160:161]
	s_nop 0
	v_pk_add_f32 v[246:247], v[246:247], v[254:255]
	s_nop 0
	v_add_f32_e32 v165, v246, v247
	v_add_f32_dpp v162, v162, v162 row_shr:1 row_mask:0xf bank_mask:0xf bound_ctrl:1
	v_add_f32_dpp v163, v163, v163 row_shr:1 row_mask:0xf bank_mask:0xf bound_ctrl:1
	v_add_f32_dpp v164, v164, v164 row_shr:1 row_mask:0xf bank_mask:0xf bound_ctrl:1
	v_add_f32_dpp v165, v165, v165 row_shr:1 row_mask:0xf bank_mask:0xf bound_ctrl:1
	v_add_f32_dpp v162, v162, v162 row_shr:2 row_mask:0xf bank_mask:0xf bound_ctrl:1
	v_add_f32_dpp v163, v163, v163 row_shr:2 row_mask:0xf bank_mask:0xf bound_ctrl:1
	v_add_f32_dpp v164, v164, v164 row_shr:2 row_mask:0xf bank_mask:0xf bound_ctrl:1
	v_add_f32_dpp v165, v165, v165 row_shr:2 row_mask:0xf bank_mask:0xf bound_ctrl:1
	v_add_f32_dpp v162, v162, v162 row_shr:4 row_mask:0xf bank_mask:0xf bound_ctrl:1
	v_add_f32_dpp v163, v163, v163 row_shr:4 row_mask:0xf bank_mask:0xf bound_ctrl:1
	v_add_f32_dpp v164, v164, v164 row_shr:4 row_mask:0xf bank_mask:0xf bound_ctrl:1
	v_add_f32_dpp v165, v165, v165 row_shr:4 row_mask:0xf bank_mask:0xf bound_ctrl:1
	v_add_f32_dpp v162, v162, v162 row_shr:8 row_mask:0xf bank_mask:0xf bound_ctrl:1
	v_add_f32_dpp v163, v163, v163 row_shr:8 row_mask:0xf bank_mask:0xf bound_ctrl:1
	v_add_f32_dpp v164, v164, v164 row_shr:8 row_mask:0xf bank_mask:0xf bound_ctrl:1
	v_add_f32_dpp v165, v165, v165 row_shr:8 row_mask:0xf bank_mask:0xf bound_ctrl:1
	v_add_f32_dpp v162, v162, v162 row_bcast:15 row_mask:0xa bank_mask:0xf
	v_add_f32_dpp v163, v163, v163 row_bcast:15 row_mask:0xa bank_mask:0xf
	v_add_f32_dpp v164, v164, v164 row_bcast:15 row_mask:0xa bank_mask:0xf
	v_add_f32_dpp v165, v165, v165 row_bcast:15 row_mask:0xa bank_mask:0xf
	s_nop 1
	v_readlane_b32 s46, v162, 31
	v_readlane_b32 s47, v162, 63
	v_readlane_b32 s48, v163, 31
	v_readlane_b32 s49, v163, 63
	v_readlane_b32 s50, v164, 31
	v_readlane_b32 s51, v164, 63
	v_readlane_b32 s52, v165, 31
	v_readlane_b32 s53, v165, 63
	v_writelane_b32 v166, s46, 40
	s_nop 1
	v_writelane_b32 v166, s47, 41
	v_writelane_b32 v166, s48, 42
	v_writelane_b32 v166, s49, 43
	v_writelane_b32 v166, s50, 44
	v_writelane_b32 v166, s51, 45
	v_writelane_b32 v166, s52, 46
	v_writelane_b32 v166, s53, 47
	v_readlane_b32 s54, v90, 0
	v_readlane_b32 s55, v90, 1
	s_mul_i32 s0, s54, 0x300
	s_mul_i32 s1, s55, 0x300
	v_add_u32_e32 v167, s0, v195
	s_and_saveexec_b64 s[98:99], s[40:41]
	v_add_u32_e32 v167, s1, v195
	s_mov_b64 exec, s[98:99]
	s_waitcnt vmcnt(14)
; __device__ void peer_gather_phase(const Params& P, int l, bool do_store) {
;     ...
;         const int ea = __builtin_amdgcn_readlane(evs, kb + 2 * pr), eb = __builtin_amdgcn_readlane(evs, kb + 2 * pr + 1);
;         const uint2* up = (const uint2*)(U + (size_t)(uphi ? eb : ea) * 768);
;         u6[3 * pr] = up[0]; u6[3 * pr + 1] = up[1]; u6[3 * pr + 2] = up[2];
;     ...
;         v6u_t qv; qv[0] = u6[3 * pr].x; qv[1] = u6[3 * pr].y; qv[2] = u6[3 * pr + 1].x; qv[3] = u6[3 * pr + 1].y; qv[4] = u6[3 * pr + 2].x; qv[5] = u6[3 * pr + 2].y;
;         const v32f_t wv = __builtin_amdgcn_cvt_scalef32_pk32_f32_fp6(qv, 1.0f);
;         f32x2 a2 = f32x2{0.f, 0.f};
; #pragma unroll
;         for (int i = 0; i < 16; ++i) a2 += f32x2{wv[2 * i], wv[2 * i + 1]} * xu[i];
;         float hs = a2.x + a2.y;
	v_cvt_scalef32_pk32_f32_fp6 v[0:31], v[50:55], 1.0
	global_load_dwordx2 v[54:55], v167, s[62:63] offset:16
	global_load_dwordx4 v[50:53], v167, s[62:63]
	v_pk_mul_f32 v[246:247], v[0:1], v[96:97]
	v_pk_mul_f32 v[254:255], v[2:3], v[98:99]
	v_pk_mul_f32 v[160:161], v[4:5], v[100:101]
	v_pk_fma_f32 v[246:247], v[6:7], v[102:103], v[246:247]
	v_pk_fma_f32 v[254:255], v[8:9], v[104:105], v[254:255]
	v_pk_fma_f32 v[160:161], v[10:11], v[106:107], v[160:161]
	v_pk_fma_f32 v[246:247], v[12:13], v[108:109], v[246:247]
	v_pk_fma_f32 v[254:255], v[14:15], v[110:111], v[254:255]
	v_pk_fma_f32 v[160:161], v[16:17], v[112:113], v[160:161]
	v_pk_fma_f32 v[246:247], v[18:19], v[114:115], v[246:247]
	v_pk_fma_f32 v[254:255], v[20:21], v[116:117], v[254:255]
	v_pk_fma_f32 v[160:161], v[22:23], v[118:119], v[160:161]
	v_pk_fma_f32 v[246:247], v[24:25], v[120:121], v[246:247]
	v_pk_fma_f32 v[254:255], v[26:27], v[122:123], v[254:255]
	v_pk_fma_f32 v[160:161], v[28:29], v[124:125], v[160:161]
	v_pk_fma_f32 v[246:247], v[30:31], v[126:127], v[246:247]
	v_pk_add_f32 v[254:255], v[254:255], v[160:161]
	v_readlane_b32 s54, v90, 2
	v_pk_add_f32 v[246:247], v[246:247], v[254:255]
	v_readlane_b32 s55, v90, 3
	v_add_f32_e32 v162, v246, v247
	s_mul_i32 s0, s54, 0x300
	s_mul_i32 s1, s55, 0x300
	v_add_u32_e32 v167, s0, v195
	s_and_saveexec_b64 s[98:99], s[40:41]
	v_add_u32_e32 v167, s1, v195
	s_mov_b64 exec, s[98:99]
	s_waitcnt vmcnt(14)
	v_cvt_scalef32_pk32_f32_fp6 v[0:31], v[44:49], 1.0
	global_load_dwordx2 v[48:49], v167, s[62:63] offset:16
	global_load_dwordx4 v[44:47], v167, s[62:63]
	v_pk_mul_f32 v[246:247], v[0:1], v[96:97]
	v_pk_mul_f32 v[254:255], v[2:3], v[98:99]
	v_pk_mul_f32 v[160:161], v[4:5], v[100:101]
	v_pk_fma_f32 v[246:247], v[6:7], v[102:103], v[246:247]
	v_pk_fma_f32 v[254:255], v[8:9], v[104:105], v[254:255]
	v_pk_fma_f32 v[160:161], v[10:11], v[106:107], v[160:161]
	v_pk_fma_f32 v[246:247], v[12:13], v[108:109], v[246:247]
	v_pk_fma_f32 v[254:255], v[14:15], v[110:111], v[254:255]
	v_pk_fma_f32 v[160:161], v[16:17], v[112:113], v[160:161]
	v_pk_fma_f32 v[246:247], v[18:19], v[114:115], v[246:247]
	v_pk_fma_f32 v[254:255], v[20:21], v[116:117], v[254:255]
	v_pk_fma_f32 v[160:161], v[22:23], v[118:119], v[160:161]
	v_pk_fma_f32 v[246:247], v[24:25], v[120:121], v[246:247]
	v_pk_fma_f32 v[254:255], v[26:27], v[122:123], v[254:255]
	v_pk_fma_f32 v[160:161], v[28:29], v[124:125], v[160:161]
	v_pk_fma_f32 v[246:247], v[30:31], v[126:127], v[246:247]
	v_pk_add_f32 v[254:255], v[254:255], v[160:161]
	v_readlane_b32 s54, v90, 4
	v_pk_add_f32 v[246:247], v[246:247], v[254:255]
	v_readlane_b32 s55, v90, 5
	v_add_f32_e32 v163, v246, v247
	s_mul_i32 s0, s54, 0x300
	s_mul_i32 s1, s55, 0x300
	v_add_u32_e32 v167, s0, v195
	s_and_saveexec_b64 s[98:99], s[40:41]
	v_add_u32_e32 v167, s1, v195
	s_mov_b64 exec, s[98:99]
	s_waitcnt vmcnt(14)
	v_cvt_scalef32_pk32_f32_fp6 v[0:31], v[38:43], 1.0
	global_load_dwordx2 v[42:43], v167, s[62:63] offset:16
	global_load_dwordx4 v[38:41], v167, s[62:63]
	v_pk_mul_f32 v[246:247], v[0:1], v[96:97]
	v_pk_mul_f32 v[254:255], v[2:3], v[98:99]
	v_pk_mul_f32 v[160:161], v[4:5], v[100:101]
	v_pk_fma_f32 v[246:247], v[6:7], v[102:103], v[246:247]
	v_pk_fma_f32 v[254:255], v[8:9], v[104:105], v[254:255]
	v_pk_fma_f32 v[160:161], v[10:11], v[106:107], v[160:161]
	v_pk_fma_f32 v[246:247], v[12:13], v[108:109], v[246:247]
	v_pk_fma_f32 v[254:255], v[14:15], v[110:111], v[254:255]
	v_pk_fma_f32 v[160:161], v[16:17], v[112:113], v[160:161]
	v_pk_fma_f32 v[246:247], v[18:19], v[114:115], v[246:247]
	v_pk_fma_f32 v[254:255], v[20:21], v[116:117], v[254:255]
	v_pk_fma_f32 v[160:161], v[22:23], v[118:119], v[160:161]
	v_pk_fma_f32 v[246:247], v[24:25], v[120:121], v[246:247]
	v_pk_fma_f32 v[254:255], v[26:27], v[122:123], v[254:255]
	v_pk_fma_f32 v[160:161], v[28:29], v[124:125], v[160:161]
	v_pk_fma_f32 v[246:247], v[30:31], v[126:127], v[246:247]
	v_pk_add_f32 v[254:255], v[254:255], v[160:161]
	v_readlane_b32 s54, v90, 6
	v_pk_add_f32 v[246:247], v[246:247], v[254:255]
	v_readlane_b32 s55, v90, 7
	v_add_f32_e32 v164, v246, v247
	s_mul_i32 s0, s54, 0x300
	s_mul_i32 s1, s55, 0x300
	v_add_u32_e32 v167, s0, v195
	s_and_saveexec_b64 s[98:99], s[40:41]
	v_add_u32_e32 v167, s1, v195
	s_mov_b64 exec, s[98:99]
	s_waitcnt vmcnt(14)
; __device__ void peer_gather_phase(const Params& P, int l, bool do_store) {
;     ...
;         const int ea = __builtin_amdgcn_readlane(evs, kb + 2 * pr), eb = __builtin_amdgcn_readlane(evs, kb + 2 * pr + 1);
;         const uint2* up = (const uint2*)(U + (size_t)(uphi ? eb : ea) * 768);
;         u6[3 * pr] = up[0]; u6[3 * pr + 1] = up[1]; u6[3 * pr + 2] = up[2];
;     ...
;         v6u_t qv; qv[0] = u6[3 * pr].x; qv[1] = u6[3 * pr].y; qv[2] = u6[3 * pr + 1].x; qv[3] = u6[3 * pr + 1].y; qv[4] = u6[3 * pr + 2].x; qv[5] = u6[3 * pr + 2].y;
;         const v32f_t wv = __builtin_amdgcn_cvt_scalef32_pk32_f32_fp6(qv, 1.0f);
;         f32x2 a2 = f32x2{0.f, 0.f};
; #pragma unroll
;         for (int i = 0; i < 16; ++i) a2 += f32x2{wv[2 * i], wv[2 * i + 1]} * xu[i];
;         float hs = a2.x + a2.y;
;         hs += dpp_row_shr(hs, 1); hs += dpp_row_shr(hs, 2); hs += dpp_row_shr(hs, 4); hs += dpp_row_shr(hs, 8);
;         hs += __builtin_bit_cast(float, __builtin_amdgcn_update_dpp(0, __builtin_bit_cast(int, hs), 0x142, 0xa, 0xf, false));
;         const float da = __builtin_bit_cast(float, __builtin_amdgcn_readlane(__builtin_bit_cast(int, hs), 31));
;         const float db = __builtin_bit_cast(float, __builtin_amdgcn_readlane(__builtin_bit_cast(int, hs), 63));
;         dvec = (lane == kb + 2 * pr) ? da : dvec;
;         dvec = (lane == kb + 2 * pr + 1) ? db : dvec;
	v_cvt_scalef32_pk32_f32_fp6 v[0:31], v[32:37], 1.0
	global_load_dwordx2 v[36:37], v167, s[62:63] offset:16
	global_load_dwordx4 v[32:35], v167, s[62:63]
	v_pk_mul_f32 v[246:247], v[0:1], v[96:97]
	v_pk_mul_f32 v[254:255], v[2:3], v[98:99]
	v_pk_mul_f32 v[160:161], v[4:5], v[100:101]
	v_pk_fma_f32 v[246:247], v[6:7], v[102:103], v[246:247]
	v_pk_fma_f32 v[254:255], v[8:9], v[104:105], v[254:255]
	v_pk_fma_f32 v[160:161], v[10:11], v[106:107], v[160:161]
	v_pk_fma_f32 v[246:247], v[12:13], v[108:109], v[246:247]
	v_pk_fma_f32 v[254:255], v[14:15], v[110:111], v[254:255]
	v_pk_fma_f32 v[160:161], v[16:17], v[112:113], v[160:161]
	v_pk_fma_f32 v[246:247], v[18:19], v[114:115], v[246:247]
	v_pk_fma_f32 v[254:255], v[20:21], v[116:117], v[254:255]
	v_pk_fma_f32 v[160:161], v[22:23], v[118:119], v[160:161]
	v_pk_fma_f32 v[246:247], v[24:25], v[120:121], v[246:247]
	v_pk_fma_f32 v[254:255], v[26:27], v[122:123], v[254:255]
	v_pk_fma_f32 v[160:161], v[28:29], v[124:125], v[160:161]
	v_pk_fma_f32 v[246:247], v[30:31], v[126:127], v[246:247]
	v_pk_add_f32 v[254:255], v[254:255], v[160:161]
	s_nop 0
	v_pk_add_f32 v[246:247], v[246:247], v[254:255]
	s_nop 0
	v_add_f32_e32 v165, v246, v247
	v_add_f32_dpp v162, v162, v162 row_shr:1 row_mask:0xf bank_mask:0xf bound_ctrl:1
	v_add_f32_dpp v163, v163, v163 row_shr:1 row_mask:0xf bank_mask:0xf bound_ctrl:1
	v_add_f32_dpp v164, v164, v164 row_shr:1 row_mask:0xf bank_mask:0xf bound_ctrl:1
	v_add_f32_dpp v165, v165, v165 row_shr:1 row_mask:0xf bank_mask:0xf bound_ctrl:1
	v_add_f32_dpp v162, v162, v162 row_shr:2 row_mask:0xf bank_mask:0xf bound_ctrl:1
	v_add_f32_dpp v163, v163, v163 row_shr:2 row_mask:0xf bank_mask:0xf bound_ctrl:1
	v_add_f32_dpp v164, v164, v164 row_shr:2 row_mask:0xf bank_mask:0xf bound_ctrl:1
	v_add_f32_dpp v165, v165, v165 row_shr:2 row_mask:0xf bank_mask:0xf bound_ctrl:1
	v_add_f32_dpp v162, v162, v162 row_shr:4 row_mask:0xf bank_mask:0xf bound_ctrl:1
	v_add_f32_dpp v163, v163, v163 row_shr:4 row_mask:0xf bank_mask:0xf bound_ctrl:1
	v_add_f32_dpp v164, v164, v164 row_shr:4 row_mask:0xf bank_mask:0xf bound_ctrl:1
	v_add_f32_dpp v165, v165, v165 row_shr:4 row_mask:0xf bank_mask:0xf bound_ctrl:1
	v_add_f32_dpp v162, v162, v162 row_shr:8 row_mask:0xf bank_mask:0xf bound_ctrl:1
	v_add_f32_dpp v163, v163, v163 row_shr:8 row_mask:0xf bank_mask:0xf bound_ctrl:1
	v_add_f32_dpp v164, v164, v164 row_shr:8 row_mask:0xf bank_mask:0xf bound_ctrl:1
	v_add_f32_dpp v165, v165, v165 row_shr:8 row_mask:0xf bank_mask:0xf bound_ctrl:1
	v_add_f32_dpp v162, v162, v162 row_bcast:15 row_mask:0xa bank_mask:0xf
	v_add_f32_dpp v163, v163, v163 row_bcast:15 row_mask:0xa bank_mask:0xf
	v_add_f32_dpp v164, v164, v164 row_bcast:15 row_mask:0xa bank_mask:0xf
	v_add_f32_dpp v165, v165, v165 row_bcast:15 row_mask:0xa bank_mask:0xf
	s_nop 1
	v_readlane_b32 s46, v162, 31
	v_readlane_b32 s47, v162, 63
	v_readlane_b32 s48, v163, 31
	v_readlane_b32 s49, v163, 63
	v_readlane_b32 s50, v164, 31
	v_readlane_b32 s51, v164, 63
	v_readlane_b32 s52, v165, 31
	v_readlane_b32 s53, v165, 63
	v_writelane_b32 v166, s46, 48
	s_nop 1
	v_writelane_b32 v166, s47, 49
	v_writelane_b32 v166, s48, 50
	v_writelane_b32 v166, s49, 51
	v_writelane_b32 v166, s50, 52
	v_writelane_b32 v166, s51, 53
	v_writelane_b32 v166, s52, 54
	v_writelane_b32 v166, s53, 55
	v_readlane_b32 s54, v90, 8
	v_readlane_b32 s55, v90, 9
	s_mul_i32 s0, s54, 0x300
	s_mul_i32 s1, s55, 0x300
	v_add_u32_e32 v167, s0, v195
	s_and_saveexec_b64 s[98:99], s[40:41]
	v_add_u32_e32 v167, s1, v195
	s_mov_b64 exec, s[98:99]
	s_waitcnt vmcnt(14)
	v_cvt_scalef32_pk32_f32_fp6 v[0:31], v[196:201], 1.0
	global_load_dwordx2 v[200:201], v167, s[62:63] offset:16
	global_load_dwordx4 v[196:199], v167, s[62:63]
	v_pk_mul_f32 v[246:247], v[0:1], v[96:97]
	v_pk_mul_f32 v[254:255], v[2:3], v[98:99]
	v_pk_mul_f32 v[160:161], v[4:5], v[100:101]
	v_pk_fma_f32 v[246:247], v[6:7], v[102:103], v[246:247]
	v_pk_fma_f32 v[254:255], v[8:9], v[104:105], v[254:255]
	v_pk_fma_f32 v[160:161], v[10:11], v[106:107], v[160:161]
	v_pk_fma_f32 v[246:247], v[12:13], v[108:109], v[246:247]
	v_pk_fma_f32 v[254:255], v[14:15], v[110:111], v[254:255]
	v_pk_fma_f32 v[160:161], v[16:17], v[112:113], v[160:161]
	v_pk_fma_f32 v[246:247], v[18:19], v[114:115], v[246:247]
	v_pk_fma_f32 v[254:255], v[20:21], v[116:117], v[254:255]
	v_pk_fma_f32 v[160:161], v[22:23], v[118:119], v[160:161]
	v_pk_fma_f32 v[246:247], v[24:25], v[120:121], v[246:247]
	v_pk_fma_f32 v[254:255], v[26:27], v[122:123], v[254:255]
	v_pk_fma_f32 v[160:161], v[28:29], v[124:125], v[160:161]
	v_pk_fma_f32 v[246:247], v[30:31], v[126:127], v[246:247]
	v_pk_add_f32 v[254:255], v[254:255], v[160:161]
	v_readlane_b32 s54, v90, 10
	v_pk_add_f32 v[246:247], v[246:247], v[254:255]
	v_readlane_b32 s55, v90, 11
	v_add_f32_e32 v162, v246, v247
	s_mul_i32 s0, s54, 0x300
	s_mul_i32 s1, s55, 0x300
	v_add_u32_e32 v167, s0, v195
	s_and_saveexec_b64 s[98:99], s[40:41]
	v_add_u32_e32 v167, s1, v195
	s_mov_b64 exec, s[98:99]
	s_waitcnt vmcnt(14)
; DEV float gelu_t(float x) {
;   float z = 0.7978845608028654f * (x + 0.044715f * x * x * x);
;   float e = __expf(2.f * z);
;   float th = 1.f - 2.f / (e + 1.f);
;   return 0.5f * x * (1.f + th);
; }
; __device__ void peer_gather_phase(const Params& P, int l, bool do_store) {
;     ...
;         v6u_t qv; qv[0] = u6[3 * pr].x; qv[1] = u6[3 * pr].y; qv[2] = u6[3 * pr + 1].x; qv[3] = u6[3 * pr + 1].y; qv[4] = u6[3 * pr + 2].x; qv[5] = u6[3 * pr + 2].y;
;         const v32f_t wv = __builtin_amdgcn_cvt_scalef32_pk32_f32_fp6(qv, 1.0f);
;         f32x2 a2 = f32x2{0.f, 0.f};
; #pragma unroll
;         for (int i = 0; i < 16; ++i) a2 += f32x2{wv[2 * i], wv[2 * i + 1]} * xu[i];
;         float hs = a2.x + a2.y;
;         hs += dpp_row_shr(hs, 1); hs += dpp_row_shr(hs, 2); hs += dpp_row_shr(hs, 4); hs += dpp_row_shr(hs, 8);
;         hs += __builtin_bit_cast(float, __builtin_amdgcn_update_dpp(0, __builtin_bit_cast(int, hs), 0x142, 0xa, 0xf, false));
;         const float da = __builtin_bit_cast(float, __builtin_amdgcn_readlane(__builtin_bit_cast(int, hs), 31));
;         const float db = __builtin_bit_cast(float, __builtin_amdgcn_readlane(__builtin_bit_cast(int, hs), 63));
;         dvec = (lane == kb + 2 * pr) ? da : dvec;
;         dvec = (lane == kb + 2 * pr + 1) ? db : dvec;
;       }
;       const float sux = (bt < 8) ? sux0 : sux1;
;       const float gsx = (bt < 8) ? gsx0 : gsx1;
;       const float avec = gelu_t(dvec * sux) * gsx;
	v_cvt_scalef32_pk32_f32_fp6 v[0:31], v[228:233], 1.0
	global_load_dwordx2 v[232:233], v167, s[62:63] offset:16
	global_load_dwordx4 v[228:231], v167, s[62:63]
	v_pk_mul_f32 v[246:247], v[0:1], v[96:97]
	v_pk_mul_f32 v[254:255], v[2:3], v[98:99]
	v_pk_mul_f32 v[160:161], v[4:5], v[100:101]
	v_pk_fma_f32 v[246:247], v[6:7], v[102:103], v[246:247]
	v_pk_fma_f32 v[254:255], v[8:9], v[104:105], v[254:255]
	v_pk_fma_f32 v[160:161], v[10:11], v[106:107], v[160:161]
	v_pk_fma_f32 v[246:247], v[12:13], v[108:109], v[246:247]
	v_pk_fma_f32 v[254:255], v[14:15], v[110:111], v[254:255]
	v_pk_fma_f32 v[160:161], v[16:17], v[112:113], v[160:161]
	v_pk_fma_f32 v[246:247], v[18:19], v[114:115], v[246:247]
	v_pk_fma_f32 v[254:255], v[20:21], v[116:117], v[254:255]
	v_pk_fma_f32 v[160:161], v[22:23], v[118:119], v[160:161]
	v_pk_fma_f32 v[246:247], v[24:25], v[120:121], v[246:247]
	v_pk_fma_f32 v[254:255], v[26:27], v[122:123], v[254:255]
	v_pk_fma_f32 v[160:161], v[28:29], v[124:125], v[160:161]
	v_pk_fma_f32 v[246:247], v[30:31], v[126:127], v[246:247]
	v_pk_add_f32 v[254:255], v[254:255], v[160:161]
	v_readlane_b32 s54, v90, 12
	v_pk_add_f32 v[246:247], v[246:247], v[254:255]
	v_readlane_b32 s55, v90, 13
	v_add_f32_e32 v163, v246, v247
	s_mul_i32 s0, s54, 0x300
	s_mul_i32 s1, s55, 0x300
	v_add_u32_e32 v167, s0, v195
	s_and_saveexec_b64 s[98:99], s[40:41]
	v_add_u32_e32 v167, s1, v195
	s_mov_b64 exec, s[98:99]
	s_waitcnt vmcnt(14)
	v_cvt_scalef32_pk32_f32_fp6 v[0:31], v[234:239], 1.0
	global_load_dwordx2 v[238:239], v167, s[62:63] offset:16
	global_load_dwordx4 v[234:237], v167, s[62:63]
	v_pk_mul_f32 v[246:247], v[0:1], v[96:97]
	v_pk_mul_f32 v[254:255], v[2:3], v[98:99]
	v_pk_mul_f32 v[160:161], v[4:5], v[100:101]
	v_pk_fma_f32 v[246:247], v[6:7], v[102:103], v[246:247]
	v_pk_fma_f32 v[254:255], v[8:9], v[104:105], v[254:255]
	v_pk_fma_f32 v[160:161], v[10:11], v[106:107], v[160:161]
	v_pk_fma_f32 v[246:247], v[12:13], v[108:109], v[246:247]
	v_pk_fma_f32 v[254:255], v[14:15], v[110:111], v[254:255]
	v_pk_fma_f32 v[160:161], v[16:17], v[112:113], v[160:161]
	v_pk_fma_f32 v[246:247], v[18:19], v[114:115], v[246:247]
	v_pk_fma_f32 v[254:255], v[20:21], v[116:117], v[254:255]
	v_pk_fma_f32 v[160:161], v[22:23], v[118:119], v[160:161]
	v_pk_fma_f32 v[246:247], v[24:25], v[120:121], v[246:247]
	v_pk_fma_f32 v[254:255], v[26:27], v[122:123], v[254:255]
	v_pk_fma_f32 v[160:161], v[28:29], v[124:125], v[160:161]
	v_pk_fma_f32 v[246:247], v[30:31], v[126:127], v[246:247]
	v_pk_add_f32 v[254:255], v[254:255], v[160:161]
	v_readlane_b32 s54, v90, 14
	v_pk_add_f32 v[246:247], v[246:247], v[254:255]
	v_readlane_b32 s55, v90, 15
	v_add_f32_e32 v164, v246, v247
	s_mul_i32 s0, s54, 0x300
	s_mul_i32 s1, s55, 0x300
	v_add_u32_e32 v167, s0, v195
	s_and_saveexec_b64 s[98:99], s[40:41]
	v_add_u32_e32 v167, s1, v195
	s_mov_b64 exec, s[98:99]
	s_waitcnt vmcnt(14)
	v_cvt_scalef32_pk32_f32_fp6 v[0:31], v[240:245], 1.0
	global_load_dwordx2 v[244:245], v167, s[62:63] offset:16
	global_load_dwordx4 v[240:243], v167, s[62:63]
	v_pk_mul_f32 v[246:247], v[0:1], v[96:97]
	v_pk_mul_f32 v[254:255], v[2:3], v[98:99]
	v_pk_mul_f32 v[160:161], v[4:5], v[100:101]
	v_pk_fma_f32 v[246:247], v[6:7], v[102:103], v[246:247]
	v_pk_fma_f32 v[254:255], v[8:9], v[104:105], v[254:255]
	v_pk_fma_f32 v[160:161], v[10:11], v[106:107], v[160:161]
	v_pk_fma_f32 v[246:247], v[12:13], v[108:109], v[246:247]
	v_pk_fma_f32 v[254:255], v[14:15], v[110:111], v[254:255]
	v_pk_fma_f32 v[160:161], v[16:17], v[112:113], v[160:161]
	v_pk_fma_f32 v[246:247], v[18:19], v[114:115], v[246:247]
	v_pk_fma_f32 v[254:255], v[20:21], v[116:117], v[254:255]
	v_pk_fma_f32 v[160:161], v[22:23], v[118:119], v[160:161]
	v_pk_fma_f32 v[246:247], v[24:25], v[120:121], v[246:247]
	v_pk_fma_f32 v[254:255], v[26:27], v[122:123], v[254:255]
	v_pk_fma_f32 v[160:161], v[28:29], v[124:125], v[160:161]
	v_pk_fma_f32 v[246:247], v[30:31], v[126:127], v[246:247]
	v_pk_add_f32 v[254:255], v[254:255], v[160:161]
	s_nop 0
	v_pk_add_f32 v[246:247], v[246:247], v[254:255]
	s_nop 0
	v_add_f32_e32 v165, v246, v247
	v_add_f32_dpp v162, v162, v162 row_shr:1 row_mask:0xf bank_mask:0xf bound_ctrl:1
	v_add_f32_dpp v163, v163, v163 row_shr:1 row_mask:0xf bank_mask:0xf bound_ctrl:1
	v_add_f32_dpp v164, v164, v164 row_shr:1 row_mask:0xf bank_mask:0xf bound_ctrl:1
	v_add_f32_dpp v165, v165, v165 row_shr:1 row_mask:0xf bank_mask:0xf bound_ctrl:1
	v_add_f32_dpp v162, v162, v162 row_shr:2 row_mask:0xf bank_mask:0xf bound_ctrl:1
	v_add_f32_dpp v163, v163, v163 row_shr:2 row_mask:0xf bank_mask:0xf bound_ctrl:1
	v_add_f32_dpp v164, v164, v164 row_shr:2 row_mask:0xf bank_mask:0xf bound_ctrl:1
	v_add_f32_dpp v165, v165, v165 row_shr:2 row_mask:0xf bank_mask:0xf bound_ctrl:1
	v_add_f32_dpp v162, v162, v162 row_shr:4 row_mask:0xf bank_mask:0xf bound_ctrl:1
	v_add_f32_dpp v163, v163, v163 row_shr:4 row_mask:0xf bank_mask:0xf bound_ctrl:1
	v_add_f32_dpp v164, v164, v164 row_shr:4 row_mask:0xf bank_mask:0xf bound_ctrl:1
	v_add_f32_dpp v165, v165, v165 row_shr:4 row_mask:0xf bank_mask:0xf bound_ctrl:1
	v_add_f32_dpp v162, v162, v162 row_shr:8 row_mask:0xf bank_mask:0xf bound_ctrl:1
	v_add_f32_dpp v163, v163, v163 row_shr:8 row_mask:0xf bank_mask:0xf bound_ctrl:1
	v_add_f32_dpp v164, v164, v164 row_shr:8 row_mask:0xf bank_mask:0xf bound_ctrl:1
	v_add_f32_dpp v165, v165, v165 row_shr:8 row_mask:0xf bank_mask:0xf bound_ctrl:1
	v_add_f32_dpp v162, v162, v162 row_bcast:15 row_mask:0xa bank_mask:0xf
	v_add_f32_dpp v163, v163, v163 row_bcast:15 row_mask:0xa bank_mask:0xf
	v_add_f32_dpp v164, v164, v164 row_bcast:15 row_mask:0xa bank_mask:0xf
	v_add_f32_dpp v165, v165, v165 row_bcast:15 row_mask:0xa bank_mask:0xf
	s_nop 1
	v_readlane_b32 s46, v162, 31
	v_readlane_b32 s47, v162, 63
	v_readlane_b32 s48, v163, 31
	v_readlane_b32 s49, v163, 63
	v_readlane_b32 s50, v164, 31
	v_readlane_b32 s51, v164, 63
	v_readlane_b32 s52, v165, 31
	v_readlane_b32 s53, v165, 63
	v_writelane_b32 v166, s46, 56
	s_nop 1
	v_writelane_b32 v166, s47, 57
	v_writelane_b32 v166, s48, 58
	v_writelane_b32 v166, s49, 59
	v_writelane_b32 v166, s50, 60
	v_writelane_b32 v166, s51, 61
	v_writelane_b32 v166, s52, 62
	v_writelane_b32 v166, s53, 63
	s_nop 1
	v_mul_f32_e32 v0, v189, v166
	v_mul_f32_e32 v1, 0x3d372713, v0
	v_mul_f32_e32 v1, v0, v1
	v_fma_f32 v1, v0, v1, v0
	v_mul_f32_e32 v1, 0x3f4c422a, v1
	v_add_f32_e32 v1, v1, v1
	v_mul_f32_e32 v1, 0x3fb8aa3b, v1
	v_exp_f32_e32 v1, v1
	v_mul_f32_e32 v0, 0.5, v0
	v_add_f32_e32 v1, 1.0, v1
	v_div_scale_f32 v2, s[0:1], v1, v1, 2.0
	v_rcp_f32_e32 v3, v2
	s_nop 0
	v_fma_f32 v4, -v2, v3, 1.0
	v_fmac_f32_e32 v3, v4, v3
	v_div_scale_f32 v4, vcc, 2.0, v1, 2.0
	v_mul_f32_e32 v5, v4, v3
	v_fma_f32 v6, -v2, v5, v4
	v_fmac_f32_e32 v5, v6, v3
	v_fma_f32 v2, -v2, v5, v4
	v_div_fmas_f32 v2, v2, v3, v5
	v_div_fixup_f32 v1, v2, v1, 2.0
	v_sub_f32_e32 v1, 1.0, v1
	v_add_f32_e32 v1, 1.0, v1
	v_mul_f32_e32 v0, v0, v1
	v_mul_f32_e32 v167, v191, v0
	s_nop 1
	v_readlane_b32 s0, v167, 0
	s_waitcnt vmcnt(48)
; __device__ void peer_gather_phase(const Params& P, int l, bool do_store) {
;     ...
;         v8[2 * pr] = *(const uint2*)(V + (size_t)ea * 512);
;         v8[2 * pr + 1] = *(const uint2*)(V + (size_t)eb * 512);
;     ...
;       for (int j = 0; j < 8; ++j) {
;         const float a = __builtin_bit_cast(float, __builtin_amdgcn_readlane(__builtin_bit_cast(int, avec), kb + j));
;         const f32x2 aa = f32x2{a, a};
;         y[0] += aa * __builtin_amdgcn_cvt_scalef32_pk_f32_fp4(v8[j].x, 1.0f, 0); y[1] += aa * __builtin_amdgcn_cvt_scalef32_pk_f32_fp4(v8[j].x, 1.0f, 1);
;         y[2] += aa * __builtin_amdgcn_cvt_scalef32_pk_f32_fp4(v8[j].x, 1.0f, 2); y[3] += aa * __builtin_amdgcn_cvt_scalef32_pk_f32_fp4(v8[j].x, 1.0f, 3);
;         y[4] += aa * __builtin_amdgcn_cvt_scalef32_pk_f32_fp4(v8[j].y, 1.0f, 0); y[5] += aa * __builtin_amdgcn_cvt_scalef32_pk_f32_fp4(v8[j].y, 1.0f, 1);
;         y[6] += aa * __builtin_amdgcn_cvt_scalef32_pk_f32_fp4(v8[j].y, 1.0f, 2); y[7] += aa * __builtin_amdgcn_cvt_scalef32_pk_f32_fp4(v8[j].y, 1.0f, 3);
;       }
	v_cvt_scalef32_pk_f32_fp4 v[0:1], v144, 1.0
	v_cvt_scalef32_pk_f32_fp4 v[2:3], v144, 1.0 op_sel:[1,0,0]
	v_cvt_scalef32_pk_f32_fp4 v[4:5], v144, 1.0 op_sel:[0,1,0]
	v_cvt_scalef32_pk_f32_fp4 v[6:7], v144, 1.0 op_sel:[1,1,0]
	v_cvt_scalef32_pk_f32_fp4 v[8:9], v145, 1.0
	v_cvt_scalef32_pk_f32_fp4 v[10:11], v145, 1.0 op_sel:[1,0,0]
	v_cvt_scalef32_pk_f32_fp4 v[12:13], v145, 1.0 op_sel:[0,1,0]
	v_cvt_scalef32_pk_f32_fp4 v[14:15], v145, 1.0 op_sel:[1,1,0]
	v_readlane_b32 s54, v92, 16
	s_lshl_b32 s56, s54, 9
	s_add_u32 s56, s64, s56
	s_addc_u32 s57, s65, 0
	global_load_dwordx2 v[144:145], v227, s[56:57]
	v_pk_fma_f32 v[130:131], v[0:1], s[0:1], v[130:131] op_sel_hi:[1,0,1]
	v_pk_fma_f32 v[138:139], v[2:3], s[0:1], v[138:139] op_sel_hi:[1,0,1]
	v_pk_fma_f32 v[140:141], v[4:5], s[0:1], v[140:141] op_sel_hi:[1,0,1]
	v_pk_fma_f32 v[142:143], v[6:7], s[0:1], v[142:143] op_sel_hi:[1,0,1]
	v_pk_fma_f32 v[128:129], v[8:9], s[0:1], v[128:129] op_sel_hi:[1,0,1]
	v_pk_fma_f32 v[132:133], v[10:11], s[0:1], v[132:133] op_sel_hi:[1,0,1]
	v_pk_fma_f32 v[134:135], v[12:13], s[0:1], v[134:135] op_sel_hi:[1,0,1]
	v_pk_fma_f32 v[136:137], v[14:15], s[0:1], v[136:137] op_sel_hi:[1,0,1]
	v_readlane_b32 s0, v167, 1
	s_waitcnt vmcnt(48)
	v_cvt_scalef32_pk_f32_fp4 v[0:1], v146, 1.0
	v_cvt_scalef32_pk_f32_fp4 v[2:3], v146, 1.0 op_sel:[1,0,0]
	v_cvt_scalef32_pk_f32_fp4 v[4:5], v146, 1.0 op_sel:[0,1,0]
	v_cvt_scalef32_pk_f32_fp4 v[6:7], v146, 1.0 op_sel:[1,1,0]
	v_cvt_scalef32_pk_f32_fp4 v[8:9], v147, 1.0
	v_cvt_scalef32_pk_f32_fp4 v[10:11], v147, 1.0 op_sel:[1,0,0]
	v_cvt_scalef32_pk_f32_fp4 v[12:13], v147, 1.0 op_sel:[0,1,0]
	v_cvt_scalef32_pk_f32_fp4 v[14:15], v147, 1.0 op_sel:[1,1,0]
	v_readlane_b32 s54, v92, 17
	s_lshl_b32 s56, s54, 9
	s_add_u32 s56, s64, s56
	s_addc_u32 s57, s65, 0
	global_load_dwordx2 v[146:147], v227, s[56:57]
	v_pk_fma_f32 v[130:131], v[0:1], s[0:1], v[130:131] op_sel_hi:[1,0,1]
	v_pk_fma_f32 v[138:139], v[2:3], s[0:1], v[138:139] op_sel_hi:[1,0,1]
	v_pk_fma_f32 v[140:141], v[4:5], s[0:1], v[140:141] op_sel_hi:[1,0,1]
	v_pk_fma_f32 v[142:143], v[6:7], s[0:1], v[142:143] op_sel_hi:[1,0,1]
	v_pk_fma_f32 v[128:129], v[8:9], s[0:1], v[128:129] op_sel_hi:[1,0,1]
	v_pk_fma_f32 v[132:133], v[10:11], s[0:1], v[132:133] op_sel_hi:[1,0,1]
	v_pk_fma_f32 v[134:135], v[12:13], s[0:1], v[134:135] op_sel_hi:[1,0,1]
	v_pk_fma_f32 v[136:137], v[14:15], s[0:1], v[136:137] op_sel_hi:[1,0,1]
	v_readlane_b32 s0, v167, 2
	s_waitcnt vmcnt(48)
	v_cvt_scalef32_pk_f32_fp4 v[0:1], v148, 1.0
	v_cvt_scalef32_pk_f32_fp4 v[2:3], v148, 1.0 op_sel:[1,0,0]
	v_cvt_scalef32_pk_f32_fp4 v[4:5], v148, 1.0 op_sel:[0,1,0]
	v_cvt_scalef32_pk_f32_fp4 v[6:7], v148, 1.0 op_sel:[1,1,0]
	v_cvt_scalef32_pk_f32_fp4 v[8:9], v149, 1.0
	v_cvt_scalef32_pk_f32_fp4 v[10:11], v149, 1.0 op_sel:[1,0,0]
	v_cvt_scalef32_pk_f32_fp4 v[12:13], v149, 1.0 op_sel:[0,1,0]
	v_cvt_scalef32_pk_f32_fp4 v[14:15], v149, 1.0 op_sel:[1,1,0]
	v_readlane_b32 s54, v92, 18
	s_lshl_b32 s56, s54, 9
	s_add_u32 s56, s64, s56
	s_addc_u32 s57, s65, 0
	global_load_dwordx2 v[148:149], v227, s[56:57]
	v_pk_fma_f32 v[130:131], v[0:1], s[0:1], v[130:131] op_sel_hi:[1,0,1]
	v_pk_fma_f32 v[138:139], v[2:3], s[0:1], v[138:139] op_sel_hi:[1,0,1]
	v_pk_fma_f32 v[140:141], v[4:5], s[0:1], v[140:141] op_sel_hi:[1,0,1]
	v_pk_fma_f32 v[142:143], v[6:7], s[0:1], v[142:143] op_sel_hi:[1,0,1]
	v_pk_fma_f32 v[128:129], v[8:9], s[0:1], v[128:129] op_sel_hi:[1,0,1]
	v_pk_fma_f32 v[132:133], v[10:11], s[0:1], v[132:133] op_sel_hi:[1,0,1]
	v_pk_fma_f32 v[134:135], v[12:13], s[0:1], v[134:135] op_sel_hi:[1,0,1]
	v_pk_fma_f32 v[136:137], v[14:15], s[0:1], v[136:137] op_sel_hi:[1,0,1]
	v_readlane_b32 s0, v167, 3
	s_waitcnt vmcnt(48)
	v_cvt_scalef32_pk_f32_fp4 v[0:1], v150, 1.0
	v_cvt_scalef32_pk_f32_fp4 v[2:3], v150, 1.0 op_sel:[1,0,0]
	v_cvt_scalef32_pk_f32_fp4 v[4:5], v150, 1.0 op_sel:[0,1,0]
	v_cvt_scalef32_pk_f32_fp4 v[6:7], v150, 1.0 op_sel:[1,1,0]
	v_cvt_scalef32_pk_f32_fp4 v[8:9], v151, 1.0
	v_cvt_scalef32_pk_f32_fp4 v[10:11], v151, 1.0 op_sel:[1,0,0]
	v_cvt_scalef32_pk_f32_fp4 v[12:13], v151, 1.0 op_sel:[0,1,0]
	v_cvt_scalef32_pk_f32_fp4 v[14:15], v151, 1.0 op_sel:[1,1,0]
	v_readlane_b32 s54, v92, 19
	s_lshl_b32 s56, s54, 9
	s_add_u32 s56, s64, s56
	s_addc_u32 s57, s65, 0
	global_load_dwordx2 v[150:151], v227, s[56:57]
	v_pk_fma_f32 v[130:131], v[0:1], s[0:1], v[130:131] op_sel_hi:[1,0,1]
	v_pk_fma_f32 v[138:139], v[2:3], s[0:1], v[138:139] op_sel_hi:[1,0,1]
	v_pk_fma_f32 v[140:141], v[4:5], s[0:1], v[140:141] op_sel_hi:[1,0,1]
	v_pk_fma_f32 v[142:143], v[6:7], s[0:1], v[142:143] op_sel_hi:[1,0,1]
	v_pk_fma_f32 v[128:129], v[8:9], s[0:1], v[128:129] op_sel_hi:[1,0,1]
	v_pk_fma_f32 v[132:133], v[10:11], s[0:1], v[132:133] op_sel_hi:[1,0,1]
	v_pk_fma_f32 v[134:135], v[12:13], s[0:1], v[134:135] op_sel_hi:[1,0,1]
	v_pk_fma_f32 v[136:137], v[14:15], s[0:1], v[136:137] op_sel_hi:[1,0,1]
	v_readlane_b32 s0, v167, 4
	s_waitcnt vmcnt(48)
	v_cvt_scalef32_pk_f32_fp4 v[0:1], v152, 1.0
	v_cvt_scalef32_pk_f32_fp4 v[2:3], v152, 1.0 op_sel:[1,0,0]
	v_cvt_scalef32_pk_f32_fp4 v[4:5], v152, 1.0 op_sel:[0,1,0]
	v_cvt_scalef32_pk_f32_fp4 v[6:7], v152, 1.0 op_sel:[1,1,0]
	v_cvt_scalef32_pk_f32_fp4 v[8:9], v153, 1.0
	v_cvt_scalef32_pk_f32_fp4 v[10:11], v153, 1.0 op_sel:[1,0,0]
	v_cvt_scalef32_pk_f32_fp4 v[12:13], v153, 1.0 op_sel:[0,1,0]
	v_cvt_scalef32_pk_f32_fp4 v[14:15], v153, 1.0 op_sel:[1,1,0]
	v_readlane_b32 s54, v92, 20
	s_lshl_b32 s56, s54, 9
	s_add_u32 s56, s64, s56
	s_addc_u32 s57, s65, 0
	global_load_dwordx2 v[152:153], v227, s[56:57]
	v_pk_fma_f32 v[130:131], v[0:1], s[0:1], v[130:131] op_sel_hi:[1,0,1]
	v_pk_fma_f32 v[138:139], v[2:3], s[0:1], v[138:139] op_sel_hi:[1,0,1]
	v_pk_fma_f32 v[140:141], v[4:5], s[0:1], v[140:141] op_sel_hi:[1,0,1]
	v_pk_fma_f32 v[142:143], v[6:7], s[0:1], v[142:143] op_sel_hi:[1,0,1]
	v_pk_fma_f32 v[128:129], v[8:9], s[0:1], v[128:129] op_sel_hi:[1,0,1]
	v_pk_fma_f32 v[132:133], v[10:11], s[0:1], v[132:133] op_sel_hi:[1,0,1]
	v_pk_fma_f32 v[134:135], v[12:13], s[0:1], v[134:135] op_sel_hi:[1,0,1]
	v_pk_fma_f32 v[136:137], v[14:15], s[0:1], v[136:137] op_sel_hi:[1,0,1]
	v_readlane_b32 s0, v167, 5
	s_waitcnt vmcnt(48)
; __device__ void peer_gather_phase(const Params& P, int l, bool do_store) {
;     ...
;         v8[2 * pr] = *(const uint2*)(V + (size_t)ea * 512);
;         v8[2 * pr + 1] = *(const uint2*)(V + (size_t)eb * 512);
;     ...
;       for (int j = 0; j < 8; ++j) {
;         const float a = __builtin_bit_cast(float, __builtin_amdgcn_readlane(__builtin_bit_cast(int, avec), kb + j));
;         const f32x2 aa = f32x2{a, a};
;         y[0] += aa * __builtin_amdgcn_cvt_scalef32_pk_f32_fp4(v8[j].x, 1.0f, 0); y[1] += aa * __builtin_amdgcn_cvt_scalef32_pk_f32_fp4(v8[j].x, 1.0f, 1);
;         y[2] += aa * __builtin_amdgcn_cvt_scalef32_pk_f32_fp4(v8[j].x, 1.0f, 2); y[3] += aa * __builtin_amdgcn_cvt_scalef32_pk_f32_fp4(v8[j].x, 1.0f, 3);
;         y[4] += aa * __builtin_amdgcn_cvt_scalef32_pk_f32_fp4(v8[j].y, 1.0f, 0); y[5] += aa * __builtin_amdgcn_cvt_scalef32_pk_f32_fp4(v8[j].y, 1.0f, 1);
;         y[6] += aa * __builtin_amdgcn_cvt_scalef32_pk_f32_fp4(v8[j].y, 1.0f, 2); y[7] += aa * __builtin_amdgcn_cvt_scalef32_pk_f32_fp4(v8[j].y, 1.0f, 3);
;       }
	v_cvt_scalef32_pk_f32_fp4 v[0:1], v154, 1.0
	v_cvt_scalef32_pk_f32_fp4 v[2:3], v154, 1.0 op_sel:[1,0,0]
	v_cvt_scalef32_pk_f32_fp4 v[4:5], v154, 1.0 op_sel:[0,1,0]
	v_cvt_scalef32_pk_f32_fp4 v[6:7], v154, 1.0 op_sel:[1,1,0]
	v_cvt_scalef32_pk_f32_fp4 v[8:9], v155, 1.0
	v_cvt_scalef32_pk_f32_fp4 v[10:11], v155, 1.0 op_sel:[1,0,0]
	v_cvt_scalef32_pk_f32_fp4 v[12:13], v155, 1.0 op_sel:[0,1,0]
	v_cvt_scalef32_pk_f32_fp4 v[14:15], v155, 1.0 op_sel:[1,1,0]
	v_readlane_b32 s54, v92, 21
	s_lshl_b32 s56, s54, 9
	s_add_u32 s56, s64, s56
	s_addc_u32 s57, s65, 0
	global_load_dwordx2 v[154:155], v227, s[56:57]
	v_pk_fma_f32 v[130:131], v[0:1], s[0:1], v[130:131] op_sel_hi:[1,0,1]
	v_pk_fma_f32 v[138:139], v[2:3], s[0:1], v[138:139] op_sel_hi:[1,0,1]
	v_pk_fma_f32 v[140:141], v[4:5], s[0:1], v[140:141] op_sel_hi:[1,0,1]
	v_pk_fma_f32 v[142:143], v[6:7], s[0:1], v[142:143] op_sel_hi:[1,0,1]
	v_pk_fma_f32 v[128:129], v[8:9], s[0:1], v[128:129] op_sel_hi:[1,0,1]
	v_pk_fma_f32 v[132:133], v[10:11], s[0:1], v[132:133] op_sel_hi:[1,0,1]
	v_pk_fma_f32 v[134:135], v[12:13], s[0:1], v[134:135] op_sel_hi:[1,0,1]
	v_pk_fma_f32 v[136:137], v[14:15], s[0:1], v[136:137] op_sel_hi:[1,0,1]
	v_readlane_b32 s0, v167, 6
	s_waitcnt vmcnt(48)
	v_cvt_scalef32_pk_f32_fp4 v[0:1], v156, 1.0
	v_cvt_scalef32_pk_f32_fp4 v[2:3], v156, 1.0 op_sel:[1,0,0]
	v_cvt_scalef32_pk_f32_fp4 v[4:5], v156, 1.0 op_sel:[0,1,0]
	v_cvt_scalef32_pk_f32_fp4 v[6:7], v156, 1.0 op_sel:[1,1,0]
	v_cvt_scalef32_pk_f32_fp4 v[8:9], v157, 1.0
	v_cvt_scalef32_pk_f32_fp4 v[10:11], v157, 1.0 op_sel:[1,0,0]
	v_cvt_scalef32_pk_f32_fp4 v[12:13], v157, 1.0 op_sel:[0,1,0]
	v_cvt_scalef32_pk_f32_fp4 v[14:15], v157, 1.0 op_sel:[1,1,0]
	v_readlane_b32 s54, v92, 22
	s_lshl_b32 s56, s54, 9
	s_add_u32 s56, s64, s56
	s_addc_u32 s57, s65, 0
	global_load_dwordx2 v[156:157], v227, s[56:57]
	v_pk_fma_f32 v[130:131], v[0:1], s[0:1], v[130:131] op_sel_hi:[1,0,1]
	v_pk_fma_f32 v[138:139], v[2:3], s[0:1], v[138:139] op_sel_hi:[1,0,1]
	v_pk_fma_f32 v[140:141], v[4:5], s[0:1], v[140:141] op_sel_hi:[1,0,1]
	v_pk_fma_f32 v[142:143], v[6:7], s[0:1], v[142:143] op_sel_hi:[1,0,1]
	v_pk_fma_f32 v[128:129], v[8:9], s[0:1], v[128:129] op_sel_hi:[1,0,1]
	v_pk_fma_f32 v[132:133], v[10:11], s[0:1], v[132:133] op_sel_hi:[1,0,1]
	v_pk_fma_f32 v[134:135], v[12:13], s[0:1], v[134:135] op_sel_hi:[1,0,1]
	v_pk_fma_f32 v[136:137], v[14:15], s[0:1], v[136:137] op_sel_hi:[1,0,1]
	v_readlane_b32 s0, v167, 7
	s_waitcnt vmcnt(48)
	v_cvt_scalef32_pk_f32_fp4 v[0:1], v158, 1.0
	v_cvt_scalef32_pk_f32_fp4 v[2:3], v158, 1.0 op_sel:[1,0,0]
	v_cvt_scalef32_pk_f32_fp4 v[4:5], v158, 1.0 op_sel:[0,1,0]
	v_cvt_scalef32_pk_f32_fp4 v[6:7], v158, 1.0 op_sel:[1,1,0]
	v_cvt_scalef32_pk_f32_fp4 v[8:9], v159, 1.0
	v_cvt_scalef32_pk_f32_fp4 v[10:11], v159, 1.0 op_sel:[1,0,0]
	v_cvt_scalef32_pk_f32_fp4 v[12:13], v159, 1.0 op_sel:[0,1,0]
	v_cvt_scalef32_pk_f32_fp4 v[14:15], v159, 1.0 op_sel:[1,1,0]
	v_readlane_b32 s54, v92, 23
	s_lshl_b32 s56, s54, 9
	s_add_u32 s56, s64, s56
	s_addc_u32 s57, s65, 0
	global_load_dwordx2 v[158:159], v227, s[56:57]
	v_pk_fma_f32 v[130:131], v[0:1], s[0:1], v[130:131] op_sel_hi:[1,0,1]
	v_pk_fma_f32 v[138:139], v[2:3], s[0:1], v[138:139] op_sel_hi:[1,0,1]
	v_pk_fma_f32 v[140:141], v[4:5], s[0:1], v[140:141] op_sel_hi:[1,0,1]
	v_pk_fma_f32 v[142:143], v[6:7], s[0:1], v[142:143] op_sel_hi:[1,0,1]
	v_pk_fma_f32 v[128:129], v[8:9], s[0:1], v[128:129] op_sel_hi:[1,0,1]
	v_pk_fma_f32 v[132:133], v[10:11], s[0:1], v[132:133] op_sel_hi:[1,0,1]
	v_pk_fma_f32 v[134:135], v[12:13], s[0:1], v[134:135] op_sel_hi:[1,0,1]
	v_pk_fma_f32 v[136:137], v[14:15], s[0:1], v[136:137] op_sel_hi:[1,0,1]
	v_readlane_b32 s0, v167, 8
	s_waitcnt vmcnt(48)
	v_cvt_scalef32_pk_f32_fp4 v[0:1], v168, 1.0
	v_cvt_scalef32_pk_f32_fp4 v[2:3], v168, 1.0 op_sel:[1,0,0]
	v_cvt_scalef32_pk_f32_fp4 v[4:5], v168, 1.0 op_sel:[0,1,0]
	v_cvt_scalef32_pk_f32_fp4 v[6:7], v168, 1.0 op_sel:[1,1,0]
	v_cvt_scalef32_pk_f32_fp4 v[8:9], v169, 1.0
	v_cvt_scalef32_pk_f32_fp4 v[10:11], v169, 1.0 op_sel:[1,0,0]
	v_cvt_scalef32_pk_f32_fp4 v[12:13], v169, 1.0 op_sel:[0,1,0]
	v_cvt_scalef32_pk_f32_fp4 v[14:15], v169, 1.0 op_sel:[1,1,0]
	v_readlane_b32 s54, v92, 24
	s_lshl_b32 s56, s54, 9
	s_add_u32 s56, s64, s56
	s_addc_u32 s57, s65, 0
	global_load_dwordx2 v[168:169], v227, s[56:57]
	v_pk_fma_f32 v[130:131], v[0:1], s[0:1], v[130:131] op_sel_hi:[1,0,1]
	v_pk_fma_f32 v[138:139], v[2:3], s[0:1], v[138:139] op_sel_hi:[1,0,1]
	v_pk_fma_f32 v[140:141], v[4:5], s[0:1], v[140:141] op_sel_hi:[1,0,1]
	v_pk_fma_f32 v[142:143], v[6:7], s[0:1], v[142:143] op_sel_hi:[1,0,1]
	v_pk_fma_f32 v[128:129], v[8:9], s[0:1], v[128:129] op_sel_hi:[1,0,1]
	v_pk_fma_f32 v[132:133], v[10:11], s[0:1], v[132:133] op_sel_hi:[1,0,1]
	v_pk_fma_f32 v[134:135], v[12:13], s[0:1], v[134:135] op_sel_hi:[1,0,1]
	v_pk_fma_f32 v[136:137], v[14:15], s[0:1], v[136:137] op_sel_hi:[1,0,1]
	v_readlane_b32 s0, v167, 9
	s_waitcnt vmcnt(48)
	v_cvt_scalef32_pk_f32_fp4 v[0:1], v170, 1.0
	v_cvt_scalef32_pk_f32_fp4 v[2:3], v170, 1.0 op_sel:[1,0,0]
	v_cvt_scalef32_pk_f32_fp4 v[4:5], v170, 1.0 op_sel:[0,1,0]
	v_cvt_scalef32_pk_f32_fp4 v[6:7], v170, 1.0 op_sel:[1,1,0]
	v_cvt_scalef32_pk_f32_fp4 v[8:9], v171, 1.0
	v_cvt_scalef32_pk_f32_fp4 v[10:11], v171, 1.0 op_sel:[1,0,0]
	v_cvt_scalef32_pk_f32_fp4 v[12:13], v171, 1.0 op_sel:[0,1,0]
	v_cvt_scalef32_pk_f32_fp4 v[14:15], v171, 1.0 op_sel:[1,1,0]
	v_readlane_b32 s54, v92, 25
	s_lshl_b32 s56, s54, 9
	s_add_u32 s56, s64, s56
	s_addc_u32 s57, s65, 0
	global_load_dwordx2 v[170:171], v227, s[56:57]
	v_pk_fma_f32 v[130:131], v[0:1], s[0:1], v[130:131] op_sel_hi:[1,0,1]
	v_pk_fma_f32 v[138:139], v[2:3], s[0:1], v[138:139] op_sel_hi:[1,0,1]
	v_pk_fma_f32 v[140:141], v[4:5], s[0:1], v[140:141] op_sel_hi:[1,0,1]
	v_pk_fma_f32 v[142:143], v[6:7], s[0:1], v[142:143] op_sel_hi:[1,0,1]
	v_pk_fma_f32 v[128:129], v[8:9], s[0:1], v[128:129] op_sel_hi:[1,0,1]
	v_pk_fma_f32 v[132:133], v[10:11], s[0:1], v[132:133] op_sel_hi:[1,0,1]
	v_pk_fma_f32 v[134:135], v[12:13], s[0:1], v[134:135] op_sel_hi:[1,0,1]
	v_pk_fma_f32 v[136:137], v[14:15], s[0:1], v[136:137] op_sel_hi:[1,0,1]
	v_readlane_b32 s0, v167, 10
	s_waitcnt vmcnt(48)
; __device__ void peer_gather_phase(const Params& P, int l, bool do_store) {
;     ...
;         v8[2 * pr] = *(const uint2*)(V + (size_t)ea * 512);
;         v8[2 * pr + 1] = *(const uint2*)(V + (size_t)eb * 512);
;     ...
;       for (int j = 0; j < 8; ++j) {
;         const float a = __builtin_bit_cast(float, __builtin_amdgcn_readlane(__builtin_bit_cast(int, avec), kb + j));
;         const f32x2 aa = f32x2{a, a};
;         y[0] += aa * __builtin_amdgcn_cvt_scalef32_pk_f32_fp4(v8[j].x, 1.0f, 0); y[1] += aa * __builtin_amdgcn_cvt_scalef32_pk_f32_fp4(v8[j].x, 1.0f, 1);
;         y[2] += aa * __builtin_amdgcn_cvt_scalef32_pk_f32_fp4(v8[j].x, 1.0f, 2); y[3] += aa * __builtin_amdgcn_cvt_scalef32_pk_f32_fp4(v8[j].x, 1.0f, 3);
;         y[4] += aa * __builtin_amdgcn_cvt_scalef32_pk_f32_fp4(v8[j].y, 1.0f, 0); y[5] += aa * __builtin_amdgcn_cvt_scalef32_pk_f32_fp4(v8[j].y, 1.0f, 1);
;         y[6] += aa * __builtin_amdgcn_cvt_scalef32_pk_f32_fp4(v8[j].y, 1.0f, 2); y[7] += aa * __builtin_amdgcn_cvt_scalef32_pk_f32_fp4(v8[j].y, 1.0f, 3);
;       }
	v_cvt_scalef32_pk_f32_fp4 v[0:1], v172, 1.0
	v_cvt_scalef32_pk_f32_fp4 v[2:3], v172, 1.0 op_sel:[1,0,0]
	v_cvt_scalef32_pk_f32_fp4 v[4:5], v172, 1.0 op_sel:[0,1,0]
	v_cvt_scalef32_pk_f32_fp4 v[6:7], v172, 1.0 op_sel:[1,1,0]
	v_cvt_scalef32_pk_f32_fp4 v[8:9], v173, 1.0
	v_cvt_scalef32_pk_f32_fp4 v[10:11], v173, 1.0 op_sel:[1,0,0]
	v_cvt_scalef32_pk_f32_fp4 v[12:13], v173, 1.0 op_sel:[0,1,0]
	v_cvt_scalef32_pk_f32_fp4 v[14:15], v173, 1.0 op_sel:[1,1,0]
	v_readlane_b32 s54, v92, 26
	s_lshl_b32 s56, s54, 9
	s_add_u32 s56, s64, s56
	s_addc_u32 s57, s65, 0
	global_load_dwordx2 v[172:173], v227, s[56:57]
	v_pk_fma_f32 v[130:131], v[0:1], s[0:1], v[130:131] op_sel_hi:[1,0,1]
	v_pk_fma_f32 v[138:139], v[2:3], s[0:1], v[138:139] op_sel_hi:[1,0,1]
	v_pk_fma_f32 v[140:141], v[4:5], s[0:1], v[140:141] op_sel_hi:[1,0,1]
	v_pk_fma_f32 v[142:143], v[6:7], s[0:1], v[142:143] op_sel_hi:[1,0,1]
	v_pk_fma_f32 v[128:129], v[8:9], s[0:1], v[128:129] op_sel_hi:[1,0,1]
	v_pk_fma_f32 v[132:133], v[10:11], s[0:1], v[132:133] op_sel_hi:[1,0,1]
	v_pk_fma_f32 v[134:135], v[12:13], s[0:1], v[134:135] op_sel_hi:[1,0,1]
	v_pk_fma_f32 v[136:137], v[14:15], s[0:1], v[136:137] op_sel_hi:[1,0,1]
	v_readlane_b32 s0, v167, 11
	s_waitcnt vmcnt(48)
	v_cvt_scalef32_pk_f32_fp4 v[0:1], v174, 1.0
	v_cvt_scalef32_pk_f32_fp4 v[2:3], v174, 1.0 op_sel:[1,0,0]
	v_cvt_scalef32_pk_f32_fp4 v[4:5], v174, 1.0 op_sel:[0,1,0]
	v_cvt_scalef32_pk_f32_fp4 v[6:7], v174, 1.0 op_sel:[1,1,0]
	v_cvt_scalef32_pk_f32_fp4 v[8:9], v175, 1.0
	v_cvt_scalef32_pk_f32_fp4 v[10:11], v175, 1.0 op_sel:[1,0,0]
	v_cvt_scalef32_pk_f32_fp4 v[12:13], v175, 1.0 op_sel:[0,1,0]
	v_cvt_scalef32_pk_f32_fp4 v[14:15], v175, 1.0 op_sel:[1,1,0]
	v_readlane_b32 s54, v92, 27
	s_lshl_b32 s56, s54, 9
	s_add_u32 s56, s64, s56
	s_addc_u32 s57, s65, 0
	global_load_dwordx2 v[174:175], v227, s[56:57]
	v_pk_fma_f32 v[130:131], v[0:1], s[0:1], v[130:131] op_sel_hi:[1,0,1]
	v_pk_fma_f32 v[138:139], v[2:3], s[0:1], v[138:139] op_sel_hi:[1,0,1]
	v_pk_fma_f32 v[140:141], v[4:5], s[0:1], v[140:141] op_sel_hi:[1,0,1]
	v_pk_fma_f32 v[142:143], v[6:7], s[0:1], v[142:143] op_sel_hi:[1,0,1]
	v_pk_fma_f32 v[128:129], v[8:9], s[0:1], v[128:129] op_sel_hi:[1,0,1]
	v_pk_fma_f32 v[132:133], v[10:11], s[0:1], v[132:133] op_sel_hi:[1,0,1]
	v_pk_fma_f32 v[134:135], v[12:13], s[0:1], v[134:135] op_sel_hi:[1,0,1]
	v_pk_fma_f32 v[136:137], v[14:15], s[0:1], v[136:137] op_sel_hi:[1,0,1]
	v_readlane_b32 s0, v167, 12
	s_waitcnt vmcnt(48)
	v_cvt_scalef32_pk_f32_fp4 v[0:1], v180, 1.0
	v_cvt_scalef32_pk_f32_fp4 v[2:3], v180, 1.0 op_sel:[1,0,0]
	v_cvt_scalef32_pk_f32_fp4 v[4:5], v180, 1.0 op_sel:[0,1,0]
	v_cvt_scalef32_pk_f32_fp4 v[6:7], v180, 1.0 op_sel:[1,1,0]
	v_cvt_scalef32_pk_f32_fp4 v[8:9], v181, 1.0
	v_cvt_scalef32_pk_f32_fp4 v[10:11], v181, 1.0 op_sel:[1,0,0]
	v_cvt_scalef32_pk_f32_fp4 v[12:13], v181, 1.0 op_sel:[0,1,0]
	v_cvt_scalef32_pk_f32_fp4 v[14:15], v181, 1.0 op_sel:[1,1,0]
	v_readlane_b32 s54, v92, 28
	s_lshl_b32 s56, s54, 9
	s_add_u32 s56, s64, s56
	s_addc_u32 s57, s65, 0
	global_load_dwordx2 v[180:181], v227, s[56:57]
	v_pk_fma_f32 v[130:131], v[0:1], s[0:1], v[130:131] op_sel_hi:[1,0,1]
	v_pk_fma_f32 v[138:139], v[2:3], s[0:1], v[138:139] op_sel_hi:[1,0,1]
	v_pk_fma_f32 v[140:141], v[4:5], s[0:1], v[140:141] op_sel_hi:[1,0,1]
	v_pk_fma_f32 v[142:143], v[6:7], s[0:1], v[142:143] op_sel_hi:[1,0,1]
	v_pk_fma_f32 v[128:129], v[8:9], s[0:1], v[128:129] op_sel_hi:[1,0,1]
	v_pk_fma_f32 v[132:133], v[10:11], s[0:1], v[132:133] op_sel_hi:[1,0,1]
	v_pk_fma_f32 v[134:135], v[12:13], s[0:1], v[134:135] op_sel_hi:[1,0,1]
	v_pk_fma_f32 v[136:137], v[14:15], s[0:1], v[136:137] op_sel_hi:[1,0,1]
	v_readlane_b32 s0, v167, 13
	s_waitcnt vmcnt(48)
	v_cvt_scalef32_pk_f32_fp4 v[0:1], v182, 1.0
	v_cvt_scalef32_pk_f32_fp4 v[2:3], v182, 1.0 op_sel:[1,0,0]
	v_cvt_scalef32_pk_f32_fp4 v[4:5], v182, 1.0 op_sel:[0,1,0]
	v_cvt_scalef32_pk_f32_fp4 v[6:7], v182, 1.0 op_sel:[1,1,0]
	v_cvt_scalef32_pk_f32_fp4 v[8:9], v183, 1.0
	v_cvt_scalef32_pk_f32_fp4 v[10:11], v183, 1.0 op_sel:[1,0,0]
	v_cvt_scalef32_pk_f32_fp4 v[12:13], v183, 1.0 op_sel:[0,1,0]
	v_cvt_scalef32_pk_f32_fp4 v[14:15], v183, 1.0 op_sel:[1,1,0]
	v_readlane_b32 s54, v92, 29
	s_lshl_b32 s56, s54, 9
	s_add_u32 s56, s64, s56
	s_addc_u32 s57, s65, 0
	global_load_dwordx2 v[182:183], v227, s[56:57]
	v_pk_fma_f32 v[130:131], v[0:1], s[0:1], v[130:131] op_sel_hi:[1,0,1]
	v_pk_fma_f32 v[138:139], v[2:3], s[0:1], v[138:139] op_sel_hi:[1,0,1]
	v_pk_fma_f32 v[140:141], v[4:5], s[0:1], v[140:141] op_sel_hi:[1,0,1]
	v_pk_fma_f32 v[142:143], v[6:7], s[0:1], v[142:143] op_sel_hi:[1,0,1]
	v_pk_fma_f32 v[128:129], v[8:9], s[0:1], v[128:129] op_sel_hi:[1,0,1]
	v_pk_fma_f32 v[132:133], v[10:11], s[0:1], v[132:133] op_sel_hi:[1,0,1]
	v_pk_fma_f32 v[134:135], v[12:13], s[0:1], v[134:135] op_sel_hi:[1,0,1]
	v_pk_fma_f32 v[136:137], v[14:15], s[0:1], v[136:137] op_sel_hi:[1,0,1]
	v_readlane_b32 s0, v167, 14
	s_waitcnt vmcnt(48)
	v_cvt_scalef32_pk_f32_fp4 v[0:1], v184, 1.0
	v_cvt_scalef32_pk_f32_fp4 v[2:3], v184, 1.0 op_sel:[1,0,0]
	v_cvt_scalef32_pk_f32_fp4 v[4:5], v184, 1.0 op_sel:[0,1,0]
	v_cvt_scalef32_pk_f32_fp4 v[6:7], v184, 1.0 op_sel:[1,1,0]
	v_cvt_scalef32_pk_f32_fp4 v[8:9], v185, 1.0
	v_cvt_scalef32_pk_f32_fp4 v[10:11], v185, 1.0 op_sel:[1,0,0]
	v_cvt_scalef32_pk_f32_fp4 v[12:13], v185, 1.0 op_sel:[0,1,0]
	v_cvt_scalef32_pk_f32_fp4 v[14:15], v185, 1.0 op_sel:[1,1,0]
	v_readlane_b32 s54, v92, 30
	s_lshl_b32 s56, s54, 9
	s_add_u32 s56, s64, s56
	s_addc_u32 s57, s65, 0
	global_load_dwordx2 v[184:185], v227, s[56:57]
	v_pk_fma_f32 v[130:131], v[0:1], s[0:1], v[130:131] op_sel_hi:[1,0,1]
	v_pk_fma_f32 v[138:139], v[2:3], s[0:1], v[138:139] op_sel_hi:[1,0,1]
	v_pk_fma_f32 v[140:141], v[4:5], s[0:1], v[140:141] op_sel_hi:[1,0,1]
	v_pk_fma_f32 v[142:143], v[6:7], s[0:1], v[142:143] op_sel_hi:[1,0,1]
	v_pk_fma_f32 v[128:129], v[8:9], s[0:1], v[128:129] op_sel_hi:[1,0,1]
	v_pk_fma_f32 v[132:133], v[10:11], s[0:1], v[132:133] op_sel_hi:[1,0,1]
	v_pk_fma_f32 v[134:135], v[12:13], s[0:1], v[134:135] op_sel_hi:[1,0,1]
	v_pk_fma_f32 v[136:137], v[14:15], s[0:1], v[136:137] op_sel_hi:[1,0,1]
	v_readlane_b32 s0, v167, 15
	s_waitcnt vmcnt(48)
; __device__ void peer_gather_phase(const Params& P, int l, bool do_store) {
;     ...
;         v8[2 * pr] = *(const uint2*)(V + (size_t)ea * 512);
;         v8[2 * pr + 1] = *(const uint2*)(V + (size_t)eb * 512);
;     ...
;       for (int j = 0; j < 8; ++j) {
;         const float a = __builtin_bit_cast(float, __builtin_amdgcn_readlane(__builtin_bit_cast(int, avec), kb + j));
;         const f32x2 aa = f32x2{a, a};
;         y[0] += aa * __builtin_amdgcn_cvt_scalef32_pk_f32_fp4(v8[j].x, 1.0f, 0); y[1] += aa * __builtin_amdgcn_cvt_scalef32_pk_f32_fp4(v8[j].x, 1.0f, 1);
;         y[2] += aa * __builtin_amdgcn_cvt_scalef32_pk_f32_fp4(v8[j].x, 1.0f, 2); y[3] += aa * __builtin_amdgcn_cvt_scalef32_pk_f32_fp4(v8[j].x, 1.0f, 3);
;         y[4] += aa * __builtin_amdgcn_cvt_scalef32_pk_f32_fp4(v8[j].y, 1.0f, 0); y[5] += aa * __builtin_amdgcn_cvt_scalef32_pk_f32_fp4(v8[j].y, 1.0f, 1);
;         y[6] += aa * __builtin_amdgcn_cvt_scalef32_pk_f32_fp4(v8[j].y, 1.0f, 2); y[7] += aa * __builtin_amdgcn_cvt_scalef32_pk_f32_fp4(v8[j].y, 1.0f, 3);
;       }
	v_cvt_scalef32_pk_f32_fp4 v[0:1], v186, 1.0
	v_cvt_scalef32_pk_f32_fp4 v[2:3], v186, 1.0 op_sel:[1,0,0]
	v_cvt_scalef32_pk_f32_fp4 v[4:5], v186, 1.0 op_sel:[0,1,0]
	v_cvt_scalef32_pk_f32_fp4 v[6:7], v186, 1.0 op_sel:[1,1,0]
	v_cvt_scalef32_pk_f32_fp4 v[8:9], v187, 1.0
	v_cvt_scalef32_pk_f32_fp4 v[10:11], v187, 1.0 op_sel:[1,0,0]
	v_cvt_scalef32_pk_f32_fp4 v[12:13], v187, 1.0 op_sel:[0,1,0]
	v_cvt_scalef32_pk_f32_fp4 v[14:15], v187, 1.0 op_sel:[1,1,0]
	v_readlane_b32 s54, v92, 31
	s_lshl_b32 s56, s54, 9
	s_add_u32 s56, s64, s56
	s_addc_u32 s57, s65, 0
	global_load_dwordx2 v[186:187], v227, s[56:57]
	v_pk_fma_f32 v[130:131], v[0:1], s[0:1], v[130:131] op_sel_hi:[1,0,1]
	v_pk_fma_f32 v[138:139], v[2:3], s[0:1], v[138:139] op_sel_hi:[1,0,1]
	v_pk_fma_f32 v[140:141], v[4:5], s[0:1], v[140:141] op_sel_hi:[1,0,1]
	v_pk_fma_f32 v[142:143], v[6:7], s[0:1], v[142:143] op_sel_hi:[1,0,1]
	v_pk_fma_f32 v[128:129], v[8:9], s[0:1], v[128:129] op_sel_hi:[1,0,1]
	v_pk_fma_f32 v[132:133], v[10:11], s[0:1], v[132:133] op_sel_hi:[1,0,1]
	v_pk_fma_f32 v[134:135], v[12:13], s[0:1], v[134:135] op_sel_hi:[1,0,1]
	v_pk_fma_f32 v[136:137], v[14:15], s[0:1], v[136:137] op_sel_hi:[1,0,1]
	v_readlane_b32 s0, v167, 16
	s_waitcnt vmcnt(15)
	v_cvt_scalef32_pk_f32_fp4 v[0:1], v144, 1.0
	v_cvt_scalef32_pk_f32_fp4 v[2:3], v144, 1.0 op_sel:[1,0,0]
	v_cvt_scalef32_pk_f32_fp4 v[4:5], v144, 1.0 op_sel:[0,1,0]
	v_cvt_scalef32_pk_f32_fp4 v[6:7], v144, 1.0 op_sel:[1,1,0]
	v_cvt_scalef32_pk_f32_fp4 v[8:9], v145, 1.0
	v_cvt_scalef32_pk_f32_fp4 v[10:11], v145, 1.0 op_sel:[1,0,0]
	v_cvt_scalef32_pk_f32_fp4 v[12:13], v145, 1.0 op_sel:[0,1,0]
	v_cvt_scalef32_pk_f32_fp4 v[14:15], v145, 1.0 op_sel:[1,1,0]
	v_readlane_b32 s54, v92, 32
	s_lshl_b32 s56, s54, 9
	s_add_u32 s56, s64, s56
	s_addc_u32 s57, s65, 0
	global_load_dwordx2 v[144:145], v227, s[56:57]
	v_pk_fma_f32 v[130:131], v[0:1], s[0:1], v[130:131] op_sel_hi:[1,0,1]
	v_pk_fma_f32 v[138:139], v[2:3], s[0:1], v[138:139] op_sel_hi:[1,0,1]
	v_pk_fma_f32 v[140:141], v[4:5], s[0:1], v[140:141] op_sel_hi:[1,0,1]
	v_pk_fma_f32 v[142:143], v[6:7], s[0:1], v[142:143] op_sel_hi:[1,0,1]
	v_pk_fma_f32 v[128:129], v[8:9], s[0:1], v[128:129] op_sel_hi:[1,0,1]
	v_pk_fma_f32 v[132:133], v[10:11], s[0:1], v[132:133] op_sel_hi:[1,0,1]
	v_pk_fma_f32 v[134:135], v[12:13], s[0:1], v[134:135] op_sel_hi:[1,0,1]
	v_pk_fma_f32 v[136:137], v[14:15], s[0:1], v[136:137] op_sel_hi:[1,0,1]
	v_readlane_b32 s0, v167, 17
	s_waitcnt vmcnt(15)
	v_cvt_scalef32_pk_f32_fp4 v[0:1], v146, 1.0
	v_cvt_scalef32_pk_f32_fp4 v[2:3], v146, 1.0 op_sel:[1,0,0]
	v_cvt_scalef32_pk_f32_fp4 v[4:5], v146, 1.0 op_sel:[0,1,0]
	v_cvt_scalef32_pk_f32_fp4 v[6:7], v146, 1.0 op_sel:[1,1,0]
	v_cvt_scalef32_pk_f32_fp4 v[8:9], v147, 1.0
	v_cvt_scalef32_pk_f32_fp4 v[10:11], v147, 1.0 op_sel:[1,0,0]
	v_cvt_scalef32_pk_f32_fp4 v[12:13], v147, 1.0 op_sel:[0,1,0]
	v_cvt_scalef32_pk_f32_fp4 v[14:15], v147, 1.0 op_sel:[1,1,0]
	v_readlane_b32 s54, v92, 33
	s_lshl_b32 s56, s54, 9
	s_add_u32 s56, s64, s56
	s_addc_u32 s57, s65, 0
	global_load_dwordx2 v[146:147], v227, s[56:57]
	v_pk_fma_f32 v[130:131], v[0:1], s[0:1], v[130:131] op_sel_hi:[1,0,1]
	v_pk_fma_f32 v[138:139], v[2:3], s[0:1], v[138:139] op_sel_hi:[1,0,1]
	v_pk_fma_f32 v[140:141], v[4:5], s[0:1], v[140:141] op_sel_hi:[1,0,1]
	v_pk_fma_f32 v[142:143], v[6:7], s[0:1], v[142:143] op_sel_hi:[1,0,1]
	v_pk_fma_f32 v[128:129], v[8:9], s[0:1], v[128:129] op_sel_hi:[1,0,1]
	v_pk_fma_f32 v[132:133], v[10:11], s[0:1], v[132:133] op_sel_hi:[1,0,1]
	v_pk_fma_f32 v[134:135], v[12:13], s[0:1], v[134:135] op_sel_hi:[1,0,1]
	v_pk_fma_f32 v[136:137], v[14:15], s[0:1], v[136:137] op_sel_hi:[1,0,1]
	v_readlane_b32 s0, v167, 18
	s_waitcnt vmcnt(15)
	v_cvt_scalef32_pk_f32_fp4 v[0:1], v148, 1.0
	v_cvt_scalef32_pk_f32_fp4 v[2:3], v148, 1.0 op_sel:[1,0,0]
	v_cvt_scalef32_pk_f32_fp4 v[4:5], v148, 1.0 op_sel:[0,1,0]
	v_cvt_scalef32_pk_f32_fp4 v[6:7], v148, 1.0 op_sel:[1,1,0]
	v_cvt_scalef32_pk_f32_fp4 v[8:9], v149, 1.0
	v_cvt_scalef32_pk_f32_fp4 v[10:11], v149, 1.0 op_sel:[1,0,0]
	v_cvt_scalef32_pk_f32_fp4 v[12:13], v149, 1.0 op_sel:[0,1,0]
	v_cvt_scalef32_pk_f32_fp4 v[14:15], v149, 1.0 op_sel:[1,1,0]
	v_readlane_b32 s54, v92, 34
	s_lshl_b32 s56, s54, 9
	s_add_u32 s56, s64, s56
	s_addc_u32 s57, s65, 0
	global_load_dwordx2 v[148:149], v227, s[56:57]
	v_pk_fma_f32 v[130:131], v[0:1], s[0:1], v[130:131] op_sel_hi:[1,0,1]
	v_pk_fma_f32 v[138:139], v[2:3], s[0:1], v[138:139] op_sel_hi:[1,0,1]
	v_pk_fma_f32 v[140:141], v[4:5], s[0:1], v[140:141] op_sel_hi:[1,0,1]
	v_pk_fma_f32 v[142:143], v[6:7], s[0:1], v[142:143] op_sel_hi:[1,0,1]
	v_pk_fma_f32 v[128:129], v[8:9], s[0:1], v[128:129] op_sel_hi:[1,0,1]
	v_pk_fma_f32 v[132:133], v[10:11], s[0:1], v[132:133] op_sel_hi:[1,0,1]
	v_pk_fma_f32 v[134:135], v[12:13], s[0:1], v[134:135] op_sel_hi:[1,0,1]
	v_pk_fma_f32 v[136:137], v[14:15], s[0:1], v[136:137] op_sel_hi:[1,0,1]
	v_readlane_b32 s0, v167, 19
	s_waitcnt vmcnt(15)
	v_cvt_scalef32_pk_f32_fp4 v[0:1], v150, 1.0
	v_cvt_scalef32_pk_f32_fp4 v[2:3], v150, 1.0 op_sel:[1,0,0]
	v_cvt_scalef32_pk_f32_fp4 v[4:5], v150, 1.0 op_sel:[0,1,0]
	v_cvt_scalef32_pk_f32_fp4 v[6:7], v150, 1.0 op_sel:[1,1,0]
	v_cvt_scalef32_pk_f32_fp4 v[8:9], v151, 1.0
	v_cvt_scalef32_pk_f32_fp4 v[10:11], v151, 1.0 op_sel:[1,0,0]
	v_cvt_scalef32_pk_f32_fp4 v[12:13], v151, 1.0 op_sel:[0,1,0]
	v_cvt_scalef32_pk_f32_fp4 v[14:15], v151, 1.0 op_sel:[1,1,0]
	v_readlane_b32 s54, v92, 35
	s_lshl_b32 s56, s54, 9
	s_add_u32 s56, s64, s56
	s_addc_u32 s57, s65, 0
	global_load_dwordx2 v[150:151], v227, s[56:57]
	v_pk_fma_f32 v[130:131], v[0:1], s[0:1], v[130:131] op_sel_hi:[1,0,1]
	v_pk_fma_f32 v[138:139], v[2:3], s[0:1], v[138:139] op_sel_hi:[1,0,1]
	v_pk_fma_f32 v[140:141], v[4:5], s[0:1], v[140:141] op_sel_hi:[1,0,1]
	v_pk_fma_f32 v[142:143], v[6:7], s[0:1], v[142:143] op_sel_hi:[1,0,1]
	v_pk_fma_f32 v[128:129], v[8:9], s[0:1], v[128:129] op_sel_hi:[1,0,1]
	v_pk_fma_f32 v[132:133], v[10:11], s[0:1], v[132:133] op_sel_hi:[1,0,1]
	v_pk_fma_f32 v[134:135], v[12:13], s[0:1], v[134:135] op_sel_hi:[1,0,1]
	v_pk_fma_f32 v[136:137], v[14:15], s[0:1], v[136:137] op_sel_hi:[1,0,1]
	v_readlane_b32 s0, v167, 20
	s_waitcnt vmcnt(15)
; __device__ void peer_gather_phase(const Params& P, int l, bool do_store) {
;     ...
;         v8[2 * pr] = *(const uint2*)(V + (size_t)ea * 512);
;         v8[2 * pr + 1] = *(const uint2*)(V + (size_t)eb * 512);
;     ...
;       for (int j = 0; j < 8; ++j) {
;         const float a = __builtin_bit_cast(float, __builtin_amdgcn_readlane(__builtin_bit_cast(int, avec), kb + j));
;         const f32x2 aa = f32x2{a, a};
;         y[0] += aa * __builtin_amdgcn_cvt_scalef32_pk_f32_fp4(v8[j].x, 1.0f, 0); y[1] += aa * __builtin_amdgcn_cvt_scalef32_pk_f32_fp4(v8[j].x, 1.0f, 1);
;         y[2] += aa * __builtin_amdgcn_cvt_scalef32_pk_f32_fp4(v8[j].x, 1.0f, 2); y[3] += aa * __builtin_amdgcn_cvt_scalef32_pk_f32_fp4(v8[j].x, 1.0f, 3);
;         y[4] += aa * __builtin_amdgcn_cvt_scalef32_pk_f32_fp4(v8[j].y, 1.0f, 0); y[5] += aa * __builtin_amdgcn_cvt_scalef32_pk_f32_fp4(v8[j].y, 1.0f, 1);
;         y[6] += aa * __builtin_amdgcn_cvt_scalef32_pk_f32_fp4(v8[j].y, 1.0f, 2); y[7] += aa * __builtin_amdgcn_cvt_scalef32_pk_f32_fp4(v8[j].y, 1.0f, 3);
;       }
	v_cvt_scalef32_pk_f32_fp4 v[0:1], v152, 1.0
	v_cvt_scalef32_pk_f32_fp4 v[2:3], v152, 1.0 op_sel:[1,0,0]
	v_cvt_scalef32_pk_f32_fp4 v[4:5], v152, 1.0 op_sel:[0,1,0]
	v_cvt_scalef32_pk_f32_fp4 v[6:7], v152, 1.0 op_sel:[1,1,0]
	v_cvt_scalef32_pk_f32_fp4 v[8:9], v153, 1.0
	v_cvt_scalef32_pk_f32_fp4 v[10:11], v153, 1.0 op_sel:[1,0,0]
	v_cvt_scalef32_pk_f32_fp4 v[12:13], v153, 1.0 op_sel:[0,1,0]
	v_cvt_scalef32_pk_f32_fp4 v[14:15], v153, 1.0 op_sel:[1,1,0]
	v_readlane_b32 s54, v92, 36
	s_lshl_b32 s56, s54, 9
	s_add_u32 s56, s64, s56
	s_addc_u32 s57, s65, 0
	global_load_dwordx2 v[152:153], v227, s[56:57]
	v_pk_fma_f32 v[130:131], v[0:1], s[0:1], v[130:131] op_sel_hi:[1,0,1]
	v_pk_fma_f32 v[138:139], v[2:3], s[0:1], v[138:139] op_sel_hi:[1,0,1]
	v_pk_fma_f32 v[140:141], v[4:5], s[0:1], v[140:141] op_sel_hi:[1,0,1]
	v_pk_fma_f32 v[142:143], v[6:7], s[0:1], v[142:143] op_sel_hi:[1,0,1]
	v_pk_fma_f32 v[128:129], v[8:9], s[0:1], v[128:129] op_sel_hi:[1,0,1]
	v_pk_fma_f32 v[132:133], v[10:11], s[0:1], v[132:133] op_sel_hi:[1,0,1]
	v_pk_fma_f32 v[134:135], v[12:13], s[0:1], v[134:135] op_sel_hi:[1,0,1]
	v_pk_fma_f32 v[136:137], v[14:15], s[0:1], v[136:137] op_sel_hi:[1,0,1]
	v_readlane_b32 s0, v167, 21
	s_waitcnt vmcnt(15)
	v_cvt_scalef32_pk_f32_fp4 v[0:1], v154, 1.0
	v_cvt_scalef32_pk_f32_fp4 v[2:3], v154, 1.0 op_sel:[1,0,0]
	v_cvt_scalef32_pk_f32_fp4 v[4:5], v154, 1.0 op_sel:[0,1,0]
	v_cvt_scalef32_pk_f32_fp4 v[6:7], v154, 1.0 op_sel:[1,1,0]
	v_cvt_scalef32_pk_f32_fp4 v[8:9], v155, 1.0
	v_cvt_scalef32_pk_f32_fp4 v[10:11], v155, 1.0 op_sel:[1,0,0]
	v_cvt_scalef32_pk_f32_fp4 v[12:13], v155, 1.0 op_sel:[0,1,0]
	v_cvt_scalef32_pk_f32_fp4 v[14:15], v155, 1.0 op_sel:[1,1,0]
	v_readlane_b32 s54, v92, 37
	s_lshl_b32 s56, s54, 9
	s_add_u32 s56, s64, s56
	s_addc_u32 s57, s65, 0
	global_load_dwordx2 v[154:155], v227, s[56:57]
	v_pk_fma_f32 v[130:131], v[0:1], s[0:1], v[130:131] op_sel_hi:[1,0,1]
	v_pk_fma_f32 v[138:139], v[2:3], s[0:1], v[138:139] op_sel_hi:[1,0,1]
	v_pk_fma_f32 v[140:141], v[4:5], s[0:1], v[140:141] op_sel_hi:[1,0,1]
	v_pk_fma_f32 v[142:143], v[6:7], s[0:1], v[142:143] op_sel_hi:[1,0,1]
	v_pk_fma_f32 v[128:129], v[8:9], s[0:1], v[128:129] op_sel_hi:[1,0,1]
	v_pk_fma_f32 v[132:133], v[10:11], s[0:1], v[132:133] op_sel_hi:[1,0,1]
	v_pk_fma_f32 v[134:135], v[12:13], s[0:1], v[134:135] op_sel_hi:[1,0,1]
	v_pk_fma_f32 v[136:137], v[14:15], s[0:1], v[136:137] op_sel_hi:[1,0,1]
	v_readlane_b32 s0, v167, 22
	s_waitcnt vmcnt(15)
	v_cvt_scalef32_pk_f32_fp4 v[0:1], v156, 1.0
	v_cvt_scalef32_pk_f32_fp4 v[2:3], v156, 1.0 op_sel:[1,0,0]
	v_cvt_scalef32_pk_f32_fp4 v[4:5], v156, 1.0 op_sel:[0,1,0]
	v_cvt_scalef32_pk_f32_fp4 v[6:7], v156, 1.0 op_sel:[1,1,0]
	v_cvt_scalef32_pk_f32_fp4 v[8:9], v157, 1.0
	v_cvt_scalef32_pk_f32_fp4 v[10:11], v157, 1.0 op_sel:[1,0,0]
	v_cvt_scalef32_pk_f32_fp4 v[12:13], v157, 1.0 op_sel:[0,1,0]
	v_cvt_scalef32_pk_f32_fp4 v[14:15], v157, 1.0 op_sel:[1,1,0]
	v_readlane_b32 s54, v92, 38
	s_lshl_b32 s56, s54, 9
	s_add_u32 s56, s64, s56
	s_addc_u32 s57, s65, 0
	global_load_dwordx2 v[156:157], v227, s[56:57]
	v_pk_fma_f32 v[130:131], v[0:1], s[0:1], v[130:131] op_sel_hi:[1,0,1]
	v_pk_fma_f32 v[138:139], v[2:3], s[0:1], v[138:139] op_sel_hi:[1,0,1]
	v_pk_fma_f32 v[140:141], v[4:5], s[0:1], v[140:141] op_sel_hi:[1,0,1]
	v_pk_fma_f32 v[142:143], v[6:7], s[0:1], v[142:143] op_sel_hi:[1,0,1]
	v_pk_fma_f32 v[128:129], v[8:9], s[0:1], v[128:129] op_sel_hi:[1,0,1]
	v_pk_fma_f32 v[132:133], v[10:11], s[0:1], v[132:133] op_sel_hi:[1,0,1]
	v_pk_fma_f32 v[134:135], v[12:13], s[0:1], v[134:135] op_sel_hi:[1,0,1]
	v_pk_fma_f32 v[136:137], v[14:15], s[0:1], v[136:137] op_sel_hi:[1,0,1]
	v_readlane_b32 s0, v167, 23
	s_waitcnt vmcnt(15)
	v_cvt_scalef32_pk_f32_fp4 v[0:1], v158, 1.0
	v_cvt_scalef32_pk_f32_fp4 v[2:3], v158, 1.0 op_sel:[1,0,0]
	v_cvt_scalef32_pk_f32_fp4 v[4:5], v158, 1.0 op_sel:[0,1,0]
	v_cvt_scalef32_pk_f32_fp4 v[6:7], v158, 1.0 op_sel:[1,1,0]
	v_cvt_scalef32_pk_f32_fp4 v[8:9], v159, 1.0
	v_cvt_scalef32_pk_f32_fp4 v[10:11], v159, 1.0 op_sel:[1,0,0]
	v_cvt_scalef32_pk_f32_fp4 v[12:13], v159, 1.0 op_sel:[0,1,0]
	v_cvt_scalef32_pk_f32_fp4 v[14:15], v159, 1.0 op_sel:[1,1,0]
	v_readlane_b32 s54, v92, 39
	s_lshl_b32 s56, s54, 9
	s_add_u32 s56, s64, s56
	s_addc_u32 s57, s65, 0
	global_load_dwordx2 v[158:159], v227, s[56:57]
	v_pk_fma_f32 v[130:131], v[0:1], s[0:1], v[130:131] op_sel_hi:[1,0,1]
	v_pk_fma_f32 v[138:139], v[2:3], s[0:1], v[138:139] op_sel_hi:[1,0,1]
	v_pk_fma_f32 v[140:141], v[4:5], s[0:1], v[140:141] op_sel_hi:[1,0,1]
	v_pk_fma_f32 v[142:143], v[6:7], s[0:1], v[142:143] op_sel_hi:[1,0,1]
	v_pk_fma_f32 v[128:129], v[8:9], s[0:1], v[128:129] op_sel_hi:[1,0,1]
	v_pk_fma_f32 v[132:133], v[10:11], s[0:1], v[132:133] op_sel_hi:[1,0,1]
	v_pk_fma_f32 v[134:135], v[12:13], s[0:1], v[134:135] op_sel_hi:[1,0,1]
	v_pk_fma_f32 v[136:137], v[14:15], s[0:1], v[136:137] op_sel_hi:[1,0,1]
	v_readlane_b32 s0, v167, 24
	s_waitcnt vmcnt(15)
	v_cvt_scalef32_pk_f32_fp4 v[0:1], v168, 1.0
	v_cvt_scalef32_pk_f32_fp4 v[2:3], v168, 1.0 op_sel:[1,0,0]
	v_cvt_scalef32_pk_f32_fp4 v[4:5], v168, 1.0 op_sel:[0,1,0]
	v_cvt_scalef32_pk_f32_fp4 v[6:7], v168, 1.0 op_sel:[1,1,0]
	v_cvt_scalef32_pk_f32_fp4 v[8:9], v169, 1.0
	v_cvt_scalef32_pk_f32_fp4 v[10:11], v169, 1.0 op_sel:[1,0,0]
	v_cvt_scalef32_pk_f32_fp4 v[12:13], v169, 1.0 op_sel:[0,1,0]
	v_cvt_scalef32_pk_f32_fp4 v[14:15], v169, 1.0 op_sel:[1,1,0]
	v_readlane_b32 s54, v92, 40
	s_lshl_b32 s56, s54, 9
	s_add_u32 s56, s64, s56
	s_addc_u32 s57, s65, 0
	global_load_dwordx2 v[168:169], v227, s[56:57]
	v_pk_fma_f32 v[130:131], v[0:1], s[0:1], v[130:131] op_sel_hi:[1,0,1]
	v_pk_fma_f32 v[138:139], v[2:3], s[0:1], v[138:139] op_sel_hi:[1,0,1]
	v_pk_fma_f32 v[140:141], v[4:5], s[0:1], v[140:141] op_sel_hi:[1,0,1]
	v_pk_fma_f32 v[142:143], v[6:7], s[0:1], v[142:143] op_sel_hi:[1,0,1]
	v_pk_fma_f32 v[128:129], v[8:9], s[0:1], v[128:129] op_sel_hi:[1,0,1]
	v_pk_fma_f32 v[132:133], v[10:11], s[0:1], v[132:133] op_sel_hi:[1,0,1]
	v_pk_fma_f32 v[134:135], v[12:13], s[0:1], v[134:135] op_sel_hi:[1,0,1]
	v_pk_fma_f32 v[136:137], v[14:15], s[0:1], v[136:137] op_sel_hi:[1,0,1]
	v_readlane_b32 s0, v167, 25
	s_waitcnt vmcnt(15)
; __device__ void peer_gather_phase(const Params& P, int l, bool do_store) {
;     ...
;         v8[2 * pr] = *(const uint2*)(V + (size_t)ea * 512);
;         v8[2 * pr + 1] = *(const uint2*)(V + (size_t)eb * 512);
;     ...
;       for (int j = 0; j < 8; ++j) {
;         const float a = __builtin_bit_cast(float, __builtin_amdgcn_readlane(__builtin_bit_cast(int, avec), kb + j));
;         const f32x2 aa = f32x2{a, a};
;         y[0] += aa * __builtin_amdgcn_cvt_scalef32_pk_f32_fp4(v8[j].x, 1.0f, 0); y[1] += aa * __builtin_amdgcn_cvt_scalef32_pk_f32_fp4(v8[j].x, 1.0f, 1);
;         y[2] += aa * __builtin_amdgcn_cvt_scalef32_pk_f32_fp4(v8[j].x, 1.0f, 2); y[3] += aa * __builtin_amdgcn_cvt_scalef32_pk_f32_fp4(v8[j].x, 1.0f, 3);
;         y[4] += aa * __builtin_amdgcn_cvt_scalef32_pk_f32_fp4(v8[j].y, 1.0f, 0); y[5] += aa * __builtin_amdgcn_cvt_scalef32_pk_f32_fp4(v8[j].y, 1.0f, 1);
;         y[6] += aa * __builtin_amdgcn_cvt_scalef32_pk_f32_fp4(v8[j].y, 1.0f, 2); y[7] += aa * __builtin_amdgcn_cvt_scalef32_pk_f32_fp4(v8[j].y, 1.0f, 3);
;       }
	v_cvt_scalef32_pk_f32_fp4 v[0:1], v170, 1.0
	v_cvt_scalef32_pk_f32_fp4 v[2:3], v170, 1.0 op_sel:[1,0,0]
	v_cvt_scalef32_pk_f32_fp4 v[4:5], v170, 1.0 op_sel:[0,1,0]
	v_cvt_scalef32_pk_f32_fp4 v[6:7], v170, 1.0 op_sel:[1,1,0]
	v_cvt_scalef32_pk_f32_fp4 v[8:9], v171, 1.0
	v_cvt_scalef32_pk_f32_fp4 v[10:11], v171, 1.0 op_sel:[1,0,0]
	v_cvt_scalef32_pk_f32_fp4 v[12:13], v171, 1.0 op_sel:[0,1,0]
	v_cvt_scalef32_pk_f32_fp4 v[14:15], v171, 1.0 op_sel:[1,1,0]
	v_readlane_b32 s54, v92, 41
	s_lshl_b32 s56, s54, 9
	s_add_u32 s56, s64, s56
	s_addc_u32 s57, s65, 0
	global_load_dwordx2 v[170:171], v227, s[56:57]
	v_pk_fma_f32 v[130:131], v[0:1], s[0:1], v[130:131] op_sel_hi:[1,0,1]
	v_pk_fma_f32 v[138:139], v[2:3], s[0:1], v[138:139] op_sel_hi:[1,0,1]
	v_pk_fma_f32 v[140:141], v[4:5], s[0:1], v[140:141] op_sel_hi:[1,0,1]
	v_pk_fma_f32 v[142:143], v[6:7], s[0:1], v[142:143] op_sel_hi:[1,0,1]
	v_pk_fma_f32 v[128:129], v[8:9], s[0:1], v[128:129] op_sel_hi:[1,0,1]
	v_pk_fma_f32 v[132:133], v[10:11], s[0:1], v[132:133] op_sel_hi:[1,0,1]
	v_pk_fma_f32 v[134:135], v[12:13], s[0:1], v[134:135] op_sel_hi:[1,0,1]
	v_pk_fma_f32 v[136:137], v[14:15], s[0:1], v[136:137] op_sel_hi:[1,0,1]
	v_readlane_b32 s0, v167, 26
	s_waitcnt vmcnt(15)
	v_cvt_scalef32_pk_f32_fp4 v[0:1], v172, 1.0
	v_cvt_scalef32_pk_f32_fp4 v[2:3], v172, 1.0 op_sel:[1,0,0]
	v_cvt_scalef32_pk_f32_fp4 v[4:5], v172, 1.0 op_sel:[0,1,0]
	v_cvt_scalef32_pk_f32_fp4 v[6:7], v172, 1.0 op_sel:[1,1,0]
	v_cvt_scalef32_pk_f32_fp4 v[8:9], v173, 1.0
	v_cvt_scalef32_pk_f32_fp4 v[10:11], v173, 1.0 op_sel:[1,0,0]
	v_cvt_scalef32_pk_f32_fp4 v[12:13], v173, 1.0 op_sel:[0,1,0]
	v_cvt_scalef32_pk_f32_fp4 v[14:15], v173, 1.0 op_sel:[1,1,0]
	v_readlane_b32 s54, v92, 42
	s_lshl_b32 s56, s54, 9
	s_add_u32 s56, s64, s56
	s_addc_u32 s57, s65, 0
	global_load_dwordx2 v[172:173], v227, s[56:57]
	v_pk_fma_f32 v[130:131], v[0:1], s[0:1], v[130:131] op_sel_hi:[1,0,1]
	v_pk_fma_f32 v[138:139], v[2:3], s[0:1], v[138:139] op_sel_hi:[1,0,1]
	v_pk_fma_f32 v[140:141], v[4:5], s[0:1], v[140:141] op_sel_hi:[1,0,1]
	v_pk_fma_f32 v[142:143], v[6:7], s[0:1], v[142:143] op_sel_hi:[1,0,1]
	v_pk_fma_f32 v[128:129], v[8:9], s[0:1], v[128:129] op_sel_hi:[1,0,1]
	v_pk_fma_f32 v[132:133], v[10:11], s[0:1], v[132:133] op_sel_hi:[1,0,1]
	v_pk_fma_f32 v[134:135], v[12:13], s[0:1], v[134:135] op_sel_hi:[1,0,1]
	v_pk_fma_f32 v[136:137], v[14:15], s[0:1], v[136:137] op_sel_hi:[1,0,1]
	v_readlane_b32 s0, v167, 27
	s_waitcnt vmcnt(15)
	v_cvt_scalef32_pk_f32_fp4 v[0:1], v174, 1.0
	v_cvt_scalef32_pk_f32_fp4 v[2:3], v174, 1.0 op_sel:[1,0,0]
	v_cvt_scalef32_pk_f32_fp4 v[4:5], v174, 1.0 op_sel:[0,1,0]
	v_cvt_scalef32_pk_f32_fp4 v[6:7], v174, 1.0 op_sel:[1,1,0]
	v_cvt_scalef32_pk_f32_fp4 v[8:9], v175, 1.0
	v_cvt_scalef32_pk_f32_fp4 v[10:11], v175, 1.0 op_sel:[1,0,0]
	v_cvt_scalef32_pk_f32_fp4 v[12:13], v175, 1.0 op_sel:[0,1,0]
	v_cvt_scalef32_pk_f32_fp4 v[14:15], v175, 1.0 op_sel:[1,1,0]
	v_readlane_b32 s54, v92, 43
	s_lshl_b32 s56, s54, 9
	s_add_u32 s56, s64, s56
	s_addc_u32 s57, s65, 0
	global_load_dwordx2 v[174:175], v227, s[56:57]
	v_pk_fma_f32 v[130:131], v[0:1], s[0:1], v[130:131] op_sel_hi:[1,0,1]
	v_pk_fma_f32 v[138:139], v[2:3], s[0:1], v[138:139] op_sel_hi:[1,0,1]
	v_pk_fma_f32 v[140:141], v[4:5], s[0:1], v[140:141] op_sel_hi:[1,0,1]
	v_pk_fma_f32 v[142:143], v[6:7], s[0:1], v[142:143] op_sel_hi:[1,0,1]
	v_pk_fma_f32 v[128:129], v[8:9], s[0:1], v[128:129] op_sel_hi:[1,0,1]
	v_pk_fma_f32 v[132:133], v[10:11], s[0:1], v[132:133] op_sel_hi:[1,0,1]
	v_pk_fma_f32 v[134:135], v[12:13], s[0:1], v[134:135] op_sel_hi:[1,0,1]
	v_pk_fma_f32 v[136:137], v[14:15], s[0:1], v[136:137] op_sel_hi:[1,0,1]
	v_readlane_b32 s0, v167, 28
	s_waitcnt vmcnt(15)
	v_cvt_scalef32_pk_f32_fp4 v[0:1], v180, 1.0
	v_cvt_scalef32_pk_f32_fp4 v[2:3], v180, 1.0 op_sel:[1,0,0]
	v_cvt_scalef32_pk_f32_fp4 v[4:5], v180, 1.0 op_sel:[0,1,0]
	v_cvt_scalef32_pk_f32_fp4 v[6:7], v180, 1.0 op_sel:[1,1,0]
	v_cvt_scalef32_pk_f32_fp4 v[8:9], v181, 1.0
	v_cvt_scalef32_pk_f32_fp4 v[10:11], v181, 1.0 op_sel:[1,0,0]
	v_cvt_scalef32_pk_f32_fp4 v[12:13], v181, 1.0 op_sel:[0,1,0]
	v_cvt_scalef32_pk_f32_fp4 v[14:15], v181, 1.0 op_sel:[1,1,0]
	v_readlane_b32 s54, v92, 44
	s_lshl_b32 s56, s54, 9
	s_add_u32 s56, s64, s56
	s_addc_u32 s57, s65, 0
	global_load_dwordx2 v[180:181], v227, s[56:57]
	v_pk_fma_f32 v[130:131], v[0:1], s[0:1], v[130:131] op_sel_hi:[1,0,1]
	v_pk_fma_f32 v[138:139], v[2:3], s[0:1], v[138:139] op_sel_hi:[1,0,1]
	v_pk_fma_f32 v[140:141], v[4:5], s[0:1], v[140:141] op_sel_hi:[1,0,1]
	v_pk_fma_f32 v[142:143], v[6:7], s[0:1], v[142:143] op_sel_hi:[1,0,1]
	v_pk_fma_f32 v[128:129], v[8:9], s[0:1], v[128:129] op_sel_hi:[1,0,1]
	v_pk_fma_f32 v[132:133], v[10:11], s[0:1], v[132:133] op_sel_hi:[1,0,1]
	v_pk_fma_f32 v[134:135], v[12:13], s[0:1], v[134:135] op_sel_hi:[1,0,1]
	v_pk_fma_f32 v[136:137], v[14:15], s[0:1], v[136:137] op_sel_hi:[1,0,1]
	v_readlane_b32 s0, v167, 29
	s_waitcnt vmcnt(15)
	v_cvt_scalef32_pk_f32_fp4 v[0:1], v182, 1.0
	v_cvt_scalef32_pk_f32_fp4 v[2:3], v182, 1.0 op_sel:[1,0,0]
	v_cvt_scalef32_pk_f32_fp4 v[4:5], v182, 1.0 op_sel:[0,1,0]
	v_cvt_scalef32_pk_f32_fp4 v[6:7], v182, 1.0 op_sel:[1,1,0]
	v_cvt_scalef32_pk_f32_fp4 v[8:9], v183, 1.0
	v_cvt_scalef32_pk_f32_fp4 v[10:11], v183, 1.0 op_sel:[1,0,0]
	v_cvt_scalef32_pk_f32_fp4 v[12:13], v183, 1.0 op_sel:[0,1,0]
	v_cvt_scalef32_pk_f32_fp4 v[14:15], v183, 1.0 op_sel:[1,1,0]
	v_readlane_b32 s54, v92, 45
	s_lshl_b32 s56, s54, 9
	s_add_u32 s56, s64, s56
	s_addc_u32 s57, s65, 0
	global_load_dwordx2 v[182:183], v227, s[56:57]
	v_pk_fma_f32 v[130:131], v[0:1], s[0:1], v[130:131] op_sel_hi:[1,0,1]
	v_pk_fma_f32 v[138:139], v[2:3], s[0:1], v[138:139] op_sel_hi:[1,0,1]
	v_pk_fma_f32 v[140:141], v[4:5], s[0:1], v[140:141] op_sel_hi:[1,0,1]
	v_pk_fma_f32 v[142:143], v[6:7], s[0:1], v[142:143] op_sel_hi:[1,0,1]
	v_pk_fma_f32 v[128:129], v[8:9], s[0:1], v[128:129] op_sel_hi:[1,0,1]
	v_pk_fma_f32 v[132:133], v[10:11], s[0:1], v[132:133] op_sel_hi:[1,0,1]
	v_pk_fma_f32 v[134:135], v[12:13], s[0:1], v[134:135] op_sel_hi:[1,0,1]
	v_pk_fma_f32 v[136:137], v[14:15], s[0:1], v[136:137] op_sel_hi:[1,0,1]
	v_readlane_b32 s0, v167, 30
	s_waitcnt vmcnt(15)
; __device__ void peer_gather_phase(const Params& P, int l, bool do_store) {
;     ...
;         v8[2 * pr] = *(const uint2*)(V + (size_t)ea * 512);
;         v8[2 * pr + 1] = *(const uint2*)(V + (size_t)eb * 512);
;     ...
;       for (int j = 0; j < 8; ++j) {
;         const float a = __builtin_bit_cast(float, __builtin_amdgcn_readlane(__builtin_bit_cast(int, avec), kb + j));
;         const f32x2 aa = f32x2{a, a};
;         y[0] += aa * __builtin_amdgcn_cvt_scalef32_pk_f32_fp4(v8[j].x, 1.0f, 0); y[1] += aa * __builtin_amdgcn_cvt_scalef32_pk_f32_fp4(v8[j].x, 1.0f, 1);
;         y[2] += aa * __builtin_amdgcn_cvt_scalef32_pk_f32_fp4(v8[j].x, 1.0f, 2); y[3] += aa * __builtin_amdgcn_cvt_scalef32_pk_f32_fp4(v8[j].x, 1.0f, 3);
;         y[4] += aa * __builtin_amdgcn_cvt_scalef32_pk_f32_fp4(v8[j].y, 1.0f, 0); y[5] += aa * __builtin_amdgcn_cvt_scalef32_pk_f32_fp4(v8[j].y, 1.0f, 1);
;         y[6] += aa * __builtin_amdgcn_cvt_scalef32_pk_f32_fp4(v8[j].y, 1.0f, 2); y[7] += aa * __builtin_amdgcn_cvt_scalef32_pk_f32_fp4(v8[j].y, 1.0f, 3);
;       }
	v_cvt_scalef32_pk_f32_fp4 v[0:1], v184, 1.0
	v_cvt_scalef32_pk_f32_fp4 v[2:3], v184, 1.0 op_sel:[1,0,0]
	v_cvt_scalef32_pk_f32_fp4 v[4:5], v184, 1.0 op_sel:[0,1,0]
	v_cvt_scalef32_pk_f32_fp4 v[6:7], v184, 1.0 op_sel:[1,1,0]
	v_cvt_scalef32_pk_f32_fp4 v[8:9], v185, 1.0
	v_cvt_scalef32_pk_f32_fp4 v[10:11], v185, 1.0 op_sel:[1,0,0]
	v_cvt_scalef32_pk_f32_fp4 v[12:13], v185, 1.0 op_sel:[0,1,0]
	v_cvt_scalef32_pk_f32_fp4 v[14:15], v185, 1.0 op_sel:[1,1,0]
	v_readlane_b32 s54, v92, 46
	s_lshl_b32 s56, s54, 9
	s_add_u32 s56, s64, s56
	s_addc_u32 s57, s65, 0
	global_load_dwordx2 v[184:185], v227, s[56:57]
	v_pk_fma_f32 v[130:131], v[0:1], s[0:1], v[130:131] op_sel_hi:[1,0,1]
	v_pk_fma_f32 v[138:139], v[2:3], s[0:1], v[138:139] op_sel_hi:[1,0,1]
	v_pk_fma_f32 v[140:141], v[4:5], s[0:1], v[140:141] op_sel_hi:[1,0,1]
	v_pk_fma_f32 v[142:143], v[6:7], s[0:1], v[142:143] op_sel_hi:[1,0,1]
	v_pk_fma_f32 v[128:129], v[8:9], s[0:1], v[128:129] op_sel_hi:[1,0,1]
	v_pk_fma_f32 v[132:133], v[10:11], s[0:1], v[132:133] op_sel_hi:[1,0,1]
	v_pk_fma_f32 v[134:135], v[12:13], s[0:1], v[134:135] op_sel_hi:[1,0,1]
	v_pk_fma_f32 v[136:137], v[14:15], s[0:1], v[136:137] op_sel_hi:[1,0,1]
	v_readlane_b32 s0, v167, 31
	s_waitcnt vmcnt(15)
	v_cvt_scalef32_pk_f32_fp4 v[0:1], v186, 1.0
	v_cvt_scalef32_pk_f32_fp4 v[2:3], v186, 1.0 op_sel:[1,0,0]
	v_cvt_scalef32_pk_f32_fp4 v[4:5], v186, 1.0 op_sel:[0,1,0]
	v_cvt_scalef32_pk_f32_fp4 v[6:7], v186, 1.0 op_sel:[1,1,0]
	v_cvt_scalef32_pk_f32_fp4 v[8:9], v187, 1.0
	v_cvt_scalef32_pk_f32_fp4 v[10:11], v187, 1.0 op_sel:[1,0,0]
	v_cvt_scalef32_pk_f32_fp4 v[12:13], v187, 1.0 op_sel:[0,1,0]
	v_cvt_scalef32_pk_f32_fp4 v[14:15], v187, 1.0 op_sel:[1,1,0]
	v_readlane_b32 s54, v92, 47
	s_lshl_b32 s56, s54, 9
	s_add_u32 s56, s64, s56
	s_addc_u32 s57, s65, 0
	global_load_dwordx2 v[186:187], v227, s[56:57]
	v_pk_fma_f32 v[130:131], v[0:1], s[0:1], v[130:131] op_sel_hi:[1,0,1]
	v_pk_fma_f32 v[138:139], v[2:3], s[0:1], v[138:139] op_sel_hi:[1,0,1]
	v_pk_fma_f32 v[140:141], v[4:5], s[0:1], v[140:141] op_sel_hi:[1,0,1]
	v_pk_fma_f32 v[142:143], v[6:7], s[0:1], v[142:143] op_sel_hi:[1,0,1]
	v_pk_fma_f32 v[128:129], v[8:9], s[0:1], v[128:129] op_sel_hi:[1,0,1]
	v_pk_fma_f32 v[132:133], v[10:11], s[0:1], v[132:133] op_sel_hi:[1,0,1]
	v_pk_fma_f32 v[134:135], v[12:13], s[0:1], v[134:135] op_sel_hi:[1,0,1]
	v_pk_fma_f32 v[136:137], v[14:15], s[0:1], v[136:137] op_sel_hi:[1,0,1]
	v_readlane_b32 s0, v167, 32
	s_waitcnt vmcnt(15)
	v_cvt_scalef32_pk_f32_fp4 v[0:1], v144, 1.0
	v_cvt_scalef32_pk_f32_fp4 v[2:3], v144, 1.0 op_sel:[1,0,0]
	v_cvt_scalef32_pk_f32_fp4 v[4:5], v144, 1.0 op_sel:[0,1,0]
	v_cvt_scalef32_pk_f32_fp4 v[6:7], v144, 1.0 op_sel:[1,1,0]
	v_cvt_scalef32_pk_f32_fp4 v[8:9], v145, 1.0
	v_cvt_scalef32_pk_f32_fp4 v[10:11], v145, 1.0 op_sel:[1,0,0]
	v_cvt_scalef32_pk_f32_fp4 v[12:13], v145, 1.0 op_sel:[0,1,0]
	v_cvt_scalef32_pk_f32_fp4 v[14:15], v145, 1.0 op_sel:[1,1,0]
	v_readlane_b32 s54, v92, 48
	s_lshl_b32 s56, s54, 9
	s_add_u32 s56, s64, s56
	s_addc_u32 s57, s65, 0
	global_load_dwordx2 v[144:145], v227, s[56:57]
	v_pk_fma_f32 v[130:131], v[0:1], s[0:1], v[130:131] op_sel_hi:[1,0,1]
	v_pk_fma_f32 v[138:139], v[2:3], s[0:1], v[138:139] op_sel_hi:[1,0,1]
	v_pk_fma_f32 v[140:141], v[4:5], s[0:1], v[140:141] op_sel_hi:[1,0,1]
	v_pk_fma_f32 v[142:143], v[6:7], s[0:1], v[142:143] op_sel_hi:[1,0,1]
	v_pk_fma_f32 v[128:129], v[8:9], s[0:1], v[128:129] op_sel_hi:[1,0,1]
	v_pk_fma_f32 v[132:133], v[10:11], s[0:1], v[132:133] op_sel_hi:[1,0,1]
	v_pk_fma_f32 v[134:135], v[12:13], s[0:1], v[134:135] op_sel_hi:[1,0,1]
	v_pk_fma_f32 v[136:137], v[14:15], s[0:1], v[136:137] op_sel_hi:[1,0,1]
	v_readlane_b32 s0, v167, 33
	s_waitcnt vmcnt(15)
	v_cvt_scalef32_pk_f32_fp4 v[0:1], v146, 1.0
	v_cvt_scalef32_pk_f32_fp4 v[2:3], v146, 1.0 op_sel:[1,0,0]
	v_cvt_scalef32_pk_f32_fp4 v[4:5], v146, 1.0 op_sel:[0,1,0]
	v_cvt_scalef32_pk_f32_fp4 v[6:7], v146, 1.0 op_sel:[1,1,0]
	v_cvt_scalef32_pk_f32_fp4 v[8:9], v147, 1.0
	v_cvt_scalef32_pk_f32_fp4 v[10:11], v147, 1.0 op_sel:[1,0,0]
	v_cvt_scalef32_pk_f32_fp4 v[12:13], v147, 1.0 op_sel:[0,1,0]
	v_cvt_scalef32_pk_f32_fp4 v[14:15], v147, 1.0 op_sel:[1,1,0]
	v_readlane_b32 s54, v92, 49
	s_lshl_b32 s56, s54, 9
	s_add_u32 s56, s64, s56
	s_addc_u32 s57, s65, 0
	global_load_dwordx2 v[146:147], v227, s[56:57]
	v_pk_fma_f32 v[130:131], v[0:1], s[0:1], v[130:131] op_sel_hi:[1,0,1]
	v_pk_fma_f32 v[138:139], v[2:3], s[0:1], v[138:139] op_sel_hi:[1,0,1]
	v_pk_fma_f32 v[140:141], v[4:5], s[0:1], v[140:141] op_sel_hi:[1,0,1]
	v_pk_fma_f32 v[142:143], v[6:7], s[0:1], v[142:143] op_sel_hi:[1,0,1]
	v_pk_fma_f32 v[128:129], v[8:9], s[0:1], v[128:129] op_sel_hi:[1,0,1]
	v_pk_fma_f32 v[132:133], v[10:11], s[0:1], v[132:133] op_sel_hi:[1,0,1]
	v_pk_fma_f32 v[134:135], v[12:13], s[0:1], v[134:135] op_sel_hi:[1,0,1]
	v_pk_fma_f32 v[136:137], v[14:15], s[0:1], v[136:137] op_sel_hi:[1,0,1]
	v_readlane_b32 s0, v167, 34
	s_waitcnt vmcnt(15)
	v_cvt_scalef32_pk_f32_fp4 v[0:1], v148, 1.0
	v_cvt_scalef32_pk_f32_fp4 v[2:3], v148, 1.0 op_sel:[1,0,0]
	v_cvt_scalef32_pk_f32_fp4 v[4:5], v148, 1.0 op_sel:[0,1,0]
	v_cvt_scalef32_pk_f32_fp4 v[6:7], v148, 1.0 op_sel:[1,1,0]
	v_cvt_scalef32_pk_f32_fp4 v[8:9], v149, 1.0
	v_cvt_scalef32_pk_f32_fp4 v[10:11], v149, 1.0 op_sel:[1,0,0]
	v_cvt_scalef32_pk_f32_fp4 v[12:13], v149, 1.0 op_sel:[0,1,0]
	v_cvt_scalef32_pk_f32_fp4 v[14:15], v149, 1.0 op_sel:[1,1,0]
	v_readlane_b32 s54, v92, 50
	s_lshl_b32 s56, s54, 9
	s_add_u32 s56, s64, s56
	s_addc_u32 s57, s65, 0
	global_load_dwordx2 v[148:149], v227, s[56:57]
	v_pk_fma_f32 v[130:131], v[0:1], s[0:1], v[130:131] op_sel_hi:[1,0,1]
	v_pk_fma_f32 v[138:139], v[2:3], s[0:1], v[138:139] op_sel_hi:[1,0,1]
	v_pk_fma_f32 v[140:141], v[4:5], s[0:1], v[140:141] op_sel_hi:[1,0,1]
	v_pk_fma_f32 v[142:143], v[6:7], s[0:1], v[142:143] op_sel_hi:[1,0,1]
	v_pk_fma_f32 v[128:129], v[8:9], s[0:1], v[128:129] op_sel_hi:[1,0,1]
	v_pk_fma_f32 v[132:133], v[10:11], s[0:1], v[132:133] op_sel_hi:[1,0,1]
	v_pk_fma_f32 v[134:135], v[12:13], s[0:1], v[134:135] op_sel_hi:[1,0,1]
	v_pk_fma_f32 v[136:137], v[14:15], s[0:1], v[136:137] op_sel_hi:[1,0,1]
	v_readlane_b32 s0, v167, 35
	s_waitcnt vmcnt(15)
; __device__ void peer_gather_phase(const Params& P, int l, bool do_store) {
;     ...
;         v8[2 * pr] = *(const uint2*)(V + (size_t)ea * 512);
;         v8[2 * pr + 1] = *(const uint2*)(V + (size_t)eb * 512);
;     ...
;       for (int j = 0; j < 8; ++j) {
;         const float a = __builtin_bit_cast(float, __builtin_amdgcn_readlane(__builtin_bit_cast(int, avec), kb + j));
;         const f32x2 aa = f32x2{a, a};
;         y[0] += aa * __builtin_amdgcn_cvt_scalef32_pk_f32_fp4(v8[j].x, 1.0f, 0); y[1] += aa * __builtin_amdgcn_cvt_scalef32_pk_f32_fp4(v8[j].x, 1.0f, 1);
;         y[2] += aa * __builtin_amdgcn_cvt_scalef32_pk_f32_fp4(v8[j].x, 1.0f, 2); y[3] += aa * __builtin_amdgcn_cvt_scalef32_pk_f32_fp4(v8[j].x, 1.0f, 3);
;         y[4] += aa * __builtin_amdgcn_cvt_scalef32_pk_f32_fp4(v8[j].y, 1.0f, 0); y[5] += aa * __builtin_amdgcn_cvt_scalef32_pk_f32_fp4(v8[j].y, 1.0f, 1);
;         y[6] += aa * __builtin_amdgcn_cvt_scalef32_pk_f32_fp4(v8[j].y, 1.0f, 2); y[7] += aa * __builtin_amdgcn_cvt_scalef32_pk_f32_fp4(v8[j].y, 1.0f, 3);
;       }
	v_cvt_scalef32_pk_f32_fp4 v[0:1], v150, 1.0
	v_cvt_scalef32_pk_f32_fp4 v[2:3], v150, 1.0 op_sel:[1,0,0]
	v_cvt_scalef32_pk_f32_fp4 v[4:5], v150, 1.0 op_sel:[0,1,0]
	v_cvt_scalef32_pk_f32_fp4 v[6:7], v150, 1.0 op_sel:[1,1,0]
	v_cvt_scalef32_pk_f32_fp4 v[8:9], v151, 1.0
	v_cvt_scalef32_pk_f32_fp4 v[10:11], v151, 1.0 op_sel:[1,0,0]
	v_cvt_scalef32_pk_f32_fp4 v[12:13], v151, 1.0 op_sel:[0,1,0]
	v_cvt_scalef32_pk_f32_fp4 v[14:15], v151, 1.0 op_sel:[1,1,0]
	v_readlane_b32 s54, v92, 51
	s_lshl_b32 s56, s54, 9
	s_add_u32 s56, s64, s56
	s_addc_u32 s57, s65, 0
	global_load_dwordx2 v[150:151], v227, s[56:57]
	v_pk_fma_f32 v[130:131], v[0:1], s[0:1], v[130:131] op_sel_hi:[1,0,1]
	v_pk_fma_f32 v[138:139], v[2:3], s[0:1], v[138:139] op_sel_hi:[1,0,1]
	v_pk_fma_f32 v[140:141], v[4:5], s[0:1], v[140:141] op_sel_hi:[1,0,1]
	v_pk_fma_f32 v[142:143], v[6:7], s[0:1], v[142:143] op_sel_hi:[1,0,1]
	v_pk_fma_f32 v[128:129], v[8:9], s[0:1], v[128:129] op_sel_hi:[1,0,1]
	v_pk_fma_f32 v[132:133], v[10:11], s[0:1], v[132:133] op_sel_hi:[1,0,1]
	v_pk_fma_f32 v[134:135], v[12:13], s[0:1], v[134:135] op_sel_hi:[1,0,1]
	v_pk_fma_f32 v[136:137], v[14:15], s[0:1], v[136:137] op_sel_hi:[1,0,1]
	v_readlane_b32 s0, v167, 36
	s_waitcnt vmcnt(15)
	v_cvt_scalef32_pk_f32_fp4 v[0:1], v152, 1.0
	v_cvt_scalef32_pk_f32_fp4 v[2:3], v152, 1.0 op_sel:[1,0,0]
	v_cvt_scalef32_pk_f32_fp4 v[4:5], v152, 1.0 op_sel:[0,1,0]
	v_cvt_scalef32_pk_f32_fp4 v[6:7], v152, 1.0 op_sel:[1,1,0]
	v_cvt_scalef32_pk_f32_fp4 v[8:9], v153, 1.0
	v_cvt_scalef32_pk_f32_fp4 v[10:11], v153, 1.0 op_sel:[1,0,0]
	v_cvt_scalef32_pk_f32_fp4 v[12:13], v153, 1.0 op_sel:[0,1,0]
	v_cvt_scalef32_pk_f32_fp4 v[14:15], v153, 1.0 op_sel:[1,1,0]
	v_readlane_b32 s54, v92, 52
	s_lshl_b32 s56, s54, 9
	s_add_u32 s56, s64, s56
	s_addc_u32 s57, s65, 0
	global_load_dwordx2 v[152:153], v227, s[56:57]
	v_pk_fma_f32 v[130:131], v[0:1], s[0:1], v[130:131] op_sel_hi:[1,0,1]
	v_pk_fma_f32 v[138:139], v[2:3], s[0:1], v[138:139] op_sel_hi:[1,0,1]
	v_pk_fma_f32 v[140:141], v[4:5], s[0:1], v[140:141] op_sel_hi:[1,0,1]
	v_pk_fma_f32 v[142:143], v[6:7], s[0:1], v[142:143] op_sel_hi:[1,0,1]
	v_pk_fma_f32 v[128:129], v[8:9], s[0:1], v[128:129] op_sel_hi:[1,0,1]
	v_pk_fma_f32 v[132:133], v[10:11], s[0:1], v[132:133] op_sel_hi:[1,0,1]
	v_pk_fma_f32 v[134:135], v[12:13], s[0:1], v[134:135] op_sel_hi:[1,0,1]
	v_pk_fma_f32 v[136:137], v[14:15], s[0:1], v[136:137] op_sel_hi:[1,0,1]
	v_readlane_b32 s0, v167, 37
	s_waitcnt vmcnt(15)
	v_cvt_scalef32_pk_f32_fp4 v[0:1], v154, 1.0
	v_cvt_scalef32_pk_f32_fp4 v[2:3], v154, 1.0 op_sel:[1,0,0]
	v_cvt_scalef32_pk_f32_fp4 v[4:5], v154, 1.0 op_sel:[0,1,0]
	v_cvt_scalef32_pk_f32_fp4 v[6:7], v154, 1.0 op_sel:[1,1,0]
	v_cvt_scalef32_pk_f32_fp4 v[8:9], v155, 1.0
	v_cvt_scalef32_pk_f32_fp4 v[10:11], v155, 1.0 op_sel:[1,0,0]
	v_cvt_scalef32_pk_f32_fp4 v[12:13], v155, 1.0 op_sel:[0,1,0]
	v_cvt_scalef32_pk_f32_fp4 v[14:15], v155, 1.0 op_sel:[1,1,0]
	v_readlane_b32 s54, v92, 53
	s_lshl_b32 s56, s54, 9
	s_add_u32 s56, s64, s56
	s_addc_u32 s57, s65, 0
	global_load_dwordx2 v[154:155], v227, s[56:57]
	v_pk_fma_f32 v[130:131], v[0:1], s[0:1], v[130:131] op_sel_hi:[1,0,1]
	v_pk_fma_f32 v[138:139], v[2:3], s[0:1], v[138:139] op_sel_hi:[1,0,1]
	v_pk_fma_f32 v[140:141], v[4:5], s[0:1], v[140:141] op_sel_hi:[1,0,1]
	v_pk_fma_f32 v[142:143], v[6:7], s[0:1], v[142:143] op_sel_hi:[1,0,1]
	v_pk_fma_f32 v[128:129], v[8:9], s[0:1], v[128:129] op_sel_hi:[1,0,1]
	v_pk_fma_f32 v[132:133], v[10:11], s[0:1], v[132:133] op_sel_hi:[1,0,1]
	v_pk_fma_f32 v[134:135], v[12:13], s[0:1], v[134:135] op_sel_hi:[1,0,1]
	v_pk_fma_f32 v[136:137], v[14:15], s[0:1], v[136:137] op_sel_hi:[1,0,1]
	v_readlane_b32 s0, v167, 38
	s_waitcnt vmcnt(15)
	v_cvt_scalef32_pk_f32_fp4 v[0:1], v156, 1.0
	v_cvt_scalef32_pk_f32_fp4 v[2:3], v156, 1.0 op_sel:[1,0,0]
	v_cvt_scalef32_pk_f32_fp4 v[4:5], v156, 1.0 op_sel:[0,1,0]
	v_cvt_scalef32_pk_f32_fp4 v[6:7], v156, 1.0 op_sel:[1,1,0]
	v_cvt_scalef32_pk_f32_fp4 v[8:9], v157, 1.0
	v_cvt_scalef32_pk_f32_fp4 v[10:11], v157, 1.0 op_sel:[1,0,0]
	v_cvt_scalef32_pk_f32_fp4 v[12:13], v157, 1.0 op_sel:[0,1,0]
	v_cvt_scalef32_pk_f32_fp4 v[14:15], v157, 1.0 op_sel:[1,1,0]
	v_readlane_b32 s54, v92, 54
	s_lshl_b32 s56, s54, 9
	s_add_u32 s56, s64, s56
	s_addc_u32 s57, s65, 0
	global_load_dwordx2 v[156:157], v227, s[56:57]
	v_pk_fma_f32 v[130:131], v[0:1], s[0:1], v[130:131] op_sel_hi:[1,0,1]
	v_pk_fma_f32 v[138:139], v[2:3], s[0:1], v[138:139] op_sel_hi:[1,0,1]
	v_pk_fma_f32 v[140:141], v[4:5], s[0:1], v[140:141] op_sel_hi:[1,0,1]
	v_pk_fma_f32 v[142:143], v[6:7], s[0:1], v[142:143] op_sel_hi:[1,0,1]
	v_pk_fma_f32 v[128:129], v[8:9], s[0:1], v[128:129] op_sel_hi:[1,0,1]
	v_pk_fma_f32 v[132:133], v[10:11], s[0:1], v[132:133] op_sel_hi:[1,0,1]
	v_pk_fma_f32 v[134:135], v[12:13], s[0:1], v[134:135] op_sel_hi:[1,0,1]
	v_pk_fma_f32 v[136:137], v[14:15], s[0:1], v[136:137] op_sel_hi:[1,0,1]
	v_readlane_b32 s0, v167, 39
	s_waitcnt vmcnt(15)
	v_cvt_scalef32_pk_f32_fp4 v[0:1], v158, 1.0
	v_cvt_scalef32_pk_f32_fp4 v[2:3], v158, 1.0 op_sel:[1,0,0]
	v_cvt_scalef32_pk_f32_fp4 v[4:5], v158, 1.0 op_sel:[0,1,0]
	v_cvt_scalef32_pk_f32_fp4 v[6:7], v158, 1.0 op_sel:[1,1,0]
	v_cvt_scalef32_pk_f32_fp4 v[8:9], v159, 1.0
	v_cvt_scalef32_pk_f32_fp4 v[10:11], v159, 1.0 op_sel:[1,0,0]
	v_cvt_scalef32_pk_f32_fp4 v[12:13], v159, 1.0 op_sel:[0,1,0]
	v_cvt_scalef32_pk_f32_fp4 v[14:15], v159, 1.0 op_sel:[1,1,0]
	v_readlane_b32 s54, v92, 55
	s_lshl_b32 s56, s54, 9
	s_add_u32 s56, s64, s56
	s_addc_u32 s57, s65, 0
	global_load_dwordx2 v[158:159], v227, s[56:57]
	v_pk_fma_f32 v[130:131], v[0:1], s[0:1], v[130:131] op_sel_hi:[1,0,1]
	v_pk_fma_f32 v[138:139], v[2:3], s[0:1], v[138:139] op_sel_hi:[1,0,1]
	v_pk_fma_f32 v[140:141], v[4:5], s[0:1], v[140:141] op_sel_hi:[1,0,1]
	v_pk_fma_f32 v[142:143], v[6:7], s[0:1], v[142:143] op_sel_hi:[1,0,1]
	v_pk_fma_f32 v[128:129], v[8:9], s[0:1], v[128:129] op_sel_hi:[1,0,1]
	v_pk_fma_f32 v[132:133], v[10:11], s[0:1], v[132:133] op_sel_hi:[1,0,1]
	v_pk_fma_f32 v[134:135], v[12:13], s[0:1], v[134:135] op_sel_hi:[1,0,1]
	v_pk_fma_f32 v[136:137], v[14:15], s[0:1], v[136:137] op_sel_hi:[1,0,1]
	v_readlane_b32 s0, v167, 40
	s_waitcnt vmcnt(15)
; __device__ void peer_gather_phase(const Params& P, int l, bool do_store) {
;     ...
;         v8[2 * pr] = *(const uint2*)(V + (size_t)ea * 512);
;         v8[2 * pr + 1] = *(const uint2*)(V + (size_t)eb * 512);
;     ...
;       for (int j = 0; j < 8; ++j) {
;         const float a = __builtin_bit_cast(float, __builtin_amdgcn_readlane(__builtin_bit_cast(int, avec), kb + j));
;         const f32x2 aa = f32x2{a, a};
;         y[0] += aa * __builtin_amdgcn_cvt_scalef32_pk_f32_fp4(v8[j].x, 1.0f, 0); y[1] += aa * __builtin_amdgcn_cvt_scalef32_pk_f32_fp4(v8[j].x, 1.0f, 1);
;         y[2] += aa * __builtin_amdgcn_cvt_scalef32_pk_f32_fp4(v8[j].x, 1.0f, 2); y[3] += aa * __builtin_amdgcn_cvt_scalef32_pk_f32_fp4(v8[j].x, 1.0f, 3);
;         y[4] += aa * __builtin_amdgcn_cvt_scalef32_pk_f32_fp4(v8[j].y, 1.0f, 0); y[5] += aa * __builtin_amdgcn_cvt_scalef32_pk_f32_fp4(v8[j].y, 1.0f, 1);
;         y[6] += aa * __builtin_amdgcn_cvt_scalef32_pk_f32_fp4(v8[j].y, 1.0f, 2); y[7] += aa * __builtin_amdgcn_cvt_scalef32_pk_f32_fp4(v8[j].y, 1.0f, 3);
;       }
	v_cvt_scalef32_pk_f32_fp4 v[0:1], v168, 1.0
	v_cvt_scalef32_pk_f32_fp4 v[2:3], v168, 1.0 op_sel:[1,0,0]
	v_cvt_scalef32_pk_f32_fp4 v[4:5], v168, 1.0 op_sel:[0,1,0]
	v_cvt_scalef32_pk_f32_fp4 v[6:7], v168, 1.0 op_sel:[1,1,0]
	v_cvt_scalef32_pk_f32_fp4 v[8:9], v169, 1.0
	v_cvt_scalef32_pk_f32_fp4 v[10:11], v169, 1.0 op_sel:[1,0,0]
	v_cvt_scalef32_pk_f32_fp4 v[12:13], v169, 1.0 op_sel:[0,1,0]
	v_cvt_scalef32_pk_f32_fp4 v[14:15], v169, 1.0 op_sel:[1,1,0]
	v_readlane_b32 s54, v92, 56
	s_lshl_b32 s56, s54, 9
	s_add_u32 s56, s64, s56
	s_addc_u32 s57, s65, 0
	global_load_dwordx2 v[168:169], v227, s[56:57]
	v_pk_fma_f32 v[130:131], v[0:1], s[0:1], v[130:131] op_sel_hi:[1,0,1]
	v_pk_fma_f32 v[138:139], v[2:3], s[0:1], v[138:139] op_sel_hi:[1,0,1]
	v_pk_fma_f32 v[140:141], v[4:5], s[0:1], v[140:141] op_sel_hi:[1,0,1]
	v_pk_fma_f32 v[142:143], v[6:7], s[0:1], v[142:143] op_sel_hi:[1,0,1]
	v_pk_fma_f32 v[128:129], v[8:9], s[0:1], v[128:129] op_sel_hi:[1,0,1]
	v_pk_fma_f32 v[132:133], v[10:11], s[0:1], v[132:133] op_sel_hi:[1,0,1]
	v_pk_fma_f32 v[134:135], v[12:13], s[0:1], v[134:135] op_sel_hi:[1,0,1]
	v_pk_fma_f32 v[136:137], v[14:15], s[0:1], v[136:137] op_sel_hi:[1,0,1]
	v_readlane_b32 s0, v167, 41
	s_waitcnt vmcnt(15)
	v_cvt_scalef32_pk_f32_fp4 v[0:1], v170, 1.0
	v_cvt_scalef32_pk_f32_fp4 v[2:3], v170, 1.0 op_sel:[1,0,0]
	v_cvt_scalef32_pk_f32_fp4 v[4:5], v170, 1.0 op_sel:[0,1,0]
	v_cvt_scalef32_pk_f32_fp4 v[6:7], v170, 1.0 op_sel:[1,1,0]
	v_cvt_scalef32_pk_f32_fp4 v[8:9], v171, 1.0
	v_cvt_scalef32_pk_f32_fp4 v[10:11], v171, 1.0 op_sel:[1,0,0]
	v_cvt_scalef32_pk_f32_fp4 v[12:13], v171, 1.0 op_sel:[0,1,0]
	v_cvt_scalef32_pk_f32_fp4 v[14:15], v171, 1.0 op_sel:[1,1,0]
	v_readlane_b32 s54, v92, 57
	s_lshl_b32 s56, s54, 9
	s_add_u32 s56, s64, s56
	s_addc_u32 s57, s65, 0
	global_load_dwordx2 v[170:171], v227, s[56:57]
	v_pk_fma_f32 v[130:131], v[0:1], s[0:1], v[130:131] op_sel_hi:[1,0,1]
	v_pk_fma_f32 v[138:139], v[2:3], s[0:1], v[138:139] op_sel_hi:[1,0,1]
	v_pk_fma_f32 v[140:141], v[4:5], s[0:1], v[140:141] op_sel_hi:[1,0,1]
	v_pk_fma_f32 v[142:143], v[6:7], s[0:1], v[142:143] op_sel_hi:[1,0,1]
	v_pk_fma_f32 v[128:129], v[8:9], s[0:1], v[128:129] op_sel_hi:[1,0,1]
	v_pk_fma_f32 v[132:133], v[10:11], s[0:1], v[132:133] op_sel_hi:[1,0,1]
	v_pk_fma_f32 v[134:135], v[12:13], s[0:1], v[134:135] op_sel_hi:[1,0,1]
	v_pk_fma_f32 v[136:137], v[14:15], s[0:1], v[136:137] op_sel_hi:[1,0,1]
	v_readlane_b32 s0, v167, 42
	s_waitcnt vmcnt(15)
	v_cvt_scalef32_pk_f32_fp4 v[0:1], v172, 1.0
	v_cvt_scalef32_pk_f32_fp4 v[2:3], v172, 1.0 op_sel:[1,0,0]
	v_cvt_scalef32_pk_f32_fp4 v[4:5], v172, 1.0 op_sel:[0,1,0]
	v_cvt_scalef32_pk_f32_fp4 v[6:7], v172, 1.0 op_sel:[1,1,0]
	v_cvt_scalef32_pk_f32_fp4 v[8:9], v173, 1.0
	v_cvt_scalef32_pk_f32_fp4 v[10:11], v173, 1.0 op_sel:[1,0,0]
	v_cvt_scalef32_pk_f32_fp4 v[12:13], v173, 1.0 op_sel:[0,1,0]
	v_cvt_scalef32_pk_f32_fp4 v[14:15], v173, 1.0 op_sel:[1,1,0]
	v_readlane_b32 s54, v92, 58
	s_lshl_b32 s56, s54, 9
	s_add_u32 s56, s64, s56
	s_addc_u32 s57, s65, 0
	global_load_dwordx2 v[172:173], v227, s[56:57]
	v_pk_fma_f32 v[130:131], v[0:1], s[0:1], v[130:131] op_sel_hi:[1,0,1]
	v_pk_fma_f32 v[138:139], v[2:3], s[0:1], v[138:139] op_sel_hi:[1,0,1]
	v_pk_fma_f32 v[140:141], v[4:5], s[0:1], v[140:141] op_sel_hi:[1,0,1]
	v_pk_fma_f32 v[142:143], v[6:7], s[0:1], v[142:143] op_sel_hi:[1,0,1]
	v_pk_fma_f32 v[128:129], v[8:9], s[0:1], v[128:129] op_sel_hi:[1,0,1]
	v_pk_fma_f32 v[132:133], v[10:11], s[0:1], v[132:133] op_sel_hi:[1,0,1]
	v_pk_fma_f32 v[134:135], v[12:13], s[0:1], v[134:135] op_sel_hi:[1,0,1]
	v_pk_fma_f32 v[136:137], v[14:15], s[0:1], v[136:137] op_sel_hi:[1,0,1]
	v_readlane_b32 s0, v167, 43
	s_waitcnt vmcnt(15)
	v_cvt_scalef32_pk_f32_fp4 v[0:1], v174, 1.0
	v_cvt_scalef32_pk_f32_fp4 v[2:3], v174, 1.0 op_sel:[1,0,0]
	v_cvt_scalef32_pk_f32_fp4 v[4:5], v174, 1.0 op_sel:[0,1,0]
	v_cvt_scalef32_pk_f32_fp4 v[6:7], v174, 1.0 op_sel:[1,1,0]
	v_cvt_scalef32_pk_f32_fp4 v[8:9], v175, 1.0
	v_cvt_scalef32_pk_f32_fp4 v[10:11], v175, 1.0 op_sel:[1,0,0]
	v_cvt_scalef32_pk_f32_fp4 v[12:13], v175, 1.0 op_sel:[0,1,0]
	v_cvt_scalef32_pk_f32_fp4 v[14:15], v175, 1.0 op_sel:[1,1,0]
	v_readlane_b32 s54, v92, 59
	s_lshl_b32 s56, s54, 9
	s_add_u32 s56, s64, s56
	s_addc_u32 s57, s65, 0
	global_load_dwordx2 v[174:175], v227, s[56:57]
	v_pk_fma_f32 v[130:131], v[0:1], s[0:1], v[130:131] op_sel_hi:[1,0,1]
	v_pk_fma_f32 v[138:139], v[2:3], s[0:1], v[138:139] op_sel_hi:[1,0,1]
	v_pk_fma_f32 v[140:141], v[4:5], s[0:1], v[140:141] op_sel_hi:[1,0,1]
	v_pk_fma_f32 v[142:143], v[6:7], s[0:1], v[142:143] op_sel_hi:[1,0,1]
	v_pk_fma_f32 v[128:129], v[8:9], s[0:1], v[128:129] op_sel_hi:[1,0,1]
	v_pk_fma_f32 v[132:133], v[10:11], s[0:1], v[132:133] op_sel_hi:[1,0,1]
	v_pk_fma_f32 v[134:135], v[12:13], s[0:1], v[134:135] op_sel_hi:[1,0,1]
	v_pk_fma_f32 v[136:137], v[14:15], s[0:1], v[136:137] op_sel_hi:[1,0,1]
	v_readlane_b32 s0, v167, 44
	s_waitcnt vmcnt(15)
	v_cvt_scalef32_pk_f32_fp4 v[0:1], v180, 1.0
	v_cvt_scalef32_pk_f32_fp4 v[2:3], v180, 1.0 op_sel:[1,0,0]
	v_cvt_scalef32_pk_f32_fp4 v[4:5], v180, 1.0 op_sel:[0,1,0]
	v_cvt_scalef32_pk_f32_fp4 v[6:7], v180, 1.0 op_sel:[1,1,0]
	v_cvt_scalef32_pk_f32_fp4 v[8:9], v181, 1.0
	v_cvt_scalef32_pk_f32_fp4 v[10:11], v181, 1.0 op_sel:[1,0,0]
	v_cvt_scalef32_pk_f32_fp4 v[12:13], v181, 1.0 op_sel:[0,1,0]
	v_cvt_scalef32_pk_f32_fp4 v[14:15], v181, 1.0 op_sel:[1,1,0]
	v_readlane_b32 s54, v92, 60
	s_lshl_b32 s56, s54, 9
	s_add_u32 s56, s64, s56
	s_addc_u32 s57, s65, 0
	global_load_dwordx2 v[180:181], v227, s[56:57]
	v_pk_fma_f32 v[130:131], v[0:1], s[0:1], v[130:131] op_sel_hi:[1,0,1]
	v_pk_fma_f32 v[138:139], v[2:3], s[0:1], v[138:139] op_sel_hi:[1,0,1]
	v_pk_fma_f32 v[140:141], v[4:5], s[0:1], v[140:141] op_sel_hi:[1,0,1]
	v_pk_fma_f32 v[142:143], v[6:7], s[0:1], v[142:143] op_sel_hi:[1,0,1]
	v_pk_fma_f32 v[128:129], v[8:9], s[0:1], v[128:129] op_sel_hi:[1,0,1]
	v_pk_fma_f32 v[132:133], v[10:11], s[0:1], v[132:133] op_sel_hi:[1,0,1]
	v_pk_fma_f32 v[134:135], v[12:13], s[0:1], v[134:135] op_sel_hi:[1,0,1]
	v_pk_fma_f32 v[136:137], v[14:15], s[0:1], v[136:137] op_sel_hi:[1,0,1]
	v_readlane_b32 s0, v167, 45
	s_waitcnt vmcnt(15)
; __device__ void peer_gather_phase(const Params& P, int l, bool do_store) {
;     ...
;         v8[2 * pr] = *(const uint2*)(V + (size_t)ea * 512);
;         v8[2 * pr + 1] = *(const uint2*)(V + (size_t)eb * 512);
;     ...
;       for (int j = 0; j < 8; ++j) {
;         const float a = __builtin_bit_cast(float, __builtin_amdgcn_readlane(__builtin_bit_cast(int, avec), kb + j));
;         const f32x2 aa = f32x2{a, a};
;         y[0] += aa * __builtin_amdgcn_cvt_scalef32_pk_f32_fp4(v8[j].x, 1.0f, 0); y[1] += aa * __builtin_amdgcn_cvt_scalef32_pk_f32_fp4(v8[j].x, 1.0f, 1);
;         y[2] += aa * __builtin_amdgcn_cvt_scalef32_pk_f32_fp4(v8[j].x, 1.0f, 2); y[3] += aa * __builtin_amdgcn_cvt_scalef32_pk_f32_fp4(v8[j].x, 1.0f, 3);
;         y[4] += aa * __builtin_amdgcn_cvt_scalef32_pk_f32_fp4(v8[j].y, 1.0f, 0); y[5] += aa * __builtin_amdgcn_cvt_scalef32_pk_f32_fp4(v8[j].y, 1.0f, 1);
;         y[6] += aa * __builtin_amdgcn_cvt_scalef32_pk_f32_fp4(v8[j].y, 1.0f, 2); y[7] += aa * __builtin_amdgcn_cvt_scalef32_pk_f32_fp4(v8[j].y, 1.0f, 3);
;       }
	v_cvt_scalef32_pk_f32_fp4 v[0:1], v182, 1.0
	v_cvt_scalef32_pk_f32_fp4 v[2:3], v182, 1.0 op_sel:[1,0,0]
	v_cvt_scalef32_pk_f32_fp4 v[4:5], v182, 1.0 op_sel:[0,1,0]
	v_cvt_scalef32_pk_f32_fp4 v[6:7], v182, 1.0 op_sel:[1,1,0]
	v_cvt_scalef32_pk_f32_fp4 v[8:9], v183, 1.0
	v_cvt_scalef32_pk_f32_fp4 v[10:11], v183, 1.0 op_sel:[1,0,0]
	v_cvt_scalef32_pk_f32_fp4 v[12:13], v183, 1.0 op_sel:[0,1,0]
	v_cvt_scalef32_pk_f32_fp4 v[14:15], v183, 1.0 op_sel:[1,1,0]
	v_readlane_b32 s54, v92, 61
	s_lshl_b32 s56, s54, 9
	s_add_u32 s56, s64, s56
	s_addc_u32 s57, s65, 0
	global_load_dwordx2 v[182:183], v227, s[56:57]
	v_pk_fma_f32 v[130:131], v[0:1], s[0:1], v[130:131] op_sel_hi:[1,0,1]
	v_pk_fma_f32 v[138:139], v[2:3], s[0:1], v[138:139] op_sel_hi:[1,0,1]
	v_pk_fma_f32 v[140:141], v[4:5], s[0:1], v[140:141] op_sel_hi:[1,0,1]
	v_pk_fma_f32 v[142:143], v[6:7], s[0:1], v[142:143] op_sel_hi:[1,0,1]
	v_pk_fma_f32 v[128:129], v[8:9], s[0:1], v[128:129] op_sel_hi:[1,0,1]
	v_pk_fma_f32 v[132:133], v[10:11], s[0:1], v[132:133] op_sel_hi:[1,0,1]
	v_pk_fma_f32 v[134:135], v[12:13], s[0:1], v[134:135] op_sel_hi:[1,0,1]
	v_pk_fma_f32 v[136:137], v[14:15], s[0:1], v[136:137] op_sel_hi:[1,0,1]
	v_readlane_b32 s0, v167, 46
	s_waitcnt vmcnt(15)
	v_cvt_scalef32_pk_f32_fp4 v[0:1], v184, 1.0
	v_cvt_scalef32_pk_f32_fp4 v[2:3], v184, 1.0 op_sel:[1,0,0]
	v_cvt_scalef32_pk_f32_fp4 v[4:5], v184, 1.0 op_sel:[0,1,0]
	v_cvt_scalef32_pk_f32_fp4 v[6:7], v184, 1.0 op_sel:[1,1,0]
	v_cvt_scalef32_pk_f32_fp4 v[8:9], v185, 1.0
	v_cvt_scalef32_pk_f32_fp4 v[10:11], v185, 1.0 op_sel:[1,0,0]
	v_cvt_scalef32_pk_f32_fp4 v[12:13], v185, 1.0 op_sel:[0,1,0]
	v_cvt_scalef32_pk_f32_fp4 v[14:15], v185, 1.0 op_sel:[1,1,0]
	v_readlane_b32 s54, v92, 62
	s_lshl_b32 s56, s54, 9
	s_add_u32 s56, s64, s56
	s_addc_u32 s57, s65, 0
	global_load_dwordx2 v[184:185], v227, s[56:57]
	v_pk_fma_f32 v[130:131], v[0:1], s[0:1], v[130:131] op_sel_hi:[1,0,1]
	v_pk_fma_f32 v[138:139], v[2:3], s[0:1], v[138:139] op_sel_hi:[1,0,1]
	v_pk_fma_f32 v[140:141], v[4:5], s[0:1], v[140:141] op_sel_hi:[1,0,1]
	v_pk_fma_f32 v[142:143], v[6:7], s[0:1], v[142:143] op_sel_hi:[1,0,1]
	v_pk_fma_f32 v[128:129], v[8:9], s[0:1], v[128:129] op_sel_hi:[1,0,1]
	v_pk_fma_f32 v[132:133], v[10:11], s[0:1], v[132:133] op_sel_hi:[1,0,1]
	v_pk_fma_f32 v[134:135], v[12:13], s[0:1], v[134:135] op_sel_hi:[1,0,1]
	v_pk_fma_f32 v[136:137], v[14:15], s[0:1], v[136:137] op_sel_hi:[1,0,1]
	v_readlane_b32 s0, v167, 47
	s_waitcnt vmcnt(15)
	v_cvt_scalef32_pk_f32_fp4 v[0:1], v186, 1.0
	v_cvt_scalef32_pk_f32_fp4 v[2:3], v186, 1.0 op_sel:[1,0,0]
	v_cvt_scalef32_pk_f32_fp4 v[4:5], v186, 1.0 op_sel:[0,1,0]
	v_cvt_scalef32_pk_f32_fp4 v[6:7], v186, 1.0 op_sel:[1,1,0]
	v_cvt_scalef32_pk_f32_fp4 v[8:9], v187, 1.0
	v_cvt_scalef32_pk_f32_fp4 v[10:11], v187, 1.0 op_sel:[1,0,0]
	v_cvt_scalef32_pk_f32_fp4 v[12:13], v187, 1.0 op_sel:[0,1,0]
	v_cvt_scalef32_pk_f32_fp4 v[14:15], v187, 1.0 op_sel:[1,1,0]
	v_readlane_b32 s54, v92, 63
	s_lshl_b32 s56, s54, 9
	s_add_u32 s56, s64, s56
	s_addc_u32 s57, s65, 0
	global_load_dwordx2 v[186:187], v227, s[56:57]
	v_pk_fma_f32 v[130:131], v[0:1], s[0:1], v[130:131] op_sel_hi:[1,0,1]
	v_pk_fma_f32 v[138:139], v[2:3], s[0:1], v[138:139] op_sel_hi:[1,0,1]
	v_pk_fma_f32 v[140:141], v[4:5], s[0:1], v[140:141] op_sel_hi:[1,0,1]
	v_pk_fma_f32 v[142:143], v[6:7], s[0:1], v[142:143] op_sel_hi:[1,0,1]
	v_pk_fma_f32 v[128:129], v[8:9], s[0:1], v[128:129] op_sel_hi:[1,0,1]
	v_pk_fma_f32 v[132:133], v[10:11], s[0:1], v[132:133] op_sel_hi:[1,0,1]
	v_pk_fma_f32 v[134:135], v[12:13], s[0:1], v[134:135] op_sel_hi:[1,0,1]
	v_pk_fma_f32 v[136:137], v[14:15], s[0:1], v[136:137] op_sel_hi:[1,0,1]
	v_readlane_b32 s0, v167, 48
	s_waitcnt vmcnt(15)
	v_cvt_scalef32_pk_f32_fp4 v[0:1], v144, 1.0
	v_cvt_scalef32_pk_f32_fp4 v[2:3], v144, 1.0 op_sel:[1,0,0]
	v_cvt_scalef32_pk_f32_fp4 v[4:5], v144, 1.0 op_sel:[0,1,0]
	v_cvt_scalef32_pk_f32_fp4 v[6:7], v144, 1.0 op_sel:[1,1,0]
	v_cvt_scalef32_pk_f32_fp4 v[8:9], v145, 1.0
	v_cvt_scalef32_pk_f32_fp4 v[10:11], v145, 1.0 op_sel:[1,0,0]
	v_cvt_scalef32_pk_f32_fp4 v[12:13], v145, 1.0 op_sel:[0,1,0]
	v_cvt_scalef32_pk_f32_fp4 v[14:15], v145, 1.0 op_sel:[1,1,0]
	v_readlane_b32 s54, v90, 0
	s_lshl_b32 s56, s54, 9
	s_add_u32 s56, s64, s56
	s_addc_u32 s57, s65, 0
	global_load_dwordx2 v[144:145], v227, s[56:57]
	v_pk_fma_f32 v[130:131], v[0:1], s[0:1], v[130:131] op_sel_hi:[1,0,1]
	v_pk_fma_f32 v[138:139], v[2:3], s[0:1], v[138:139] op_sel_hi:[1,0,1]
	v_pk_fma_f32 v[140:141], v[4:5], s[0:1], v[140:141] op_sel_hi:[1,0,1]
	v_pk_fma_f32 v[142:143], v[6:7], s[0:1], v[142:143] op_sel_hi:[1,0,1]
	v_pk_fma_f32 v[128:129], v[8:9], s[0:1], v[128:129] op_sel_hi:[1,0,1]
	v_pk_fma_f32 v[132:133], v[10:11], s[0:1], v[132:133] op_sel_hi:[1,0,1]
	v_pk_fma_f32 v[134:135], v[12:13], s[0:1], v[134:135] op_sel_hi:[1,0,1]
	v_pk_fma_f32 v[136:137], v[14:15], s[0:1], v[136:137] op_sel_hi:[1,0,1]
	v_readlane_b32 s0, v167, 49
	s_waitcnt vmcnt(15)
	v_cvt_scalef32_pk_f32_fp4 v[0:1], v146, 1.0
	v_cvt_scalef32_pk_f32_fp4 v[2:3], v146, 1.0 op_sel:[1,0,0]
	v_cvt_scalef32_pk_f32_fp4 v[4:5], v146, 1.0 op_sel:[0,1,0]
	v_cvt_scalef32_pk_f32_fp4 v[6:7], v146, 1.0 op_sel:[1,1,0]
	v_cvt_scalef32_pk_f32_fp4 v[8:9], v147, 1.0
	v_cvt_scalef32_pk_f32_fp4 v[10:11], v147, 1.0 op_sel:[1,0,0]
	v_cvt_scalef32_pk_f32_fp4 v[12:13], v147, 1.0 op_sel:[0,1,0]
	v_cvt_scalef32_pk_f32_fp4 v[14:15], v147, 1.0 op_sel:[1,1,0]
	v_readlane_b32 s54, v90, 1
	s_lshl_b32 s56, s54, 9
	s_add_u32 s56, s64, s56
	s_addc_u32 s57, s65, 0
	global_load_dwordx2 v[146:147], v227, s[56:57]
	v_pk_fma_f32 v[130:131], v[0:1], s[0:1], v[130:131] op_sel_hi:[1,0,1]
	v_pk_fma_f32 v[138:139], v[2:3], s[0:1], v[138:139] op_sel_hi:[1,0,1]
	v_pk_fma_f32 v[140:141], v[4:5], s[0:1], v[140:141] op_sel_hi:[1,0,1]
	v_pk_fma_f32 v[142:143], v[6:7], s[0:1], v[142:143] op_sel_hi:[1,0,1]
	v_pk_fma_f32 v[128:129], v[8:9], s[0:1], v[128:129] op_sel_hi:[1,0,1]
	v_pk_fma_f32 v[132:133], v[10:11], s[0:1], v[132:133] op_sel_hi:[1,0,1]
	v_pk_fma_f32 v[134:135], v[12:13], s[0:1], v[134:135] op_sel_hi:[1,0,1]
	v_pk_fma_f32 v[136:137], v[14:15], s[0:1], v[136:137] op_sel_hi:[1,0,1]
	v_readlane_b32 s0, v167, 50
	s_waitcnt vmcnt(15)
; __device__ void peer_gather_phase(const Params& P, int l, bool do_store) {
;     ...
;         v8[2 * pr] = *(const uint2*)(V + (size_t)ea * 512);
;         v8[2 * pr + 1] = *(const uint2*)(V + (size_t)eb * 512);
;     ...
;       for (int j = 0; j < 8; ++j) {
;         const float a = __builtin_bit_cast(float, __builtin_amdgcn_readlane(__builtin_bit_cast(int, avec), kb + j));
;         const f32x2 aa = f32x2{a, a};
;         y[0] += aa * __builtin_amdgcn_cvt_scalef32_pk_f32_fp4(v8[j].x, 1.0f, 0); y[1] += aa * __builtin_amdgcn_cvt_scalef32_pk_f32_fp4(v8[j].x, 1.0f, 1);
;         y[2] += aa * __builtin_amdgcn_cvt_scalef32_pk_f32_fp4(v8[j].x, 1.0f, 2); y[3] += aa * __builtin_amdgcn_cvt_scalef32_pk_f32_fp4(v8[j].x, 1.0f, 3);
;         y[4] += aa * __builtin_amdgcn_cvt_scalef32_pk_f32_fp4(v8[j].y, 1.0f, 0); y[5] += aa * __builtin_amdgcn_cvt_scalef32_pk_f32_fp4(v8[j].y, 1.0f, 1);
;         y[6] += aa * __builtin_amdgcn_cvt_scalef32_pk_f32_fp4(v8[j].y, 1.0f, 2); y[7] += aa * __builtin_amdgcn_cvt_scalef32_pk_f32_fp4(v8[j].y, 1.0f, 3);
;       }
	v_cvt_scalef32_pk_f32_fp4 v[0:1], v148, 1.0
	v_cvt_scalef32_pk_f32_fp4 v[2:3], v148, 1.0 op_sel:[1,0,0]
	v_cvt_scalef32_pk_f32_fp4 v[4:5], v148, 1.0 op_sel:[0,1,0]
	v_cvt_scalef32_pk_f32_fp4 v[6:7], v148, 1.0 op_sel:[1,1,0]
	v_cvt_scalef32_pk_f32_fp4 v[8:9], v149, 1.0
	v_cvt_scalef32_pk_f32_fp4 v[10:11], v149, 1.0 op_sel:[1,0,0]
	v_cvt_scalef32_pk_f32_fp4 v[12:13], v149, 1.0 op_sel:[0,1,0]
	v_cvt_scalef32_pk_f32_fp4 v[14:15], v149, 1.0 op_sel:[1,1,0]
	v_readlane_b32 s54, v90, 2
	s_lshl_b32 s56, s54, 9
	s_add_u32 s56, s64, s56
	s_addc_u32 s57, s65, 0
	global_load_dwordx2 v[148:149], v227, s[56:57]
	v_pk_fma_f32 v[130:131], v[0:1], s[0:1], v[130:131] op_sel_hi:[1,0,1]
	v_pk_fma_f32 v[138:139], v[2:3], s[0:1], v[138:139] op_sel_hi:[1,0,1]
	v_pk_fma_f32 v[140:141], v[4:5], s[0:1], v[140:141] op_sel_hi:[1,0,1]
	v_pk_fma_f32 v[142:143], v[6:7], s[0:1], v[142:143] op_sel_hi:[1,0,1]
	v_pk_fma_f32 v[128:129], v[8:9], s[0:1], v[128:129] op_sel_hi:[1,0,1]
	v_pk_fma_f32 v[132:133], v[10:11], s[0:1], v[132:133] op_sel_hi:[1,0,1]
	v_pk_fma_f32 v[134:135], v[12:13], s[0:1], v[134:135] op_sel_hi:[1,0,1]
	v_pk_fma_f32 v[136:137], v[14:15], s[0:1], v[136:137] op_sel_hi:[1,0,1]
	v_readlane_b32 s0, v167, 51
	s_waitcnt vmcnt(15)
	v_cvt_scalef32_pk_f32_fp4 v[0:1], v150, 1.0
	v_cvt_scalef32_pk_f32_fp4 v[2:3], v150, 1.0 op_sel:[1,0,0]
	v_cvt_scalef32_pk_f32_fp4 v[4:5], v150, 1.0 op_sel:[0,1,0]
	v_cvt_scalef32_pk_f32_fp4 v[6:7], v150, 1.0 op_sel:[1,1,0]
	v_cvt_scalef32_pk_f32_fp4 v[8:9], v151, 1.0
	v_cvt_scalef32_pk_f32_fp4 v[10:11], v151, 1.0 op_sel:[1,0,0]
	v_cvt_scalef32_pk_f32_fp4 v[12:13], v151, 1.0 op_sel:[0,1,0]
	v_cvt_scalef32_pk_f32_fp4 v[14:15], v151, 1.0 op_sel:[1,1,0]
	v_readlane_b32 s54, v90, 3
	s_lshl_b32 s56, s54, 9
	s_add_u32 s56, s64, s56
	s_addc_u32 s57, s65, 0
	global_load_dwordx2 v[150:151], v227, s[56:57]
	v_pk_fma_f32 v[130:131], v[0:1], s[0:1], v[130:131] op_sel_hi:[1,0,1]
	v_pk_fma_f32 v[138:139], v[2:3], s[0:1], v[138:139] op_sel_hi:[1,0,1]
	v_pk_fma_f32 v[140:141], v[4:5], s[0:1], v[140:141] op_sel_hi:[1,0,1]
	v_pk_fma_f32 v[142:143], v[6:7], s[0:1], v[142:143] op_sel_hi:[1,0,1]
	v_pk_fma_f32 v[128:129], v[8:9], s[0:1], v[128:129] op_sel_hi:[1,0,1]
	v_pk_fma_f32 v[132:133], v[10:11], s[0:1], v[132:133] op_sel_hi:[1,0,1]
	v_pk_fma_f32 v[134:135], v[12:13], s[0:1], v[134:135] op_sel_hi:[1,0,1]
	v_pk_fma_f32 v[136:137], v[14:15], s[0:1], v[136:137] op_sel_hi:[1,0,1]
	v_readlane_b32 s0, v167, 52
	s_waitcnt vmcnt(15)
	v_cvt_scalef32_pk_f32_fp4 v[0:1], v152, 1.0
	v_cvt_scalef32_pk_f32_fp4 v[2:3], v152, 1.0 op_sel:[1,0,0]
	v_cvt_scalef32_pk_f32_fp4 v[4:5], v152, 1.0 op_sel:[0,1,0]
	v_cvt_scalef32_pk_f32_fp4 v[6:7], v152, 1.0 op_sel:[1,1,0]
	v_cvt_scalef32_pk_f32_fp4 v[8:9], v153, 1.0
	v_cvt_scalef32_pk_f32_fp4 v[10:11], v153, 1.0 op_sel:[1,0,0]
	v_cvt_scalef32_pk_f32_fp4 v[12:13], v153, 1.0 op_sel:[0,1,0]
	v_cvt_scalef32_pk_f32_fp4 v[14:15], v153, 1.0 op_sel:[1,1,0]
	v_readlane_b32 s54, v90, 4
	s_lshl_b32 s56, s54, 9
	s_add_u32 s56, s64, s56
	s_addc_u32 s57, s65, 0
	global_load_dwordx2 v[152:153], v227, s[56:57]
	v_pk_fma_f32 v[130:131], v[0:1], s[0:1], v[130:131] op_sel_hi:[1,0,1]
	v_pk_fma_f32 v[138:139], v[2:3], s[0:1], v[138:139] op_sel_hi:[1,0,1]
	v_pk_fma_f32 v[140:141], v[4:5], s[0:1], v[140:141] op_sel_hi:[1,0,1]
	v_pk_fma_f32 v[142:143], v[6:7], s[0:1], v[142:143] op_sel_hi:[1,0,1]
	v_pk_fma_f32 v[128:129], v[8:9], s[0:1], v[128:129] op_sel_hi:[1,0,1]
	v_pk_fma_f32 v[132:133], v[10:11], s[0:1], v[132:133] op_sel_hi:[1,0,1]
	v_pk_fma_f32 v[134:135], v[12:13], s[0:1], v[134:135] op_sel_hi:[1,0,1]
	v_pk_fma_f32 v[136:137], v[14:15], s[0:1], v[136:137] op_sel_hi:[1,0,1]
	v_readlane_b32 s0, v167, 53
	s_waitcnt vmcnt(15)
	v_cvt_scalef32_pk_f32_fp4 v[0:1], v154, 1.0
	v_cvt_scalef32_pk_f32_fp4 v[2:3], v154, 1.0 op_sel:[1,0,0]
	v_cvt_scalef32_pk_f32_fp4 v[4:5], v154, 1.0 op_sel:[0,1,0]
	v_cvt_scalef32_pk_f32_fp4 v[6:7], v154, 1.0 op_sel:[1,1,0]
	v_cvt_scalef32_pk_f32_fp4 v[8:9], v155, 1.0
	v_cvt_scalef32_pk_f32_fp4 v[10:11], v155, 1.0 op_sel:[1,0,0]
	v_cvt_scalef32_pk_f32_fp4 v[12:13], v155, 1.0 op_sel:[0,1,0]
	v_cvt_scalef32_pk_f32_fp4 v[14:15], v155, 1.0 op_sel:[1,1,0]
	v_readlane_b32 s54, v90, 5
	s_lshl_b32 s56, s54, 9
	s_add_u32 s56, s64, s56
	s_addc_u32 s57, s65, 0
	global_load_dwordx2 v[154:155], v227, s[56:57]
	v_pk_fma_f32 v[130:131], v[0:1], s[0:1], v[130:131] op_sel_hi:[1,0,1]
	v_pk_fma_f32 v[138:139], v[2:3], s[0:1], v[138:139] op_sel_hi:[1,0,1]
	v_pk_fma_f32 v[140:141], v[4:5], s[0:1], v[140:141] op_sel_hi:[1,0,1]
	v_pk_fma_f32 v[142:143], v[6:7], s[0:1], v[142:143] op_sel_hi:[1,0,1]
	v_pk_fma_f32 v[128:129], v[8:9], s[0:1], v[128:129] op_sel_hi:[1,0,1]
	v_pk_fma_f32 v[132:133], v[10:11], s[0:1], v[132:133] op_sel_hi:[1,0,1]
	v_pk_fma_f32 v[134:135], v[12:13], s[0:1], v[134:135] op_sel_hi:[1,0,1]
	v_pk_fma_f32 v[136:137], v[14:15], s[0:1], v[136:137] op_sel_hi:[1,0,1]
	v_readlane_b32 s0, v167, 54
	s_waitcnt vmcnt(15)
	v_cvt_scalef32_pk_f32_fp4 v[0:1], v156, 1.0
	v_cvt_scalef32_pk_f32_fp4 v[2:3], v156, 1.0 op_sel:[1,0,0]
	v_cvt_scalef32_pk_f32_fp4 v[4:5], v156, 1.0 op_sel:[0,1,0]
	v_cvt_scalef32_pk_f32_fp4 v[6:7], v156, 1.0 op_sel:[1,1,0]
	v_cvt_scalef32_pk_f32_fp4 v[8:9], v157, 1.0
	v_cvt_scalef32_pk_f32_fp4 v[10:11], v157, 1.0 op_sel:[1,0,0]
	v_cvt_scalef32_pk_f32_fp4 v[12:13], v157, 1.0 op_sel:[0,1,0]
	v_cvt_scalef32_pk_f32_fp4 v[14:15], v157, 1.0 op_sel:[1,1,0]
	v_readlane_b32 s54, v90, 6
	s_lshl_b32 s56, s54, 9
	s_add_u32 s56, s64, s56
	s_addc_u32 s57, s65, 0
	global_load_dwordx2 v[156:157], v227, s[56:57]
	v_pk_fma_f32 v[130:131], v[0:1], s[0:1], v[130:131] op_sel_hi:[1,0,1]
	v_pk_fma_f32 v[138:139], v[2:3], s[0:1], v[138:139] op_sel_hi:[1,0,1]
	v_pk_fma_f32 v[140:141], v[4:5], s[0:1], v[140:141] op_sel_hi:[1,0,1]
	v_pk_fma_f32 v[142:143], v[6:7], s[0:1], v[142:143] op_sel_hi:[1,0,1]
	v_pk_fma_f32 v[128:129], v[8:9], s[0:1], v[128:129] op_sel_hi:[1,0,1]
	v_pk_fma_f32 v[132:133], v[10:11], s[0:1], v[132:133] op_sel_hi:[1,0,1]
	v_pk_fma_f32 v[134:135], v[12:13], s[0:1], v[134:135] op_sel_hi:[1,0,1]
	v_pk_fma_f32 v[136:137], v[14:15], s[0:1], v[136:137] op_sel_hi:[1,0,1]
	v_readlane_b32 s0, v167, 55
	s_waitcnt vmcnt(15)
; __device__ void peer_gather_phase(const Params& P, int l, bool do_store) {
;     ...
;         v8[2 * pr] = *(const uint2*)(V + (size_t)ea * 512);
;         v8[2 * pr + 1] = *(const uint2*)(V + (size_t)eb * 512);
;     ...
;       for (int j = 0; j < 8; ++j) {
;         const float a = __builtin_bit_cast(float, __builtin_amdgcn_readlane(__builtin_bit_cast(int, avec), kb + j));
;         const f32x2 aa = f32x2{a, a};
;         y[0] += aa * __builtin_amdgcn_cvt_scalef32_pk_f32_fp4(v8[j].x, 1.0f, 0); y[1] += aa * __builtin_amdgcn_cvt_scalef32_pk_f32_fp4(v8[j].x, 1.0f, 1);
;         y[2] += aa * __builtin_amdgcn_cvt_scalef32_pk_f32_fp4(v8[j].x, 1.0f, 2); y[3] += aa * __builtin_amdgcn_cvt_scalef32_pk_f32_fp4(v8[j].x, 1.0f, 3);
;         y[4] += aa * __builtin_amdgcn_cvt_scalef32_pk_f32_fp4(v8[j].y, 1.0f, 0); y[5] += aa * __builtin_amdgcn_cvt_scalef32_pk_f32_fp4(v8[j].y, 1.0f, 1);
;         y[6] += aa * __builtin_amdgcn_cvt_scalef32_pk_f32_fp4(v8[j].y, 1.0f, 2); y[7] += aa * __builtin_amdgcn_cvt_scalef32_pk_f32_fp4(v8[j].y, 1.0f, 3);
;       }
	v_cvt_scalef32_pk_f32_fp4 v[0:1], v158, 1.0
	v_cvt_scalef32_pk_f32_fp4 v[2:3], v158, 1.0 op_sel:[1,0,0]
	v_cvt_scalef32_pk_f32_fp4 v[4:5], v158, 1.0 op_sel:[0,1,0]
	v_cvt_scalef32_pk_f32_fp4 v[6:7], v158, 1.0 op_sel:[1,1,0]
	v_cvt_scalef32_pk_f32_fp4 v[8:9], v159, 1.0
	v_cvt_scalef32_pk_f32_fp4 v[10:11], v159, 1.0 op_sel:[1,0,0]
	v_cvt_scalef32_pk_f32_fp4 v[12:13], v159, 1.0 op_sel:[0,1,0]
	v_cvt_scalef32_pk_f32_fp4 v[14:15], v159, 1.0 op_sel:[1,1,0]
	v_readlane_b32 s54, v90, 7
	s_lshl_b32 s56, s54, 9
	s_add_u32 s56, s64, s56
	s_addc_u32 s57, s65, 0
	global_load_dwordx2 v[158:159], v227, s[56:57]
	v_pk_fma_f32 v[130:131], v[0:1], s[0:1], v[130:131] op_sel_hi:[1,0,1]
	v_pk_fma_f32 v[138:139], v[2:3], s[0:1], v[138:139] op_sel_hi:[1,0,1]
	v_pk_fma_f32 v[140:141], v[4:5], s[0:1], v[140:141] op_sel_hi:[1,0,1]
	v_pk_fma_f32 v[142:143], v[6:7], s[0:1], v[142:143] op_sel_hi:[1,0,1]
	v_pk_fma_f32 v[128:129], v[8:9], s[0:1], v[128:129] op_sel_hi:[1,0,1]
	v_pk_fma_f32 v[132:133], v[10:11], s[0:1], v[132:133] op_sel_hi:[1,0,1]
	v_pk_fma_f32 v[134:135], v[12:13], s[0:1], v[134:135] op_sel_hi:[1,0,1]
	v_pk_fma_f32 v[136:137], v[14:15], s[0:1], v[136:137] op_sel_hi:[1,0,1]
	v_readlane_b32 s0, v167, 56
	s_waitcnt vmcnt(15)
	v_cvt_scalef32_pk_f32_fp4 v[0:1], v168, 1.0
	v_cvt_scalef32_pk_f32_fp4 v[2:3], v168, 1.0 op_sel:[1,0,0]
	v_cvt_scalef32_pk_f32_fp4 v[4:5], v168, 1.0 op_sel:[0,1,0]
	v_cvt_scalef32_pk_f32_fp4 v[6:7], v168, 1.0 op_sel:[1,1,0]
	v_cvt_scalef32_pk_f32_fp4 v[8:9], v169, 1.0
	v_cvt_scalef32_pk_f32_fp4 v[10:11], v169, 1.0 op_sel:[1,0,0]
	v_cvt_scalef32_pk_f32_fp4 v[12:13], v169, 1.0 op_sel:[0,1,0]
	v_cvt_scalef32_pk_f32_fp4 v[14:15], v169, 1.0 op_sel:[1,1,0]
	v_readlane_b32 s54, v90, 8
	s_lshl_b32 s56, s54, 9
	s_add_u32 s56, s64, s56
	s_addc_u32 s57, s65, 0
	global_load_dwordx2 v[168:169], v227, s[56:57]
	v_pk_fma_f32 v[130:131], v[0:1], s[0:1], v[130:131] op_sel_hi:[1,0,1]
	v_pk_fma_f32 v[138:139], v[2:3], s[0:1], v[138:139] op_sel_hi:[1,0,1]
	v_pk_fma_f32 v[140:141], v[4:5], s[0:1], v[140:141] op_sel_hi:[1,0,1]
	v_pk_fma_f32 v[142:143], v[6:7], s[0:1], v[142:143] op_sel_hi:[1,0,1]
	v_pk_fma_f32 v[128:129], v[8:9], s[0:1], v[128:129] op_sel_hi:[1,0,1]
	v_pk_fma_f32 v[132:133], v[10:11], s[0:1], v[132:133] op_sel_hi:[1,0,1]
	v_pk_fma_f32 v[134:135], v[12:13], s[0:1], v[134:135] op_sel_hi:[1,0,1]
	v_pk_fma_f32 v[136:137], v[14:15], s[0:1], v[136:137] op_sel_hi:[1,0,1]
	v_readlane_b32 s0, v167, 57
	s_waitcnt vmcnt(15)
	v_cvt_scalef32_pk_f32_fp4 v[0:1], v170, 1.0
	v_cvt_scalef32_pk_f32_fp4 v[2:3], v170, 1.0 op_sel:[1,0,0]
	v_cvt_scalef32_pk_f32_fp4 v[4:5], v170, 1.0 op_sel:[0,1,0]
	v_cvt_scalef32_pk_f32_fp4 v[6:7], v170, 1.0 op_sel:[1,1,0]
	v_cvt_scalef32_pk_f32_fp4 v[8:9], v171, 1.0
	v_cvt_scalef32_pk_f32_fp4 v[10:11], v171, 1.0 op_sel:[1,0,0]
	v_cvt_scalef32_pk_f32_fp4 v[12:13], v171, 1.0 op_sel:[0,1,0]
	v_cvt_scalef32_pk_f32_fp4 v[14:15], v171, 1.0 op_sel:[1,1,0]
	v_readlane_b32 s54, v90, 9
	s_lshl_b32 s56, s54, 9
	s_add_u32 s56, s64, s56
	s_addc_u32 s57, s65, 0
	global_load_dwordx2 v[170:171], v227, s[56:57]
	v_pk_fma_f32 v[130:131], v[0:1], s[0:1], v[130:131] op_sel_hi:[1,0,1]
	v_pk_fma_f32 v[138:139], v[2:3], s[0:1], v[138:139] op_sel_hi:[1,0,1]
	v_pk_fma_f32 v[140:141], v[4:5], s[0:1], v[140:141] op_sel_hi:[1,0,1]
	v_pk_fma_f32 v[142:143], v[6:7], s[0:1], v[142:143] op_sel_hi:[1,0,1]
	v_pk_fma_f32 v[128:129], v[8:9], s[0:1], v[128:129] op_sel_hi:[1,0,1]
	v_pk_fma_f32 v[132:133], v[10:11], s[0:1], v[132:133] op_sel_hi:[1,0,1]
	v_pk_fma_f32 v[134:135], v[12:13], s[0:1], v[134:135] op_sel_hi:[1,0,1]
	v_pk_fma_f32 v[136:137], v[14:15], s[0:1], v[136:137] op_sel_hi:[1,0,1]
	v_readlane_b32 s0, v167, 58
	s_waitcnt vmcnt(15)
	v_cvt_scalef32_pk_f32_fp4 v[0:1], v172, 1.0
	v_cvt_scalef32_pk_f32_fp4 v[2:3], v172, 1.0 op_sel:[1,0,0]
	v_cvt_scalef32_pk_f32_fp4 v[4:5], v172, 1.0 op_sel:[0,1,0]
	v_cvt_scalef32_pk_f32_fp4 v[6:7], v172, 1.0 op_sel:[1,1,0]
	v_cvt_scalef32_pk_f32_fp4 v[8:9], v173, 1.0
	v_cvt_scalef32_pk_f32_fp4 v[10:11], v173, 1.0 op_sel:[1,0,0]
	v_cvt_scalef32_pk_f32_fp4 v[12:13], v173, 1.0 op_sel:[0,1,0]
	v_cvt_scalef32_pk_f32_fp4 v[14:15], v173, 1.0 op_sel:[1,1,0]
	v_readlane_b32 s54, v90, 10
	s_lshl_b32 s56, s54, 9
	s_add_u32 s56, s64, s56
	s_addc_u32 s57, s65, 0
	global_load_dwordx2 v[172:173], v227, s[56:57]
	v_pk_fma_f32 v[130:131], v[0:1], s[0:1], v[130:131] op_sel_hi:[1,0,1]
	v_pk_fma_f32 v[138:139], v[2:3], s[0:1], v[138:139] op_sel_hi:[1,0,1]
	v_pk_fma_f32 v[140:141], v[4:5], s[0:1], v[140:141] op_sel_hi:[1,0,1]
	v_pk_fma_f32 v[142:143], v[6:7], s[0:1], v[142:143] op_sel_hi:[1,0,1]
	v_pk_fma_f32 v[128:129], v[8:9], s[0:1], v[128:129] op_sel_hi:[1,0,1]
	v_pk_fma_f32 v[132:133], v[10:11], s[0:1], v[132:133] op_sel_hi:[1,0,1]
	v_pk_fma_f32 v[134:135], v[12:13], s[0:1], v[134:135] op_sel_hi:[1,0,1]
	v_pk_fma_f32 v[136:137], v[14:15], s[0:1], v[136:137] op_sel_hi:[1,0,1]
	v_readlane_b32 s0, v167, 59
	s_waitcnt vmcnt(15)
	v_cvt_scalef32_pk_f32_fp4 v[0:1], v174, 1.0
	v_cvt_scalef32_pk_f32_fp4 v[2:3], v174, 1.0 op_sel:[1,0,0]
	v_cvt_scalef32_pk_f32_fp4 v[4:5], v174, 1.0 op_sel:[0,1,0]
	v_cvt_scalef32_pk_f32_fp4 v[6:7], v174, 1.0 op_sel:[1,1,0]
	v_cvt_scalef32_pk_f32_fp4 v[8:9], v175, 1.0
	v_cvt_scalef32_pk_f32_fp4 v[10:11], v175, 1.0 op_sel:[1,0,0]
	v_cvt_scalef32_pk_f32_fp4 v[12:13], v175, 1.0 op_sel:[0,1,0]
	v_cvt_scalef32_pk_f32_fp4 v[14:15], v175, 1.0 op_sel:[1,1,0]
	v_readlane_b32 s54, v90, 11
	s_lshl_b32 s56, s54, 9
	s_add_u32 s56, s64, s56
	s_addc_u32 s57, s65, 0
	global_load_dwordx2 v[174:175], v227, s[56:57]
	v_pk_fma_f32 v[130:131], v[0:1], s[0:1], v[130:131] op_sel_hi:[1,0,1]
	v_pk_fma_f32 v[138:139], v[2:3], s[0:1], v[138:139] op_sel_hi:[1,0,1]
	v_pk_fma_f32 v[140:141], v[4:5], s[0:1], v[140:141] op_sel_hi:[1,0,1]
	v_pk_fma_f32 v[142:143], v[6:7], s[0:1], v[142:143] op_sel_hi:[1,0,1]
	v_pk_fma_f32 v[128:129], v[8:9], s[0:1], v[128:129] op_sel_hi:[1,0,1]
	v_pk_fma_f32 v[132:133], v[10:11], s[0:1], v[132:133] op_sel_hi:[1,0,1]
	v_pk_fma_f32 v[134:135], v[12:13], s[0:1], v[134:135] op_sel_hi:[1,0,1]
	v_pk_fma_f32 v[136:137], v[14:15], s[0:1], v[136:137] op_sel_hi:[1,0,1]
	v_readlane_b32 s0, v167, 60
	s_waitcnt vmcnt(15)
; __device__ void peer_gather_phase(const Params& P, int l, bool do_store) {
;     ...
;       for (int pr = 0; pr < 4; ++pr) {
;         const int ea = __builtin_amdgcn_readlane(evs, kb + 2 * pr), eb = __builtin_amdgcn_readlane(evs, kb + 2 * pr + 1);
;         const uint2* up = (const uint2*)(U + (size_t)(uphi ? eb : ea) * 768);
;         u6[3 * pr] = up[0]; u6[3 * pr + 1] = up[1]; u6[3 * pr + 2] = up[2];
;         v8[2 * pr] = *(const uint2*)(V + (size_t)ea * 512);
;         v8[2 * pr + 1] = *(const uint2*)(V + (size_t)eb * 512);
;     ...
; #pragma unroll
;       for (int j = 0; j < 8; ++j) {
;         const float a = __builtin_bit_cast(float, __builtin_amdgcn_readlane(__builtin_bit_cast(int, avec), kb + j));
;         const f32x2 aa = f32x2{a, a};
;         y[0] += aa * __builtin_amdgcn_cvt_scalef32_pk_f32_fp4(v8[j].x, 1.0f, 0); y[1] += aa * __builtin_amdgcn_cvt_scalef32_pk_f32_fp4(v8[j].x, 1.0f, 1);
;         y[2] += aa * __builtin_amdgcn_cvt_scalef32_pk_f32_fp4(v8[j].x, 1.0f, 2); y[3] += aa * __builtin_amdgcn_cvt_scalef32_pk_f32_fp4(v8[j].x, 1.0f, 3);
;         y[4] += aa * __builtin_amdgcn_cvt_scalef32_pk_f32_fp4(v8[j].y, 1.0f, 0); y[5] += aa * __builtin_amdgcn_cvt_scalef32_pk_f32_fp4(v8[j].y, 1.0f, 1);
;         y[6] += aa * __builtin_amdgcn_cvt_scalef32_pk_f32_fp4(v8[j].y, 1.0f, 2); y[7] += aa * __builtin_amdgcn_cvt_scalef32_pk_f32_fp4(v8[j].y, 1.0f, 3);
;       }
	v_cvt_scalef32_pk_f32_fp4 v[0:1], v180, 1.0
	v_cvt_scalef32_pk_f32_fp4 v[2:3], v180, 1.0 op_sel:[1,0,0]
	v_cvt_scalef32_pk_f32_fp4 v[4:5], v180, 1.0 op_sel:[0,1,0]
	v_cvt_scalef32_pk_f32_fp4 v[6:7], v180, 1.0 op_sel:[1,1,0]
	v_cvt_scalef32_pk_f32_fp4 v[8:9], v181, 1.0
	v_cvt_scalef32_pk_f32_fp4 v[10:11], v181, 1.0 op_sel:[1,0,0]
	v_cvt_scalef32_pk_f32_fp4 v[12:13], v181, 1.0 op_sel:[0,1,0]
	v_cvt_scalef32_pk_f32_fp4 v[14:15], v181, 1.0 op_sel:[1,1,0]
	v_readlane_b32 s54, v90, 12
	s_lshl_b32 s56, s54, 9
	s_add_u32 s56, s64, s56
	s_addc_u32 s57, s65, 0
	global_load_dwordx2 v[180:181], v227, s[56:57]
	v_pk_fma_f32 v[130:131], v[0:1], s[0:1], v[130:131] op_sel_hi:[1,0,1]
	v_pk_fma_f32 v[138:139], v[2:3], s[0:1], v[138:139] op_sel_hi:[1,0,1]
	v_pk_fma_f32 v[140:141], v[4:5], s[0:1], v[140:141] op_sel_hi:[1,0,1]
	v_pk_fma_f32 v[142:143], v[6:7], s[0:1], v[142:143] op_sel_hi:[1,0,1]
	v_pk_fma_f32 v[128:129], v[8:9], s[0:1], v[128:129] op_sel_hi:[1,0,1]
	v_pk_fma_f32 v[132:133], v[10:11], s[0:1], v[132:133] op_sel_hi:[1,0,1]
	v_pk_fma_f32 v[134:135], v[12:13], s[0:1], v[134:135] op_sel_hi:[1,0,1]
	v_pk_fma_f32 v[136:137], v[14:15], s[0:1], v[136:137] op_sel_hi:[1,0,1]
	v_readlane_b32 s0, v167, 61
	s_waitcnt vmcnt(15)
	v_cvt_scalef32_pk_f32_fp4 v[0:1], v182, 1.0
	v_cvt_scalef32_pk_f32_fp4 v[2:3], v182, 1.0 op_sel:[1,0,0]
	v_cvt_scalef32_pk_f32_fp4 v[4:5], v182, 1.0 op_sel:[0,1,0]
	v_cvt_scalef32_pk_f32_fp4 v[6:7], v182, 1.0 op_sel:[1,1,0]
	v_cvt_scalef32_pk_f32_fp4 v[8:9], v183, 1.0
	v_cvt_scalef32_pk_f32_fp4 v[10:11], v183, 1.0 op_sel:[1,0,0]
	v_cvt_scalef32_pk_f32_fp4 v[12:13], v183, 1.0 op_sel:[0,1,0]
	v_cvt_scalef32_pk_f32_fp4 v[14:15], v183, 1.0 op_sel:[1,1,0]
	v_readlane_b32 s54, v90, 13
	s_lshl_b32 s56, s54, 9
	s_add_u32 s56, s64, s56
	s_addc_u32 s57, s65, 0
	global_load_dwordx2 v[182:183], v227, s[56:57]
	v_pk_fma_f32 v[130:131], v[0:1], s[0:1], v[130:131] op_sel_hi:[1,0,1]
	v_pk_fma_f32 v[138:139], v[2:3], s[0:1], v[138:139] op_sel_hi:[1,0,1]
	v_pk_fma_f32 v[140:141], v[4:5], s[0:1], v[140:141] op_sel_hi:[1,0,1]
	v_pk_fma_f32 v[142:143], v[6:7], s[0:1], v[142:143] op_sel_hi:[1,0,1]
	v_pk_fma_f32 v[128:129], v[8:9], s[0:1], v[128:129] op_sel_hi:[1,0,1]
	v_pk_fma_f32 v[132:133], v[10:11], s[0:1], v[132:133] op_sel_hi:[1,0,1]
	v_pk_fma_f32 v[134:135], v[12:13], s[0:1], v[134:135] op_sel_hi:[1,0,1]
	v_pk_fma_f32 v[136:137], v[14:15], s[0:1], v[136:137] op_sel_hi:[1,0,1]
	v_readlane_b32 s0, v167, 62
	s_waitcnt vmcnt(15)
	v_cvt_scalef32_pk_f32_fp4 v[0:1], v184, 1.0
	v_cvt_scalef32_pk_f32_fp4 v[2:3], v184, 1.0 op_sel:[1,0,0]
	v_cvt_scalef32_pk_f32_fp4 v[4:5], v184, 1.0 op_sel:[0,1,0]
	v_cvt_scalef32_pk_f32_fp4 v[6:7], v184, 1.0 op_sel:[1,1,0]
	v_cvt_scalef32_pk_f32_fp4 v[8:9], v185, 1.0
	v_cvt_scalef32_pk_f32_fp4 v[10:11], v185, 1.0 op_sel:[1,0,0]
	v_cvt_scalef32_pk_f32_fp4 v[12:13], v185, 1.0 op_sel:[0,1,0]
	v_cvt_scalef32_pk_f32_fp4 v[14:15], v185, 1.0 op_sel:[1,1,0]
	v_readlane_b32 s54, v90, 14
	s_lshl_b32 s56, s54, 9
	s_add_u32 s56, s64, s56
	s_addc_u32 s57, s65, 0
	global_load_dwordx2 v[184:185], v227, s[56:57]
	v_pk_fma_f32 v[130:131], v[0:1], s[0:1], v[130:131] op_sel_hi:[1,0,1]
	v_pk_fma_f32 v[138:139], v[2:3], s[0:1], v[138:139] op_sel_hi:[1,0,1]
	v_pk_fma_f32 v[140:141], v[4:5], s[0:1], v[140:141] op_sel_hi:[1,0,1]
	v_pk_fma_f32 v[142:143], v[6:7], s[0:1], v[142:143] op_sel_hi:[1,0,1]
	v_pk_fma_f32 v[128:129], v[8:9], s[0:1], v[128:129] op_sel_hi:[1,0,1]
	v_pk_fma_f32 v[132:133], v[10:11], s[0:1], v[132:133] op_sel_hi:[1,0,1]
	v_pk_fma_f32 v[134:135], v[12:13], s[0:1], v[134:135] op_sel_hi:[1,0,1]
	v_pk_fma_f32 v[136:137], v[14:15], s[0:1], v[136:137] op_sel_hi:[1,0,1]
	v_readlane_b32 s0, v167, 63
	s_waitcnt vmcnt(15)
	v_cvt_scalef32_pk_f32_fp4 v[0:1], v186, 1.0
	v_cvt_scalef32_pk_f32_fp4 v[2:3], v186, 1.0 op_sel:[1,0,0]
	v_cvt_scalef32_pk_f32_fp4 v[4:5], v186, 1.0 op_sel:[0,1,0]
	v_cvt_scalef32_pk_f32_fp4 v[6:7], v186, 1.0 op_sel:[1,1,0]
	v_cvt_scalef32_pk_f32_fp4 v[8:9], v187, 1.0
	v_cvt_scalef32_pk_f32_fp4 v[10:11], v187, 1.0 op_sel:[1,0,0]
	v_cvt_scalef32_pk_f32_fp4 v[12:13], v187, 1.0 op_sel:[0,1,0]
	v_cvt_scalef32_pk_f32_fp4 v[14:15], v187, 1.0 op_sel:[1,1,0]
	v_readlane_b32 s54, v90, 15
	s_lshl_b32 s56, s54, 9
	s_add_u32 s56, s64, s56
	s_addc_u32 s57, s65, 0
	global_load_dwordx2 v[186:187], v227, s[56:57]
	v_pk_fma_f32 v[130:131], v[0:1], s[0:1], v[130:131] op_sel_hi:[1,0,1]
	v_pk_fma_f32 v[138:139], v[2:3], s[0:1], v[138:139] op_sel_hi:[1,0,1]
	v_pk_fma_f32 v[140:141], v[4:5], s[0:1], v[140:141] op_sel_hi:[1,0,1]
	v_pk_fma_f32 v[142:143], v[6:7], s[0:1], v[142:143] op_sel_hi:[1,0,1]
	v_pk_fma_f32 v[128:129], v[8:9], s[0:1], v[128:129] op_sel_hi:[1,0,1]
	v_pk_fma_f32 v[132:133], v[10:11], s[0:1], v[132:133] op_sel_hi:[1,0,1]
	v_pk_fma_f32 v[134:135], v[12:13], s[0:1], v[134:135] op_sel_hi:[1,0,1]
	v_pk_fma_f32 v[136:137], v[14:15], s[0:1], v[136:137] op_sel_hi:[1,0,1]
	v_readlane_b32 s54, v90, 16
	v_readlane_b32 s55, v90, 17
	s_mul_i32 s0, s54, 0x300
	s_mul_i32 s1, s55, 0x300
	v_add_u32_e32 v167, s0, v195
	s_and_saveexec_b64 s[98:99], s[40:41]
	v_add_u32_e32 v167, s1, v195
	s_mov_b64 exec, s[98:99]
	s_waitcnt vmcnt(48)
; __device__ void peer_gather_phase(const Params& P, int l, bool do_store) {
;     ...
;       for (int pr = 0; pr < 4; ++pr) {
;         const int ea = __builtin_amdgcn_readlane(evs, kb + 2 * pr), eb = __builtin_amdgcn_readlane(evs, kb + 2 * pr + 1);
;         const uint2* up = (const uint2*)(U + (size_t)(uphi ? eb : ea) * 768);
;         u6[3 * pr] = up[0]; u6[3 * pr + 1] = up[1]; u6[3 * pr + 2] = up[2];
;     ...
;         v6u_t qv; qv[0] = u6[3 * pr].x; qv[1] = u6[3 * pr].y; qv[2] = u6[3 * pr + 1].x; qv[3] = u6[3 * pr + 1].y; qv[4] = u6[3 * pr + 2].x; qv[5] = u6[3 * pr + 2].y;
;         const v32f_t wv = __builtin_amdgcn_cvt_scalef32_pk32_f32_fp6(qv, 1.0f);
;         f32x2 a2 = f32x2{0.f, 0.f};
; #pragma unroll
;         for (int i = 0; i < 16; ++i) a2 += f32x2{wv[2 * i], wv[2 * i + 1]} * xu[i];
;         float hs = a2.x + a2.y;
	v_cvt_scalef32_pk32_f32_fp6 v[0:31], v[50:55], 1.0
	global_load_dwordx2 v[54:55], v167, s[62:63] offset:16
	global_load_dwordx4 v[50:53], v167, s[62:63]
	v_pk_mul_f32 v[246:247], v[0:1], v[96:97]
	v_pk_mul_f32 v[254:255], v[2:3], v[98:99]
	v_pk_mul_f32 v[160:161], v[4:5], v[100:101]
	v_pk_fma_f32 v[246:247], v[6:7], v[102:103], v[246:247]
	v_pk_fma_f32 v[254:255], v[8:9], v[104:105], v[254:255]
	v_pk_fma_f32 v[160:161], v[10:11], v[106:107], v[160:161]
	v_pk_fma_f32 v[246:247], v[12:13], v[108:109], v[246:247]
	v_pk_fma_f32 v[254:255], v[14:15], v[110:111], v[254:255]
	v_pk_fma_f32 v[160:161], v[16:17], v[112:113], v[160:161]
	v_pk_fma_f32 v[246:247], v[18:19], v[114:115], v[246:247]
	v_pk_fma_f32 v[254:255], v[20:21], v[116:117], v[254:255]
	v_pk_fma_f32 v[160:161], v[22:23], v[118:119], v[160:161]
	v_pk_fma_f32 v[246:247], v[24:25], v[120:121], v[246:247]
	v_pk_fma_f32 v[254:255], v[26:27], v[122:123], v[254:255]
	v_pk_fma_f32 v[160:161], v[28:29], v[124:125], v[160:161]
	v_pk_fma_f32 v[246:247], v[30:31], v[126:127], v[246:247]
	v_pk_add_f32 v[254:255], v[254:255], v[160:161]
	v_readlane_b32 s54, v90, 18
	v_pk_add_f32 v[246:247], v[246:247], v[254:255]
	v_readlane_b32 s55, v90, 19
	v_add_f32_e32 v162, v246, v247
	s_mul_i32 s0, s54, 0x300
	s_mul_i32 s1, s55, 0x300
	v_add_u32_e32 v167, s0, v195
	s_and_saveexec_b64 s[98:99], s[40:41]
	v_add_u32_e32 v167, s1, v195
	s_mov_b64 exec, s[98:99]
	s_waitcnt vmcnt(48)
	v_cvt_scalef32_pk32_f32_fp6 v[0:31], v[44:49], 1.0
	global_load_dwordx2 v[48:49], v167, s[62:63] offset:16
	global_load_dwordx4 v[44:47], v167, s[62:63]
	v_pk_mul_f32 v[246:247], v[0:1], v[96:97]
	v_pk_mul_f32 v[254:255], v[2:3], v[98:99]
	v_pk_mul_f32 v[160:161], v[4:5], v[100:101]
	v_pk_fma_f32 v[246:247], v[6:7], v[102:103], v[246:247]
	v_pk_fma_f32 v[254:255], v[8:9], v[104:105], v[254:255]
	v_pk_fma_f32 v[160:161], v[10:11], v[106:107], v[160:161]
	v_pk_fma_f32 v[246:247], v[12:13], v[108:109], v[246:247]
	v_pk_fma_f32 v[254:255], v[14:15], v[110:111], v[254:255]
	v_pk_fma_f32 v[160:161], v[16:17], v[112:113], v[160:161]
	v_pk_fma_f32 v[246:247], v[18:19], v[114:115], v[246:247]
	v_pk_fma_f32 v[254:255], v[20:21], v[116:117], v[254:255]
	v_pk_fma_f32 v[160:161], v[22:23], v[118:119], v[160:161]
	v_pk_fma_f32 v[246:247], v[24:25], v[120:121], v[246:247]
	v_pk_fma_f32 v[254:255], v[26:27], v[122:123], v[254:255]
	v_pk_fma_f32 v[160:161], v[28:29], v[124:125], v[160:161]
	v_pk_fma_f32 v[246:247], v[30:31], v[126:127], v[246:247]
	v_pk_add_f32 v[254:255], v[254:255], v[160:161]
	v_readlane_b32 s54, v90, 20
	v_pk_add_f32 v[246:247], v[246:247], v[254:255]
	v_readlane_b32 s55, v90, 21
	v_add_f32_e32 v163, v246, v247
	s_mul_i32 s0, s54, 0x300
	s_mul_i32 s1, s55, 0x300
	v_add_u32_e32 v167, s0, v195
	s_and_saveexec_b64 s[98:99], s[40:41]
	v_add_u32_e32 v167, s1, v195
	s_mov_b64 exec, s[98:99]
	s_waitcnt vmcnt(48)
	v_cvt_scalef32_pk32_f32_fp6 v[0:31], v[38:43], 1.0
	global_load_dwordx2 v[42:43], v167, s[62:63] offset:16
	global_load_dwordx4 v[38:41], v167, s[62:63]
	v_pk_mul_f32 v[246:247], v[0:1], v[96:97]
	v_pk_mul_f32 v[254:255], v[2:3], v[98:99]
	v_pk_mul_f32 v[160:161], v[4:5], v[100:101]
	v_pk_fma_f32 v[246:247], v[6:7], v[102:103], v[246:247]
	v_pk_fma_f32 v[254:255], v[8:9], v[104:105], v[254:255]
	v_pk_fma_f32 v[160:161], v[10:11], v[106:107], v[160:161]
	v_pk_fma_f32 v[246:247], v[12:13], v[108:109], v[246:247]
	v_pk_fma_f32 v[254:255], v[14:15], v[110:111], v[254:255]
	v_pk_fma_f32 v[160:161], v[16:17], v[112:113], v[160:161]
	v_pk_fma_f32 v[246:247], v[18:19], v[114:115], v[246:247]
	v_pk_fma_f32 v[254:255], v[20:21], v[116:117], v[254:255]
	v_pk_fma_f32 v[160:161], v[22:23], v[118:119], v[160:161]
	v_pk_fma_f32 v[246:247], v[24:25], v[120:121], v[246:247]
	v_pk_fma_f32 v[254:255], v[26:27], v[122:123], v[254:255]
	v_pk_fma_f32 v[160:161], v[28:29], v[124:125], v[160:161]
	v_pk_fma_f32 v[246:247], v[30:31], v[126:127], v[246:247]
	v_pk_add_f32 v[254:255], v[254:255], v[160:161]
	v_readlane_b32 s54, v90, 22
	v_pk_add_f32 v[246:247], v[246:247], v[254:255]
	v_readlane_b32 s55, v90, 23
	v_add_f32_e32 v164, v246, v247
	s_mul_i32 s0, s54, 0x300
	s_mul_i32 s1, s55, 0x300
	v_add_u32_e32 v167, s0, v195
	s_and_saveexec_b64 s[98:99], s[40:41]
	v_add_u32_e32 v167, s1, v195
	s_mov_b64 exec, s[98:99]
	s_waitcnt vmcnt(48)
; __device__ void peer_gather_phase(const Params& P, int l, bool do_store) {
;     ...
;         v6u_t qv; qv[0] = u6[3 * pr].x; qv[1] = u6[3 * pr].y; qv[2] = u6[3 * pr + 1].x; qv[3] = u6[3 * pr + 1].y; qv[4] = u6[3 * pr + 2].x; qv[5] = u6[3 * pr + 2].y;
;         const v32f_t wv = __builtin_amdgcn_cvt_scalef32_pk32_f32_fp6(qv, 1.0f);
;         f32x2 a2 = f32x2{0.f, 0.f};
; #pragma unroll
;         for (int i = 0; i < 16; ++i) a2 += f32x2{wv[2 * i], wv[2 * i + 1]} * xu[i];
;         float hs = a2.x + a2.y;
;         hs += dpp_row_shr(hs, 1); hs += dpp_row_shr(hs, 2); hs += dpp_row_shr(hs, 4); hs += dpp_row_shr(hs, 8);
;         hs += __builtin_bit_cast(float, __builtin_amdgcn_update_dpp(0, __builtin_bit_cast(int, hs), 0x142, 0xa, 0xf, false));
;         const float da = __builtin_bit_cast(float, __builtin_amdgcn_readlane(__builtin_bit_cast(int, hs), 31));
;         const float db = __builtin_bit_cast(float, __builtin_amdgcn_readlane(__builtin_bit_cast(int, hs), 63));
;         dvec = (lane == kb + 2 * pr) ? da : dvec;
;         dvec = (lane == kb + 2 * pr + 1) ? db : dvec;
;       }
	v_cvt_scalef32_pk32_f32_fp6 v[0:31], v[32:37], 1.0
	global_load_dwordx2 v[36:37], v167, s[62:63] offset:16
	global_load_dwordx4 v[32:35], v167, s[62:63]
	v_pk_mul_f32 v[246:247], v[0:1], v[96:97]
	v_pk_mul_f32 v[254:255], v[2:3], v[98:99]
	v_pk_mul_f32 v[160:161], v[4:5], v[100:101]
	v_pk_fma_f32 v[246:247], v[6:7], v[102:103], v[246:247]
	v_pk_fma_f32 v[254:255], v[8:9], v[104:105], v[254:255]
	v_pk_fma_f32 v[160:161], v[10:11], v[106:107], v[160:161]
	v_pk_fma_f32 v[246:247], v[12:13], v[108:109], v[246:247]
	v_pk_fma_f32 v[254:255], v[14:15], v[110:111], v[254:255]
	v_pk_fma_f32 v[160:161], v[16:17], v[112:113], v[160:161]
	v_pk_fma_f32 v[246:247], v[18:19], v[114:115], v[246:247]
	v_pk_fma_f32 v[254:255], v[20:21], v[116:117], v[254:255]
	v_pk_fma_f32 v[160:161], v[22:23], v[118:119], v[160:161]
	v_pk_fma_f32 v[246:247], v[24:25], v[120:121], v[246:247]
	v_pk_fma_f32 v[254:255], v[26:27], v[122:123], v[254:255]
	v_pk_fma_f32 v[160:161], v[28:29], v[124:125], v[160:161]
	v_pk_fma_f32 v[246:247], v[30:31], v[126:127], v[246:247]
	v_pk_add_f32 v[254:255], v[254:255], v[160:161]
	s_nop 0
	v_pk_add_f32 v[246:247], v[246:247], v[254:255]
	s_nop 0
	v_add_f32_e32 v165, v246, v247
	v_add_f32_dpp v162, v162, v162 row_shr:1 row_mask:0xf bank_mask:0xf bound_ctrl:1
	v_add_f32_dpp v163, v163, v163 row_shr:1 row_mask:0xf bank_mask:0xf bound_ctrl:1
	v_add_f32_dpp v164, v164, v164 row_shr:1 row_mask:0xf bank_mask:0xf bound_ctrl:1
	v_add_f32_dpp v165, v165, v165 row_shr:1 row_mask:0xf bank_mask:0xf bound_ctrl:1
	v_add_f32_dpp v162, v162, v162 row_shr:2 row_mask:0xf bank_mask:0xf bound_ctrl:1
	v_add_f32_dpp v163, v163, v163 row_shr:2 row_mask:0xf bank_mask:0xf bound_ctrl:1
	v_add_f32_dpp v164, v164, v164 row_shr:2 row_mask:0xf bank_mask:0xf bound_ctrl:1
	v_add_f32_dpp v165, v165, v165 row_shr:2 row_mask:0xf bank_mask:0xf bound_ctrl:1
	v_add_f32_dpp v162, v162, v162 row_shr:4 row_mask:0xf bank_mask:0xf bound_ctrl:1
	v_add_f32_dpp v163, v163, v163 row_shr:4 row_mask:0xf bank_mask:0xf bound_ctrl:1
	v_add_f32_dpp v164, v164, v164 row_shr:4 row_mask:0xf bank_mask:0xf bound_ctrl:1
	v_add_f32_dpp v165, v165, v165 row_shr:4 row_mask:0xf bank_mask:0xf bound_ctrl:1
	v_add_f32_dpp v162, v162, v162 row_shr:8 row_mask:0xf bank_mask:0xf bound_ctrl:1
	v_add_f32_dpp v163, v163, v163 row_shr:8 row_mask:0xf bank_mask:0xf bound_ctrl:1
	v_add_f32_dpp v164, v164, v164 row_shr:8 row_mask:0xf bank_mask:0xf bound_ctrl:1
	v_add_f32_dpp v165, v165, v165 row_shr:8 row_mask:0xf bank_mask:0xf bound_ctrl:1
	v_add_f32_dpp v162, v162, v162 row_bcast:15 row_mask:0xa bank_mask:0xf
	v_add_f32_dpp v163, v163, v163 row_bcast:15 row_mask:0xa bank_mask:0xf
	v_add_f32_dpp v164, v164, v164 row_bcast:15 row_mask:0xa bank_mask:0xf
	v_add_f32_dpp v165, v165, v165 row_bcast:15 row_mask:0xa bank_mask:0xf
	s_nop 1
	v_readlane_b32 s46, v162, 31
	v_readlane_b32 s47, v162, 63
	v_readlane_b32 s48, v163, 31
	v_readlane_b32 s49, v163, 63
	v_readlane_b32 s50, v164, 31
	v_readlane_b32 s51, v164, 63
	v_readlane_b32 s52, v165, 31
	v_readlane_b32 s53, v165, 63
	v_writelane_b32 v166, s46, 0
	s_nop 1
	v_writelane_b32 v166, s47, 1
	v_writelane_b32 v166, s48, 2
	v_writelane_b32 v166, s49, 3
	v_writelane_b32 v166, s50, 4
	v_writelane_b32 v166, s51, 5
	v_writelane_b32 v166, s52, 6
	v_writelane_b32 v166, s53, 7
	v_readlane_b32 s54, v90, 24
	v_readlane_b32 s55, v90, 25
	s_mul_i32 s0, s54, 0x300
	s_mul_i32 s1, s55, 0x300
	v_add_u32_e32 v167, s0, v195
	s_and_saveexec_b64 s[98:99], s[40:41]
	v_add_u32_e32 v167, s1, v195
	s_mov_b64 exec, s[98:99]
	s_waitcnt vmcnt(48)
	v_cvt_scalef32_pk32_f32_fp6 v[0:31], v[196:201], 1.0
	global_load_dwordx2 v[200:201], v167, s[62:63] offset:16
	global_load_dwordx4 v[196:199], v167, s[62:63]
	v_pk_mul_f32 v[246:247], v[0:1], v[96:97]
	v_pk_mul_f32 v[254:255], v[2:3], v[98:99]
	v_pk_mul_f32 v[160:161], v[4:5], v[100:101]
	v_pk_fma_f32 v[246:247], v[6:7], v[102:103], v[246:247]
	v_pk_fma_f32 v[254:255], v[8:9], v[104:105], v[254:255]
	v_pk_fma_f32 v[160:161], v[10:11], v[106:107], v[160:161]
	v_pk_fma_f32 v[246:247], v[12:13], v[108:109], v[246:247]
	v_pk_fma_f32 v[254:255], v[14:15], v[110:111], v[254:255]
	v_pk_fma_f32 v[160:161], v[16:17], v[112:113], v[160:161]
	v_pk_fma_f32 v[246:247], v[18:19], v[114:115], v[246:247]
	v_pk_fma_f32 v[254:255], v[20:21], v[116:117], v[254:255]
	v_pk_fma_f32 v[160:161], v[22:23], v[118:119], v[160:161]
	v_pk_fma_f32 v[246:247], v[24:25], v[120:121], v[246:247]
	v_pk_fma_f32 v[254:255], v[26:27], v[122:123], v[254:255]
	v_pk_fma_f32 v[160:161], v[28:29], v[124:125], v[160:161]
	v_pk_fma_f32 v[246:247], v[30:31], v[126:127], v[246:247]
	v_pk_add_f32 v[254:255], v[254:255], v[160:161]
	v_readlane_b32 s54, v90, 26
	v_pk_add_f32 v[246:247], v[246:247], v[254:255]
	v_readlane_b32 s55, v90, 27
	v_add_f32_e32 v162, v246, v247
	s_mul_i32 s0, s54, 0x300
	s_mul_i32 s1, s55, 0x300
	v_add_u32_e32 v167, s0, v195
	s_and_saveexec_b64 s[98:99], s[40:41]
	v_add_u32_e32 v167, s1, v195
	s_mov_b64 exec, s[98:99]
	s_waitcnt vmcnt(48)
; __device__ void peer_gather_phase(const Params& P, int l, bool do_store) {
;     ...
;         v6u_t qv; qv[0] = u6[3 * pr].x; qv[1] = u6[3 * pr].y; qv[2] = u6[3 * pr + 1].x; qv[3] = u6[3 * pr + 1].y; qv[4] = u6[3 * pr + 2].x; qv[5] = u6[3 * pr + 2].y;
;         const v32f_t wv = __builtin_amdgcn_cvt_scalef32_pk32_f32_fp6(qv, 1.0f);
;         f32x2 a2 = f32x2{0.f, 0.f};
; #pragma unroll
;         for (int i = 0; i < 16; ++i) a2 += f32x2{wv[2 * i], wv[2 * i + 1]} * xu[i];
;         float hs = a2.x + a2.y;
;         hs += dpp_row_shr(hs, 1); hs += dpp_row_shr(hs, 2); hs += dpp_row_shr(hs, 4); hs += dpp_row_shr(hs, 8);
;         hs += __builtin_bit_cast(float, __builtin_amdgcn_update_dpp(0, __builtin_bit_cast(int, hs), 0x142, 0xa, 0xf, false));
;         const float da = __builtin_bit_cast(float, __builtin_amdgcn_readlane(__builtin_bit_cast(int, hs), 31));
;         const float db = __builtin_bit_cast(float, __builtin_amdgcn_readlane(__builtin_bit_cast(int, hs), 63));
;         dvec = (lane == kb + 2 * pr) ? da : dvec;
;         dvec = (lane == kb + 2 * pr + 1) ? db : dvec;
;       }
	v_cvt_scalef32_pk32_f32_fp6 v[0:31], v[228:233], 1.0
	global_load_dwordx2 v[232:233], v167, s[62:63] offset:16
	global_load_dwordx4 v[228:231], v167, s[62:63]
	v_pk_mul_f32 v[246:247], v[0:1], v[96:97]
	v_pk_mul_f32 v[254:255], v[2:3], v[98:99]
	v_pk_mul_f32 v[160:161], v[4:5], v[100:101]
	v_pk_fma_f32 v[246:247], v[6:7], v[102:103], v[246:247]
	v_pk_fma_f32 v[254:255], v[8:9], v[104:105], v[254:255]
	v_pk_fma_f32 v[160:161], v[10:11], v[106:107], v[160:161]
	v_pk_fma_f32 v[246:247], v[12:13], v[108:109], v[246:247]
	v_pk_fma_f32 v[254:255], v[14:15], v[110:111], v[254:255]
	v_pk_fma_f32 v[160:161], v[16:17], v[112:113], v[160:161]
	v_pk_fma_f32 v[246:247], v[18:19], v[114:115], v[246:247]
	v_pk_fma_f32 v[254:255], v[20:21], v[116:117], v[254:255]
	v_pk_fma_f32 v[160:161], v[22:23], v[118:119], v[160:161]
	v_pk_fma_f32 v[246:247], v[24:25], v[120:121], v[246:247]
	v_pk_fma_f32 v[254:255], v[26:27], v[122:123], v[254:255]
	v_pk_fma_f32 v[160:161], v[28:29], v[124:125], v[160:161]
	v_pk_fma_f32 v[246:247], v[30:31], v[126:127], v[246:247]
	v_pk_add_f32 v[254:255], v[254:255], v[160:161]
	v_readlane_b32 s54, v90, 28
	v_pk_add_f32 v[246:247], v[246:247], v[254:255]
	v_readlane_b32 s55, v90, 29
	v_add_f32_e32 v163, v246, v247
	s_mul_i32 s0, s54, 0x300
	s_mul_i32 s1, s55, 0x300
	v_add_u32_e32 v167, s0, v195
	s_and_saveexec_b64 s[98:99], s[40:41]
	v_add_u32_e32 v167, s1, v195
	s_mov_b64 exec, s[98:99]
	s_waitcnt vmcnt(48)
	v_cvt_scalef32_pk32_f32_fp6 v[0:31], v[234:239], 1.0
	global_load_dwordx2 v[238:239], v167, s[62:63] offset:16
	global_load_dwordx4 v[234:237], v167, s[62:63]
	v_pk_mul_f32 v[246:247], v[0:1], v[96:97]
	v_pk_mul_f32 v[254:255], v[2:3], v[98:99]
	v_pk_mul_f32 v[160:161], v[4:5], v[100:101]
	v_pk_fma_f32 v[246:247], v[6:7], v[102:103], v[246:247]
	v_pk_fma_f32 v[254:255], v[8:9], v[104:105], v[254:255]
	v_pk_fma_f32 v[160:161], v[10:11], v[106:107], v[160:161]
	v_pk_fma_f32 v[246:247], v[12:13], v[108:109], v[246:247]
	v_pk_fma_f32 v[254:255], v[14:15], v[110:111], v[254:255]
	v_pk_fma_f32 v[160:161], v[16:17], v[112:113], v[160:161]
	v_pk_fma_f32 v[246:247], v[18:19], v[114:115], v[246:247]
	v_pk_fma_f32 v[254:255], v[20:21], v[116:117], v[254:255]
	v_pk_fma_f32 v[160:161], v[22:23], v[118:119], v[160:161]
	v_pk_fma_f32 v[246:247], v[24:25], v[120:121], v[246:247]
	v_pk_fma_f32 v[254:255], v[26:27], v[122:123], v[254:255]
	v_pk_fma_f32 v[160:161], v[28:29], v[124:125], v[160:161]
	v_pk_fma_f32 v[246:247], v[30:31], v[126:127], v[246:247]
	v_pk_add_f32 v[254:255], v[254:255], v[160:161]
	v_readlane_b32 s54, v90, 30
	v_pk_add_f32 v[246:247], v[246:247], v[254:255]
	v_readlane_b32 s55, v90, 31
	v_add_f32_e32 v164, v246, v247
	s_mul_i32 s0, s54, 0x300
	s_mul_i32 s1, s55, 0x300
	v_add_u32_e32 v167, s0, v195
	s_and_saveexec_b64 s[98:99], s[40:41]
	v_add_u32_e32 v167, s1, v195
	s_mov_b64 exec, s[98:99]
	s_waitcnt vmcnt(48)
	v_cvt_scalef32_pk32_f32_fp6 v[0:31], v[240:245], 1.0
	global_load_dwordx2 v[244:245], v167, s[62:63] offset:16
	global_load_dwordx4 v[240:243], v167, s[62:63]
	v_pk_mul_f32 v[246:247], v[0:1], v[96:97]
	v_pk_mul_f32 v[254:255], v[2:3], v[98:99]
	v_pk_mul_f32 v[160:161], v[4:5], v[100:101]
	v_pk_fma_f32 v[246:247], v[6:7], v[102:103], v[246:247]
	v_pk_fma_f32 v[254:255], v[8:9], v[104:105], v[254:255]
	v_pk_fma_f32 v[160:161], v[10:11], v[106:107], v[160:161]
	v_pk_fma_f32 v[246:247], v[12:13], v[108:109], v[246:247]
	v_pk_fma_f32 v[254:255], v[14:15], v[110:111], v[254:255]
	v_pk_fma_f32 v[160:161], v[16:17], v[112:113], v[160:161]
	v_pk_fma_f32 v[246:247], v[18:19], v[114:115], v[246:247]
	v_pk_fma_f32 v[254:255], v[20:21], v[116:117], v[254:255]
	v_pk_fma_f32 v[160:161], v[22:23], v[118:119], v[160:161]
	v_pk_fma_f32 v[246:247], v[24:25], v[120:121], v[246:247]
	v_pk_fma_f32 v[254:255], v[26:27], v[122:123], v[254:255]
	v_pk_fma_f32 v[160:161], v[28:29], v[124:125], v[160:161]
	v_pk_fma_f32 v[246:247], v[30:31], v[126:127], v[246:247]
	v_pk_add_f32 v[254:255], v[254:255], v[160:161]
	s_nop 0
	v_pk_add_f32 v[246:247], v[246:247], v[254:255]
	s_nop 0
	v_add_f32_e32 v165, v246, v247
	v_add_f32_dpp v162, v162, v162 row_shr:1 row_mask:0xf bank_mask:0xf bound_ctrl:1
	v_add_f32_dpp v163, v163, v163 row_shr:1 row_mask:0xf bank_mask:0xf bound_ctrl:1
	v_add_f32_dpp v164, v164, v164 row_shr:1 row_mask:0xf bank_mask:0xf bound_ctrl:1
	v_add_f32_dpp v165, v165, v165 row_shr:1 row_mask:0xf bank_mask:0xf bound_ctrl:1
	v_add_f32_dpp v162, v162, v162 row_shr:2 row_mask:0xf bank_mask:0xf bound_ctrl:1
	v_add_f32_dpp v163, v163, v163 row_shr:2 row_mask:0xf bank_mask:0xf bound_ctrl:1
	v_add_f32_dpp v164, v164, v164 row_shr:2 row_mask:0xf bank_mask:0xf bound_ctrl:1
	v_add_f32_dpp v165, v165, v165 row_shr:2 row_mask:0xf bank_mask:0xf bound_ctrl:1
	v_add_f32_dpp v162, v162, v162 row_shr:4 row_mask:0xf bank_mask:0xf bound_ctrl:1
	v_add_f32_dpp v163, v163, v163 row_shr:4 row_mask:0xf bank_mask:0xf bound_ctrl:1
	v_add_f32_dpp v164, v164, v164 row_shr:4 row_mask:0xf bank_mask:0xf bound_ctrl:1
	v_add_f32_dpp v165, v165, v165 row_shr:4 row_mask:0xf bank_mask:0xf bound_ctrl:1
	v_add_f32_dpp v162, v162, v162 row_shr:8 row_mask:0xf bank_mask:0xf bound_ctrl:1
	v_add_f32_dpp v163, v163, v163 row_shr:8 row_mask:0xf bank_mask:0xf bound_ctrl:1
	v_add_f32_dpp v164, v164, v164 row_shr:8 row_mask:0xf bank_mask:0xf bound_ctrl:1
	v_add_f32_dpp v165, v165, v165 row_shr:8 row_mask:0xf bank_mask:0xf bound_ctrl:1
	v_add_f32_dpp v162, v162, v162 row_bcast:15 row_mask:0xa bank_mask:0xf
	v_add_f32_dpp v163, v163, v163 row_bcast:15 row_mask:0xa bank_mask:0xf
	v_add_f32_dpp v164, v164, v164 row_bcast:15 row_mask:0xa bank_mask:0xf
	v_add_f32_dpp v165, v165, v165 row_bcast:15 row_mask:0xa bank_mask:0xf
	s_nop 1
	v_readlane_b32 s46, v162, 31
	v_readlane_b32 s47, v162, 63
	v_readlane_b32 s48, v163, 31
	v_readlane_b32 s49, v163, 63
	v_readlane_b32 s50, v164, 31
	v_readlane_b32 s51, v164, 63
	v_readlane_b32 s52, v165, 31
	v_readlane_b32 s53, v165, 63
	v_writelane_b32 v166, s46, 8
	s_nop 1
	v_writelane_b32 v166, s47, 9
	v_writelane_b32 v166, s48, 10
	v_writelane_b32 v166, s49, 11
	v_writelane_b32 v166, s50, 12
	v_writelane_b32 v166, s51, 13
	v_writelane_b32 v166, s52, 14
	v_writelane_b32 v166, s53, 15
	v_readlane_b32 s54, v90, 32
	v_readlane_b32 s55, v90, 33
	s_mul_i32 s0, s54, 0x300
	s_mul_i32 s1, s55, 0x300
	v_add_u32_e32 v167, s0, v195
	s_and_saveexec_b64 s[98:99], s[40:41]
	v_add_u32_e32 v167, s1, v195
	s_mov_b64 exec, s[98:99]
	s_waitcnt vmcnt(14)
; __device__ void peer_gather_phase(const Params& P, int l, bool do_store) {
;     ...
;       for (int pr = 0; pr < 4; ++pr) {
;         const int ea = __builtin_amdgcn_readlane(evs, kb + 2 * pr), eb = __builtin_amdgcn_readlane(evs, kb + 2 * pr + 1);
;         const uint2* up = (const uint2*)(U + (size_t)(uphi ? eb : ea) * 768);
;         u6[3 * pr] = up[0]; u6[3 * pr + 1] = up[1]; u6[3 * pr + 2] = up[2];
;     ...
;         v6u_t qv; qv[0] = u6[3 * pr].x; qv[1] = u6[3 * pr].y; qv[2] = u6[3 * pr + 1].x; qv[3] = u6[3 * pr + 1].y; qv[4] = u6[3 * pr + 2].x; qv[5] = u6[3 * pr + 2].y;
;         const v32f_t wv = __builtin_amdgcn_cvt_scalef32_pk32_f32_fp6(qv, 1.0f);
;         f32x2 a2 = f32x2{0.f, 0.f};
; #pragma unroll
;         for (int i = 0; i < 16; ++i) a2 += f32x2{wv[2 * i], wv[2 * i + 1]} * xu[i];
;         float hs = a2.x + a2.y;
	v_cvt_scalef32_pk32_f32_fp6 v[0:31], v[50:55], 1.0
	global_load_dwordx2 v[54:55], v167, s[62:63] offset:16
	global_load_dwordx4 v[50:53], v167, s[62:63]
	v_pk_mul_f32 v[246:247], v[0:1], v[96:97]
	v_pk_mul_f32 v[254:255], v[2:3], v[98:99]
	v_pk_mul_f32 v[160:161], v[4:5], v[100:101]
	v_pk_fma_f32 v[246:247], v[6:7], v[102:103], v[246:247]
	v_pk_fma_f32 v[254:255], v[8:9], v[104:105], v[254:255]
	v_pk_fma_f32 v[160:161], v[10:11], v[106:107], v[160:161]
	v_pk_fma_f32 v[246:247], v[12:13], v[108:109], v[246:247]
	v_pk_fma_f32 v[254:255], v[14:15], v[110:111], v[254:255]
	v_pk_fma_f32 v[160:161], v[16:17], v[112:113], v[160:161]
	v_pk_fma_f32 v[246:247], v[18:19], v[114:115], v[246:247]
	v_pk_fma_f32 v[254:255], v[20:21], v[116:117], v[254:255]
	v_pk_fma_f32 v[160:161], v[22:23], v[118:119], v[160:161]
	v_pk_fma_f32 v[246:247], v[24:25], v[120:121], v[246:247]
	v_pk_fma_f32 v[254:255], v[26:27], v[122:123], v[254:255]
	v_pk_fma_f32 v[160:161], v[28:29], v[124:125], v[160:161]
	v_pk_fma_f32 v[246:247], v[30:31], v[126:127], v[246:247]
	v_pk_add_f32 v[254:255], v[254:255], v[160:161]
	v_readlane_b32 s54, v90, 34
	v_pk_add_f32 v[246:247], v[246:247], v[254:255]
	v_readlane_b32 s55, v90, 35
	v_add_f32_e32 v162, v246, v247
	s_mul_i32 s0, s54, 0x300
	s_mul_i32 s1, s55, 0x300
	v_add_u32_e32 v167, s0, v195
	s_and_saveexec_b64 s[98:99], s[40:41]
	v_add_u32_e32 v167, s1, v195
	s_mov_b64 exec, s[98:99]
	s_waitcnt vmcnt(14)
	v_cvt_scalef32_pk32_f32_fp6 v[0:31], v[44:49], 1.0
	global_load_dwordx2 v[48:49], v167, s[62:63] offset:16
	global_load_dwordx4 v[44:47], v167, s[62:63]
	v_pk_mul_f32 v[246:247], v[0:1], v[96:97]
	v_pk_mul_f32 v[254:255], v[2:3], v[98:99]
	v_pk_mul_f32 v[160:161], v[4:5], v[100:101]
	v_pk_fma_f32 v[246:247], v[6:7], v[102:103], v[246:247]
	v_pk_fma_f32 v[254:255], v[8:9], v[104:105], v[254:255]
	v_pk_fma_f32 v[160:161], v[10:11], v[106:107], v[160:161]
	v_pk_fma_f32 v[246:247], v[12:13], v[108:109], v[246:247]
	v_pk_fma_f32 v[254:255], v[14:15], v[110:111], v[254:255]
	v_pk_fma_f32 v[160:161], v[16:17], v[112:113], v[160:161]
	v_pk_fma_f32 v[246:247], v[18:19], v[114:115], v[246:247]
	v_pk_fma_f32 v[254:255], v[20:21], v[116:117], v[254:255]
	v_pk_fma_f32 v[160:161], v[22:23], v[118:119], v[160:161]
	v_pk_fma_f32 v[246:247], v[24:25], v[120:121], v[246:247]
	v_pk_fma_f32 v[254:255], v[26:27], v[122:123], v[254:255]
	v_pk_fma_f32 v[160:161], v[28:29], v[124:125], v[160:161]
	v_pk_fma_f32 v[246:247], v[30:31], v[126:127], v[246:247]
	v_pk_add_f32 v[254:255], v[254:255], v[160:161]
	v_readlane_b32 s54, v90, 36
	v_pk_add_f32 v[246:247], v[246:247], v[254:255]
	v_readlane_b32 s55, v90, 37
	v_add_f32_e32 v163, v246, v247
	s_mul_i32 s0, s54, 0x300
	s_mul_i32 s1, s55, 0x300
	v_add_u32_e32 v167, s0, v195
	s_and_saveexec_b64 s[98:99], s[40:41]
	v_add_u32_e32 v167, s1, v195
	s_mov_b64 exec, s[98:99]
	s_waitcnt vmcnt(14)
	v_cvt_scalef32_pk32_f32_fp6 v[0:31], v[38:43], 1.0
	global_load_dwordx2 v[42:43], v167, s[62:63] offset:16
	global_load_dwordx4 v[38:41], v167, s[62:63]
	v_pk_mul_f32 v[246:247], v[0:1], v[96:97]
	v_pk_mul_f32 v[254:255], v[2:3], v[98:99]
	v_pk_mul_f32 v[160:161], v[4:5], v[100:101]
	v_pk_fma_f32 v[246:247], v[6:7], v[102:103], v[246:247]
	v_pk_fma_f32 v[254:255], v[8:9], v[104:105], v[254:255]
	v_pk_fma_f32 v[160:161], v[10:11], v[106:107], v[160:161]
	v_pk_fma_f32 v[246:247], v[12:13], v[108:109], v[246:247]
	v_pk_fma_f32 v[254:255], v[14:15], v[110:111], v[254:255]
	v_pk_fma_f32 v[160:161], v[16:17], v[112:113], v[160:161]
	v_pk_fma_f32 v[246:247], v[18:19], v[114:115], v[246:247]
	v_pk_fma_f32 v[254:255], v[20:21], v[116:117], v[254:255]
	v_pk_fma_f32 v[160:161], v[22:23], v[118:119], v[160:161]
	v_pk_fma_f32 v[246:247], v[24:25], v[120:121], v[246:247]
	v_pk_fma_f32 v[254:255], v[26:27], v[122:123], v[254:255]
	v_pk_fma_f32 v[160:161], v[28:29], v[124:125], v[160:161]
	v_pk_fma_f32 v[246:247], v[30:31], v[126:127], v[246:247]
	v_pk_add_f32 v[254:255], v[254:255], v[160:161]
	v_readlane_b32 s54, v90, 38
	v_pk_add_f32 v[246:247], v[246:247], v[254:255]
	v_readlane_b32 s55, v90, 39
	v_add_f32_e32 v164, v246, v247
	s_mul_i32 s0, s54, 0x300
	s_mul_i32 s1, s55, 0x300
	v_add_u32_e32 v167, s0, v195
	s_and_saveexec_b64 s[98:99], s[40:41]
	v_add_u32_e32 v167, s1, v195
	s_mov_b64 exec, s[98:99]
	s_waitcnt vmcnt(14)
; __device__ void peer_gather_phase(const Params& P, int l, bool do_store) {
;     ...
;         v6u_t qv; qv[0] = u6[3 * pr].x; qv[1] = u6[3 * pr].y; qv[2] = u6[3 * pr + 1].x; qv[3] = u6[3 * pr + 1].y; qv[4] = u6[3 * pr + 2].x; qv[5] = u6[3 * pr + 2].y;
;         const v32f_t wv = __builtin_amdgcn_cvt_scalef32_pk32_f32_fp6(qv, 1.0f);
;         f32x2 a2 = f32x2{0.f, 0.f};
; #pragma unroll
;         for (int i = 0; i < 16; ++i) a2 += f32x2{wv[2 * i], wv[2 * i + 1]} * xu[i];
;         float hs = a2.x + a2.y;
;         hs += dpp_row_shr(hs, 1); hs += dpp_row_shr(hs, 2); hs += dpp_row_shr(hs, 4); hs += dpp_row_shr(hs, 8);
;         hs += __builtin_bit_cast(float, __builtin_amdgcn_update_dpp(0, __builtin_bit_cast(int, hs), 0x142, 0xa, 0xf, false));
;         const float da = __builtin_bit_cast(float, __builtin_amdgcn_readlane(__builtin_bit_cast(int, hs), 31));
;         const float db = __builtin_bit_cast(float, __builtin_amdgcn_readlane(__builtin_bit_cast(int, hs), 63));
;         dvec = (lane == kb + 2 * pr) ? da : dvec;
;         dvec = (lane == kb + 2 * pr + 1) ? db : dvec;
;       }
	v_cvt_scalef32_pk32_f32_fp6 v[0:31], v[32:37], 1.0
	global_load_dwordx2 v[36:37], v167, s[62:63] offset:16
	global_load_dwordx4 v[32:35], v167, s[62:63]
	v_pk_mul_f32 v[246:247], v[0:1], v[96:97]
	v_pk_mul_f32 v[254:255], v[2:3], v[98:99]
	v_pk_mul_f32 v[160:161], v[4:5], v[100:101]
	v_pk_fma_f32 v[246:247], v[6:7], v[102:103], v[246:247]
	v_pk_fma_f32 v[254:255], v[8:9], v[104:105], v[254:255]
	v_pk_fma_f32 v[160:161], v[10:11], v[106:107], v[160:161]
	v_pk_fma_f32 v[246:247], v[12:13], v[108:109], v[246:247]
	v_pk_fma_f32 v[254:255], v[14:15], v[110:111], v[254:255]
	v_pk_fma_f32 v[160:161], v[16:17], v[112:113], v[160:161]
	v_pk_fma_f32 v[246:247], v[18:19], v[114:115], v[246:247]
	v_pk_fma_f32 v[254:255], v[20:21], v[116:117], v[254:255]
	v_pk_fma_f32 v[160:161], v[22:23], v[118:119], v[160:161]
	v_pk_fma_f32 v[246:247], v[24:25], v[120:121], v[246:247]
	v_pk_fma_f32 v[254:255], v[26:27], v[122:123], v[254:255]
	v_pk_fma_f32 v[160:161], v[28:29], v[124:125], v[160:161]
	v_pk_fma_f32 v[246:247], v[30:31], v[126:127], v[246:247]
	v_pk_add_f32 v[254:255], v[254:255], v[160:161]
	s_nop 0
	v_pk_add_f32 v[246:247], v[246:247], v[254:255]
	s_nop 0
	v_add_f32_e32 v165, v246, v247
	v_add_f32_dpp v162, v162, v162 row_shr:1 row_mask:0xf bank_mask:0xf bound_ctrl:1
	v_add_f32_dpp v163, v163, v163 row_shr:1 row_mask:0xf bank_mask:0xf bound_ctrl:1
	v_add_f32_dpp v164, v164, v164 row_shr:1 row_mask:0xf bank_mask:0xf bound_ctrl:1
	v_add_f32_dpp v165, v165, v165 row_shr:1 row_mask:0xf bank_mask:0xf bound_ctrl:1
	v_add_f32_dpp v162, v162, v162 row_shr:2 row_mask:0xf bank_mask:0xf bound_ctrl:1
	v_add_f32_dpp v163, v163, v163 row_shr:2 row_mask:0xf bank_mask:0xf bound_ctrl:1
	v_add_f32_dpp v164, v164, v164 row_shr:2 row_mask:0xf bank_mask:0xf bound_ctrl:1
	v_add_f32_dpp v165, v165, v165 row_shr:2 row_mask:0xf bank_mask:0xf bound_ctrl:1
	v_add_f32_dpp v162, v162, v162 row_shr:4 row_mask:0xf bank_mask:0xf bound_ctrl:1
	v_add_f32_dpp v163, v163, v163 row_shr:4 row_mask:0xf bank_mask:0xf bound_ctrl:1
	v_add_f32_dpp v164, v164, v164 row_shr:4 row_mask:0xf bank_mask:0xf bound_ctrl:1
	v_add_f32_dpp v165, v165, v165 row_shr:4 row_mask:0xf bank_mask:0xf bound_ctrl:1
	v_add_f32_dpp v162, v162, v162 row_shr:8 row_mask:0xf bank_mask:0xf bound_ctrl:1
	v_add_f32_dpp v163, v163, v163 row_shr:8 row_mask:0xf bank_mask:0xf bound_ctrl:1
	v_add_f32_dpp v164, v164, v164 row_shr:8 row_mask:0xf bank_mask:0xf bound_ctrl:1
	v_add_f32_dpp v165, v165, v165 row_shr:8 row_mask:0xf bank_mask:0xf bound_ctrl:1
	v_add_f32_dpp v162, v162, v162 row_bcast:15 row_mask:0xa bank_mask:0xf
	v_add_f32_dpp v163, v163, v163 row_bcast:15 row_mask:0xa bank_mask:0xf
	v_add_f32_dpp v164, v164, v164 row_bcast:15 row_mask:0xa bank_mask:0xf
	v_add_f32_dpp v165, v165, v165 row_bcast:15 row_mask:0xa bank_mask:0xf
	s_nop 1
	v_readlane_b32 s46, v162, 31
	v_readlane_b32 s47, v162, 63
	v_readlane_b32 s48, v163, 31
	v_readlane_b32 s49, v163, 63
	v_readlane_b32 s50, v164, 31
	v_readlane_b32 s51, v164, 63
	v_readlane_b32 s52, v165, 31
	v_readlane_b32 s53, v165, 63
	v_writelane_b32 v166, s46, 16
	s_nop 1
	v_writelane_b32 v166, s47, 17
	v_writelane_b32 v166, s48, 18
	v_writelane_b32 v166, s49, 19
	v_writelane_b32 v166, s50, 20
	v_writelane_b32 v166, s51, 21
	v_writelane_b32 v166, s52, 22
	v_writelane_b32 v166, s53, 23
	v_readlane_b32 s54, v90, 40
	v_readlane_b32 s55, v90, 41
	s_mul_i32 s0, s54, 0x300
	s_mul_i32 s1, s55, 0x300
	v_add_u32_e32 v167, s0, v195
	s_and_saveexec_b64 s[98:99], s[40:41]
	v_add_u32_e32 v167, s1, v195
	s_mov_b64 exec, s[98:99]
	s_waitcnt vmcnt(14)
	v_cvt_scalef32_pk32_f32_fp6 v[0:31], v[196:201], 1.0
	global_load_dwordx2 v[200:201], v167, s[62:63] offset:16
	global_load_dwordx4 v[196:199], v167, s[62:63]
	v_pk_mul_f32 v[246:247], v[0:1], v[96:97]
	v_pk_mul_f32 v[254:255], v[2:3], v[98:99]
	v_pk_mul_f32 v[160:161], v[4:5], v[100:101]
	v_pk_fma_f32 v[246:247], v[6:7], v[102:103], v[246:247]
	v_pk_fma_f32 v[254:255], v[8:9], v[104:105], v[254:255]
	v_pk_fma_f32 v[160:161], v[10:11], v[106:107], v[160:161]
	v_pk_fma_f32 v[246:247], v[12:13], v[108:109], v[246:247]
	v_pk_fma_f32 v[254:255], v[14:15], v[110:111], v[254:255]
	v_pk_fma_f32 v[160:161], v[16:17], v[112:113], v[160:161]
	v_pk_fma_f32 v[246:247], v[18:19], v[114:115], v[246:247]
	v_pk_fma_f32 v[254:255], v[20:21], v[116:117], v[254:255]
	v_pk_fma_f32 v[160:161], v[22:23], v[118:119], v[160:161]
	v_pk_fma_f32 v[246:247], v[24:25], v[120:121], v[246:247]
	v_pk_fma_f32 v[254:255], v[26:27], v[122:123], v[254:255]
	v_pk_fma_f32 v[160:161], v[28:29], v[124:125], v[160:161]
	v_pk_fma_f32 v[246:247], v[30:31], v[126:127], v[246:247]
	v_pk_add_f32 v[254:255], v[254:255], v[160:161]
	v_readlane_b32 s54, v90, 42
	v_pk_add_f32 v[246:247], v[246:247], v[254:255]
	v_readlane_b32 s55, v90, 43
	v_add_f32_e32 v162, v246, v247
	s_mul_i32 s0, s54, 0x300
	s_mul_i32 s1, s55, 0x300
	v_add_u32_e32 v167, s0, v195
	s_and_saveexec_b64 s[98:99], s[40:41]
	v_add_u32_e32 v167, s1, v195
	s_mov_b64 exec, s[98:99]
	s_waitcnt vmcnt(14)
; __device__ void peer_gather_phase(const Params& P, int l, bool do_store) {
;     ...
;         v6u_t qv; qv[0] = u6[3 * pr].x; qv[1] = u6[3 * pr].y; qv[2] = u6[3 * pr + 1].x; qv[3] = u6[3 * pr + 1].y; qv[4] = u6[3 * pr + 2].x; qv[5] = u6[3 * pr + 2].y;
;         const v32f_t wv = __builtin_amdgcn_cvt_scalef32_pk32_f32_fp6(qv, 1.0f);
;         f32x2 a2 = f32x2{0.f, 0.f};
; #pragma unroll
;         for (int i = 0; i < 16; ++i) a2 += f32x2{wv[2 * i], wv[2 * i + 1]} * xu[i];
;         float hs = a2.x + a2.y;
;         hs += dpp_row_shr(hs, 1); hs += dpp_row_shr(hs, 2); hs += dpp_row_shr(hs, 4); hs += dpp_row_shr(hs, 8);
;         hs += __builtin_bit_cast(float, __builtin_amdgcn_update_dpp(0, __builtin_bit_cast(int, hs), 0x142, 0xa, 0xf, false));
;         const float da = __builtin_bit_cast(float, __builtin_amdgcn_readlane(__builtin_bit_cast(int, hs), 31));
;         const float db = __builtin_bit_cast(float, __builtin_amdgcn_readlane(__builtin_bit_cast(int, hs), 63));
;         dvec = (lane == kb + 2 * pr) ? da : dvec;
;         dvec = (lane == kb + 2 * pr + 1) ? db : dvec;
;       }
	v_cvt_scalef32_pk32_f32_fp6 v[0:31], v[228:233], 1.0
	global_load_dwordx2 v[232:233], v167, s[62:63] offset:16
	global_load_dwordx4 v[228:231], v167, s[62:63]
	v_pk_mul_f32 v[246:247], v[0:1], v[96:97]
	v_pk_mul_f32 v[254:255], v[2:3], v[98:99]
	v_pk_mul_f32 v[160:161], v[4:5], v[100:101]
	v_pk_fma_f32 v[246:247], v[6:7], v[102:103], v[246:247]
	v_pk_fma_f32 v[254:255], v[8:9], v[104:105], v[254:255]
	v_pk_fma_f32 v[160:161], v[10:11], v[106:107], v[160:161]
	v_pk_fma_f32 v[246:247], v[12:13], v[108:109], v[246:247]
	v_pk_fma_f32 v[254:255], v[14:15], v[110:111], v[254:255]
	v_pk_fma_f32 v[160:161], v[16:17], v[112:113], v[160:161]
	v_pk_fma_f32 v[246:247], v[18:19], v[114:115], v[246:247]
	v_pk_fma_f32 v[254:255], v[20:21], v[116:117], v[254:255]
	v_pk_fma_f32 v[160:161], v[22:23], v[118:119], v[160:161]
	v_pk_fma_f32 v[246:247], v[24:25], v[120:121], v[246:247]
	v_pk_fma_f32 v[254:255], v[26:27], v[122:123], v[254:255]
	v_pk_fma_f32 v[160:161], v[28:29], v[124:125], v[160:161]
	v_pk_fma_f32 v[246:247], v[30:31], v[126:127], v[246:247]
	v_pk_add_f32 v[254:255], v[254:255], v[160:161]
	v_readlane_b32 s54, v90, 44
	v_pk_add_f32 v[246:247], v[246:247], v[254:255]
	v_readlane_b32 s55, v90, 45
	v_add_f32_e32 v163, v246, v247
	s_mul_i32 s0, s54, 0x300
	s_mul_i32 s1, s55, 0x300
	v_add_u32_e32 v167, s0, v195
	s_and_saveexec_b64 s[98:99], s[40:41]
	v_add_u32_e32 v167, s1, v195
	s_mov_b64 exec, s[98:99]
	s_waitcnt vmcnt(14)
	v_cvt_scalef32_pk32_f32_fp6 v[0:31], v[234:239], 1.0
	global_load_dwordx2 v[238:239], v167, s[62:63] offset:16
	global_load_dwordx4 v[234:237], v167, s[62:63]
	v_pk_mul_f32 v[246:247], v[0:1], v[96:97]
	v_pk_mul_f32 v[254:255], v[2:3], v[98:99]
	v_pk_mul_f32 v[160:161], v[4:5], v[100:101]
	v_pk_fma_f32 v[246:247], v[6:7], v[102:103], v[246:247]
	v_pk_fma_f32 v[254:255], v[8:9], v[104:105], v[254:255]
	v_pk_fma_f32 v[160:161], v[10:11], v[106:107], v[160:161]
	v_pk_fma_f32 v[246:247], v[12:13], v[108:109], v[246:247]
	v_pk_fma_f32 v[254:255], v[14:15], v[110:111], v[254:255]
	v_pk_fma_f32 v[160:161], v[16:17], v[112:113], v[160:161]
	v_pk_fma_f32 v[246:247], v[18:19], v[114:115], v[246:247]
	v_pk_fma_f32 v[254:255], v[20:21], v[116:117], v[254:255]
	v_pk_fma_f32 v[160:161], v[22:23], v[118:119], v[160:161]
	v_pk_fma_f32 v[246:247], v[24:25], v[120:121], v[246:247]
	v_pk_fma_f32 v[254:255], v[26:27], v[122:123], v[254:255]
	v_pk_fma_f32 v[160:161], v[28:29], v[124:125], v[160:161]
	v_pk_fma_f32 v[246:247], v[30:31], v[126:127], v[246:247]
	v_pk_add_f32 v[254:255], v[254:255], v[160:161]
	v_readlane_b32 s54, v90, 46
	v_pk_add_f32 v[246:247], v[246:247], v[254:255]
	v_readlane_b32 s55, v90, 47
	v_add_f32_e32 v164, v246, v247
	s_mul_i32 s0, s54, 0x300
	s_mul_i32 s1, s55, 0x300
	v_add_u32_e32 v167, s0, v195
	s_and_saveexec_b64 s[98:99], s[40:41]
	v_add_u32_e32 v167, s1, v195
	s_mov_b64 exec, s[98:99]
	s_waitcnt vmcnt(14)
	v_cvt_scalef32_pk32_f32_fp6 v[0:31], v[240:245], 1.0
	global_load_dwordx2 v[244:245], v167, s[62:63] offset:16
	global_load_dwordx4 v[240:243], v167, s[62:63]
	v_pk_mul_f32 v[246:247], v[0:1], v[96:97]
	v_pk_mul_f32 v[254:255], v[2:3], v[98:99]
	v_pk_mul_f32 v[160:161], v[4:5], v[100:101]
	v_pk_fma_f32 v[246:247], v[6:7], v[102:103], v[246:247]
	v_pk_fma_f32 v[254:255], v[8:9], v[104:105], v[254:255]
	v_pk_fma_f32 v[160:161], v[10:11], v[106:107], v[160:161]
	v_pk_fma_f32 v[246:247], v[12:13], v[108:109], v[246:247]
	v_pk_fma_f32 v[254:255], v[14:15], v[110:111], v[254:255]
	v_pk_fma_f32 v[160:161], v[16:17], v[112:113], v[160:161]
	v_pk_fma_f32 v[246:247], v[18:19], v[114:115], v[246:247]
	v_pk_fma_f32 v[254:255], v[20:21], v[116:117], v[254:255]
	v_pk_fma_f32 v[160:161], v[22:23], v[118:119], v[160:161]
	v_pk_fma_f32 v[246:247], v[24:25], v[120:121], v[246:247]
	v_pk_fma_f32 v[254:255], v[26:27], v[122:123], v[254:255]
	v_pk_fma_f32 v[160:161], v[28:29], v[124:125], v[160:161]
	v_pk_fma_f32 v[246:247], v[30:31], v[126:127], v[246:247]
	v_pk_add_f32 v[254:255], v[254:255], v[160:161]
	s_nop 0
	v_pk_add_f32 v[246:247], v[246:247], v[254:255]
	s_nop 0
	v_add_f32_e32 v165, v246, v247
	v_add_f32_dpp v162, v162, v162 row_shr:1 row_mask:0xf bank_mask:0xf bound_ctrl:1
	v_add_f32_dpp v163, v163, v163 row_shr:1 row_mask:0xf bank_mask:0xf bound_ctrl:1
	v_add_f32_dpp v164, v164, v164 row_shr:1 row_mask:0xf bank_mask:0xf bound_ctrl:1
	v_add_f32_dpp v165, v165, v165 row_shr:1 row_mask:0xf bank_mask:0xf bound_ctrl:1
	v_add_f32_dpp v162, v162, v162 row_shr:2 row_mask:0xf bank_mask:0xf bound_ctrl:1
	v_add_f32_dpp v163, v163, v163 row_shr:2 row_mask:0xf bank_mask:0xf bound_ctrl:1
	v_add_f32_dpp v164, v164, v164 row_shr:2 row_mask:0xf bank_mask:0xf bound_ctrl:1
	v_add_f32_dpp v165, v165, v165 row_shr:2 row_mask:0xf bank_mask:0xf bound_ctrl:1
	v_add_f32_dpp v162, v162, v162 row_shr:4 row_mask:0xf bank_mask:0xf bound_ctrl:1
	v_add_f32_dpp v163, v163, v163 row_shr:4 row_mask:0xf bank_mask:0xf bound_ctrl:1
	v_add_f32_dpp v164, v164, v164 row_shr:4 row_mask:0xf bank_mask:0xf bound_ctrl:1
	v_add_f32_dpp v165, v165, v165 row_shr:4 row_mask:0xf bank_mask:0xf bound_ctrl:1
	v_add_f32_dpp v162, v162, v162 row_shr:8 row_mask:0xf bank_mask:0xf bound_ctrl:1
	v_add_f32_dpp v163, v163, v163 row_shr:8 row_mask:0xf bank_mask:0xf bound_ctrl:1
	v_add_f32_dpp v164, v164, v164 row_shr:8 row_mask:0xf bank_mask:0xf bound_ctrl:1
	v_add_f32_dpp v165, v165, v165 row_shr:8 row_mask:0xf bank_mask:0xf bound_ctrl:1
	v_add_f32_dpp v162, v162, v162 row_bcast:15 row_mask:0xa bank_mask:0xf
	v_add_f32_dpp v163, v163, v163 row_bcast:15 row_mask:0xa bank_mask:0xf
	v_add_f32_dpp v164, v164, v164 row_bcast:15 row_mask:0xa bank_mask:0xf
	v_add_f32_dpp v165, v165, v165 row_bcast:15 row_mask:0xa bank_mask:0xf
	s_nop 1
	v_readlane_b32 s46, v162, 31
	v_readlane_b32 s47, v162, 63
	v_readlane_b32 s48, v163, 31
	v_readlane_b32 s49, v163, 63
	v_readlane_b32 s50, v164, 31
	v_readlane_b32 s51, v164, 63
	v_readlane_b32 s52, v165, 31
	v_readlane_b32 s53, v165, 63
	v_writelane_b32 v166, s46, 24
	s_nop 1
	v_writelane_b32 v166, s47, 25
	v_writelane_b32 v166, s48, 26
	v_writelane_b32 v166, s49, 27
	v_writelane_b32 v166, s50, 28
	v_writelane_b32 v166, s51, 29
	v_writelane_b32 v166, s52, 30
	v_writelane_b32 v166, s53, 31
	v_readlane_b32 s54, v90, 48
	v_readlane_b32 s55, v90, 49
	s_mul_i32 s0, s54, 0x300
	s_mul_i32 s1, s55, 0x300
	v_add_u32_e32 v167, s0, v195
	s_and_saveexec_b64 s[98:99], s[40:41]
	v_add_u32_e32 v167, s1, v195
	s_mov_b64 exec, s[98:99]
	s_waitcnt vmcnt(14)
; __device__ void peer_gather_phase(const Params& P, int l, bool do_store) {
;     ...
;       for (int pr = 0; pr < 4; ++pr) {
;         const int ea = __builtin_amdgcn_readlane(evs, kb + 2 * pr), eb = __builtin_amdgcn_readlane(evs, kb + 2 * pr + 1);
;         const uint2* up = (const uint2*)(U + (size_t)(uphi ? eb : ea) * 768);
;         u6[3 * pr] = up[0]; u6[3 * pr + 1] = up[1]; u6[3 * pr + 2] = up[2];
;     ...
;         v6u_t qv; qv[0] = u6[3 * pr].x; qv[1] = u6[3 * pr].y; qv[2] = u6[3 * pr + 1].x; qv[3] = u6[3 * pr + 1].y; qv[4] = u6[3 * pr + 2].x; qv[5] = u6[3 * pr + 2].y;
;         const v32f_t wv = __builtin_amdgcn_cvt_scalef32_pk32_f32_fp6(qv, 1.0f);
;         f32x2 a2 = f32x2{0.f, 0.f};
; #pragma unroll
;         for (int i = 0; i < 16; ++i) a2 += f32x2{wv[2 * i], wv[2 * i + 1]} * xu[i];
;         float hs = a2.x + a2.y;
	v_cvt_scalef32_pk32_f32_fp6 v[0:31], v[50:55], 1.0
	global_load_dwordx2 v[54:55], v167, s[62:63] offset:16
	global_load_dwordx4 v[50:53], v167, s[62:63]
	v_pk_mul_f32 v[246:247], v[0:1], v[96:97]
	v_pk_mul_f32 v[254:255], v[2:3], v[98:99]
	v_pk_mul_f32 v[160:161], v[4:5], v[100:101]
	v_pk_fma_f32 v[246:247], v[6:7], v[102:103], v[246:247]
	v_pk_fma_f32 v[254:255], v[8:9], v[104:105], v[254:255]
	v_pk_fma_f32 v[160:161], v[10:11], v[106:107], v[160:161]
	v_pk_fma_f32 v[246:247], v[12:13], v[108:109], v[246:247]
	v_pk_fma_f32 v[254:255], v[14:15], v[110:111], v[254:255]
	v_pk_fma_f32 v[160:161], v[16:17], v[112:113], v[160:161]
	v_pk_fma_f32 v[246:247], v[18:19], v[114:115], v[246:247]
	v_pk_fma_f32 v[254:255], v[20:21], v[116:117], v[254:255]
	v_pk_fma_f32 v[160:161], v[22:23], v[118:119], v[160:161]
	v_pk_fma_f32 v[246:247], v[24:25], v[120:121], v[246:247]
	v_pk_fma_f32 v[254:255], v[26:27], v[122:123], v[254:255]
	v_pk_fma_f32 v[160:161], v[28:29], v[124:125], v[160:161]
	v_pk_fma_f32 v[246:247], v[30:31], v[126:127], v[246:247]
	v_pk_add_f32 v[254:255], v[254:255], v[160:161]
	v_readlane_b32 s54, v90, 50
	v_pk_add_f32 v[246:247], v[246:247], v[254:255]
	v_readlane_b32 s55, v90, 51
	v_add_f32_e32 v162, v246, v247
	s_mul_i32 s0, s54, 0x300
	s_mul_i32 s1, s55, 0x300
	v_add_u32_e32 v167, s0, v195
	s_and_saveexec_b64 s[98:99], s[40:41]
	v_add_u32_e32 v167, s1, v195
	s_mov_b64 exec, s[98:99]
	s_waitcnt vmcnt(14)
	v_cvt_scalef32_pk32_f32_fp6 v[0:31], v[44:49], 1.0
	global_load_dwordx2 v[48:49], v167, s[62:63] offset:16
	global_load_dwordx4 v[44:47], v167, s[62:63]
	v_pk_mul_f32 v[246:247], v[0:1], v[96:97]
	v_pk_mul_f32 v[254:255], v[2:3], v[98:99]
	v_pk_mul_f32 v[160:161], v[4:5], v[100:101]
	v_pk_fma_f32 v[246:247], v[6:7], v[102:103], v[246:247]
	v_pk_fma_f32 v[254:255], v[8:9], v[104:105], v[254:255]
	v_pk_fma_f32 v[160:161], v[10:11], v[106:107], v[160:161]
	v_pk_fma_f32 v[246:247], v[12:13], v[108:109], v[246:247]
	v_pk_fma_f32 v[254:255], v[14:15], v[110:111], v[254:255]
	v_pk_fma_f32 v[160:161], v[16:17], v[112:113], v[160:161]
	v_pk_fma_f32 v[246:247], v[18:19], v[114:115], v[246:247]
	v_pk_fma_f32 v[254:255], v[20:21], v[116:117], v[254:255]
	v_pk_fma_f32 v[160:161], v[22:23], v[118:119], v[160:161]
	v_pk_fma_f32 v[246:247], v[24:25], v[120:121], v[246:247]
	v_pk_fma_f32 v[254:255], v[26:27], v[122:123], v[254:255]
	v_pk_fma_f32 v[160:161], v[28:29], v[124:125], v[160:161]
	v_pk_fma_f32 v[246:247], v[30:31], v[126:127], v[246:247]
	v_pk_add_f32 v[254:255], v[254:255], v[160:161]
	v_readlane_b32 s54, v90, 52
	v_pk_add_f32 v[246:247], v[246:247], v[254:255]
	v_readlane_b32 s55, v90, 53
	v_add_f32_e32 v163, v246, v247
	s_mul_i32 s0, s54, 0x300
	s_mul_i32 s1, s55, 0x300
	v_add_u32_e32 v167, s0, v195
	s_and_saveexec_b64 s[98:99], s[40:41]
	v_add_u32_e32 v167, s1, v195
	s_mov_b64 exec, s[98:99]
	s_waitcnt vmcnt(14)
	v_cvt_scalef32_pk32_f32_fp6 v[0:31], v[38:43], 1.0
	global_load_dwordx2 v[42:43], v167, s[62:63] offset:16
	global_load_dwordx4 v[38:41], v167, s[62:63]
	v_pk_mul_f32 v[246:247], v[0:1], v[96:97]
	v_pk_mul_f32 v[254:255], v[2:3], v[98:99]
	v_pk_mul_f32 v[160:161], v[4:5], v[100:101]
	v_pk_fma_f32 v[246:247], v[6:7], v[102:103], v[246:247]
	v_pk_fma_f32 v[254:255], v[8:9], v[104:105], v[254:255]
	v_pk_fma_f32 v[160:161], v[10:11], v[106:107], v[160:161]
	v_pk_fma_f32 v[246:247], v[12:13], v[108:109], v[246:247]
	v_pk_fma_f32 v[254:255], v[14:15], v[110:111], v[254:255]
	v_pk_fma_f32 v[160:161], v[16:17], v[112:113], v[160:161]
	v_pk_fma_f32 v[246:247], v[18:19], v[114:115], v[246:247]
	v_pk_fma_f32 v[254:255], v[20:21], v[116:117], v[254:255]
	v_pk_fma_f32 v[160:161], v[22:23], v[118:119], v[160:161]
	v_pk_fma_f32 v[246:247], v[24:25], v[120:121], v[246:247]
	v_pk_fma_f32 v[254:255], v[26:27], v[122:123], v[254:255]
	v_pk_fma_f32 v[160:161], v[28:29], v[124:125], v[160:161]
	v_pk_fma_f32 v[246:247], v[30:31], v[126:127], v[246:247]
	v_pk_add_f32 v[254:255], v[254:255], v[160:161]
	v_readlane_b32 s54, v90, 54
	v_pk_add_f32 v[246:247], v[246:247], v[254:255]
	v_readlane_b32 s55, v90, 55
	v_add_f32_e32 v164, v246, v247
	s_mul_i32 s0, s54, 0x300
	s_mul_i32 s1, s55, 0x300
	v_add_u32_e32 v167, s0, v195
	s_and_saveexec_b64 s[98:99], s[40:41]
	v_add_u32_e32 v167, s1, v195
	s_mov_b64 exec, s[98:99]
	s_waitcnt vmcnt(14)
; __device__ void peer_gather_phase(const Params& P, int l, bool do_store) {
;     ...
;         v6u_t qv; qv[0] = u6[3 * pr].x; qv[1] = u6[3 * pr].y; qv[2] = u6[3 * pr + 1].x; qv[3] = u6[3 * pr + 1].y; qv[4] = u6[3 * pr + 2].x; qv[5] = u6[3 * pr + 2].y;
;         const v32f_t wv = __builtin_amdgcn_cvt_scalef32_pk32_f32_fp6(qv, 1.0f);
;         f32x2 a2 = f32x2{0.f, 0.f};
; #pragma unroll
;         for (int i = 0; i < 16; ++i) a2 += f32x2{wv[2 * i], wv[2 * i + 1]} * xu[i];
;         float hs = a2.x + a2.y;
;         hs += dpp_row_shr(hs, 1); hs += dpp_row_shr(hs, 2); hs += dpp_row_shr(hs, 4); hs += dpp_row_shr(hs, 8);
;         hs += __builtin_bit_cast(float, __builtin_amdgcn_update_dpp(0, __builtin_bit_cast(int, hs), 0x142, 0xa, 0xf, false));
;         const float da = __builtin_bit_cast(float, __builtin_amdgcn_readlane(__builtin_bit_cast(int, hs), 31));
;         const float db = __builtin_bit_cast(float, __builtin_amdgcn_readlane(__builtin_bit_cast(int, hs), 63));
;         dvec = (lane == kb + 2 * pr) ? da : dvec;
;         dvec = (lane == kb + 2 * pr + 1) ? db : dvec;
;       }
	v_cvt_scalef32_pk32_f32_fp6 v[0:31], v[32:37], 1.0
	global_load_dwordx2 v[36:37], v167, s[62:63] offset:16
	global_load_dwordx4 v[32:35], v167, s[62:63]
	v_pk_mul_f32 v[246:247], v[0:1], v[96:97]
	v_pk_mul_f32 v[254:255], v[2:3], v[98:99]
	v_pk_mul_f32 v[160:161], v[4:5], v[100:101]
	v_pk_fma_f32 v[246:247], v[6:7], v[102:103], v[246:247]
	v_pk_fma_f32 v[254:255], v[8:9], v[104:105], v[254:255]
	v_pk_fma_f32 v[160:161], v[10:11], v[106:107], v[160:161]
	v_pk_fma_f32 v[246:247], v[12:13], v[108:109], v[246:247]
	v_pk_fma_f32 v[254:255], v[14:15], v[110:111], v[254:255]
	v_pk_fma_f32 v[160:161], v[16:17], v[112:113], v[160:161]
	v_pk_fma_f32 v[246:247], v[18:19], v[114:115], v[246:247]
	v_pk_fma_f32 v[254:255], v[20:21], v[116:117], v[254:255]
	v_pk_fma_f32 v[160:161], v[22:23], v[118:119], v[160:161]
	v_pk_fma_f32 v[246:247], v[24:25], v[120:121], v[246:247]
	v_pk_fma_f32 v[254:255], v[26:27], v[122:123], v[254:255]
	v_pk_fma_f32 v[160:161], v[28:29], v[124:125], v[160:161]
	v_pk_fma_f32 v[246:247], v[30:31], v[126:127], v[246:247]
	v_pk_add_f32 v[254:255], v[254:255], v[160:161]
	s_nop 0
	v_pk_add_f32 v[246:247], v[246:247], v[254:255]
	s_nop 0
	v_add_f32_e32 v165, v246, v247
	v_add_f32_dpp v162, v162, v162 row_shr:1 row_mask:0xf bank_mask:0xf bound_ctrl:1
	v_add_f32_dpp v163, v163, v163 row_shr:1 row_mask:0xf bank_mask:0xf bound_ctrl:1
	v_add_f32_dpp v164, v164, v164 row_shr:1 row_mask:0xf bank_mask:0xf bound_ctrl:1
	v_add_f32_dpp v165, v165, v165 row_shr:1 row_mask:0xf bank_mask:0xf bound_ctrl:1
	v_add_f32_dpp v162, v162, v162 row_shr:2 row_mask:0xf bank_mask:0xf bound_ctrl:1
	v_add_f32_dpp v163, v163, v163 row_shr:2 row_mask:0xf bank_mask:0xf bound_ctrl:1
	v_add_f32_dpp v164, v164, v164 row_shr:2 row_mask:0xf bank_mask:0xf bound_ctrl:1
	v_add_f32_dpp v165, v165, v165 row_shr:2 row_mask:0xf bank_mask:0xf bound_ctrl:1
	v_add_f32_dpp v162, v162, v162 row_shr:4 row_mask:0xf bank_mask:0xf bound_ctrl:1
	v_add_f32_dpp v163, v163, v163 row_shr:4 row_mask:0xf bank_mask:0xf bound_ctrl:1
	v_add_f32_dpp v164, v164, v164 row_shr:4 row_mask:0xf bank_mask:0xf bound_ctrl:1
	v_add_f32_dpp v165, v165, v165 row_shr:4 row_mask:0xf bank_mask:0xf bound_ctrl:1
	v_add_f32_dpp v162, v162, v162 row_shr:8 row_mask:0xf bank_mask:0xf bound_ctrl:1
	v_add_f32_dpp v163, v163, v163 row_shr:8 row_mask:0xf bank_mask:0xf bound_ctrl:1
	v_add_f32_dpp v164, v164, v164 row_shr:8 row_mask:0xf bank_mask:0xf bound_ctrl:1
	v_add_f32_dpp v165, v165, v165 row_shr:8 row_mask:0xf bank_mask:0xf bound_ctrl:1
	v_add_f32_dpp v162, v162, v162 row_bcast:15 row_mask:0xa bank_mask:0xf
	v_add_f32_dpp v163, v163, v163 row_bcast:15 row_mask:0xa bank_mask:0xf
	v_add_f32_dpp v164, v164, v164 row_bcast:15 row_mask:0xa bank_mask:0xf
	v_add_f32_dpp v165, v165, v165 row_bcast:15 row_mask:0xa bank_mask:0xf
	s_nop 1
	v_readlane_b32 s46, v162, 31
	v_readlane_b32 s47, v162, 63
	v_readlane_b32 s48, v163, 31
	v_readlane_b32 s49, v163, 63
	v_readlane_b32 s50, v164, 31
	v_readlane_b32 s51, v164, 63
	v_readlane_b32 s52, v165, 31
	v_readlane_b32 s53, v165, 63
	v_writelane_b32 v166, s46, 32
	s_nop 1
	v_writelane_b32 v166, s47, 33
	v_writelane_b32 v166, s48, 34
	v_writelane_b32 v166, s49, 35
	v_writelane_b32 v166, s50, 36
	v_writelane_b32 v166, s51, 37
	v_writelane_b32 v166, s52, 38
	v_writelane_b32 v166, s53, 39
	v_readlane_b32 s54, v90, 56
	v_readlane_b32 s55, v90, 57
	s_mul_i32 s0, s54, 0x300
	s_mul_i32 s1, s55, 0x300
	v_add_u32_e32 v167, s0, v195
	s_and_saveexec_b64 s[98:99], s[40:41]
	v_add_u32_e32 v167, s1, v195
	s_mov_b64 exec, s[98:99]
	s_waitcnt vmcnt(14)
	v_cvt_scalef32_pk32_f32_fp6 v[0:31], v[196:201], 1.0
	global_load_dwordx2 v[200:201], v167, s[62:63] offset:16
	global_load_dwordx4 v[196:199], v167, s[62:63]
	v_pk_mul_f32 v[246:247], v[0:1], v[96:97]
	v_pk_mul_f32 v[254:255], v[2:3], v[98:99]
	v_pk_mul_f32 v[160:161], v[4:5], v[100:101]
	v_pk_fma_f32 v[246:247], v[6:7], v[102:103], v[246:247]
	v_pk_fma_f32 v[254:255], v[8:9], v[104:105], v[254:255]
	v_pk_fma_f32 v[160:161], v[10:11], v[106:107], v[160:161]
	v_pk_fma_f32 v[246:247], v[12:13], v[108:109], v[246:247]
	v_pk_fma_f32 v[254:255], v[14:15], v[110:111], v[254:255]
	v_pk_fma_f32 v[160:161], v[16:17], v[112:113], v[160:161]
	v_pk_fma_f32 v[246:247], v[18:19], v[114:115], v[246:247]
	v_pk_fma_f32 v[254:255], v[20:21], v[116:117], v[254:255]
	v_pk_fma_f32 v[160:161], v[22:23], v[118:119], v[160:161]
	v_pk_fma_f32 v[246:247], v[24:25], v[120:121], v[246:247]
	v_pk_fma_f32 v[254:255], v[26:27], v[122:123], v[254:255]
	v_pk_fma_f32 v[160:161], v[28:29], v[124:125], v[160:161]
	v_pk_fma_f32 v[246:247], v[30:31], v[126:127], v[246:247]
	v_pk_add_f32 v[254:255], v[254:255], v[160:161]
	v_readlane_b32 s54, v90, 58
	v_pk_add_f32 v[246:247], v[246:247], v[254:255]
	v_readlane_b32 s55, v90, 59
	v_add_f32_e32 v162, v246, v247
	s_mul_i32 s0, s54, 0x300
	s_mul_i32 s1, s55, 0x300
	v_add_u32_e32 v167, s0, v195
	s_and_saveexec_b64 s[98:99], s[40:41]
	v_add_u32_e32 v167, s1, v195
	s_mov_b64 exec, s[98:99]
	s_waitcnt vmcnt(14)
; __device__ void peer_gather_phase(const Params& P, int l, bool do_store) {
;     ...
;         v6u_t qv; qv[0] = u6[3 * pr].x; qv[1] = u6[3 * pr].y; qv[2] = u6[3 * pr + 1].x; qv[3] = u6[3 * pr + 1].y; qv[4] = u6[3 * pr + 2].x; qv[5] = u6[3 * pr + 2].y;
;         const v32f_t wv = __builtin_amdgcn_cvt_scalef32_pk32_f32_fp6(qv, 1.0f);
;         f32x2 a2 = f32x2{0.f, 0.f};
; #pragma unroll
;         for (int i = 0; i < 16; ++i) a2 += f32x2{wv[2 * i], wv[2 * i + 1]} * xu[i];
;         float hs = a2.x + a2.y;
;         hs += dpp_row_shr(hs, 1); hs += dpp_row_shr(hs, 2); hs += dpp_row_shr(hs, 4); hs += dpp_row_shr(hs, 8);
;         hs += __builtin_bit_cast(float, __builtin_amdgcn_update_dpp(0, __builtin_bit_cast(int, hs), 0x142, 0xa, 0xf, false));
;         const float da = __builtin_bit_cast(float, __builtin_amdgcn_readlane(__builtin_bit_cast(int, hs), 31));
;         const float db = __builtin_bit_cast(float, __builtin_amdgcn_readlane(__builtin_bit_cast(int, hs), 63));
;         dvec = (lane == kb + 2 * pr) ? da : dvec;
;         dvec = (lane == kb + 2 * pr + 1) ? db : dvec;
;       }
	v_cvt_scalef32_pk32_f32_fp6 v[0:31], v[228:233], 1.0
	global_load_dwordx2 v[232:233], v167, s[62:63] offset:16
	global_load_dwordx4 v[228:231], v167, s[62:63]
	v_pk_mul_f32 v[246:247], v[0:1], v[96:97]
	v_pk_mul_f32 v[254:255], v[2:3], v[98:99]
	v_pk_mul_f32 v[160:161], v[4:5], v[100:101]
	v_pk_fma_f32 v[246:247], v[6:7], v[102:103], v[246:247]
	v_pk_fma_f32 v[254:255], v[8:9], v[104:105], v[254:255]
	v_pk_fma_f32 v[160:161], v[10:11], v[106:107], v[160:161]
	v_pk_fma_f32 v[246:247], v[12:13], v[108:109], v[246:247]
	v_pk_fma_f32 v[254:255], v[14:15], v[110:111], v[254:255]
	v_pk_fma_f32 v[160:161], v[16:17], v[112:113], v[160:161]
	v_pk_fma_f32 v[246:247], v[18:19], v[114:115], v[246:247]
	v_pk_fma_f32 v[254:255], v[20:21], v[116:117], v[254:255]
	v_pk_fma_f32 v[160:161], v[22:23], v[118:119], v[160:161]
	v_pk_fma_f32 v[246:247], v[24:25], v[120:121], v[246:247]
	v_pk_fma_f32 v[254:255], v[26:27], v[122:123], v[254:255]
	v_pk_fma_f32 v[160:161], v[28:29], v[124:125], v[160:161]
	v_pk_fma_f32 v[246:247], v[30:31], v[126:127], v[246:247]
	v_pk_add_f32 v[254:255], v[254:255], v[160:161]
	v_readlane_b32 s54, v90, 60
	v_pk_add_f32 v[246:247], v[246:247], v[254:255]
	v_readlane_b32 s55, v90, 61
	v_add_f32_e32 v163, v246, v247
	s_mul_i32 s0, s54, 0x300
	s_mul_i32 s1, s55, 0x300
	v_add_u32_e32 v167, s0, v195
	s_and_saveexec_b64 s[98:99], s[40:41]
	v_add_u32_e32 v167, s1, v195
	s_mov_b64 exec, s[98:99]
	s_waitcnt vmcnt(14)
	v_cvt_scalef32_pk32_f32_fp6 v[0:31], v[234:239], 1.0
	global_load_dwordx2 v[238:239], v167, s[62:63] offset:16
	global_load_dwordx4 v[234:237], v167, s[62:63]
	v_pk_mul_f32 v[246:247], v[0:1], v[96:97]
	v_pk_mul_f32 v[254:255], v[2:3], v[98:99]
	v_pk_mul_f32 v[160:161], v[4:5], v[100:101]
	v_pk_fma_f32 v[246:247], v[6:7], v[102:103], v[246:247]
	v_pk_fma_f32 v[254:255], v[8:9], v[104:105], v[254:255]
	v_pk_fma_f32 v[160:161], v[10:11], v[106:107], v[160:161]
	v_pk_fma_f32 v[246:247], v[12:13], v[108:109], v[246:247]
	v_pk_fma_f32 v[254:255], v[14:15], v[110:111], v[254:255]
	v_pk_fma_f32 v[160:161], v[16:17], v[112:113], v[160:161]
	v_pk_fma_f32 v[246:247], v[18:19], v[114:115], v[246:247]
	v_pk_fma_f32 v[254:255], v[20:21], v[116:117], v[254:255]
	v_pk_fma_f32 v[160:161], v[22:23], v[118:119], v[160:161]
	v_pk_fma_f32 v[246:247], v[24:25], v[120:121], v[246:247]
	v_pk_fma_f32 v[254:255], v[26:27], v[122:123], v[254:255]
	v_pk_fma_f32 v[160:161], v[28:29], v[124:125], v[160:161]
	v_pk_fma_f32 v[246:247], v[30:31], v[126:127], v[246:247]
	v_pk_add_f32 v[254:255], v[254:255], v[160:161]
	v_readlane_b32 s54, v90, 62
	v_pk_add_f32 v[246:247], v[246:247], v[254:255]
	v_readlane_b32 s55, v90, 63
	v_add_f32_e32 v164, v246, v247
	s_mul_i32 s0, s54, 0x300
	s_mul_i32 s1, s55, 0x300
	v_add_u32_e32 v167, s0, v195
	s_and_saveexec_b64 s[98:99], s[40:41]
	v_add_u32_e32 v167, s1, v195
	s_mov_b64 exec, s[98:99]
	s_waitcnt vmcnt(14)
	v_cvt_scalef32_pk32_f32_fp6 v[0:31], v[240:245], 1.0
	global_load_dwordx2 v[244:245], v167, s[62:63] offset:16
	global_load_dwordx4 v[240:243], v167, s[62:63]
	v_pk_mul_f32 v[246:247], v[0:1], v[96:97]
	v_pk_mul_f32 v[254:255], v[2:3], v[98:99]
	v_pk_mul_f32 v[160:161], v[4:5], v[100:101]
	v_pk_fma_f32 v[246:247], v[6:7], v[102:103], v[246:247]
	v_pk_fma_f32 v[254:255], v[8:9], v[104:105], v[254:255]
	v_pk_fma_f32 v[160:161], v[10:11], v[106:107], v[160:161]
	v_pk_fma_f32 v[246:247], v[12:13], v[108:109], v[246:247]
	v_pk_fma_f32 v[254:255], v[14:15], v[110:111], v[254:255]
	v_pk_fma_f32 v[160:161], v[16:17], v[112:113], v[160:161]
	v_pk_fma_f32 v[246:247], v[18:19], v[114:115], v[246:247]
	v_pk_fma_f32 v[254:255], v[20:21], v[116:117], v[254:255]
	v_pk_fma_f32 v[160:161], v[22:23], v[118:119], v[160:161]
	v_pk_fma_f32 v[246:247], v[24:25], v[120:121], v[246:247]
	v_pk_fma_f32 v[254:255], v[26:27], v[122:123], v[254:255]
	v_pk_fma_f32 v[160:161], v[28:29], v[124:125], v[160:161]
	v_pk_fma_f32 v[246:247], v[30:31], v[126:127], v[246:247]
	v_pk_add_f32 v[254:255], v[254:255], v[160:161]
	s_nop 0
	v_pk_add_f32 v[246:247], v[246:247], v[254:255]
	s_nop 0
	v_add_f32_e32 v165, v246, v247
	v_add_f32_dpp v162, v162, v162 row_shr:1 row_mask:0xf bank_mask:0xf bound_ctrl:1
	v_add_f32_dpp v163, v163, v163 row_shr:1 row_mask:0xf bank_mask:0xf bound_ctrl:1
	v_add_f32_dpp v164, v164, v164 row_shr:1 row_mask:0xf bank_mask:0xf bound_ctrl:1
	v_add_f32_dpp v165, v165, v165 row_shr:1 row_mask:0xf bank_mask:0xf bound_ctrl:1
	v_add_f32_dpp v162, v162, v162 row_shr:2 row_mask:0xf bank_mask:0xf bound_ctrl:1
	v_add_f32_dpp v163, v163, v163 row_shr:2 row_mask:0xf bank_mask:0xf bound_ctrl:1
	v_add_f32_dpp v164, v164, v164 row_shr:2 row_mask:0xf bank_mask:0xf bound_ctrl:1
	v_add_f32_dpp v165, v165, v165 row_shr:2 row_mask:0xf bank_mask:0xf bound_ctrl:1
	v_add_f32_dpp v162, v162, v162 row_shr:4 row_mask:0xf bank_mask:0xf bound_ctrl:1
	v_add_f32_dpp v163, v163, v163 row_shr:4 row_mask:0xf bank_mask:0xf bound_ctrl:1
	v_add_f32_dpp v164, v164, v164 row_shr:4 row_mask:0xf bank_mask:0xf bound_ctrl:1
	v_add_f32_dpp v165, v165, v165 row_shr:4 row_mask:0xf bank_mask:0xf bound_ctrl:1
	v_add_f32_dpp v162, v162, v162 row_shr:8 row_mask:0xf bank_mask:0xf bound_ctrl:1
	v_add_f32_dpp v163, v163, v163 row_shr:8 row_mask:0xf bank_mask:0xf bound_ctrl:1
	v_add_f32_dpp v164, v164, v164 row_shr:8 row_mask:0xf bank_mask:0xf bound_ctrl:1
	v_add_f32_dpp v165, v165, v165 row_shr:8 row_mask:0xf bank_mask:0xf bound_ctrl:1
	v_add_f32_dpp v162, v162, v162 row_bcast:15 row_mask:0xa bank_mask:0xf
	v_add_f32_dpp v163, v163, v163 row_bcast:15 row_mask:0xa bank_mask:0xf
	v_add_f32_dpp v164, v164, v164 row_bcast:15 row_mask:0xa bank_mask:0xf
	v_add_f32_dpp v165, v165, v165 row_bcast:15 row_mask:0xa bank_mask:0xf
	s_nop 1
	v_readlane_b32 s46, v162, 31
	v_readlane_b32 s47, v162, 63
	v_readlane_b32 s48, v163, 31
	v_readlane_b32 s49, v163, 63
	v_readlane_b32 s50, v164, 31
	v_readlane_b32 s51, v164, 63
	v_readlane_b32 s52, v165, 31
	v_readlane_b32 s53, v165, 63
	v_writelane_b32 v166, s46, 40
	s_nop 1
	v_writelane_b32 v166, s47, 41
	v_writelane_b32 v166, s48, 42
	v_writelane_b32 v166, s49, 43
	v_writelane_b32 v166, s50, 44
	v_writelane_b32 v166, s51, 45
	v_writelane_b32 v166, s52, 46
	v_writelane_b32 v166, s53, 47
	s_waitcnt vmcnt(14)
; __device__ void peer_gather_phase(const Params& P, int l, bool do_store) {
;     ...
;         v6u_t qv; qv[0] = u6[3 * pr].x; qv[1] = u6[3 * pr].y; qv[2] = u6[3 * pr + 1].x; qv[3] = u6[3 * pr + 1].y; qv[4] = u6[3 * pr + 2].x; qv[5] = u6[3 * pr + 2].y;
;         const v32f_t wv = __builtin_amdgcn_cvt_scalef32_pk32_f32_fp6(qv, 1.0f);
;         f32x2 a2 = f32x2{0.f, 0.f};
; #pragma unroll
;         for (int i = 0; i < 16; ++i) a2 += f32x2{wv[2 * i], wv[2 * i + 1]} * xu[i];
;         float hs = a2.x + a2.y;
;         hs += dpp_row_shr(hs, 1); hs += dpp_row_shr(hs, 2); hs += dpp_row_shr(hs, 4); hs += dpp_row_shr(hs, 8);
;         hs += __builtin_bit_cast(float, __builtin_amdgcn_update_dpp(0, __builtin_bit_cast(int, hs), 0x142, 0xa, 0xf, false));
;         const float da = __builtin_bit_cast(float, __builtin_amdgcn_readlane(__builtin_bit_cast(int, hs), 31));
;         const float db = __builtin_bit_cast(float, __builtin_amdgcn_readlane(__builtin_bit_cast(int, hs), 63));
;         dvec = (lane == kb + 2 * pr) ? da : dvec;
;         dvec = (lane == kb + 2 * pr + 1) ? db : dvec;
;       }
	v_cvt_scalef32_pk32_f32_fp6 v[0:31], v[50:55], 1.0
	v_pk_mul_f32 v[246:247], v[0:1], v[96:97]
	v_pk_mul_f32 v[254:255], v[2:3], v[98:99]
	v_pk_mul_f32 v[160:161], v[4:5], v[100:101]
	v_pk_fma_f32 v[246:247], v[6:7], v[102:103], v[246:247]
	v_pk_fma_f32 v[254:255], v[8:9], v[104:105], v[254:255]
	v_pk_fma_f32 v[160:161], v[10:11], v[106:107], v[160:161]
	v_pk_fma_f32 v[246:247], v[12:13], v[108:109], v[246:247]
	v_pk_fma_f32 v[254:255], v[14:15], v[110:111], v[254:255]
	v_pk_fma_f32 v[160:161], v[16:17], v[112:113], v[160:161]
	v_pk_fma_f32 v[246:247], v[18:19], v[114:115], v[246:247]
	v_pk_fma_f32 v[254:255], v[20:21], v[116:117], v[254:255]
	v_pk_fma_f32 v[160:161], v[22:23], v[118:119], v[160:161]
	v_pk_fma_f32 v[246:247], v[24:25], v[120:121], v[246:247]
	v_pk_fma_f32 v[254:255], v[26:27], v[122:123], v[254:255]
	v_pk_fma_f32 v[160:161], v[28:29], v[124:125], v[160:161]
	v_pk_fma_f32 v[246:247], v[30:31], v[126:127], v[246:247]
	v_pk_add_f32 v[254:255], v[254:255], v[160:161]
	s_nop 0
	v_pk_add_f32 v[246:247], v[246:247], v[254:255]
	s_nop 0
	v_add_f32_e32 v162, v246, v247
	s_waitcnt vmcnt(12)
	v_cvt_scalef32_pk32_f32_fp6 v[0:31], v[44:49], 1.0
	v_pk_mul_f32 v[246:247], v[0:1], v[96:97]
	v_pk_mul_f32 v[254:255], v[2:3], v[98:99]
	v_pk_mul_f32 v[160:161], v[4:5], v[100:101]
	v_pk_fma_f32 v[246:247], v[6:7], v[102:103], v[246:247]
	v_pk_fma_f32 v[254:255], v[8:9], v[104:105], v[254:255]
	v_pk_fma_f32 v[160:161], v[10:11], v[106:107], v[160:161]
	v_pk_fma_f32 v[246:247], v[12:13], v[108:109], v[246:247]
	v_pk_fma_f32 v[254:255], v[14:15], v[110:111], v[254:255]
	v_pk_fma_f32 v[160:161], v[16:17], v[112:113], v[160:161]
	v_pk_fma_f32 v[246:247], v[18:19], v[114:115], v[246:247]
	v_pk_fma_f32 v[254:255], v[20:21], v[116:117], v[254:255]
	v_pk_fma_f32 v[160:161], v[22:23], v[118:119], v[160:161]
	v_pk_fma_f32 v[246:247], v[24:25], v[120:121], v[246:247]
	v_pk_fma_f32 v[254:255], v[26:27], v[122:123], v[254:255]
	v_pk_fma_f32 v[160:161], v[28:29], v[124:125], v[160:161]
	v_pk_fma_f32 v[246:247], v[30:31], v[126:127], v[246:247]
	v_pk_add_f32 v[254:255], v[254:255], v[160:161]
	s_nop 0
	v_pk_add_f32 v[246:247], v[246:247], v[254:255]
	s_nop 0
	v_add_f32_e32 v163, v246, v247
	s_waitcnt vmcnt(10)
	v_cvt_scalef32_pk32_f32_fp6 v[0:31], v[38:43], 1.0
	v_pk_mul_f32 v[246:247], v[0:1], v[96:97]
	v_pk_mul_f32 v[254:255], v[2:3], v[98:99]
	v_pk_mul_f32 v[160:161], v[4:5], v[100:101]
	v_pk_fma_f32 v[246:247], v[6:7], v[102:103], v[246:247]
	v_pk_fma_f32 v[254:255], v[8:9], v[104:105], v[254:255]
	v_pk_fma_f32 v[160:161], v[10:11], v[106:107], v[160:161]
	v_pk_fma_f32 v[246:247], v[12:13], v[108:109], v[246:247]
	v_pk_fma_f32 v[254:255], v[14:15], v[110:111], v[254:255]
	v_pk_fma_f32 v[160:161], v[16:17], v[112:113], v[160:161]
	v_pk_fma_f32 v[246:247], v[18:19], v[114:115], v[246:247]
	v_pk_fma_f32 v[254:255], v[20:21], v[116:117], v[254:255]
	v_pk_fma_f32 v[160:161], v[22:23], v[118:119], v[160:161]
	v_pk_fma_f32 v[246:247], v[24:25], v[120:121], v[246:247]
	v_pk_fma_f32 v[254:255], v[26:27], v[122:123], v[254:255]
	v_pk_fma_f32 v[160:161], v[28:29], v[124:125], v[160:161]
	v_pk_fma_f32 v[246:247], v[30:31], v[126:127], v[246:247]
	v_pk_add_f32 v[254:255], v[254:255], v[160:161]
	s_nop 0
	v_pk_add_f32 v[246:247], v[246:247], v[254:255]
	s_nop 0
	v_add_f32_e32 v164, v246, v247
	s_waitcnt vmcnt(8)
	v_cvt_scalef32_pk32_f32_fp6 v[0:31], v[32:37], 1.0
	v_pk_mul_f32 v[246:247], v[0:1], v[96:97]
	v_pk_mul_f32 v[254:255], v[2:3], v[98:99]
	v_pk_mul_f32 v[160:161], v[4:5], v[100:101]
	v_pk_fma_f32 v[246:247], v[6:7], v[102:103], v[246:247]
	v_pk_fma_f32 v[254:255], v[8:9], v[104:105], v[254:255]
	v_pk_fma_f32 v[160:161], v[10:11], v[106:107], v[160:161]
	v_pk_fma_f32 v[246:247], v[12:13], v[108:109], v[246:247]
	v_pk_fma_f32 v[254:255], v[14:15], v[110:111], v[254:255]
	v_pk_fma_f32 v[160:161], v[16:17], v[112:113], v[160:161]
	v_pk_fma_f32 v[246:247], v[18:19], v[114:115], v[246:247]
	v_pk_fma_f32 v[254:255], v[20:21], v[116:117], v[254:255]
	v_pk_fma_f32 v[160:161], v[22:23], v[118:119], v[160:161]
	v_pk_fma_f32 v[246:247], v[24:25], v[120:121], v[246:247]
	v_pk_fma_f32 v[254:255], v[26:27], v[122:123], v[254:255]
	v_pk_fma_f32 v[160:161], v[28:29], v[124:125], v[160:161]
	v_pk_fma_f32 v[246:247], v[30:31], v[126:127], v[246:247]
	v_pk_add_f32 v[254:255], v[254:255], v[160:161]
	s_nop 0
	v_pk_add_f32 v[246:247], v[246:247], v[254:255]
	s_nop 0
	v_add_f32_e32 v165, v246, v247
	v_add_f32_dpp v162, v162, v162 row_shr:1 row_mask:0xf bank_mask:0xf bound_ctrl:1
	v_add_f32_dpp v163, v163, v163 row_shr:1 row_mask:0xf bank_mask:0xf bound_ctrl:1
	v_add_f32_dpp v164, v164, v164 row_shr:1 row_mask:0xf bank_mask:0xf bound_ctrl:1
	v_add_f32_dpp v165, v165, v165 row_shr:1 row_mask:0xf bank_mask:0xf bound_ctrl:1
	v_add_f32_dpp v162, v162, v162 row_shr:2 row_mask:0xf bank_mask:0xf bound_ctrl:1
	v_add_f32_dpp v163, v163, v163 row_shr:2 row_mask:0xf bank_mask:0xf bound_ctrl:1
	v_add_f32_dpp v164, v164, v164 row_shr:2 row_mask:0xf bank_mask:0xf bound_ctrl:1
	v_add_f32_dpp v165, v165, v165 row_shr:2 row_mask:0xf bank_mask:0xf bound_ctrl:1
	v_add_f32_dpp v162, v162, v162 row_shr:4 row_mask:0xf bank_mask:0xf bound_ctrl:1
	v_add_f32_dpp v163, v163, v163 row_shr:4 row_mask:0xf bank_mask:0xf bound_ctrl:1
	v_add_f32_dpp v164, v164, v164 row_shr:4 row_mask:0xf bank_mask:0xf bound_ctrl:1
	v_add_f32_dpp v165, v165, v165 row_shr:4 row_mask:0xf bank_mask:0xf bound_ctrl:1
	v_add_f32_dpp v162, v162, v162 row_shr:8 row_mask:0xf bank_mask:0xf bound_ctrl:1
	v_add_f32_dpp v163, v163, v163 row_shr:8 row_mask:0xf bank_mask:0xf bound_ctrl:1
	v_add_f32_dpp v164, v164, v164 row_shr:8 row_mask:0xf bank_mask:0xf bound_ctrl:1
	v_add_f32_dpp v165, v165, v165 row_shr:8 row_mask:0xf bank_mask:0xf bound_ctrl:1
	v_add_f32_dpp v162, v162, v162 row_bcast:15 row_mask:0xa bank_mask:0xf
	v_add_f32_dpp v163, v163, v163 row_bcast:15 row_mask:0xa bank_mask:0xf
	v_add_f32_dpp v164, v164, v164 row_bcast:15 row_mask:0xa bank_mask:0xf
	v_add_f32_dpp v165, v165, v165 row_bcast:15 row_mask:0xa bank_mask:0xf
	s_nop 1
	v_readlane_b32 s46, v162, 31
	v_readlane_b32 s47, v162, 63
	v_readlane_b32 s48, v163, 31
	v_readlane_b32 s49, v163, 63
	v_readlane_b32 s50, v164, 31
	v_readlane_b32 s51, v164, 63
	v_readlane_b32 s52, v165, 31
	v_readlane_b32 s53, v165, 63
	v_writelane_b32 v166, s46, 48
	s_nop 1
	v_writelane_b32 v166, s47, 49
	v_writelane_b32 v166, s48, 50
	v_writelane_b32 v166, s49, 51
	v_writelane_b32 v166, s50, 52
	v_writelane_b32 v166, s51, 53
	v_writelane_b32 v166, s52, 54
	v_writelane_b32 v166, s53, 55
	s_waitcnt vmcnt(6)
; __device__ void peer_gather_phase(const Params& P, int l, bool do_store) {
;     ...
;         v6u_t qv; qv[0] = u6[3 * pr].x; qv[1] = u6[3 * pr].y; qv[2] = u6[3 * pr + 1].x; qv[3] = u6[3 * pr + 1].y; qv[4] = u6[3 * pr + 2].x; qv[5] = u6[3 * pr + 2].y;
;         const v32f_t wv = __builtin_amdgcn_cvt_scalef32_pk32_f32_fp6(qv, 1.0f);
;         f32x2 a2 = f32x2{0.f, 0.f};
; #pragma unroll
;         for (int i = 0; i < 16; ++i) a2 += f32x2{wv[2 * i], wv[2 * i + 1]} * xu[i];
;         float hs = a2.x + a2.y;
;         hs += dpp_row_shr(hs, 1); hs += dpp_row_shr(hs, 2); hs += dpp_row_shr(hs, 4); hs += dpp_row_shr(hs, 8);
;         hs += __builtin_bit_cast(float, __builtin_amdgcn_update_dpp(0, __builtin_bit_cast(int, hs), 0x142, 0xa, 0xf, false));
;         const float da = __builtin_bit_cast(float, __builtin_amdgcn_readlane(__builtin_bit_cast(int, hs), 31));
	v_cvt_scalef32_pk32_f32_fp6 v[0:31], v[196:201], 1.0
	v_pk_mul_f32 v[246:247], v[0:1], v[96:97]
	v_pk_mul_f32 v[254:255], v[2:3], v[98:99]
	v_pk_mul_f32 v[160:161], v[4:5], v[100:101]
	v_pk_fma_f32 v[246:247], v[6:7], v[102:103], v[246:247]
	v_pk_fma_f32 v[254:255], v[8:9], v[104:105], v[254:255]
	v_pk_fma_f32 v[160:161], v[10:11], v[106:107], v[160:161]
	v_pk_fma_f32 v[246:247], v[12:13], v[108:109], v[246:247]
	v_pk_fma_f32 v[254:255], v[14:15], v[110:111], v[254:255]
	v_pk_fma_f32 v[160:161], v[16:17], v[112:113], v[160:161]
	v_pk_fma_f32 v[246:247], v[18:19], v[114:115], v[246:247]
	v_pk_fma_f32 v[254:255], v[20:21], v[116:117], v[254:255]
	v_pk_fma_f32 v[160:161], v[22:23], v[118:119], v[160:161]
	v_pk_fma_f32 v[246:247], v[24:25], v[120:121], v[246:247]
	v_pk_fma_f32 v[254:255], v[26:27], v[122:123], v[254:255]
	v_pk_fma_f32 v[160:161], v[28:29], v[124:125], v[160:161]
	v_pk_fma_f32 v[246:247], v[30:31], v[126:127], v[246:247]
	v_pk_add_f32 v[254:255], v[254:255], v[160:161]
	s_nop 0
	v_pk_add_f32 v[246:247], v[246:247], v[254:255]
	s_nop 0
	v_add_f32_e32 v162, v246, v247
	s_waitcnt vmcnt(4)
	v_cvt_scalef32_pk32_f32_fp6 v[0:31], v[228:233], 1.0
	v_pk_mul_f32 v[246:247], v[0:1], v[96:97]
	v_pk_mul_f32 v[254:255], v[2:3], v[98:99]
	v_pk_mul_f32 v[160:161], v[4:5], v[100:101]
	v_pk_fma_f32 v[246:247], v[6:7], v[102:103], v[246:247]
	v_pk_fma_f32 v[254:255], v[8:9], v[104:105], v[254:255]
	v_pk_fma_f32 v[160:161], v[10:11], v[106:107], v[160:161]
	v_pk_fma_f32 v[246:247], v[12:13], v[108:109], v[246:247]
	v_pk_fma_f32 v[254:255], v[14:15], v[110:111], v[254:255]
	v_pk_fma_f32 v[160:161], v[16:17], v[112:113], v[160:161]
	v_pk_fma_f32 v[246:247], v[18:19], v[114:115], v[246:247]
	v_pk_fma_f32 v[254:255], v[20:21], v[116:117], v[254:255]
	v_pk_fma_f32 v[160:161], v[22:23], v[118:119], v[160:161]
	v_pk_fma_f32 v[246:247], v[24:25], v[120:121], v[246:247]
	v_pk_fma_f32 v[254:255], v[26:27], v[122:123], v[254:255]
	v_pk_fma_f32 v[160:161], v[28:29], v[124:125], v[160:161]
	v_pk_fma_f32 v[246:247], v[30:31], v[126:127], v[246:247]
	v_pk_add_f32 v[254:255], v[254:255], v[160:161]
	s_nop 0
	v_pk_add_f32 v[246:247], v[246:247], v[254:255]
	s_nop 0
	v_add_f32_e32 v163, v246, v247
	s_waitcnt vmcnt(2)
	v_cvt_scalef32_pk32_f32_fp6 v[0:31], v[234:239], 1.0
	v_pk_mul_f32 v[246:247], v[0:1], v[96:97]
	v_pk_mul_f32 v[254:255], v[2:3], v[98:99]
	v_pk_mul_f32 v[160:161], v[4:5], v[100:101]
	v_pk_fma_f32 v[246:247], v[6:7], v[102:103], v[246:247]
	v_pk_fma_f32 v[254:255], v[8:9], v[104:105], v[254:255]
	v_pk_fma_f32 v[160:161], v[10:11], v[106:107], v[160:161]
	v_pk_fma_f32 v[246:247], v[12:13], v[108:109], v[246:247]
	v_pk_fma_f32 v[254:255], v[14:15], v[110:111], v[254:255]
	v_pk_fma_f32 v[160:161], v[16:17], v[112:113], v[160:161]
	v_pk_fma_f32 v[246:247], v[18:19], v[114:115], v[246:247]
	v_pk_fma_f32 v[254:255], v[20:21], v[116:117], v[254:255]
	v_pk_fma_f32 v[160:161], v[22:23], v[118:119], v[160:161]
	v_pk_fma_f32 v[246:247], v[24:25], v[120:121], v[246:247]
	v_pk_fma_f32 v[254:255], v[26:27], v[122:123], v[254:255]
	v_pk_fma_f32 v[160:161], v[28:29], v[124:125], v[160:161]
	v_pk_fma_f32 v[246:247], v[30:31], v[126:127], v[246:247]
	v_pk_add_f32 v[254:255], v[254:255], v[160:161]
	s_nop 0
	v_pk_add_f32 v[246:247], v[246:247], v[254:255]
	s_nop 0
	v_add_f32_e32 v164, v246, v247
	s_waitcnt vmcnt(0)
	v_cvt_scalef32_pk32_f32_fp6 v[0:31], v[240:245], 1.0
	v_pk_mul_f32 v[246:247], v[0:1], v[96:97]
	v_pk_mul_f32 v[254:255], v[2:3], v[98:99]
	v_pk_mul_f32 v[160:161], v[4:5], v[100:101]
	v_pk_fma_f32 v[246:247], v[6:7], v[102:103], v[246:247]
	v_pk_fma_f32 v[254:255], v[8:9], v[104:105], v[254:255]
	v_pk_fma_f32 v[160:161], v[10:11], v[106:107], v[160:161]
	v_pk_fma_f32 v[246:247], v[12:13], v[108:109], v[246:247]
	v_pk_fma_f32 v[254:255], v[14:15], v[110:111], v[254:255]
	v_pk_fma_f32 v[160:161], v[16:17], v[112:113], v[160:161]
	v_pk_fma_f32 v[246:247], v[18:19], v[114:115], v[246:247]
	v_pk_fma_f32 v[254:255], v[20:21], v[116:117], v[254:255]
	v_pk_fma_f32 v[160:161], v[22:23], v[118:119], v[160:161]
	v_pk_fma_f32 v[246:247], v[24:25], v[120:121], v[246:247]
	v_pk_fma_f32 v[254:255], v[26:27], v[122:123], v[254:255]
	v_pk_fma_f32 v[160:161], v[28:29], v[124:125], v[160:161]
	v_pk_fma_f32 v[246:247], v[30:31], v[126:127], v[246:247]
	v_pk_add_f32 v[254:255], v[254:255], v[160:161]
	s_nop 0
	v_pk_add_f32 v[246:247], v[246:247], v[254:255]
	s_nop 0
	v_add_f32_e32 v165, v246, v247
	v_add_f32_dpp v162, v162, v162 row_shr:1 row_mask:0xf bank_mask:0xf bound_ctrl:1
	v_add_f32_dpp v163, v163, v163 row_shr:1 row_mask:0xf bank_mask:0xf bound_ctrl:1
	v_add_f32_dpp v164, v164, v164 row_shr:1 row_mask:0xf bank_mask:0xf bound_ctrl:1
	v_add_f32_dpp v165, v165, v165 row_shr:1 row_mask:0xf bank_mask:0xf bound_ctrl:1
	v_add_f32_dpp v162, v162, v162 row_shr:2 row_mask:0xf bank_mask:0xf bound_ctrl:1
	v_add_f32_dpp v163, v163, v163 row_shr:2 row_mask:0xf bank_mask:0xf bound_ctrl:1
	v_add_f32_dpp v164, v164, v164 row_shr:2 row_mask:0xf bank_mask:0xf bound_ctrl:1
	v_add_f32_dpp v165, v165, v165 row_shr:2 row_mask:0xf bank_mask:0xf bound_ctrl:1
	v_add_f32_dpp v162, v162, v162 row_shr:4 row_mask:0xf bank_mask:0xf bound_ctrl:1
	v_add_f32_dpp v163, v163, v163 row_shr:4 row_mask:0xf bank_mask:0xf bound_ctrl:1
	v_add_f32_dpp v164, v164, v164 row_shr:4 row_mask:0xf bank_mask:0xf bound_ctrl:1
	v_add_f32_dpp v165, v165, v165 row_shr:4 row_mask:0xf bank_mask:0xf bound_ctrl:1
	v_add_f32_dpp v162, v162, v162 row_shr:8 row_mask:0xf bank_mask:0xf bound_ctrl:1
	v_add_f32_dpp v163, v163, v163 row_shr:8 row_mask:0xf bank_mask:0xf bound_ctrl:1
	v_add_f32_dpp v164, v164, v164 row_shr:8 row_mask:0xf bank_mask:0xf bound_ctrl:1
; DEV float gelu_t(float x) {
;   float z = 0.7978845608028654f * (x + 0.044715f * x * x * x);
;   float e = __expf(2.f * z);
;   float th = 1.f - 2.f / (e + 1.f);
;   return 0.5f * x * (1.f + th);
; }
; __device__ void peer_gather_phase(const Params& P, int l, bool do_store) {
;     ...
;         hs += dpp_row_shr(hs, 1); hs += dpp_row_shr(hs, 2); hs += dpp_row_shr(hs, 4); hs += dpp_row_shr(hs, 8);
;         hs += __builtin_bit_cast(float, __builtin_amdgcn_update_dpp(0, __builtin_bit_cast(int, hs), 0x142, 0xa, 0xf, false));
;         const float da = __builtin_bit_cast(float, __builtin_amdgcn_readlane(__builtin_bit_cast(int, hs), 31));
;         const float db = __builtin_bit_cast(float, __builtin_amdgcn_readlane(__builtin_bit_cast(int, hs), 63));
;         dvec = (lane == kb + 2 * pr) ? da : dvec;
;         dvec = (lane == kb + 2 * pr + 1) ? db : dvec;
;       }
;       const float sux = (bt < 8) ? sux0 : sux1;
;       const float gsx = (bt < 8) ? gsx0 : gsx1;
;       const float avec = gelu_t(dvec * sux) * gsx;
; #pragma unroll
;       for (int j = 0; j < 8; ++j) {
;         const float a = __builtin_bit_cast(float, __builtin_amdgcn_readlane(__builtin_bit_cast(int, avec), kb + j));
;         const f32x2 aa = f32x2{a, a};
;         y[0] += aa * __builtin_amdgcn_cvt_scalef32_pk_f32_fp4(v8[j].x, 1.0f, 0); y[1] += aa * __builtin_amdgcn_cvt_scalef32_pk_f32_fp4(v8[j].x, 1.0f, 1);
;         y[2] += aa * __builtin_amdgcn_cvt_scalef32_pk_f32_fp4(v8[j].x, 1.0f, 2); y[3] += aa * __builtin_amdgcn_cvt_scalef32_pk_f32_fp4(v8[j].x, 1.0f, 3);
;         y[4] += aa * __builtin_amdgcn_cvt_scalef32_pk_f32_fp4(v8[j].y, 1.0f, 0); y[5] += aa * __builtin_amdgcn_cvt_scalef32_pk_f32_fp4(v8[j].y, 1.0f, 1);
;         y[6] += aa * __builtin_amdgcn_cvt_scalef32_pk_f32_fp4(v8[j].y, 1.0f, 2); y[7] += aa * __builtin_amdgcn_cvt_scalef32_pk_f32_fp4(v8[j].y, 1.0f, 3);
;       }
	v_add_f32_dpp v165, v165, v165 row_shr:8 row_mask:0xf bank_mask:0xf bound_ctrl:1
	v_add_f32_dpp v162, v162, v162 row_bcast:15 row_mask:0xa bank_mask:0xf
	v_add_f32_dpp v163, v163, v163 row_bcast:15 row_mask:0xa bank_mask:0xf
	v_add_f32_dpp v164, v164, v164 row_bcast:15 row_mask:0xa bank_mask:0xf
	v_add_f32_dpp v165, v165, v165 row_bcast:15 row_mask:0xa bank_mask:0xf
	s_nop 1
	v_readlane_b32 s46, v162, 31
	v_readlane_b32 s47, v162, 63
	v_readlane_b32 s48, v163, 31
	v_readlane_b32 s49, v163, 63
	v_readlane_b32 s50, v164, 31
	v_readlane_b32 s51, v164, 63
	v_readlane_b32 s52, v165, 31
	v_readlane_b32 s53, v165, 63
	v_writelane_b32 v166, s46, 56
	s_nop 1
	v_writelane_b32 v166, s47, 57
	v_writelane_b32 v166, s48, 58
	v_writelane_b32 v166, s49, 59
	v_writelane_b32 v166, s50, 60
	v_writelane_b32 v166, s51, 61
	v_writelane_b32 v166, s52, 62
	v_writelane_b32 v166, s53, 63
	s_nop 1
	v_mul_f32_e32 v0, v190, v166
	v_mul_f32_e32 v1, 0x3d372713, v0
	v_mul_f32_e32 v1, v0, v1
	v_fma_f32 v1, v0, v1, v0
	v_mul_f32_e32 v1, 0x3f4c422a, v1
	v_add_f32_e32 v1, v1, v1
	v_mul_f32_e32 v1, 0x3fb8aa3b, v1
	v_exp_f32_e32 v1, v1
	v_mul_f32_e32 v0, 0.5, v0
	v_add_f32_e32 v1, 1.0, v1
	v_div_scale_f32 v2, s[0:1], v1, v1, 2.0
	v_rcp_f32_e32 v3, v2
	s_nop 0
	v_fma_f32 v4, -v2, v3, 1.0
	v_fmac_f32_e32 v3, v4, v3
	v_div_scale_f32 v4, vcc, 2.0, v1, 2.0
	v_mul_f32_e32 v5, v4, v3
	v_fma_f32 v6, -v2, v5, v4
	v_fmac_f32_e32 v5, v6, v3
	v_fma_f32 v2, -v2, v5, v4
	v_div_fmas_f32 v2, v2, v3, v5
	v_div_fixup_f32 v1, v2, v1, 2.0
	v_sub_f32_e32 v1, 1.0, v1
	v_add_f32_e32 v1, 1.0, v1
	v_mul_f32_e32 v0, v0, v1
	v_mul_f32_e32 v167, v192, v0
	s_nop 1
	v_readlane_b32 s0, v167, 0
	s_waitcnt vmcnt(48)
	v_cvt_scalef32_pk_f32_fp4 v[0:1], v144, 1.0
	v_cvt_scalef32_pk_f32_fp4 v[2:3], v144, 1.0 op_sel:[1,0,0]
	v_cvt_scalef32_pk_f32_fp4 v[4:5], v144, 1.0 op_sel:[0,1,0]
	v_cvt_scalef32_pk_f32_fp4 v[6:7], v144, 1.0 op_sel:[1,1,0]
	v_cvt_scalef32_pk_f32_fp4 v[8:9], v145, 1.0
	v_cvt_scalef32_pk_f32_fp4 v[10:11], v145, 1.0 op_sel:[1,0,0]
	v_cvt_scalef32_pk_f32_fp4 v[12:13], v145, 1.0 op_sel:[0,1,0]
	v_cvt_scalef32_pk_f32_fp4 v[14:15], v145, 1.0 op_sel:[1,1,0]
	v_readlane_b32 s54, v90, 16
	s_lshl_b32 s56, s54, 9
	s_add_u32 s56, s64, s56
	s_addc_u32 s57, s65, 0
	global_load_dwordx2 v[144:145], v227, s[56:57]
	v_pk_fma_f32 v[130:131], v[0:1], s[0:1], v[130:131] op_sel_hi:[1,0,1]
	v_pk_fma_f32 v[138:139], v[2:3], s[0:1], v[138:139] op_sel_hi:[1,0,1]
	v_pk_fma_f32 v[140:141], v[4:5], s[0:1], v[140:141] op_sel_hi:[1,0,1]
	v_pk_fma_f32 v[142:143], v[6:7], s[0:1], v[142:143] op_sel_hi:[1,0,1]
	v_pk_fma_f32 v[128:129], v[8:9], s[0:1], v[128:129] op_sel_hi:[1,0,1]
	v_pk_fma_f32 v[132:133], v[10:11], s[0:1], v[132:133] op_sel_hi:[1,0,1]
	v_pk_fma_f32 v[134:135], v[12:13], s[0:1], v[134:135] op_sel_hi:[1,0,1]
	v_pk_fma_f32 v[136:137], v[14:15], s[0:1], v[136:137] op_sel_hi:[1,0,1]
	v_readlane_b32 s0, v167, 1
	s_waitcnt vmcnt(48)
	v_cvt_scalef32_pk_f32_fp4 v[0:1], v146, 1.0
	v_cvt_scalef32_pk_f32_fp4 v[2:3], v146, 1.0 op_sel:[1,0,0]
	v_cvt_scalef32_pk_f32_fp4 v[4:5], v146, 1.0 op_sel:[0,1,0]
	v_cvt_scalef32_pk_f32_fp4 v[6:7], v146, 1.0 op_sel:[1,1,0]
	v_cvt_scalef32_pk_f32_fp4 v[8:9], v147, 1.0
	v_cvt_scalef32_pk_f32_fp4 v[10:11], v147, 1.0 op_sel:[1,0,0]
	v_cvt_scalef32_pk_f32_fp4 v[12:13], v147, 1.0 op_sel:[0,1,0]
	v_cvt_scalef32_pk_f32_fp4 v[14:15], v147, 1.0 op_sel:[1,1,0]
	v_readlane_b32 s54, v90, 17
	s_lshl_b32 s56, s54, 9
	s_add_u32 s56, s64, s56
	s_addc_u32 s57, s65, 0
	global_load_dwordx2 v[146:147], v227, s[56:57]
	v_pk_fma_f32 v[130:131], v[0:1], s[0:1], v[130:131] op_sel_hi:[1,0,1]
	v_pk_fma_f32 v[138:139], v[2:3], s[0:1], v[138:139] op_sel_hi:[1,0,1]
	v_pk_fma_f32 v[140:141], v[4:5], s[0:1], v[140:141] op_sel_hi:[1,0,1]
	v_pk_fma_f32 v[142:143], v[6:7], s[0:1], v[142:143] op_sel_hi:[1,0,1]
	v_pk_fma_f32 v[128:129], v[8:9], s[0:1], v[128:129] op_sel_hi:[1,0,1]
	v_pk_fma_f32 v[132:133], v[10:11], s[0:1], v[132:133] op_sel_hi:[1,0,1]
	v_pk_fma_f32 v[134:135], v[12:13], s[0:1], v[134:135] op_sel_hi:[1,0,1]
	v_pk_fma_f32 v[136:137], v[14:15], s[0:1], v[136:137] op_sel_hi:[1,0,1]
	v_readlane_b32 s0, v167, 2
	s_waitcnt vmcnt(48)
	v_cvt_scalef32_pk_f32_fp4 v[0:1], v148, 1.0
	v_cvt_scalef32_pk_f32_fp4 v[2:3], v148, 1.0 op_sel:[1,0,0]
	v_cvt_scalef32_pk_f32_fp4 v[4:5], v148, 1.0 op_sel:[0,1,0]
	v_cvt_scalef32_pk_f32_fp4 v[6:7], v148, 1.0 op_sel:[1,1,0]
	v_cvt_scalef32_pk_f32_fp4 v[8:9], v149, 1.0
	v_cvt_scalef32_pk_f32_fp4 v[10:11], v149, 1.0 op_sel:[1,0,0]
	v_cvt_scalef32_pk_f32_fp4 v[12:13], v149, 1.0 op_sel:[0,1,0]
	v_cvt_scalef32_pk_f32_fp4 v[14:15], v149, 1.0 op_sel:[1,1,0]
	v_readlane_b32 s54, v90, 18
	s_lshl_b32 s56, s54, 9
	s_add_u32 s56, s64, s56
	s_addc_u32 s57, s65, 0
	global_load_dwordx2 v[148:149], v227, s[56:57]
	v_pk_fma_f32 v[130:131], v[0:1], s[0:1], v[130:131] op_sel_hi:[1,0,1]
	v_pk_fma_f32 v[138:139], v[2:3], s[0:1], v[138:139] op_sel_hi:[1,0,1]
	v_pk_fma_f32 v[140:141], v[4:5], s[0:1], v[140:141] op_sel_hi:[1,0,1]
	v_pk_fma_f32 v[142:143], v[6:7], s[0:1], v[142:143] op_sel_hi:[1,0,1]
	v_pk_fma_f32 v[128:129], v[8:9], s[0:1], v[128:129] op_sel_hi:[1,0,1]
	v_pk_fma_f32 v[132:133], v[10:11], s[0:1], v[132:133] op_sel_hi:[1,0,1]
	v_pk_fma_f32 v[134:135], v[12:13], s[0:1], v[134:135] op_sel_hi:[1,0,1]
	v_pk_fma_f32 v[136:137], v[14:15], s[0:1], v[136:137] op_sel_hi:[1,0,1]
	v_readlane_b32 s0, v167, 3
	s_waitcnt vmcnt(48)
; __device__ void peer_gather_phase(const Params& P, int l, bool do_store) {
;     ...
;       for (int pr = 0; pr < 4; ++pr) {
;         const int ea = __builtin_amdgcn_readlane(evs, kb + 2 * pr), eb = __builtin_amdgcn_readlane(evs, kb + 2 * pr + 1);
;         const uint2* up = (const uint2*)(U + (size_t)(uphi ? eb : ea) * 768);
;         u6[3 * pr] = up[0]; u6[3 * pr + 1] = up[1]; u6[3 * pr + 2] = up[2];
;         v8[2 * pr] = *(const uint2*)(V + (size_t)ea * 512);
;         v8[2 * pr + 1] = *(const uint2*)(V + (size_t)eb * 512);
;     ...
; #pragma unroll
;       for (int j = 0; j < 8; ++j) {
;         const float a = __builtin_bit_cast(float, __builtin_amdgcn_readlane(__builtin_bit_cast(int, avec), kb + j));
;         const f32x2 aa = f32x2{a, a};
;         y[0] += aa * __builtin_amdgcn_cvt_scalef32_pk_f32_fp4(v8[j].x, 1.0f, 0); y[1] += aa * __builtin_amdgcn_cvt_scalef32_pk_f32_fp4(v8[j].x, 1.0f, 1);
;         y[2] += aa * __builtin_amdgcn_cvt_scalef32_pk_f32_fp4(v8[j].x, 1.0f, 2); y[3] += aa * __builtin_amdgcn_cvt_scalef32_pk_f32_fp4(v8[j].x, 1.0f, 3);
;         y[4] += aa * __builtin_amdgcn_cvt_scalef32_pk_f32_fp4(v8[j].y, 1.0f, 0); y[5] += aa * __builtin_amdgcn_cvt_scalef32_pk_f32_fp4(v8[j].y, 1.0f, 1);
;         y[6] += aa * __builtin_amdgcn_cvt_scalef32_pk_f32_fp4(v8[j].y, 1.0f, 2); y[7] += aa * __builtin_amdgcn_cvt_scalef32_pk_f32_fp4(v8[j].y, 1.0f, 3);
;       }
	v_cvt_scalef32_pk_f32_fp4 v[0:1], v150, 1.0
	v_cvt_scalef32_pk_f32_fp4 v[2:3], v150, 1.0 op_sel:[1,0,0]
	v_cvt_scalef32_pk_f32_fp4 v[4:5], v150, 1.0 op_sel:[0,1,0]
	v_cvt_scalef32_pk_f32_fp4 v[6:7], v150, 1.0 op_sel:[1,1,0]
	v_cvt_scalef32_pk_f32_fp4 v[8:9], v151, 1.0
	v_cvt_scalef32_pk_f32_fp4 v[10:11], v151, 1.0 op_sel:[1,0,0]
	v_cvt_scalef32_pk_f32_fp4 v[12:13], v151, 1.0 op_sel:[0,1,0]
	v_cvt_scalef32_pk_f32_fp4 v[14:15], v151, 1.0 op_sel:[1,1,0]
	v_readlane_b32 s54, v90, 19
	s_lshl_b32 s56, s54, 9
	s_add_u32 s56, s64, s56
	s_addc_u32 s57, s65, 0
	global_load_dwordx2 v[150:151], v227, s[56:57]
	v_pk_fma_f32 v[130:131], v[0:1], s[0:1], v[130:131] op_sel_hi:[1,0,1]
	v_pk_fma_f32 v[138:139], v[2:3], s[0:1], v[138:139] op_sel_hi:[1,0,1]
	v_pk_fma_f32 v[140:141], v[4:5], s[0:1], v[140:141] op_sel_hi:[1,0,1]
	v_pk_fma_f32 v[142:143], v[6:7], s[0:1], v[142:143] op_sel_hi:[1,0,1]
	v_pk_fma_f32 v[128:129], v[8:9], s[0:1], v[128:129] op_sel_hi:[1,0,1]
	v_pk_fma_f32 v[132:133], v[10:11], s[0:1], v[132:133] op_sel_hi:[1,0,1]
	v_pk_fma_f32 v[134:135], v[12:13], s[0:1], v[134:135] op_sel_hi:[1,0,1]
	v_pk_fma_f32 v[136:137], v[14:15], s[0:1], v[136:137] op_sel_hi:[1,0,1]
	v_readlane_b32 s0, v167, 4
	s_waitcnt vmcnt(48)
	v_cvt_scalef32_pk_f32_fp4 v[0:1], v152, 1.0
	v_cvt_scalef32_pk_f32_fp4 v[2:3], v152, 1.0 op_sel:[1,0,0]
	v_cvt_scalef32_pk_f32_fp4 v[4:5], v152, 1.0 op_sel:[0,1,0]
	v_cvt_scalef32_pk_f32_fp4 v[6:7], v152, 1.0 op_sel:[1,1,0]
	v_cvt_scalef32_pk_f32_fp4 v[8:9], v153, 1.0
	v_cvt_scalef32_pk_f32_fp4 v[10:11], v153, 1.0 op_sel:[1,0,0]
	v_cvt_scalef32_pk_f32_fp4 v[12:13], v153, 1.0 op_sel:[0,1,0]
	v_cvt_scalef32_pk_f32_fp4 v[14:15], v153, 1.0 op_sel:[1,1,0]
	v_readlane_b32 s54, v90, 20
	s_lshl_b32 s56, s54, 9
	s_add_u32 s56, s64, s56
	s_addc_u32 s57, s65, 0
	global_load_dwordx2 v[152:153], v227, s[56:57]
	v_pk_fma_f32 v[130:131], v[0:1], s[0:1], v[130:131] op_sel_hi:[1,0,1]
	v_pk_fma_f32 v[138:139], v[2:3], s[0:1], v[138:139] op_sel_hi:[1,0,1]
	v_pk_fma_f32 v[140:141], v[4:5], s[0:1], v[140:141] op_sel_hi:[1,0,1]
	v_pk_fma_f32 v[142:143], v[6:7], s[0:1], v[142:143] op_sel_hi:[1,0,1]
	v_pk_fma_f32 v[128:129], v[8:9], s[0:1], v[128:129] op_sel_hi:[1,0,1]
	v_pk_fma_f32 v[132:133], v[10:11], s[0:1], v[132:133] op_sel_hi:[1,0,1]
	v_pk_fma_f32 v[134:135], v[12:13], s[0:1], v[134:135] op_sel_hi:[1,0,1]
	v_pk_fma_f32 v[136:137], v[14:15], s[0:1], v[136:137] op_sel_hi:[1,0,1]
	v_readlane_b32 s0, v167, 5
	s_waitcnt vmcnt(48)
	v_cvt_scalef32_pk_f32_fp4 v[0:1], v154, 1.0
	v_cvt_scalef32_pk_f32_fp4 v[2:3], v154, 1.0 op_sel:[1,0,0]
	v_cvt_scalef32_pk_f32_fp4 v[4:5], v154, 1.0 op_sel:[0,1,0]
	v_cvt_scalef32_pk_f32_fp4 v[6:7], v154, 1.0 op_sel:[1,1,0]
	v_cvt_scalef32_pk_f32_fp4 v[8:9], v155, 1.0
	v_cvt_scalef32_pk_f32_fp4 v[10:11], v155, 1.0 op_sel:[1,0,0]
	v_cvt_scalef32_pk_f32_fp4 v[12:13], v155, 1.0 op_sel:[0,1,0]
	v_cvt_scalef32_pk_f32_fp4 v[14:15], v155, 1.0 op_sel:[1,1,0]
	v_readlane_b32 s54, v90, 21
	s_lshl_b32 s56, s54, 9
	s_add_u32 s56, s64, s56
	s_addc_u32 s57, s65, 0
	global_load_dwordx2 v[154:155], v227, s[56:57]
	v_pk_fma_f32 v[130:131], v[0:1], s[0:1], v[130:131] op_sel_hi:[1,0,1]
	v_pk_fma_f32 v[138:139], v[2:3], s[0:1], v[138:139] op_sel_hi:[1,0,1]
	v_pk_fma_f32 v[140:141], v[4:5], s[0:1], v[140:141] op_sel_hi:[1,0,1]
	v_pk_fma_f32 v[142:143], v[6:7], s[0:1], v[142:143] op_sel_hi:[1,0,1]
	v_pk_fma_f32 v[128:129], v[8:9], s[0:1], v[128:129] op_sel_hi:[1,0,1]
	v_pk_fma_f32 v[132:133], v[10:11], s[0:1], v[132:133] op_sel_hi:[1,0,1]
	v_pk_fma_f32 v[134:135], v[12:13], s[0:1], v[134:135] op_sel_hi:[1,0,1]
	v_pk_fma_f32 v[136:137], v[14:15], s[0:1], v[136:137] op_sel_hi:[1,0,1]
	v_readlane_b32 s0, v167, 6
	s_waitcnt vmcnt(48)
	v_cvt_scalef32_pk_f32_fp4 v[0:1], v156, 1.0
	v_cvt_scalef32_pk_f32_fp4 v[2:3], v156, 1.0 op_sel:[1,0,0]
	v_cvt_scalef32_pk_f32_fp4 v[4:5], v156, 1.0 op_sel:[0,1,0]
	v_cvt_scalef32_pk_f32_fp4 v[6:7], v156, 1.0 op_sel:[1,1,0]
	v_cvt_scalef32_pk_f32_fp4 v[8:9], v157, 1.0
	v_cvt_scalef32_pk_f32_fp4 v[10:11], v157, 1.0 op_sel:[1,0,0]
	v_cvt_scalef32_pk_f32_fp4 v[12:13], v157, 1.0 op_sel:[0,1,0]
	v_cvt_scalef32_pk_f32_fp4 v[14:15], v157, 1.0 op_sel:[1,1,0]
	v_readlane_b32 s54, v90, 22
	s_lshl_b32 s56, s54, 9
	s_add_u32 s56, s64, s56
	s_addc_u32 s57, s65, 0
	global_load_dwordx2 v[156:157], v227, s[56:57]
	v_pk_fma_f32 v[130:131], v[0:1], s[0:1], v[130:131] op_sel_hi:[1,0,1]
	v_pk_fma_f32 v[138:139], v[2:3], s[0:1], v[138:139] op_sel_hi:[1,0,1]
	v_pk_fma_f32 v[140:141], v[4:5], s[0:1], v[140:141] op_sel_hi:[1,0,1]
	v_pk_fma_f32 v[142:143], v[6:7], s[0:1], v[142:143] op_sel_hi:[1,0,1]
	v_pk_fma_f32 v[128:129], v[8:9], s[0:1], v[128:129] op_sel_hi:[1,0,1]
	v_pk_fma_f32 v[132:133], v[10:11], s[0:1], v[132:133] op_sel_hi:[1,0,1]
	v_pk_fma_f32 v[134:135], v[12:13], s[0:1], v[134:135] op_sel_hi:[1,0,1]
	v_pk_fma_f32 v[136:137], v[14:15], s[0:1], v[136:137] op_sel_hi:[1,0,1]
	v_readlane_b32 s0, v167, 7
	s_waitcnt vmcnt(48)
	v_cvt_scalef32_pk_f32_fp4 v[0:1], v158, 1.0
	v_cvt_scalef32_pk_f32_fp4 v[2:3], v158, 1.0 op_sel:[1,0,0]
	v_cvt_scalef32_pk_f32_fp4 v[4:5], v158, 1.0 op_sel:[0,1,0]
	v_cvt_scalef32_pk_f32_fp4 v[6:7], v158, 1.0 op_sel:[1,1,0]
	v_cvt_scalef32_pk_f32_fp4 v[8:9], v159, 1.0
	v_cvt_scalef32_pk_f32_fp4 v[10:11], v159, 1.0 op_sel:[1,0,0]
	v_cvt_scalef32_pk_f32_fp4 v[12:13], v159, 1.0 op_sel:[0,1,0]
	v_cvt_scalef32_pk_f32_fp4 v[14:15], v159, 1.0 op_sel:[1,1,0]
	v_readlane_b32 s54, v90, 23
	s_lshl_b32 s56, s54, 9
	s_add_u32 s56, s64, s56
	s_addc_u32 s57, s65, 0
	global_load_dwordx2 v[158:159], v227, s[56:57]
	v_pk_fma_f32 v[130:131], v[0:1], s[0:1], v[130:131] op_sel_hi:[1,0,1]
	v_pk_fma_f32 v[138:139], v[2:3], s[0:1], v[138:139] op_sel_hi:[1,0,1]
	v_pk_fma_f32 v[140:141], v[4:5], s[0:1], v[140:141] op_sel_hi:[1,0,1]
	v_pk_fma_f32 v[142:143], v[6:7], s[0:1], v[142:143] op_sel_hi:[1,0,1]
	v_pk_fma_f32 v[128:129], v[8:9], s[0:1], v[128:129] op_sel_hi:[1,0,1]
	v_pk_fma_f32 v[132:133], v[10:11], s[0:1], v[132:133] op_sel_hi:[1,0,1]
	v_pk_fma_f32 v[134:135], v[12:13], s[0:1], v[134:135] op_sel_hi:[1,0,1]
	v_pk_fma_f32 v[136:137], v[14:15], s[0:1], v[136:137] op_sel_hi:[1,0,1]
	v_readlane_b32 s0, v167, 8
	s_waitcnt vmcnt(48)
; __device__ void peer_gather_phase(const Params& P, int l, bool do_store) {
;     ...
;       for (int pr = 0; pr < 4; ++pr) {
;         const int ea = __builtin_amdgcn_readlane(evs, kb + 2 * pr), eb = __builtin_amdgcn_readlane(evs, kb + 2 * pr + 1);
;         const uint2* up = (const uint2*)(U + (size_t)(uphi ? eb : ea) * 768);
;         u6[3 * pr] = up[0]; u6[3 * pr + 1] = up[1]; u6[3 * pr + 2] = up[2];
;         v8[2 * pr] = *(const uint2*)(V + (size_t)ea * 512);
;         v8[2 * pr + 1] = *(const uint2*)(V + (size_t)eb * 512);
;     ...
; #pragma unroll
;       for (int j = 0; j < 8; ++j) {
;         const float a = __builtin_bit_cast(float, __builtin_amdgcn_readlane(__builtin_bit_cast(int, avec), kb + j));
;         const f32x2 aa = f32x2{a, a};
;         y[0] += aa * __builtin_amdgcn_cvt_scalef32_pk_f32_fp4(v8[j].x, 1.0f, 0); y[1] += aa * __builtin_amdgcn_cvt_scalef32_pk_f32_fp4(v8[j].x, 1.0f, 1);
;         y[2] += aa * __builtin_amdgcn_cvt_scalef32_pk_f32_fp4(v8[j].x, 1.0f, 2); y[3] += aa * __builtin_amdgcn_cvt_scalef32_pk_f32_fp4(v8[j].x, 1.0f, 3);
;         y[4] += aa * __builtin_amdgcn_cvt_scalef32_pk_f32_fp4(v8[j].y, 1.0f, 0); y[5] += aa * __builtin_amdgcn_cvt_scalef32_pk_f32_fp4(v8[j].y, 1.0f, 1);
;         y[6] += aa * __builtin_amdgcn_cvt_scalef32_pk_f32_fp4(v8[j].y, 1.0f, 2); y[7] += aa * __builtin_amdgcn_cvt_scalef32_pk_f32_fp4(v8[j].y, 1.0f, 3);
;       }
	v_cvt_scalef32_pk_f32_fp4 v[0:1], v168, 1.0
	v_cvt_scalef32_pk_f32_fp4 v[2:3], v168, 1.0 op_sel:[1,0,0]
	v_cvt_scalef32_pk_f32_fp4 v[4:5], v168, 1.0 op_sel:[0,1,0]
	v_cvt_scalef32_pk_f32_fp4 v[6:7], v168, 1.0 op_sel:[1,1,0]
	v_cvt_scalef32_pk_f32_fp4 v[8:9], v169, 1.0
	v_cvt_scalef32_pk_f32_fp4 v[10:11], v169, 1.0 op_sel:[1,0,0]
	v_cvt_scalef32_pk_f32_fp4 v[12:13], v169, 1.0 op_sel:[0,1,0]
	v_cvt_scalef32_pk_f32_fp4 v[14:15], v169, 1.0 op_sel:[1,1,0]
	v_readlane_b32 s54, v90, 24
	s_lshl_b32 s56, s54, 9
	s_add_u32 s56, s64, s56
	s_addc_u32 s57, s65, 0
	global_load_dwordx2 v[168:169], v227, s[56:57]
	v_pk_fma_f32 v[130:131], v[0:1], s[0:1], v[130:131] op_sel_hi:[1,0,1]
	v_pk_fma_f32 v[138:139], v[2:3], s[0:1], v[138:139] op_sel_hi:[1,0,1]
	v_pk_fma_f32 v[140:141], v[4:5], s[0:1], v[140:141] op_sel_hi:[1,0,1]
	v_pk_fma_f32 v[142:143], v[6:7], s[0:1], v[142:143] op_sel_hi:[1,0,1]
	v_pk_fma_f32 v[128:129], v[8:9], s[0:1], v[128:129] op_sel_hi:[1,0,1]
	v_pk_fma_f32 v[132:133], v[10:11], s[0:1], v[132:133] op_sel_hi:[1,0,1]
	v_pk_fma_f32 v[134:135], v[12:13], s[0:1], v[134:135] op_sel_hi:[1,0,1]
	v_pk_fma_f32 v[136:137], v[14:15], s[0:1], v[136:137] op_sel_hi:[1,0,1]
	v_readlane_b32 s0, v167, 9
	s_waitcnt vmcnt(48)
	v_cvt_scalef32_pk_f32_fp4 v[0:1], v170, 1.0
	v_cvt_scalef32_pk_f32_fp4 v[2:3], v170, 1.0 op_sel:[1,0,0]
	v_cvt_scalef32_pk_f32_fp4 v[4:5], v170, 1.0 op_sel:[0,1,0]
	v_cvt_scalef32_pk_f32_fp4 v[6:7], v170, 1.0 op_sel:[1,1,0]
	v_cvt_scalef32_pk_f32_fp4 v[8:9], v171, 1.0
	v_cvt_scalef32_pk_f32_fp4 v[10:11], v171, 1.0 op_sel:[1,0,0]
	v_cvt_scalef32_pk_f32_fp4 v[12:13], v171, 1.0 op_sel:[0,1,0]
	v_cvt_scalef32_pk_f32_fp4 v[14:15], v171, 1.0 op_sel:[1,1,0]
	v_readlane_b32 s54, v90, 25
	s_lshl_b32 s56, s54, 9
	s_add_u32 s56, s64, s56
	s_addc_u32 s57, s65, 0
	global_load_dwordx2 v[170:171], v227, s[56:57]
	v_pk_fma_f32 v[130:131], v[0:1], s[0:1], v[130:131] op_sel_hi:[1,0,1]
	v_pk_fma_f32 v[138:139], v[2:3], s[0:1], v[138:139] op_sel_hi:[1,0,1]
	v_pk_fma_f32 v[140:141], v[4:5], s[0:1], v[140:141] op_sel_hi:[1,0,1]
	v_pk_fma_f32 v[142:143], v[6:7], s[0:1], v[142:143] op_sel_hi:[1,0,1]
	v_pk_fma_f32 v[128:129], v[8:9], s[0:1], v[128:129] op_sel_hi:[1,0,1]
	v_pk_fma_f32 v[132:133], v[10:11], s[0:1], v[132:133] op_sel_hi:[1,0,1]
	v_pk_fma_f32 v[134:135], v[12:13], s[0:1], v[134:135] op_sel_hi:[1,0,1]
	v_pk_fma_f32 v[136:137], v[14:15], s[0:1], v[136:137] op_sel_hi:[1,0,1]
	v_readlane_b32 s0, v167, 10
	s_waitcnt vmcnt(48)
	v_cvt_scalef32_pk_f32_fp4 v[0:1], v172, 1.0
	v_cvt_scalef32_pk_f32_fp4 v[2:3], v172, 1.0 op_sel:[1,0,0]
	v_cvt_scalef32_pk_f32_fp4 v[4:5], v172, 1.0 op_sel:[0,1,0]
	v_cvt_scalef32_pk_f32_fp4 v[6:7], v172, 1.0 op_sel:[1,1,0]
	v_cvt_scalef32_pk_f32_fp4 v[8:9], v173, 1.0
	v_cvt_scalef32_pk_f32_fp4 v[10:11], v173, 1.0 op_sel:[1,0,0]
	v_cvt_scalef32_pk_f32_fp4 v[12:13], v173, 1.0 op_sel:[0,1,0]
	v_cvt_scalef32_pk_f32_fp4 v[14:15], v173, 1.0 op_sel:[1,1,0]
	v_readlane_b32 s54, v90, 26
	s_lshl_b32 s56, s54, 9
	s_add_u32 s56, s64, s56
	s_addc_u32 s57, s65, 0
	global_load_dwordx2 v[172:173], v227, s[56:57]
	v_pk_fma_f32 v[130:131], v[0:1], s[0:1], v[130:131] op_sel_hi:[1,0,1]
	v_pk_fma_f32 v[138:139], v[2:3], s[0:1], v[138:139] op_sel_hi:[1,0,1]
	v_pk_fma_f32 v[140:141], v[4:5], s[0:1], v[140:141] op_sel_hi:[1,0,1]
	v_pk_fma_f32 v[142:143], v[6:7], s[0:1], v[142:143] op_sel_hi:[1,0,1]
	v_pk_fma_f32 v[128:129], v[8:9], s[0:1], v[128:129] op_sel_hi:[1,0,1]
	v_pk_fma_f32 v[132:133], v[10:11], s[0:1], v[132:133] op_sel_hi:[1,0,1]
	v_pk_fma_f32 v[134:135], v[12:13], s[0:1], v[134:135] op_sel_hi:[1,0,1]
	v_pk_fma_f32 v[136:137], v[14:15], s[0:1], v[136:137] op_sel_hi:[1,0,1]
	v_readlane_b32 s0, v167, 11
	s_waitcnt vmcnt(48)
	v_cvt_scalef32_pk_f32_fp4 v[0:1], v174, 1.0
	v_cvt_scalef32_pk_f32_fp4 v[2:3], v174, 1.0 op_sel:[1,0,0]
	v_cvt_scalef32_pk_f32_fp4 v[4:5], v174, 1.0 op_sel:[0,1,0]
	v_cvt_scalef32_pk_f32_fp4 v[6:7], v174, 1.0 op_sel:[1,1,0]
	v_cvt_scalef32_pk_f32_fp4 v[8:9], v175, 1.0
	v_cvt_scalef32_pk_f32_fp4 v[10:11], v175, 1.0 op_sel:[1,0,0]
	v_cvt_scalef32_pk_f32_fp4 v[12:13], v175, 1.0 op_sel:[0,1,0]
	v_cvt_scalef32_pk_f32_fp4 v[14:15], v175, 1.0 op_sel:[1,1,0]
	v_readlane_b32 s54, v90, 27
	s_lshl_b32 s56, s54, 9
	s_add_u32 s56, s64, s56
	s_addc_u32 s57, s65, 0
	global_load_dwordx2 v[174:175], v227, s[56:57]
	v_pk_fma_f32 v[130:131], v[0:1], s[0:1], v[130:131] op_sel_hi:[1,0,1]
	v_pk_fma_f32 v[138:139], v[2:3], s[0:1], v[138:139] op_sel_hi:[1,0,1]
	v_pk_fma_f32 v[140:141], v[4:5], s[0:1], v[140:141] op_sel_hi:[1,0,1]
	v_pk_fma_f32 v[142:143], v[6:7], s[0:1], v[142:143] op_sel_hi:[1,0,1]
	v_pk_fma_f32 v[128:129], v[8:9], s[0:1], v[128:129] op_sel_hi:[1,0,1]
	v_pk_fma_f32 v[132:133], v[10:11], s[0:1], v[132:133] op_sel_hi:[1,0,1]
	v_pk_fma_f32 v[134:135], v[12:13], s[0:1], v[134:135] op_sel_hi:[1,0,1]
	v_pk_fma_f32 v[136:137], v[14:15], s[0:1], v[136:137] op_sel_hi:[1,0,1]
	v_readlane_b32 s0, v167, 12
	s_waitcnt vmcnt(48)
	v_cvt_scalef32_pk_f32_fp4 v[0:1], v180, 1.0
	v_cvt_scalef32_pk_f32_fp4 v[2:3], v180, 1.0 op_sel:[1,0,0]
	v_cvt_scalef32_pk_f32_fp4 v[4:5], v180, 1.0 op_sel:[0,1,0]
	v_cvt_scalef32_pk_f32_fp4 v[6:7], v180, 1.0 op_sel:[1,1,0]
	v_cvt_scalef32_pk_f32_fp4 v[8:9], v181, 1.0
	v_cvt_scalef32_pk_f32_fp4 v[10:11], v181, 1.0 op_sel:[1,0,0]
	v_cvt_scalef32_pk_f32_fp4 v[12:13], v181, 1.0 op_sel:[0,1,0]
	v_cvt_scalef32_pk_f32_fp4 v[14:15], v181, 1.0 op_sel:[1,1,0]
	v_readlane_b32 s54, v90, 28
	s_lshl_b32 s56, s54, 9
	s_add_u32 s56, s64, s56
	s_addc_u32 s57, s65, 0
	global_load_dwordx2 v[180:181], v227, s[56:57]
	v_pk_fma_f32 v[130:131], v[0:1], s[0:1], v[130:131] op_sel_hi:[1,0,1]
	v_pk_fma_f32 v[138:139], v[2:3], s[0:1], v[138:139] op_sel_hi:[1,0,1]
	v_pk_fma_f32 v[140:141], v[4:5], s[0:1], v[140:141] op_sel_hi:[1,0,1]
	v_pk_fma_f32 v[142:143], v[6:7], s[0:1], v[142:143] op_sel_hi:[1,0,1]
	v_pk_fma_f32 v[128:129], v[8:9], s[0:1], v[128:129] op_sel_hi:[1,0,1]
	v_pk_fma_f32 v[132:133], v[10:11], s[0:1], v[132:133] op_sel_hi:[1,0,1]
	v_pk_fma_f32 v[134:135], v[12:13], s[0:1], v[134:135] op_sel_hi:[1,0,1]
	v_pk_fma_f32 v[136:137], v[14:15], s[0:1], v[136:137] op_sel_hi:[1,0,1]
	v_readlane_b32 s0, v167, 13
	s_waitcnt vmcnt(48)
; __device__ void peer_gather_phase(const Params& P, int l, bool do_store) {
;     ...
;       for (int pr = 0; pr < 4; ++pr) {
;         const int ea = __builtin_amdgcn_readlane(evs, kb + 2 * pr), eb = __builtin_amdgcn_readlane(evs, kb + 2 * pr + 1);
;         const uint2* up = (const uint2*)(U + (size_t)(uphi ? eb : ea) * 768);
;         u6[3 * pr] = up[0]; u6[3 * pr + 1] = up[1]; u6[3 * pr + 2] = up[2];
;         v8[2 * pr] = *(const uint2*)(V + (size_t)ea * 512);
;         v8[2 * pr + 1] = *(const uint2*)(V + (size_t)eb * 512);
;     ...
; #pragma unroll
;       for (int j = 0; j < 8; ++j) {
;         const float a = __builtin_bit_cast(float, __builtin_amdgcn_readlane(__builtin_bit_cast(int, avec), kb + j));
;         const f32x2 aa = f32x2{a, a};
;         y[0] += aa * __builtin_amdgcn_cvt_scalef32_pk_f32_fp4(v8[j].x, 1.0f, 0); y[1] += aa * __builtin_amdgcn_cvt_scalef32_pk_f32_fp4(v8[j].x, 1.0f, 1);
;         y[2] += aa * __builtin_amdgcn_cvt_scalef32_pk_f32_fp4(v8[j].x, 1.0f, 2); y[3] += aa * __builtin_amdgcn_cvt_scalef32_pk_f32_fp4(v8[j].x, 1.0f, 3);
;         y[4] += aa * __builtin_amdgcn_cvt_scalef32_pk_f32_fp4(v8[j].y, 1.0f, 0); y[5] += aa * __builtin_amdgcn_cvt_scalef32_pk_f32_fp4(v8[j].y, 1.0f, 1);
;         y[6] += aa * __builtin_amdgcn_cvt_scalef32_pk_f32_fp4(v8[j].y, 1.0f, 2); y[7] += aa * __builtin_amdgcn_cvt_scalef32_pk_f32_fp4(v8[j].y, 1.0f, 3);
;       }
	v_cvt_scalef32_pk_f32_fp4 v[0:1], v182, 1.0
	v_cvt_scalef32_pk_f32_fp4 v[2:3], v182, 1.0 op_sel:[1,0,0]
	v_cvt_scalef32_pk_f32_fp4 v[4:5], v182, 1.0 op_sel:[0,1,0]
	v_cvt_scalef32_pk_f32_fp4 v[6:7], v182, 1.0 op_sel:[1,1,0]
	v_cvt_scalef32_pk_f32_fp4 v[8:9], v183, 1.0
	v_cvt_scalef32_pk_f32_fp4 v[10:11], v183, 1.0 op_sel:[1,0,0]
	v_cvt_scalef32_pk_f32_fp4 v[12:13], v183, 1.0 op_sel:[0,1,0]
	v_cvt_scalef32_pk_f32_fp4 v[14:15], v183, 1.0 op_sel:[1,1,0]
	v_readlane_b32 s54, v90, 29
	s_lshl_b32 s56, s54, 9
	s_add_u32 s56, s64, s56
	s_addc_u32 s57, s65, 0
	global_load_dwordx2 v[182:183], v227, s[56:57]
	v_pk_fma_f32 v[130:131], v[0:1], s[0:1], v[130:131] op_sel_hi:[1,0,1]
	v_pk_fma_f32 v[138:139], v[2:3], s[0:1], v[138:139] op_sel_hi:[1,0,1]
	v_pk_fma_f32 v[140:141], v[4:5], s[0:1], v[140:141] op_sel_hi:[1,0,1]
	v_pk_fma_f32 v[142:143], v[6:7], s[0:1], v[142:143] op_sel_hi:[1,0,1]
	v_pk_fma_f32 v[128:129], v[8:9], s[0:1], v[128:129] op_sel_hi:[1,0,1]
	v_pk_fma_f32 v[132:133], v[10:11], s[0:1], v[132:133] op_sel_hi:[1,0,1]
	v_pk_fma_f32 v[134:135], v[12:13], s[0:1], v[134:135] op_sel_hi:[1,0,1]
	v_pk_fma_f32 v[136:137], v[14:15], s[0:1], v[136:137] op_sel_hi:[1,0,1]
	v_readlane_b32 s0, v167, 14
	s_waitcnt vmcnt(48)
	v_cvt_scalef32_pk_f32_fp4 v[0:1], v184, 1.0
	v_cvt_scalef32_pk_f32_fp4 v[2:3], v184, 1.0 op_sel:[1,0,0]
	v_cvt_scalef32_pk_f32_fp4 v[4:5], v184, 1.0 op_sel:[0,1,0]
	v_cvt_scalef32_pk_f32_fp4 v[6:7], v184, 1.0 op_sel:[1,1,0]
	v_cvt_scalef32_pk_f32_fp4 v[8:9], v185, 1.0
	v_cvt_scalef32_pk_f32_fp4 v[10:11], v185, 1.0 op_sel:[1,0,0]
	v_cvt_scalef32_pk_f32_fp4 v[12:13], v185, 1.0 op_sel:[0,1,0]
	v_cvt_scalef32_pk_f32_fp4 v[14:15], v185, 1.0 op_sel:[1,1,0]
	v_readlane_b32 s54, v90, 30
	s_lshl_b32 s56, s54, 9
	s_add_u32 s56, s64, s56
	s_addc_u32 s57, s65, 0
	global_load_dwordx2 v[184:185], v227, s[56:57]
	v_pk_fma_f32 v[130:131], v[0:1], s[0:1], v[130:131] op_sel_hi:[1,0,1]
	v_pk_fma_f32 v[138:139], v[2:3], s[0:1], v[138:139] op_sel_hi:[1,0,1]
	v_pk_fma_f32 v[140:141], v[4:5], s[0:1], v[140:141] op_sel_hi:[1,0,1]
	v_pk_fma_f32 v[142:143], v[6:7], s[0:1], v[142:143] op_sel_hi:[1,0,1]
	v_pk_fma_f32 v[128:129], v[8:9], s[0:1], v[128:129] op_sel_hi:[1,0,1]
	v_pk_fma_f32 v[132:133], v[10:11], s[0:1], v[132:133] op_sel_hi:[1,0,1]
	v_pk_fma_f32 v[134:135], v[12:13], s[0:1], v[134:135] op_sel_hi:[1,0,1]
	v_pk_fma_f32 v[136:137], v[14:15], s[0:1], v[136:137] op_sel_hi:[1,0,1]
	v_readlane_b32 s0, v167, 15
	s_waitcnt vmcnt(48)
	v_cvt_scalef32_pk_f32_fp4 v[0:1], v186, 1.0
	v_cvt_scalef32_pk_f32_fp4 v[2:3], v186, 1.0 op_sel:[1,0,0]
	v_cvt_scalef32_pk_f32_fp4 v[4:5], v186, 1.0 op_sel:[0,1,0]
	v_cvt_scalef32_pk_f32_fp4 v[6:7], v186, 1.0 op_sel:[1,1,0]
	v_cvt_scalef32_pk_f32_fp4 v[8:9], v187, 1.0
	v_cvt_scalef32_pk_f32_fp4 v[10:11], v187, 1.0 op_sel:[1,0,0]
	v_cvt_scalef32_pk_f32_fp4 v[12:13], v187, 1.0 op_sel:[0,1,0]
	v_cvt_scalef32_pk_f32_fp4 v[14:15], v187, 1.0 op_sel:[1,1,0]
	v_readlane_b32 s54, v90, 31
	s_lshl_b32 s56, s54, 9
	s_add_u32 s56, s64, s56
	s_addc_u32 s57, s65, 0
	global_load_dwordx2 v[186:187], v227, s[56:57]
	v_pk_fma_f32 v[130:131], v[0:1], s[0:1], v[130:131] op_sel_hi:[1,0,1]
	v_pk_fma_f32 v[138:139], v[2:3], s[0:1], v[138:139] op_sel_hi:[1,0,1]
	v_pk_fma_f32 v[140:141], v[4:5], s[0:1], v[140:141] op_sel_hi:[1,0,1]
	v_pk_fma_f32 v[142:143], v[6:7], s[0:1], v[142:143] op_sel_hi:[1,0,1]
	v_pk_fma_f32 v[128:129], v[8:9], s[0:1], v[128:129] op_sel_hi:[1,0,1]
	v_pk_fma_f32 v[132:133], v[10:11], s[0:1], v[132:133] op_sel_hi:[1,0,1]
	v_pk_fma_f32 v[134:135], v[12:13], s[0:1], v[134:135] op_sel_hi:[1,0,1]
	v_pk_fma_f32 v[136:137], v[14:15], s[0:1], v[136:137] op_sel_hi:[1,0,1]
	v_readlane_b32 s0, v167, 16
	s_waitcnt vmcnt(15)
	v_cvt_scalef32_pk_f32_fp4 v[0:1], v144, 1.0
	v_cvt_scalef32_pk_f32_fp4 v[2:3], v144, 1.0 op_sel:[1,0,0]
	v_cvt_scalef32_pk_f32_fp4 v[4:5], v144, 1.0 op_sel:[0,1,0]
	v_cvt_scalef32_pk_f32_fp4 v[6:7], v144, 1.0 op_sel:[1,1,0]
	v_cvt_scalef32_pk_f32_fp4 v[8:9], v145, 1.0
	v_cvt_scalef32_pk_f32_fp4 v[10:11], v145, 1.0 op_sel:[1,0,0]
	v_cvt_scalef32_pk_f32_fp4 v[12:13], v145, 1.0 op_sel:[0,1,0]
	v_cvt_scalef32_pk_f32_fp4 v[14:15], v145, 1.0 op_sel:[1,1,0]
	v_readlane_b32 s54, v90, 32
	s_lshl_b32 s56, s54, 9
	s_add_u32 s56, s64, s56
	s_addc_u32 s57, s65, 0
	global_load_dwordx2 v[144:145], v227, s[56:57]
	v_pk_fma_f32 v[130:131], v[0:1], s[0:1], v[130:131] op_sel_hi:[1,0,1]
	v_pk_fma_f32 v[138:139], v[2:3], s[0:1], v[138:139] op_sel_hi:[1,0,1]
	v_pk_fma_f32 v[140:141], v[4:5], s[0:1], v[140:141] op_sel_hi:[1,0,1]
	v_pk_fma_f32 v[142:143], v[6:7], s[0:1], v[142:143] op_sel_hi:[1,0,1]
	v_pk_fma_f32 v[128:129], v[8:9], s[0:1], v[128:129] op_sel_hi:[1,0,1]
	v_pk_fma_f32 v[132:133], v[10:11], s[0:1], v[132:133] op_sel_hi:[1,0,1]
	v_pk_fma_f32 v[134:135], v[12:13], s[0:1], v[134:135] op_sel_hi:[1,0,1]
	v_pk_fma_f32 v[136:137], v[14:15], s[0:1], v[136:137] op_sel_hi:[1,0,1]
	v_readlane_b32 s0, v167, 17
	s_waitcnt vmcnt(15)
	v_cvt_scalef32_pk_f32_fp4 v[0:1], v146, 1.0
	v_cvt_scalef32_pk_f32_fp4 v[2:3], v146, 1.0 op_sel:[1,0,0]
	v_cvt_scalef32_pk_f32_fp4 v[4:5], v146, 1.0 op_sel:[0,1,0]
	v_cvt_scalef32_pk_f32_fp4 v[6:7], v146, 1.0 op_sel:[1,1,0]
	v_cvt_scalef32_pk_f32_fp4 v[8:9], v147, 1.0
	v_cvt_scalef32_pk_f32_fp4 v[10:11], v147, 1.0 op_sel:[1,0,0]
	v_cvt_scalef32_pk_f32_fp4 v[12:13], v147, 1.0 op_sel:[0,1,0]
	v_cvt_scalef32_pk_f32_fp4 v[14:15], v147, 1.0 op_sel:[1,1,0]
	v_readlane_b32 s54, v90, 33
	s_lshl_b32 s56, s54, 9
	s_add_u32 s56, s64, s56
	s_addc_u32 s57, s65, 0
	global_load_dwordx2 v[146:147], v227, s[56:57]
	v_pk_fma_f32 v[130:131], v[0:1], s[0:1], v[130:131] op_sel_hi:[1,0,1]
	v_pk_fma_f32 v[138:139], v[2:3], s[0:1], v[138:139] op_sel_hi:[1,0,1]
	v_pk_fma_f32 v[140:141], v[4:5], s[0:1], v[140:141] op_sel_hi:[1,0,1]
	v_pk_fma_f32 v[142:143], v[6:7], s[0:1], v[142:143] op_sel_hi:[1,0,1]
	v_pk_fma_f32 v[128:129], v[8:9], s[0:1], v[128:129] op_sel_hi:[1,0,1]
	v_pk_fma_f32 v[132:133], v[10:11], s[0:1], v[132:133] op_sel_hi:[1,0,1]
	v_pk_fma_f32 v[134:135], v[12:13], s[0:1], v[134:135] op_sel_hi:[1,0,1]
	v_pk_fma_f32 v[136:137], v[14:15], s[0:1], v[136:137] op_sel_hi:[1,0,1]
	v_readlane_b32 s0, v167, 18
	s_waitcnt vmcnt(15)
; __device__ void peer_gather_phase(const Params& P, int l, bool do_store) {
;     ...
;       for (int pr = 0; pr < 4; ++pr) {
;         const int ea = __builtin_amdgcn_readlane(evs, kb + 2 * pr), eb = __builtin_amdgcn_readlane(evs, kb + 2 * pr + 1);
;         const uint2* up = (const uint2*)(U + (size_t)(uphi ? eb : ea) * 768);
;         u6[3 * pr] = up[0]; u6[3 * pr + 1] = up[1]; u6[3 * pr + 2] = up[2];
;         v8[2 * pr] = *(const uint2*)(V + (size_t)ea * 512);
;         v8[2 * pr + 1] = *(const uint2*)(V + (size_t)eb * 512);
;     ...
; #pragma unroll
;       for (int j = 0; j < 8; ++j) {
;         const float a = __builtin_bit_cast(float, __builtin_amdgcn_readlane(__builtin_bit_cast(int, avec), kb + j));
;         const f32x2 aa = f32x2{a, a};
;         y[0] += aa * __builtin_amdgcn_cvt_scalef32_pk_f32_fp4(v8[j].x, 1.0f, 0); y[1] += aa * __builtin_amdgcn_cvt_scalef32_pk_f32_fp4(v8[j].x, 1.0f, 1);
;         y[2] += aa * __builtin_amdgcn_cvt_scalef32_pk_f32_fp4(v8[j].x, 1.0f, 2); y[3] += aa * __builtin_amdgcn_cvt_scalef32_pk_f32_fp4(v8[j].x, 1.0f, 3);
;         y[4] += aa * __builtin_amdgcn_cvt_scalef32_pk_f32_fp4(v8[j].y, 1.0f, 0); y[5] += aa * __builtin_amdgcn_cvt_scalef32_pk_f32_fp4(v8[j].y, 1.0f, 1);
;         y[6] += aa * __builtin_amdgcn_cvt_scalef32_pk_f32_fp4(v8[j].y, 1.0f, 2); y[7] += aa * __builtin_amdgcn_cvt_scalef32_pk_f32_fp4(v8[j].y, 1.0f, 3);
;       }
	v_cvt_scalef32_pk_f32_fp4 v[0:1], v148, 1.0
	v_cvt_scalef32_pk_f32_fp4 v[2:3], v148, 1.0 op_sel:[1,0,0]
	v_cvt_scalef32_pk_f32_fp4 v[4:5], v148, 1.0 op_sel:[0,1,0]
	v_cvt_scalef32_pk_f32_fp4 v[6:7], v148, 1.0 op_sel:[1,1,0]
	v_cvt_scalef32_pk_f32_fp4 v[8:9], v149, 1.0
	v_cvt_scalef32_pk_f32_fp4 v[10:11], v149, 1.0 op_sel:[1,0,0]
	v_cvt_scalef32_pk_f32_fp4 v[12:13], v149, 1.0 op_sel:[0,1,0]
	v_cvt_scalef32_pk_f32_fp4 v[14:15], v149, 1.0 op_sel:[1,1,0]
	v_readlane_b32 s54, v90, 34
	s_lshl_b32 s56, s54, 9
	s_add_u32 s56, s64, s56
	s_addc_u32 s57, s65, 0
	global_load_dwordx2 v[148:149], v227, s[56:57]
	v_pk_fma_f32 v[130:131], v[0:1], s[0:1], v[130:131] op_sel_hi:[1,0,1]
	v_pk_fma_f32 v[138:139], v[2:3], s[0:1], v[138:139] op_sel_hi:[1,0,1]
	v_pk_fma_f32 v[140:141], v[4:5], s[0:1], v[140:141] op_sel_hi:[1,0,1]
	v_pk_fma_f32 v[142:143], v[6:7], s[0:1], v[142:143] op_sel_hi:[1,0,1]
	v_pk_fma_f32 v[128:129], v[8:9], s[0:1], v[128:129] op_sel_hi:[1,0,1]
	v_pk_fma_f32 v[132:133], v[10:11], s[0:1], v[132:133] op_sel_hi:[1,0,1]
	v_pk_fma_f32 v[134:135], v[12:13], s[0:1], v[134:135] op_sel_hi:[1,0,1]
	v_pk_fma_f32 v[136:137], v[14:15], s[0:1], v[136:137] op_sel_hi:[1,0,1]
	v_readlane_b32 s0, v167, 19
	s_waitcnt vmcnt(15)
	v_cvt_scalef32_pk_f32_fp4 v[0:1], v150, 1.0
	v_cvt_scalef32_pk_f32_fp4 v[2:3], v150, 1.0 op_sel:[1,0,0]
	v_cvt_scalef32_pk_f32_fp4 v[4:5], v150, 1.0 op_sel:[0,1,0]
	v_cvt_scalef32_pk_f32_fp4 v[6:7], v150, 1.0 op_sel:[1,1,0]
	v_cvt_scalef32_pk_f32_fp4 v[8:9], v151, 1.0
	v_cvt_scalef32_pk_f32_fp4 v[10:11], v151, 1.0 op_sel:[1,0,0]
	v_cvt_scalef32_pk_f32_fp4 v[12:13], v151, 1.0 op_sel:[0,1,0]
	v_cvt_scalef32_pk_f32_fp4 v[14:15], v151, 1.0 op_sel:[1,1,0]
	v_readlane_b32 s54, v90, 35
	s_lshl_b32 s56, s54, 9
	s_add_u32 s56, s64, s56
	s_addc_u32 s57, s65, 0
	global_load_dwordx2 v[150:151], v227, s[56:57]
	v_pk_fma_f32 v[130:131], v[0:1], s[0:1], v[130:131] op_sel_hi:[1,0,1]
	v_pk_fma_f32 v[138:139], v[2:3], s[0:1], v[138:139] op_sel_hi:[1,0,1]
	v_pk_fma_f32 v[140:141], v[4:5], s[0:1], v[140:141] op_sel_hi:[1,0,1]
	v_pk_fma_f32 v[142:143], v[6:7], s[0:1], v[142:143] op_sel_hi:[1,0,1]
	v_pk_fma_f32 v[128:129], v[8:9], s[0:1], v[128:129] op_sel_hi:[1,0,1]
	v_pk_fma_f32 v[132:133], v[10:11], s[0:1], v[132:133] op_sel_hi:[1,0,1]
	v_pk_fma_f32 v[134:135], v[12:13], s[0:1], v[134:135] op_sel_hi:[1,0,1]
	v_pk_fma_f32 v[136:137], v[14:15], s[0:1], v[136:137] op_sel_hi:[1,0,1]
	v_readlane_b32 s0, v167, 20
	s_waitcnt vmcnt(15)
	v_cvt_scalef32_pk_f32_fp4 v[0:1], v152, 1.0
	v_cvt_scalef32_pk_f32_fp4 v[2:3], v152, 1.0 op_sel:[1,0,0]
	v_cvt_scalef32_pk_f32_fp4 v[4:5], v152, 1.0 op_sel:[0,1,0]
	v_cvt_scalef32_pk_f32_fp4 v[6:7], v152, 1.0 op_sel:[1,1,0]
	v_cvt_scalef32_pk_f32_fp4 v[8:9], v153, 1.0
	v_cvt_scalef32_pk_f32_fp4 v[10:11], v153, 1.0 op_sel:[1,0,0]
	v_cvt_scalef32_pk_f32_fp4 v[12:13], v153, 1.0 op_sel:[0,1,0]
	v_cvt_scalef32_pk_f32_fp4 v[14:15], v153, 1.0 op_sel:[1,1,0]
	v_readlane_b32 s54, v90, 36
	s_lshl_b32 s56, s54, 9
	s_add_u32 s56, s64, s56
	s_addc_u32 s57, s65, 0
	global_load_dwordx2 v[152:153], v227, s[56:57]
	v_pk_fma_f32 v[130:131], v[0:1], s[0:1], v[130:131] op_sel_hi:[1,0,1]
	v_pk_fma_f32 v[138:139], v[2:3], s[0:1], v[138:139] op_sel_hi:[1,0,1]
	v_pk_fma_f32 v[140:141], v[4:5], s[0:1], v[140:141] op_sel_hi:[1,0,1]
	v_pk_fma_f32 v[142:143], v[6:7], s[0:1], v[142:143] op_sel_hi:[1,0,1]
	v_pk_fma_f32 v[128:129], v[8:9], s[0:1], v[128:129] op_sel_hi:[1,0,1]
	v_pk_fma_f32 v[132:133], v[10:11], s[0:1], v[132:133] op_sel_hi:[1,0,1]
	v_pk_fma_f32 v[134:135], v[12:13], s[0:1], v[134:135] op_sel_hi:[1,0,1]
	v_pk_fma_f32 v[136:137], v[14:15], s[0:1], v[136:137] op_sel_hi:[1,0,1]
	v_readlane_b32 s0, v167, 21
	s_waitcnt vmcnt(15)
	v_cvt_scalef32_pk_f32_fp4 v[0:1], v154, 1.0
	v_cvt_scalef32_pk_f32_fp4 v[2:3], v154, 1.0 op_sel:[1,0,0]
	v_cvt_scalef32_pk_f32_fp4 v[4:5], v154, 1.0 op_sel:[0,1,0]
	v_cvt_scalef32_pk_f32_fp4 v[6:7], v154, 1.0 op_sel:[1,1,0]
	v_cvt_scalef32_pk_f32_fp4 v[8:9], v155, 1.0
	v_cvt_scalef32_pk_f32_fp4 v[10:11], v155, 1.0 op_sel:[1,0,0]
	v_cvt_scalef32_pk_f32_fp4 v[12:13], v155, 1.0 op_sel:[0,1,0]
	v_cvt_scalef32_pk_f32_fp4 v[14:15], v155, 1.0 op_sel:[1,1,0]
	v_readlane_b32 s54, v90, 37
	s_lshl_b32 s56, s54, 9
	s_add_u32 s56, s64, s56
	s_addc_u32 s57, s65, 0
	global_load_dwordx2 v[154:155], v227, s[56:57]
	v_pk_fma_f32 v[130:131], v[0:1], s[0:1], v[130:131] op_sel_hi:[1,0,1]
	v_pk_fma_f32 v[138:139], v[2:3], s[0:1], v[138:139] op_sel_hi:[1,0,1]
	v_pk_fma_f32 v[140:141], v[4:5], s[0:1], v[140:141] op_sel_hi:[1,0,1]
	v_pk_fma_f32 v[142:143], v[6:7], s[0:1], v[142:143] op_sel_hi:[1,0,1]
	v_pk_fma_f32 v[128:129], v[8:9], s[0:1], v[128:129] op_sel_hi:[1,0,1]
	v_pk_fma_f32 v[132:133], v[10:11], s[0:1], v[132:133] op_sel_hi:[1,0,1]
	v_pk_fma_f32 v[134:135], v[12:13], s[0:1], v[134:135] op_sel_hi:[1,0,1]
	v_pk_fma_f32 v[136:137], v[14:15], s[0:1], v[136:137] op_sel_hi:[1,0,1]
	v_readlane_b32 s0, v167, 22
	s_waitcnt vmcnt(15)
	v_cvt_scalef32_pk_f32_fp4 v[0:1], v156, 1.0
	v_cvt_scalef32_pk_f32_fp4 v[2:3], v156, 1.0 op_sel:[1,0,0]
	v_cvt_scalef32_pk_f32_fp4 v[4:5], v156, 1.0 op_sel:[0,1,0]
	v_cvt_scalef32_pk_f32_fp4 v[6:7], v156, 1.0 op_sel:[1,1,0]
	v_cvt_scalef32_pk_f32_fp4 v[8:9], v157, 1.0
	v_cvt_scalef32_pk_f32_fp4 v[10:11], v157, 1.0 op_sel:[1,0,0]
	v_cvt_scalef32_pk_f32_fp4 v[12:13], v157, 1.0 op_sel:[0,1,0]
	v_cvt_scalef32_pk_f32_fp4 v[14:15], v157, 1.0 op_sel:[1,1,0]
	v_readlane_b32 s54, v90, 38
	s_lshl_b32 s56, s54, 9
	s_add_u32 s56, s64, s56
	s_addc_u32 s57, s65, 0
	global_load_dwordx2 v[156:157], v227, s[56:57]
	v_pk_fma_f32 v[130:131], v[0:1], s[0:1], v[130:131] op_sel_hi:[1,0,1]
	v_pk_fma_f32 v[138:139], v[2:3], s[0:1], v[138:139] op_sel_hi:[1,0,1]
	v_pk_fma_f32 v[140:141], v[4:5], s[0:1], v[140:141] op_sel_hi:[1,0,1]
	v_pk_fma_f32 v[142:143], v[6:7], s[0:1], v[142:143] op_sel_hi:[1,0,1]
	v_pk_fma_f32 v[128:129], v[8:9], s[0:1], v[128:129] op_sel_hi:[1,0,1]
	v_pk_fma_f32 v[132:133], v[10:11], s[0:1], v[132:133] op_sel_hi:[1,0,1]
	v_pk_fma_f32 v[134:135], v[12:13], s[0:1], v[134:135] op_sel_hi:[1,0,1]
	v_pk_fma_f32 v[136:137], v[14:15], s[0:1], v[136:137] op_sel_hi:[1,0,1]
	v_readlane_b32 s0, v167, 23
	s_waitcnt vmcnt(15)
; __device__ void peer_gather_phase(const Params& P, int l, bool do_store) {
;     ...
;       for (int pr = 0; pr < 4; ++pr) {
;         const int ea = __builtin_amdgcn_readlane(evs, kb + 2 * pr), eb = __builtin_amdgcn_readlane(evs, kb + 2 * pr + 1);
;         const uint2* up = (const uint2*)(U + (size_t)(uphi ? eb : ea) * 768);
;         u6[3 * pr] = up[0]; u6[3 * pr + 1] = up[1]; u6[3 * pr + 2] = up[2];
;         v8[2 * pr] = *(const uint2*)(V + (size_t)ea * 512);
;         v8[2 * pr + 1] = *(const uint2*)(V + (size_t)eb * 512);
;     ...
; #pragma unroll
;       for (int j = 0; j < 8; ++j) {
;         const float a = __builtin_bit_cast(float, __builtin_amdgcn_readlane(__builtin_bit_cast(int, avec), kb + j));
;         const f32x2 aa = f32x2{a, a};
;         y[0] += aa * __builtin_amdgcn_cvt_scalef32_pk_f32_fp4(v8[j].x, 1.0f, 0); y[1] += aa * __builtin_amdgcn_cvt_scalef32_pk_f32_fp4(v8[j].x, 1.0f, 1);
;         y[2] += aa * __builtin_amdgcn_cvt_scalef32_pk_f32_fp4(v8[j].x, 1.0f, 2); y[3] += aa * __builtin_amdgcn_cvt_scalef32_pk_f32_fp4(v8[j].x, 1.0f, 3);
;         y[4] += aa * __builtin_amdgcn_cvt_scalef32_pk_f32_fp4(v8[j].y, 1.0f, 0); y[5] += aa * __builtin_amdgcn_cvt_scalef32_pk_f32_fp4(v8[j].y, 1.0f, 1);
;         y[6] += aa * __builtin_amdgcn_cvt_scalef32_pk_f32_fp4(v8[j].y, 1.0f, 2); y[7] += aa * __builtin_amdgcn_cvt_scalef32_pk_f32_fp4(v8[j].y, 1.0f, 3);
;       }
	v_cvt_scalef32_pk_f32_fp4 v[0:1], v158, 1.0
	v_cvt_scalef32_pk_f32_fp4 v[2:3], v158, 1.0 op_sel:[1,0,0]
	v_cvt_scalef32_pk_f32_fp4 v[4:5], v158, 1.0 op_sel:[0,1,0]
	v_cvt_scalef32_pk_f32_fp4 v[6:7], v158, 1.0 op_sel:[1,1,0]
	v_cvt_scalef32_pk_f32_fp4 v[8:9], v159, 1.0
	v_cvt_scalef32_pk_f32_fp4 v[10:11], v159, 1.0 op_sel:[1,0,0]
	v_cvt_scalef32_pk_f32_fp4 v[12:13], v159, 1.0 op_sel:[0,1,0]
	v_cvt_scalef32_pk_f32_fp4 v[14:15], v159, 1.0 op_sel:[1,1,0]
	v_readlane_b32 s54, v90, 39
	s_lshl_b32 s56, s54, 9
	s_add_u32 s56, s64, s56
	s_addc_u32 s57, s65, 0
	global_load_dwordx2 v[158:159], v227, s[56:57]
	v_pk_fma_f32 v[130:131], v[0:1], s[0:1], v[130:131] op_sel_hi:[1,0,1]
	v_pk_fma_f32 v[138:139], v[2:3], s[0:1], v[138:139] op_sel_hi:[1,0,1]
	v_pk_fma_f32 v[140:141], v[4:5], s[0:1], v[140:141] op_sel_hi:[1,0,1]
	v_pk_fma_f32 v[142:143], v[6:7], s[0:1], v[142:143] op_sel_hi:[1,0,1]
	v_pk_fma_f32 v[128:129], v[8:9], s[0:1], v[128:129] op_sel_hi:[1,0,1]
	v_pk_fma_f32 v[132:133], v[10:11], s[0:1], v[132:133] op_sel_hi:[1,0,1]
	v_pk_fma_f32 v[134:135], v[12:13], s[0:1], v[134:135] op_sel_hi:[1,0,1]
	v_pk_fma_f32 v[136:137], v[14:15], s[0:1], v[136:137] op_sel_hi:[1,0,1]
	v_readlane_b32 s0, v167, 24
	s_waitcnt vmcnt(15)
	v_cvt_scalef32_pk_f32_fp4 v[0:1], v168, 1.0
	v_cvt_scalef32_pk_f32_fp4 v[2:3], v168, 1.0 op_sel:[1,0,0]
	v_cvt_scalef32_pk_f32_fp4 v[4:5], v168, 1.0 op_sel:[0,1,0]
	v_cvt_scalef32_pk_f32_fp4 v[6:7], v168, 1.0 op_sel:[1,1,0]
	v_cvt_scalef32_pk_f32_fp4 v[8:9], v169, 1.0
	v_cvt_scalef32_pk_f32_fp4 v[10:11], v169, 1.0 op_sel:[1,0,0]
	v_cvt_scalef32_pk_f32_fp4 v[12:13], v169, 1.0 op_sel:[0,1,0]
	v_cvt_scalef32_pk_f32_fp4 v[14:15], v169, 1.0 op_sel:[1,1,0]
	v_readlane_b32 s54, v90, 40
	s_lshl_b32 s56, s54, 9
	s_add_u32 s56, s64, s56
	s_addc_u32 s57, s65, 0
	global_load_dwordx2 v[168:169], v227, s[56:57]
	v_pk_fma_f32 v[130:131], v[0:1], s[0:1], v[130:131] op_sel_hi:[1,0,1]
	v_pk_fma_f32 v[138:139], v[2:3], s[0:1], v[138:139] op_sel_hi:[1,0,1]
	v_pk_fma_f32 v[140:141], v[4:5], s[0:1], v[140:141] op_sel_hi:[1,0,1]
	v_pk_fma_f32 v[142:143], v[6:7], s[0:1], v[142:143] op_sel_hi:[1,0,1]
	v_pk_fma_f32 v[128:129], v[8:9], s[0:1], v[128:129] op_sel_hi:[1,0,1]
	v_pk_fma_f32 v[132:133], v[10:11], s[0:1], v[132:133] op_sel_hi:[1,0,1]
	v_pk_fma_f32 v[134:135], v[12:13], s[0:1], v[134:135] op_sel_hi:[1,0,1]
	v_pk_fma_f32 v[136:137], v[14:15], s[0:1], v[136:137] op_sel_hi:[1,0,1]
	v_readlane_b32 s0, v167, 25
	s_waitcnt vmcnt(15)
	v_cvt_scalef32_pk_f32_fp4 v[0:1], v170, 1.0
	v_cvt_scalef32_pk_f32_fp4 v[2:3], v170, 1.0 op_sel:[1,0,0]
	v_cvt_scalef32_pk_f32_fp4 v[4:5], v170, 1.0 op_sel:[0,1,0]
	v_cvt_scalef32_pk_f32_fp4 v[6:7], v170, 1.0 op_sel:[1,1,0]
	v_cvt_scalef32_pk_f32_fp4 v[8:9], v171, 1.0
	v_cvt_scalef32_pk_f32_fp4 v[10:11], v171, 1.0 op_sel:[1,0,0]
	v_cvt_scalef32_pk_f32_fp4 v[12:13], v171, 1.0 op_sel:[0,1,0]
	v_cvt_scalef32_pk_f32_fp4 v[14:15], v171, 1.0 op_sel:[1,1,0]
	v_readlane_b32 s54, v90, 41
	s_lshl_b32 s56, s54, 9
	s_add_u32 s56, s64, s56
	s_addc_u32 s57, s65, 0
	global_load_dwordx2 v[170:171], v227, s[56:57]
	v_pk_fma_f32 v[130:131], v[0:1], s[0:1], v[130:131] op_sel_hi:[1,0,1]
	v_pk_fma_f32 v[138:139], v[2:3], s[0:1], v[138:139] op_sel_hi:[1,0,1]
	v_pk_fma_f32 v[140:141], v[4:5], s[0:1], v[140:141] op_sel_hi:[1,0,1]
	v_pk_fma_f32 v[142:143], v[6:7], s[0:1], v[142:143] op_sel_hi:[1,0,1]
	v_pk_fma_f32 v[128:129], v[8:9], s[0:1], v[128:129] op_sel_hi:[1,0,1]
	v_pk_fma_f32 v[132:133], v[10:11], s[0:1], v[132:133] op_sel_hi:[1,0,1]
	v_pk_fma_f32 v[134:135], v[12:13], s[0:1], v[134:135] op_sel_hi:[1,0,1]
	v_pk_fma_f32 v[136:137], v[14:15], s[0:1], v[136:137] op_sel_hi:[1,0,1]
	v_readlane_b32 s0, v167, 26
	s_waitcnt vmcnt(15)
	v_cvt_scalef32_pk_f32_fp4 v[0:1], v172, 1.0
	v_cvt_scalef32_pk_f32_fp4 v[2:3], v172, 1.0 op_sel:[1,0,0]
	v_cvt_scalef32_pk_f32_fp4 v[4:5], v172, 1.0 op_sel:[0,1,0]
	v_cvt_scalef32_pk_f32_fp4 v[6:7], v172, 1.0 op_sel:[1,1,0]
	v_cvt_scalef32_pk_f32_fp4 v[8:9], v173, 1.0
	v_cvt_scalef32_pk_f32_fp4 v[10:11], v173, 1.0 op_sel:[1,0,0]
	v_cvt_scalef32_pk_f32_fp4 v[12:13], v173, 1.0 op_sel:[0,1,0]
	v_cvt_scalef32_pk_f32_fp4 v[14:15], v173, 1.0 op_sel:[1,1,0]
	v_readlane_b32 s54, v90, 42
	s_lshl_b32 s56, s54, 9
	s_add_u32 s56, s64, s56
	s_addc_u32 s57, s65, 0
	global_load_dwordx2 v[172:173], v227, s[56:57]
	v_pk_fma_f32 v[130:131], v[0:1], s[0:1], v[130:131] op_sel_hi:[1,0,1]
	v_pk_fma_f32 v[138:139], v[2:3], s[0:1], v[138:139] op_sel_hi:[1,0,1]
	v_pk_fma_f32 v[140:141], v[4:5], s[0:1], v[140:141] op_sel_hi:[1,0,1]
	v_pk_fma_f32 v[142:143], v[6:7], s[0:1], v[142:143] op_sel_hi:[1,0,1]
	v_pk_fma_f32 v[128:129], v[8:9], s[0:1], v[128:129] op_sel_hi:[1,0,1]
	v_pk_fma_f32 v[132:133], v[10:11], s[0:1], v[132:133] op_sel_hi:[1,0,1]
	v_pk_fma_f32 v[134:135], v[12:13], s[0:1], v[134:135] op_sel_hi:[1,0,1]
	v_pk_fma_f32 v[136:137], v[14:15], s[0:1], v[136:137] op_sel_hi:[1,0,1]
	v_readlane_b32 s0, v167, 27
	s_waitcnt vmcnt(15)
	v_cvt_scalef32_pk_f32_fp4 v[0:1], v174, 1.0
	v_cvt_scalef32_pk_f32_fp4 v[2:3], v174, 1.0 op_sel:[1,0,0]
	v_cvt_scalef32_pk_f32_fp4 v[4:5], v174, 1.0 op_sel:[0,1,0]
	v_cvt_scalef32_pk_f32_fp4 v[6:7], v174, 1.0 op_sel:[1,1,0]
	v_cvt_scalef32_pk_f32_fp4 v[8:9], v175, 1.0
	v_cvt_scalef32_pk_f32_fp4 v[10:11], v175, 1.0 op_sel:[1,0,0]
	v_cvt_scalef32_pk_f32_fp4 v[12:13], v175, 1.0 op_sel:[0,1,0]
	v_cvt_scalef32_pk_f32_fp4 v[14:15], v175, 1.0 op_sel:[1,1,0]
	v_readlane_b32 s54, v90, 43
	s_lshl_b32 s56, s54, 9
	s_add_u32 s56, s64, s56
	s_addc_u32 s57, s65, 0
	global_load_dwordx2 v[174:175], v227, s[56:57]
	v_pk_fma_f32 v[130:131], v[0:1], s[0:1], v[130:131] op_sel_hi:[1,0,1]
	v_pk_fma_f32 v[138:139], v[2:3], s[0:1], v[138:139] op_sel_hi:[1,0,1]
	v_pk_fma_f32 v[140:141], v[4:5], s[0:1], v[140:141] op_sel_hi:[1,0,1]
	v_pk_fma_f32 v[142:143], v[6:7], s[0:1], v[142:143] op_sel_hi:[1,0,1]
	v_pk_fma_f32 v[128:129], v[8:9], s[0:1], v[128:129] op_sel_hi:[1,0,1]
	v_pk_fma_f32 v[132:133], v[10:11], s[0:1], v[132:133] op_sel_hi:[1,0,1]
	v_pk_fma_f32 v[134:135], v[12:13], s[0:1], v[134:135] op_sel_hi:[1,0,1]
	v_pk_fma_f32 v[136:137], v[14:15], s[0:1], v[136:137] op_sel_hi:[1,0,1]
	v_readlane_b32 s0, v167, 28
	s_waitcnt vmcnt(15)
; __device__ void peer_gather_phase(const Params& P, int l, bool do_store) {
;     ...
;       for (int pr = 0; pr < 4; ++pr) {
;         const int ea = __builtin_amdgcn_readlane(evs, kb + 2 * pr), eb = __builtin_amdgcn_readlane(evs, kb + 2 * pr + 1);
;         const uint2* up = (const uint2*)(U + (size_t)(uphi ? eb : ea) * 768);
;         u6[3 * pr] = up[0]; u6[3 * pr + 1] = up[1]; u6[3 * pr + 2] = up[2];
;         v8[2 * pr] = *(const uint2*)(V + (size_t)ea * 512);
;         v8[2 * pr + 1] = *(const uint2*)(V + (size_t)eb * 512);
;     ...
; #pragma unroll
;       for (int j = 0; j < 8; ++j) {
;         const float a = __builtin_bit_cast(float, __builtin_amdgcn_readlane(__builtin_bit_cast(int, avec), kb + j));
;         const f32x2 aa = f32x2{a, a};
;         y[0] += aa * __builtin_amdgcn_cvt_scalef32_pk_f32_fp4(v8[j].x, 1.0f, 0); y[1] += aa * __builtin_amdgcn_cvt_scalef32_pk_f32_fp4(v8[j].x, 1.0f, 1);
;         y[2] += aa * __builtin_amdgcn_cvt_scalef32_pk_f32_fp4(v8[j].x, 1.0f, 2); y[3] += aa * __builtin_amdgcn_cvt_scalef32_pk_f32_fp4(v8[j].x, 1.0f, 3);
;         y[4] += aa * __builtin_amdgcn_cvt_scalef32_pk_f32_fp4(v8[j].y, 1.0f, 0); y[5] += aa * __builtin_amdgcn_cvt_scalef32_pk_f32_fp4(v8[j].y, 1.0f, 1);
;         y[6] += aa * __builtin_amdgcn_cvt_scalef32_pk_f32_fp4(v8[j].y, 1.0f, 2); y[7] += aa * __builtin_amdgcn_cvt_scalef32_pk_f32_fp4(v8[j].y, 1.0f, 3);
;       }
	v_cvt_scalef32_pk_f32_fp4 v[0:1], v180, 1.0
	v_cvt_scalef32_pk_f32_fp4 v[2:3], v180, 1.0 op_sel:[1,0,0]
	v_cvt_scalef32_pk_f32_fp4 v[4:5], v180, 1.0 op_sel:[0,1,0]
	v_cvt_scalef32_pk_f32_fp4 v[6:7], v180, 1.0 op_sel:[1,1,0]
	v_cvt_scalef32_pk_f32_fp4 v[8:9], v181, 1.0
	v_cvt_scalef32_pk_f32_fp4 v[10:11], v181, 1.0 op_sel:[1,0,0]
	v_cvt_scalef32_pk_f32_fp4 v[12:13], v181, 1.0 op_sel:[0,1,0]
	v_cvt_scalef32_pk_f32_fp4 v[14:15], v181, 1.0 op_sel:[1,1,0]
	v_readlane_b32 s54, v90, 44
	s_lshl_b32 s56, s54, 9
	s_add_u32 s56, s64, s56
	s_addc_u32 s57, s65, 0
	global_load_dwordx2 v[180:181], v227, s[56:57]
	v_pk_fma_f32 v[130:131], v[0:1], s[0:1], v[130:131] op_sel_hi:[1,0,1]
	v_pk_fma_f32 v[138:139], v[2:3], s[0:1], v[138:139] op_sel_hi:[1,0,1]
	v_pk_fma_f32 v[140:141], v[4:5], s[0:1], v[140:141] op_sel_hi:[1,0,1]
	v_pk_fma_f32 v[142:143], v[6:7], s[0:1], v[142:143] op_sel_hi:[1,0,1]
	v_pk_fma_f32 v[128:129], v[8:9], s[0:1], v[128:129] op_sel_hi:[1,0,1]
	v_pk_fma_f32 v[132:133], v[10:11], s[0:1], v[132:133] op_sel_hi:[1,0,1]
	v_pk_fma_f32 v[134:135], v[12:13], s[0:1], v[134:135] op_sel_hi:[1,0,1]
	v_pk_fma_f32 v[136:137], v[14:15], s[0:1], v[136:137] op_sel_hi:[1,0,1]
	v_readlane_b32 s0, v167, 29
	s_waitcnt vmcnt(15)
	v_cvt_scalef32_pk_f32_fp4 v[0:1], v182, 1.0
	v_cvt_scalef32_pk_f32_fp4 v[2:3], v182, 1.0 op_sel:[1,0,0]
	v_cvt_scalef32_pk_f32_fp4 v[4:5], v182, 1.0 op_sel:[0,1,0]
	v_cvt_scalef32_pk_f32_fp4 v[6:7], v182, 1.0 op_sel:[1,1,0]
	v_cvt_scalef32_pk_f32_fp4 v[8:9], v183, 1.0
	v_cvt_scalef32_pk_f32_fp4 v[10:11], v183, 1.0 op_sel:[1,0,0]
	v_cvt_scalef32_pk_f32_fp4 v[12:13], v183, 1.0 op_sel:[0,1,0]
	v_cvt_scalef32_pk_f32_fp4 v[14:15], v183, 1.0 op_sel:[1,1,0]
	v_readlane_b32 s54, v90, 45
	s_lshl_b32 s56, s54, 9
	s_add_u32 s56, s64, s56
	s_addc_u32 s57, s65, 0
	global_load_dwordx2 v[182:183], v227, s[56:57]
	v_pk_fma_f32 v[130:131], v[0:1], s[0:1], v[130:131] op_sel_hi:[1,0,1]
	v_pk_fma_f32 v[138:139], v[2:3], s[0:1], v[138:139] op_sel_hi:[1,0,1]
	v_pk_fma_f32 v[140:141], v[4:5], s[0:1], v[140:141] op_sel_hi:[1,0,1]
	v_pk_fma_f32 v[142:143], v[6:7], s[0:1], v[142:143] op_sel_hi:[1,0,1]
	v_pk_fma_f32 v[128:129], v[8:9], s[0:1], v[128:129] op_sel_hi:[1,0,1]
	v_pk_fma_f32 v[132:133], v[10:11], s[0:1], v[132:133] op_sel_hi:[1,0,1]
	v_pk_fma_f32 v[134:135], v[12:13], s[0:1], v[134:135] op_sel_hi:[1,0,1]
	v_pk_fma_f32 v[136:137], v[14:15], s[0:1], v[136:137] op_sel_hi:[1,0,1]
	v_readlane_b32 s0, v167, 30
	s_waitcnt vmcnt(15)
	v_cvt_scalef32_pk_f32_fp4 v[0:1], v184, 1.0
	v_cvt_scalef32_pk_f32_fp4 v[2:3], v184, 1.0 op_sel:[1,0,0]
	v_cvt_scalef32_pk_f32_fp4 v[4:5], v184, 1.0 op_sel:[0,1,0]
	v_cvt_scalef32_pk_f32_fp4 v[6:7], v184, 1.0 op_sel:[1,1,0]
	v_cvt_scalef32_pk_f32_fp4 v[8:9], v185, 1.0
	v_cvt_scalef32_pk_f32_fp4 v[10:11], v185, 1.0 op_sel:[1,0,0]
	v_cvt_scalef32_pk_f32_fp4 v[12:13], v185, 1.0 op_sel:[0,1,0]
	v_cvt_scalef32_pk_f32_fp4 v[14:15], v185, 1.0 op_sel:[1,1,0]
	v_readlane_b32 s54, v90, 46
	s_lshl_b32 s56, s54, 9
	s_add_u32 s56, s64, s56
	s_addc_u32 s57, s65, 0
	global_load_dwordx2 v[184:185], v227, s[56:57]
	v_pk_fma_f32 v[130:131], v[0:1], s[0:1], v[130:131] op_sel_hi:[1,0,1]
	v_pk_fma_f32 v[138:139], v[2:3], s[0:1], v[138:139] op_sel_hi:[1,0,1]
	v_pk_fma_f32 v[140:141], v[4:5], s[0:1], v[140:141] op_sel_hi:[1,0,1]
	v_pk_fma_f32 v[142:143], v[6:7], s[0:1], v[142:143] op_sel_hi:[1,0,1]
	v_pk_fma_f32 v[128:129], v[8:9], s[0:1], v[128:129] op_sel_hi:[1,0,1]
	v_pk_fma_f32 v[132:133], v[10:11], s[0:1], v[132:133] op_sel_hi:[1,0,1]
	v_pk_fma_f32 v[134:135], v[12:13], s[0:1], v[134:135] op_sel_hi:[1,0,1]
	v_pk_fma_f32 v[136:137], v[14:15], s[0:1], v[136:137] op_sel_hi:[1,0,1]
	v_readlane_b32 s0, v167, 31
	s_waitcnt vmcnt(15)
	v_cvt_scalef32_pk_f32_fp4 v[0:1], v186, 1.0
	v_cvt_scalef32_pk_f32_fp4 v[2:3], v186, 1.0 op_sel:[1,0,0]
	v_cvt_scalef32_pk_f32_fp4 v[4:5], v186, 1.0 op_sel:[0,1,0]
	v_cvt_scalef32_pk_f32_fp4 v[6:7], v186, 1.0 op_sel:[1,1,0]
	v_cvt_scalef32_pk_f32_fp4 v[8:9], v187, 1.0
	v_cvt_scalef32_pk_f32_fp4 v[10:11], v187, 1.0 op_sel:[1,0,0]
	v_cvt_scalef32_pk_f32_fp4 v[12:13], v187, 1.0 op_sel:[0,1,0]
	v_cvt_scalef32_pk_f32_fp4 v[14:15], v187, 1.0 op_sel:[1,1,0]
	v_readlane_b32 s54, v90, 47
	s_lshl_b32 s56, s54, 9
	s_add_u32 s56, s64, s56
	s_addc_u32 s57, s65, 0
	global_load_dwordx2 v[186:187], v227, s[56:57]
	v_pk_fma_f32 v[130:131], v[0:1], s[0:1], v[130:131] op_sel_hi:[1,0,1]
	v_pk_fma_f32 v[138:139], v[2:3], s[0:1], v[138:139] op_sel_hi:[1,0,1]
	v_pk_fma_f32 v[140:141], v[4:5], s[0:1], v[140:141] op_sel_hi:[1,0,1]
	v_pk_fma_f32 v[142:143], v[6:7], s[0:1], v[142:143] op_sel_hi:[1,0,1]
	v_pk_fma_f32 v[128:129], v[8:9], s[0:1], v[128:129] op_sel_hi:[1,0,1]
	v_pk_fma_f32 v[132:133], v[10:11], s[0:1], v[132:133] op_sel_hi:[1,0,1]
	v_pk_fma_f32 v[134:135], v[12:13], s[0:1], v[134:135] op_sel_hi:[1,0,1]
	v_pk_fma_f32 v[136:137], v[14:15], s[0:1], v[136:137] op_sel_hi:[1,0,1]
	v_readlane_b32 s0, v167, 32
	s_waitcnt vmcnt(15)
	v_cvt_scalef32_pk_f32_fp4 v[0:1], v144, 1.0
	v_cvt_scalef32_pk_f32_fp4 v[2:3], v144, 1.0 op_sel:[1,0,0]
	v_cvt_scalef32_pk_f32_fp4 v[4:5], v144, 1.0 op_sel:[0,1,0]
	v_cvt_scalef32_pk_f32_fp4 v[6:7], v144, 1.0 op_sel:[1,1,0]
	v_cvt_scalef32_pk_f32_fp4 v[8:9], v145, 1.0
	v_cvt_scalef32_pk_f32_fp4 v[10:11], v145, 1.0 op_sel:[1,0,0]
	v_cvt_scalef32_pk_f32_fp4 v[12:13], v145, 1.0 op_sel:[0,1,0]
	v_cvt_scalef32_pk_f32_fp4 v[14:15], v145, 1.0 op_sel:[1,1,0]
	v_readlane_b32 s54, v90, 48
	s_lshl_b32 s56, s54, 9
	s_add_u32 s56, s64, s56
	s_addc_u32 s57, s65, 0
	global_load_dwordx2 v[144:145], v227, s[56:57]
	v_pk_fma_f32 v[130:131], v[0:1], s[0:1], v[130:131] op_sel_hi:[1,0,1]
	v_pk_fma_f32 v[138:139], v[2:3], s[0:1], v[138:139] op_sel_hi:[1,0,1]
	v_pk_fma_f32 v[140:141], v[4:5], s[0:1], v[140:141] op_sel_hi:[1,0,1]
	v_pk_fma_f32 v[142:143], v[6:7], s[0:1], v[142:143] op_sel_hi:[1,0,1]
	v_pk_fma_f32 v[128:129], v[8:9], s[0:1], v[128:129] op_sel_hi:[1,0,1]
	v_pk_fma_f32 v[132:133], v[10:11], s[0:1], v[132:133] op_sel_hi:[1,0,1]
	v_pk_fma_f32 v[134:135], v[12:13], s[0:1], v[134:135] op_sel_hi:[1,0,1]
	v_pk_fma_f32 v[136:137], v[14:15], s[0:1], v[136:137] op_sel_hi:[1,0,1]
	v_readlane_b32 s0, v167, 33
	s_waitcnt vmcnt(15)
; __device__ void peer_gather_phase(const Params& P, int l, bool do_store) {
;     ...
;       for (int pr = 0; pr < 4; ++pr) {
;         const int ea = __builtin_amdgcn_readlane(evs, kb + 2 * pr), eb = __builtin_amdgcn_readlane(evs, kb + 2 * pr + 1);
;         const uint2* up = (const uint2*)(U + (size_t)(uphi ? eb : ea) * 768);
;         u6[3 * pr] = up[0]; u6[3 * pr + 1] = up[1]; u6[3 * pr + 2] = up[2];
;         v8[2 * pr] = *(const uint2*)(V + (size_t)ea * 512);
;         v8[2 * pr + 1] = *(const uint2*)(V + (size_t)eb * 512);
;     ...
; #pragma unroll
;       for (int j = 0; j < 8; ++j) {
;         const float a = __builtin_bit_cast(float, __builtin_amdgcn_readlane(__builtin_bit_cast(int, avec), kb + j));
;         const f32x2 aa = f32x2{a, a};
;         y[0] += aa * __builtin_amdgcn_cvt_scalef32_pk_f32_fp4(v8[j].x, 1.0f, 0); y[1] += aa * __builtin_amdgcn_cvt_scalef32_pk_f32_fp4(v8[j].x, 1.0f, 1);
;         y[2] += aa * __builtin_amdgcn_cvt_scalef32_pk_f32_fp4(v8[j].x, 1.0f, 2); y[3] += aa * __builtin_amdgcn_cvt_scalef32_pk_f32_fp4(v8[j].x, 1.0f, 3);
;         y[4] += aa * __builtin_amdgcn_cvt_scalef32_pk_f32_fp4(v8[j].y, 1.0f, 0); y[5] += aa * __builtin_amdgcn_cvt_scalef32_pk_f32_fp4(v8[j].y, 1.0f, 1);
;         y[6] += aa * __builtin_amdgcn_cvt_scalef32_pk_f32_fp4(v8[j].y, 1.0f, 2); y[7] += aa * __builtin_amdgcn_cvt_scalef32_pk_f32_fp4(v8[j].y, 1.0f, 3);
;       }
	v_cvt_scalef32_pk_f32_fp4 v[0:1], v146, 1.0
	v_cvt_scalef32_pk_f32_fp4 v[2:3], v146, 1.0 op_sel:[1,0,0]
	v_cvt_scalef32_pk_f32_fp4 v[4:5], v146, 1.0 op_sel:[0,1,0]
	v_cvt_scalef32_pk_f32_fp4 v[6:7], v146, 1.0 op_sel:[1,1,0]
	v_cvt_scalef32_pk_f32_fp4 v[8:9], v147, 1.0
	v_cvt_scalef32_pk_f32_fp4 v[10:11], v147, 1.0 op_sel:[1,0,0]
	v_cvt_scalef32_pk_f32_fp4 v[12:13], v147, 1.0 op_sel:[0,1,0]
	v_cvt_scalef32_pk_f32_fp4 v[14:15], v147, 1.0 op_sel:[1,1,0]
	v_readlane_b32 s54, v90, 49
	s_lshl_b32 s56, s54, 9
	s_add_u32 s56, s64, s56
	s_addc_u32 s57, s65, 0
	global_load_dwordx2 v[146:147], v227, s[56:57]
	v_pk_fma_f32 v[130:131], v[0:1], s[0:1], v[130:131] op_sel_hi:[1,0,1]
	v_pk_fma_f32 v[138:139], v[2:3], s[0:1], v[138:139] op_sel_hi:[1,0,1]
	v_pk_fma_f32 v[140:141], v[4:5], s[0:1], v[140:141] op_sel_hi:[1,0,1]
	v_pk_fma_f32 v[142:143], v[6:7], s[0:1], v[142:143] op_sel_hi:[1,0,1]
	v_pk_fma_f32 v[128:129], v[8:9], s[0:1], v[128:129] op_sel_hi:[1,0,1]
	v_pk_fma_f32 v[132:133], v[10:11], s[0:1], v[132:133] op_sel_hi:[1,0,1]
	v_pk_fma_f32 v[134:135], v[12:13], s[0:1], v[134:135] op_sel_hi:[1,0,1]
	v_pk_fma_f32 v[136:137], v[14:15], s[0:1], v[136:137] op_sel_hi:[1,0,1]
	v_readlane_b32 s0, v167, 34
	s_waitcnt vmcnt(15)
	v_cvt_scalef32_pk_f32_fp4 v[0:1], v148, 1.0
	v_cvt_scalef32_pk_f32_fp4 v[2:3], v148, 1.0 op_sel:[1,0,0]
	v_cvt_scalef32_pk_f32_fp4 v[4:5], v148, 1.0 op_sel:[0,1,0]
	v_cvt_scalef32_pk_f32_fp4 v[6:7], v148, 1.0 op_sel:[1,1,0]
	v_cvt_scalef32_pk_f32_fp4 v[8:9], v149, 1.0
	v_cvt_scalef32_pk_f32_fp4 v[10:11], v149, 1.0 op_sel:[1,0,0]
	v_cvt_scalef32_pk_f32_fp4 v[12:13], v149, 1.0 op_sel:[0,1,0]
	v_cvt_scalef32_pk_f32_fp4 v[14:15], v149, 1.0 op_sel:[1,1,0]
	v_readlane_b32 s54, v90, 50
	s_lshl_b32 s56, s54, 9
	s_add_u32 s56, s64, s56
	s_addc_u32 s57, s65, 0
	global_load_dwordx2 v[148:149], v227, s[56:57]
	v_pk_fma_f32 v[130:131], v[0:1], s[0:1], v[130:131] op_sel_hi:[1,0,1]
	v_pk_fma_f32 v[138:139], v[2:3], s[0:1], v[138:139] op_sel_hi:[1,0,1]
	v_pk_fma_f32 v[140:141], v[4:5], s[0:1], v[140:141] op_sel_hi:[1,0,1]
	v_pk_fma_f32 v[142:143], v[6:7], s[0:1], v[142:143] op_sel_hi:[1,0,1]
	v_pk_fma_f32 v[128:129], v[8:9], s[0:1], v[128:129] op_sel_hi:[1,0,1]
	v_pk_fma_f32 v[132:133], v[10:11], s[0:1], v[132:133] op_sel_hi:[1,0,1]
	v_pk_fma_f32 v[134:135], v[12:13], s[0:1], v[134:135] op_sel_hi:[1,0,1]
	v_pk_fma_f32 v[136:137], v[14:15], s[0:1], v[136:137] op_sel_hi:[1,0,1]
	v_readlane_b32 s0, v167, 35
	s_waitcnt vmcnt(15)
	v_cvt_scalef32_pk_f32_fp4 v[0:1], v150, 1.0
	v_cvt_scalef32_pk_f32_fp4 v[2:3], v150, 1.0 op_sel:[1,0,0]
	v_cvt_scalef32_pk_f32_fp4 v[4:5], v150, 1.0 op_sel:[0,1,0]
	v_cvt_scalef32_pk_f32_fp4 v[6:7], v150, 1.0 op_sel:[1,1,0]
	v_cvt_scalef32_pk_f32_fp4 v[8:9], v151, 1.0
	v_cvt_scalef32_pk_f32_fp4 v[10:11], v151, 1.0 op_sel:[1,0,0]
	v_cvt_scalef32_pk_f32_fp4 v[12:13], v151, 1.0 op_sel:[0,1,0]
	v_cvt_scalef32_pk_f32_fp4 v[14:15], v151, 1.0 op_sel:[1,1,0]
	v_readlane_b32 s54, v90, 51
	s_lshl_b32 s56, s54, 9
	s_add_u32 s56, s64, s56
	s_addc_u32 s57, s65, 0
	global_load_dwordx2 v[150:151], v227, s[56:57]
	v_pk_fma_f32 v[130:131], v[0:1], s[0:1], v[130:131] op_sel_hi:[1,0,1]
	v_pk_fma_f32 v[138:139], v[2:3], s[0:1], v[138:139] op_sel_hi:[1,0,1]
	v_pk_fma_f32 v[140:141], v[4:5], s[0:1], v[140:141] op_sel_hi:[1,0,1]
	v_pk_fma_f32 v[142:143], v[6:7], s[0:1], v[142:143] op_sel_hi:[1,0,1]
	v_pk_fma_f32 v[128:129], v[8:9], s[0:1], v[128:129] op_sel_hi:[1,0,1]
	v_pk_fma_f32 v[132:133], v[10:11], s[0:1], v[132:133] op_sel_hi:[1,0,1]
	v_pk_fma_f32 v[134:135], v[12:13], s[0:1], v[134:135] op_sel_hi:[1,0,1]
	v_pk_fma_f32 v[136:137], v[14:15], s[0:1], v[136:137] op_sel_hi:[1,0,1]
	v_readlane_b32 s0, v167, 36
	s_waitcnt vmcnt(15)
	v_cvt_scalef32_pk_f32_fp4 v[0:1], v152, 1.0
	v_cvt_scalef32_pk_f32_fp4 v[2:3], v152, 1.0 op_sel:[1,0,0]
	v_cvt_scalef32_pk_f32_fp4 v[4:5], v152, 1.0 op_sel:[0,1,0]
	v_cvt_scalef32_pk_f32_fp4 v[6:7], v152, 1.0 op_sel:[1,1,0]
	v_cvt_scalef32_pk_f32_fp4 v[8:9], v153, 1.0
	v_cvt_scalef32_pk_f32_fp4 v[10:11], v153, 1.0 op_sel:[1,0,0]
	v_cvt_scalef32_pk_f32_fp4 v[12:13], v153, 1.0 op_sel:[0,1,0]
	v_cvt_scalef32_pk_f32_fp4 v[14:15], v153, 1.0 op_sel:[1,1,0]
	v_readlane_b32 s54, v90, 52
	s_lshl_b32 s56, s54, 9
	s_add_u32 s56, s64, s56
	s_addc_u32 s57, s65, 0
	global_load_dwordx2 v[152:153], v227, s[56:57]
	v_pk_fma_f32 v[130:131], v[0:1], s[0:1], v[130:131] op_sel_hi:[1,0,1]
	v_pk_fma_f32 v[138:139], v[2:3], s[0:1], v[138:139] op_sel_hi:[1,0,1]
	v_pk_fma_f32 v[140:141], v[4:5], s[0:1], v[140:141] op_sel_hi:[1,0,1]
	v_pk_fma_f32 v[142:143], v[6:7], s[0:1], v[142:143] op_sel_hi:[1,0,1]
	v_pk_fma_f32 v[128:129], v[8:9], s[0:1], v[128:129] op_sel_hi:[1,0,1]
	v_pk_fma_f32 v[132:133], v[10:11], s[0:1], v[132:133] op_sel_hi:[1,0,1]
	v_pk_fma_f32 v[134:135], v[12:13], s[0:1], v[134:135] op_sel_hi:[1,0,1]
	v_pk_fma_f32 v[136:137], v[14:15], s[0:1], v[136:137] op_sel_hi:[1,0,1]
	v_readlane_b32 s0, v167, 37
	s_waitcnt vmcnt(15)
	v_cvt_scalef32_pk_f32_fp4 v[0:1], v154, 1.0
	v_cvt_scalef32_pk_f32_fp4 v[2:3], v154, 1.0 op_sel:[1,0,0]
	v_cvt_scalef32_pk_f32_fp4 v[4:5], v154, 1.0 op_sel:[0,1,0]
	v_cvt_scalef32_pk_f32_fp4 v[6:7], v154, 1.0 op_sel:[1,1,0]
	v_cvt_scalef32_pk_f32_fp4 v[8:9], v155, 1.0
	v_cvt_scalef32_pk_f32_fp4 v[10:11], v155, 1.0 op_sel:[1,0,0]
	v_cvt_scalef32_pk_f32_fp4 v[12:13], v155, 1.0 op_sel:[0,1,0]
	v_cvt_scalef32_pk_f32_fp4 v[14:15], v155, 1.0 op_sel:[1,1,0]
	v_readlane_b32 s54, v90, 53
	s_lshl_b32 s56, s54, 9
	s_add_u32 s56, s64, s56
	s_addc_u32 s57, s65, 0
	global_load_dwordx2 v[154:155], v227, s[56:57]
	v_pk_fma_f32 v[130:131], v[0:1], s[0:1], v[130:131] op_sel_hi:[1,0,1]
	v_pk_fma_f32 v[138:139], v[2:3], s[0:1], v[138:139] op_sel_hi:[1,0,1]
	v_pk_fma_f32 v[140:141], v[4:5], s[0:1], v[140:141] op_sel_hi:[1,0,1]
	v_pk_fma_f32 v[142:143], v[6:7], s[0:1], v[142:143] op_sel_hi:[1,0,1]
	v_pk_fma_f32 v[128:129], v[8:9], s[0:1], v[128:129] op_sel_hi:[1,0,1]
	v_pk_fma_f32 v[132:133], v[10:11], s[0:1], v[132:133] op_sel_hi:[1,0,1]
	v_pk_fma_f32 v[134:135], v[12:13], s[0:1], v[134:135] op_sel_hi:[1,0,1]
	v_pk_fma_f32 v[136:137], v[14:15], s[0:1], v[136:137] op_sel_hi:[1,0,1]
	v_readlane_b32 s0, v167, 38
	s_waitcnt vmcnt(15)
; __device__ void peer_gather_phase(const Params& P, int l, bool do_store) {
;     ...
;       for (int pr = 0; pr < 4; ++pr) {
;         const int ea = __builtin_amdgcn_readlane(evs, kb + 2 * pr), eb = __builtin_amdgcn_readlane(evs, kb + 2 * pr + 1);
;         const uint2* up = (const uint2*)(U + (size_t)(uphi ? eb : ea) * 768);
;         u6[3 * pr] = up[0]; u6[3 * pr + 1] = up[1]; u6[3 * pr + 2] = up[2];
;         v8[2 * pr] = *(const uint2*)(V + (size_t)ea * 512);
;         v8[2 * pr + 1] = *(const uint2*)(V + (size_t)eb * 512);
;     ...
; #pragma unroll
;       for (int j = 0; j < 8; ++j) {
;         const float a = __builtin_bit_cast(float, __builtin_amdgcn_readlane(__builtin_bit_cast(int, avec), kb + j));
;         const f32x2 aa = f32x2{a, a};
;         y[0] += aa * __builtin_amdgcn_cvt_scalef32_pk_f32_fp4(v8[j].x, 1.0f, 0); y[1] += aa * __builtin_amdgcn_cvt_scalef32_pk_f32_fp4(v8[j].x, 1.0f, 1);
;         y[2] += aa * __builtin_amdgcn_cvt_scalef32_pk_f32_fp4(v8[j].x, 1.0f, 2); y[3] += aa * __builtin_amdgcn_cvt_scalef32_pk_f32_fp4(v8[j].x, 1.0f, 3);
;         y[4] += aa * __builtin_amdgcn_cvt_scalef32_pk_f32_fp4(v8[j].y, 1.0f, 0); y[5] += aa * __builtin_amdgcn_cvt_scalef32_pk_f32_fp4(v8[j].y, 1.0f, 1);
;         y[6] += aa * __builtin_amdgcn_cvt_scalef32_pk_f32_fp4(v8[j].y, 1.0f, 2); y[7] += aa * __builtin_amdgcn_cvt_scalef32_pk_f32_fp4(v8[j].y, 1.0f, 3);
;       }
	v_cvt_scalef32_pk_f32_fp4 v[0:1], v156, 1.0
	v_cvt_scalef32_pk_f32_fp4 v[2:3], v156, 1.0 op_sel:[1,0,0]
	v_cvt_scalef32_pk_f32_fp4 v[4:5], v156, 1.0 op_sel:[0,1,0]
	v_cvt_scalef32_pk_f32_fp4 v[6:7], v156, 1.0 op_sel:[1,1,0]
	v_cvt_scalef32_pk_f32_fp4 v[8:9], v157, 1.0
	v_cvt_scalef32_pk_f32_fp4 v[10:11], v157, 1.0 op_sel:[1,0,0]
	v_cvt_scalef32_pk_f32_fp4 v[12:13], v157, 1.0 op_sel:[0,1,0]
	v_cvt_scalef32_pk_f32_fp4 v[14:15], v157, 1.0 op_sel:[1,1,0]
	v_readlane_b32 s54, v90, 54
	s_lshl_b32 s56, s54, 9
	s_add_u32 s56, s64, s56
	s_addc_u32 s57, s65, 0
	global_load_dwordx2 v[156:157], v227, s[56:57]
	v_pk_fma_f32 v[130:131], v[0:1], s[0:1], v[130:131] op_sel_hi:[1,0,1]
	v_pk_fma_f32 v[138:139], v[2:3], s[0:1], v[138:139] op_sel_hi:[1,0,1]
	v_pk_fma_f32 v[140:141], v[4:5], s[0:1], v[140:141] op_sel_hi:[1,0,1]
	v_pk_fma_f32 v[142:143], v[6:7], s[0:1], v[142:143] op_sel_hi:[1,0,1]
	v_pk_fma_f32 v[128:129], v[8:9], s[0:1], v[128:129] op_sel_hi:[1,0,1]
	v_pk_fma_f32 v[132:133], v[10:11], s[0:1], v[132:133] op_sel_hi:[1,0,1]
	v_pk_fma_f32 v[134:135], v[12:13], s[0:1], v[134:135] op_sel_hi:[1,0,1]
	v_pk_fma_f32 v[136:137], v[14:15], s[0:1], v[136:137] op_sel_hi:[1,0,1]
	v_readlane_b32 s0, v167, 39
	s_waitcnt vmcnt(15)
	v_cvt_scalef32_pk_f32_fp4 v[0:1], v158, 1.0
	v_cvt_scalef32_pk_f32_fp4 v[2:3], v158, 1.0 op_sel:[1,0,0]
	v_cvt_scalef32_pk_f32_fp4 v[4:5], v158, 1.0 op_sel:[0,1,0]
	v_cvt_scalef32_pk_f32_fp4 v[6:7], v158, 1.0 op_sel:[1,1,0]
	v_cvt_scalef32_pk_f32_fp4 v[8:9], v159, 1.0
	v_cvt_scalef32_pk_f32_fp4 v[10:11], v159, 1.0 op_sel:[1,0,0]
	v_cvt_scalef32_pk_f32_fp4 v[12:13], v159, 1.0 op_sel:[0,1,0]
	v_cvt_scalef32_pk_f32_fp4 v[14:15], v159, 1.0 op_sel:[1,1,0]
	v_readlane_b32 s54, v90, 55
	s_lshl_b32 s56, s54, 9
	s_add_u32 s56, s64, s56
	s_addc_u32 s57, s65, 0
	global_load_dwordx2 v[158:159], v227, s[56:57]
	v_pk_fma_f32 v[130:131], v[0:1], s[0:1], v[130:131] op_sel_hi:[1,0,1]
	v_pk_fma_f32 v[138:139], v[2:3], s[0:1], v[138:139] op_sel_hi:[1,0,1]
	v_pk_fma_f32 v[140:141], v[4:5], s[0:1], v[140:141] op_sel_hi:[1,0,1]
	v_pk_fma_f32 v[142:143], v[6:7], s[0:1], v[142:143] op_sel_hi:[1,0,1]
	v_pk_fma_f32 v[128:129], v[8:9], s[0:1], v[128:129] op_sel_hi:[1,0,1]
	v_pk_fma_f32 v[132:133], v[10:11], s[0:1], v[132:133] op_sel_hi:[1,0,1]
	v_pk_fma_f32 v[134:135], v[12:13], s[0:1], v[134:135] op_sel_hi:[1,0,1]
	v_pk_fma_f32 v[136:137], v[14:15], s[0:1], v[136:137] op_sel_hi:[1,0,1]
	v_readlane_b32 s0, v167, 40
	s_waitcnt vmcnt(15)
	v_cvt_scalef32_pk_f32_fp4 v[0:1], v168, 1.0
	v_cvt_scalef32_pk_f32_fp4 v[2:3], v168, 1.0 op_sel:[1,0,0]
	v_cvt_scalef32_pk_f32_fp4 v[4:5], v168, 1.0 op_sel:[0,1,0]
	v_cvt_scalef32_pk_f32_fp4 v[6:7], v168, 1.0 op_sel:[1,1,0]
	v_cvt_scalef32_pk_f32_fp4 v[8:9], v169, 1.0
	v_cvt_scalef32_pk_f32_fp4 v[10:11], v169, 1.0 op_sel:[1,0,0]
	v_cvt_scalef32_pk_f32_fp4 v[12:13], v169, 1.0 op_sel:[0,1,0]
	v_cvt_scalef32_pk_f32_fp4 v[14:15], v169, 1.0 op_sel:[1,1,0]
	v_readlane_b32 s54, v90, 56
	s_lshl_b32 s56, s54, 9
	s_add_u32 s56, s64, s56
	s_addc_u32 s57, s65, 0
	global_load_dwordx2 v[168:169], v227, s[56:57]
	v_pk_fma_f32 v[130:131], v[0:1], s[0:1], v[130:131] op_sel_hi:[1,0,1]
	v_pk_fma_f32 v[138:139], v[2:3], s[0:1], v[138:139] op_sel_hi:[1,0,1]
	v_pk_fma_f32 v[140:141], v[4:5], s[0:1], v[140:141] op_sel_hi:[1,0,1]
	v_pk_fma_f32 v[142:143], v[6:7], s[0:1], v[142:143] op_sel_hi:[1,0,1]
	v_pk_fma_f32 v[128:129], v[8:9], s[0:1], v[128:129] op_sel_hi:[1,0,1]
	v_pk_fma_f32 v[132:133], v[10:11], s[0:1], v[132:133] op_sel_hi:[1,0,1]
	v_pk_fma_f32 v[134:135], v[12:13], s[0:1], v[134:135] op_sel_hi:[1,0,1]
	v_pk_fma_f32 v[136:137], v[14:15], s[0:1], v[136:137] op_sel_hi:[1,0,1]
	v_readlane_b32 s0, v167, 41
	s_waitcnt vmcnt(15)
	v_cvt_scalef32_pk_f32_fp4 v[0:1], v170, 1.0
	v_cvt_scalef32_pk_f32_fp4 v[2:3], v170, 1.0 op_sel:[1,0,0]
	v_cvt_scalef32_pk_f32_fp4 v[4:5], v170, 1.0 op_sel:[0,1,0]
	v_cvt_scalef32_pk_f32_fp4 v[6:7], v170, 1.0 op_sel:[1,1,0]
	v_cvt_scalef32_pk_f32_fp4 v[8:9], v171, 1.0
	v_cvt_scalef32_pk_f32_fp4 v[10:11], v171, 1.0 op_sel:[1,0,0]
	v_cvt_scalef32_pk_f32_fp4 v[12:13], v171, 1.0 op_sel:[0,1,0]
	v_cvt_scalef32_pk_f32_fp4 v[14:15], v171, 1.0 op_sel:[1,1,0]
	v_readlane_b32 s54, v90, 57
	s_lshl_b32 s56, s54, 9
	s_add_u32 s56, s64, s56
	s_addc_u32 s57, s65, 0
	global_load_dwordx2 v[170:171], v227, s[56:57]
	v_pk_fma_f32 v[130:131], v[0:1], s[0:1], v[130:131] op_sel_hi:[1,0,1]
	v_pk_fma_f32 v[138:139], v[2:3], s[0:1], v[138:139] op_sel_hi:[1,0,1]
	v_pk_fma_f32 v[140:141], v[4:5], s[0:1], v[140:141] op_sel_hi:[1,0,1]
	v_pk_fma_f32 v[142:143], v[6:7], s[0:1], v[142:143] op_sel_hi:[1,0,1]
	v_pk_fma_f32 v[128:129], v[8:9], s[0:1], v[128:129] op_sel_hi:[1,0,1]
	v_pk_fma_f32 v[132:133], v[10:11], s[0:1], v[132:133] op_sel_hi:[1,0,1]
	v_pk_fma_f32 v[134:135], v[12:13], s[0:1], v[134:135] op_sel_hi:[1,0,1]
	v_pk_fma_f32 v[136:137], v[14:15], s[0:1], v[136:137] op_sel_hi:[1,0,1]
	v_readlane_b32 s0, v167, 42
	s_waitcnt vmcnt(15)
	v_cvt_scalef32_pk_f32_fp4 v[0:1], v172, 1.0
	v_cvt_scalef32_pk_f32_fp4 v[2:3], v172, 1.0 op_sel:[1,0,0]
	v_cvt_scalef32_pk_f32_fp4 v[4:5], v172, 1.0 op_sel:[0,1,0]
	v_cvt_scalef32_pk_f32_fp4 v[6:7], v172, 1.0 op_sel:[1,1,0]
	v_cvt_scalef32_pk_f32_fp4 v[8:9], v173, 1.0
	v_cvt_scalef32_pk_f32_fp4 v[10:11], v173, 1.0 op_sel:[1,0,0]
	v_cvt_scalef32_pk_f32_fp4 v[12:13], v173, 1.0 op_sel:[0,1,0]
	v_cvt_scalef32_pk_f32_fp4 v[14:15], v173, 1.0 op_sel:[1,1,0]
	v_readlane_b32 s54, v90, 58
	s_lshl_b32 s56, s54, 9
	s_add_u32 s56, s64, s56
	s_addc_u32 s57, s65, 0
	global_load_dwordx2 v[172:173], v227, s[56:57]
	v_pk_fma_f32 v[130:131], v[0:1], s[0:1], v[130:131] op_sel_hi:[1,0,1]
	v_pk_fma_f32 v[138:139], v[2:3], s[0:1], v[138:139] op_sel_hi:[1,0,1]
	v_pk_fma_f32 v[140:141], v[4:5], s[0:1], v[140:141] op_sel_hi:[1,0,1]
	v_pk_fma_f32 v[142:143], v[6:7], s[0:1], v[142:143] op_sel_hi:[1,0,1]
	v_pk_fma_f32 v[128:129], v[8:9], s[0:1], v[128:129] op_sel_hi:[1,0,1]
	v_pk_fma_f32 v[132:133], v[10:11], s[0:1], v[132:133] op_sel_hi:[1,0,1]
	v_pk_fma_f32 v[134:135], v[12:13], s[0:1], v[134:135] op_sel_hi:[1,0,1]
	v_pk_fma_f32 v[136:137], v[14:15], s[0:1], v[136:137] op_sel_hi:[1,0,1]
	v_readlane_b32 s0, v167, 43
	s_waitcnt vmcnt(15)
; __device__ void peer_gather_phase(const Params& P, int l, bool do_store) {
;     ...
;         v8[2 * pr] = *(const uint2*)(V + (size_t)ea * 512);
;         v8[2 * pr + 1] = *(const uint2*)(V + (size_t)eb * 512);
;     ...
; #pragma unroll
;       for (int j = 0; j < 8; ++j) {
;         const float a = __builtin_bit_cast(float, __builtin_amdgcn_readlane(__builtin_bit_cast(int, avec), kb + j));
;         const f32x2 aa = f32x2{a, a};
;         y[0] += aa * __builtin_amdgcn_cvt_scalef32_pk_f32_fp4(v8[j].x, 1.0f, 0); y[1] += aa * __builtin_amdgcn_cvt_scalef32_pk_f32_fp4(v8[j].x, 1.0f, 1);
;         y[2] += aa * __builtin_amdgcn_cvt_scalef32_pk_f32_fp4(v8[j].x, 1.0f, 2); y[3] += aa * __builtin_amdgcn_cvt_scalef32_pk_f32_fp4(v8[j].x, 1.0f, 3);
;         y[4] += aa * __builtin_amdgcn_cvt_scalef32_pk_f32_fp4(v8[j].y, 1.0f, 0); y[5] += aa * __builtin_amdgcn_cvt_scalef32_pk_f32_fp4(v8[j].y, 1.0f, 1);
;         y[6] += aa * __builtin_amdgcn_cvt_scalef32_pk_f32_fp4(v8[j].y, 1.0f, 2); y[7] += aa * __builtin_amdgcn_cvt_scalef32_pk_f32_fp4(v8[j].y, 1.0f, 3);
;       }
	v_cvt_scalef32_pk_f32_fp4 v[0:1], v174, 1.0
	v_cvt_scalef32_pk_f32_fp4 v[2:3], v174, 1.0 op_sel:[1,0,0]
	v_cvt_scalef32_pk_f32_fp4 v[4:5], v174, 1.0 op_sel:[0,1,0]
	v_cvt_scalef32_pk_f32_fp4 v[6:7], v174, 1.0 op_sel:[1,1,0]
	v_cvt_scalef32_pk_f32_fp4 v[8:9], v175, 1.0
	v_cvt_scalef32_pk_f32_fp4 v[10:11], v175, 1.0 op_sel:[1,0,0]
	v_cvt_scalef32_pk_f32_fp4 v[12:13], v175, 1.0 op_sel:[0,1,0]
	v_cvt_scalef32_pk_f32_fp4 v[14:15], v175, 1.0 op_sel:[1,1,0]
	v_readlane_b32 s54, v90, 59
	s_lshl_b32 s56, s54, 9
	s_add_u32 s56, s64, s56
	s_addc_u32 s57, s65, 0
	global_load_dwordx2 v[174:175], v227, s[56:57]
	v_pk_fma_f32 v[130:131], v[0:1], s[0:1], v[130:131] op_sel_hi:[1,0,1]
	v_pk_fma_f32 v[138:139], v[2:3], s[0:1], v[138:139] op_sel_hi:[1,0,1]
	v_pk_fma_f32 v[140:141], v[4:5], s[0:1], v[140:141] op_sel_hi:[1,0,1]
	v_pk_fma_f32 v[142:143], v[6:7], s[0:1], v[142:143] op_sel_hi:[1,0,1]
	v_pk_fma_f32 v[128:129], v[8:9], s[0:1], v[128:129] op_sel_hi:[1,0,1]
	v_pk_fma_f32 v[132:133], v[10:11], s[0:1], v[132:133] op_sel_hi:[1,0,1]
	v_pk_fma_f32 v[134:135], v[12:13], s[0:1], v[134:135] op_sel_hi:[1,0,1]
	v_pk_fma_f32 v[136:137], v[14:15], s[0:1], v[136:137] op_sel_hi:[1,0,1]
	v_readlane_b32 s0, v167, 44
	s_waitcnt vmcnt(15)
	v_cvt_scalef32_pk_f32_fp4 v[0:1], v180, 1.0
	v_cvt_scalef32_pk_f32_fp4 v[2:3], v180, 1.0 op_sel:[1,0,0]
	v_cvt_scalef32_pk_f32_fp4 v[4:5], v180, 1.0 op_sel:[0,1,0]
	v_cvt_scalef32_pk_f32_fp4 v[6:7], v180, 1.0 op_sel:[1,1,0]
	v_cvt_scalef32_pk_f32_fp4 v[8:9], v181, 1.0
	v_cvt_scalef32_pk_f32_fp4 v[10:11], v181, 1.0 op_sel:[1,0,0]
	v_cvt_scalef32_pk_f32_fp4 v[12:13], v181, 1.0 op_sel:[0,1,0]
	v_cvt_scalef32_pk_f32_fp4 v[14:15], v181, 1.0 op_sel:[1,1,0]
	v_readlane_b32 s54, v90, 60
	s_lshl_b32 s56, s54, 9
	s_add_u32 s56, s64, s56
	s_addc_u32 s57, s65, 0
	global_load_dwordx2 v[180:181], v227, s[56:57]
	v_pk_fma_f32 v[130:131], v[0:1], s[0:1], v[130:131] op_sel_hi:[1,0,1]
	v_pk_fma_f32 v[138:139], v[2:3], s[0:1], v[138:139] op_sel_hi:[1,0,1]
	v_pk_fma_f32 v[140:141], v[4:5], s[0:1], v[140:141] op_sel_hi:[1,0,1]
	v_pk_fma_f32 v[142:143], v[6:7], s[0:1], v[142:143] op_sel_hi:[1,0,1]
	v_pk_fma_f32 v[128:129], v[8:9], s[0:1], v[128:129] op_sel_hi:[1,0,1]
	v_pk_fma_f32 v[132:133], v[10:11], s[0:1], v[132:133] op_sel_hi:[1,0,1]
	v_pk_fma_f32 v[134:135], v[12:13], s[0:1], v[134:135] op_sel_hi:[1,0,1]
	v_pk_fma_f32 v[136:137], v[14:15], s[0:1], v[136:137] op_sel_hi:[1,0,1]
	v_readlane_b32 s0, v167, 45
	s_waitcnt vmcnt(15)
	v_cvt_scalef32_pk_f32_fp4 v[0:1], v182, 1.0
	v_cvt_scalef32_pk_f32_fp4 v[2:3], v182, 1.0 op_sel:[1,0,0]
	v_cvt_scalef32_pk_f32_fp4 v[4:5], v182, 1.0 op_sel:[0,1,0]
	v_cvt_scalef32_pk_f32_fp4 v[6:7], v182, 1.0 op_sel:[1,1,0]
	v_cvt_scalef32_pk_f32_fp4 v[8:9], v183, 1.0
	v_cvt_scalef32_pk_f32_fp4 v[10:11], v183, 1.0 op_sel:[1,0,0]
	v_cvt_scalef32_pk_f32_fp4 v[12:13], v183, 1.0 op_sel:[0,1,0]
	v_cvt_scalef32_pk_f32_fp4 v[14:15], v183, 1.0 op_sel:[1,1,0]
	v_readlane_b32 s54, v90, 61
	s_lshl_b32 s56, s54, 9
	s_add_u32 s56, s64, s56
	s_addc_u32 s57, s65, 0
	global_load_dwordx2 v[182:183], v227, s[56:57]
	v_pk_fma_f32 v[130:131], v[0:1], s[0:1], v[130:131] op_sel_hi:[1,0,1]
	v_pk_fma_f32 v[138:139], v[2:3], s[0:1], v[138:139] op_sel_hi:[1,0,1]
	v_pk_fma_f32 v[140:141], v[4:5], s[0:1], v[140:141] op_sel_hi:[1,0,1]
	v_pk_fma_f32 v[142:143], v[6:7], s[0:1], v[142:143] op_sel_hi:[1,0,1]
	v_pk_fma_f32 v[128:129], v[8:9], s[0:1], v[128:129] op_sel_hi:[1,0,1]
	v_pk_fma_f32 v[132:133], v[10:11], s[0:1], v[132:133] op_sel_hi:[1,0,1]
	v_pk_fma_f32 v[134:135], v[12:13], s[0:1], v[134:135] op_sel_hi:[1,0,1]
	v_pk_fma_f32 v[136:137], v[14:15], s[0:1], v[136:137] op_sel_hi:[1,0,1]
	v_readlane_b32 s0, v167, 46
	s_waitcnt vmcnt(15)
	v_cvt_scalef32_pk_f32_fp4 v[0:1], v184, 1.0
	v_cvt_scalef32_pk_f32_fp4 v[2:3], v184, 1.0 op_sel:[1,0,0]
	v_cvt_scalef32_pk_f32_fp4 v[4:5], v184, 1.0 op_sel:[0,1,0]
	v_cvt_scalef32_pk_f32_fp4 v[6:7], v184, 1.0 op_sel:[1,1,0]
	v_cvt_scalef32_pk_f32_fp4 v[8:9], v185, 1.0
	v_cvt_scalef32_pk_f32_fp4 v[10:11], v185, 1.0 op_sel:[1,0,0]
	v_cvt_scalef32_pk_f32_fp4 v[12:13], v185, 1.0 op_sel:[0,1,0]
	v_cvt_scalef32_pk_f32_fp4 v[14:15], v185, 1.0 op_sel:[1,1,0]
	v_readlane_b32 s54, v90, 62
	s_lshl_b32 s56, s54, 9
	s_add_u32 s56, s64, s56
	s_addc_u32 s57, s65, 0
	global_load_dwordx2 v[184:185], v227, s[56:57]
	v_pk_fma_f32 v[130:131], v[0:1], s[0:1], v[130:131] op_sel_hi:[1,0,1]
	v_pk_fma_f32 v[138:139], v[2:3], s[0:1], v[138:139] op_sel_hi:[1,0,1]
	v_pk_fma_f32 v[140:141], v[4:5], s[0:1], v[140:141] op_sel_hi:[1,0,1]
	v_pk_fma_f32 v[142:143], v[6:7], s[0:1], v[142:143] op_sel_hi:[1,0,1]
	v_pk_fma_f32 v[128:129], v[8:9], s[0:1], v[128:129] op_sel_hi:[1,0,1]
	v_pk_fma_f32 v[132:133], v[10:11], s[0:1], v[132:133] op_sel_hi:[1,0,1]
	v_pk_fma_f32 v[134:135], v[12:13], s[0:1], v[134:135] op_sel_hi:[1,0,1]
	v_pk_fma_f32 v[136:137], v[14:15], s[0:1], v[136:137] op_sel_hi:[1,0,1]
	v_readlane_b32 s0, v167, 47
	s_waitcnt vmcnt(15)
	v_cvt_scalef32_pk_f32_fp4 v[0:1], v186, 1.0
	v_cvt_scalef32_pk_f32_fp4 v[2:3], v186, 1.0 op_sel:[1,0,0]
	v_cvt_scalef32_pk_f32_fp4 v[4:5], v186, 1.0 op_sel:[0,1,0]
	v_cvt_scalef32_pk_f32_fp4 v[6:7], v186, 1.0 op_sel:[1,1,0]
	v_cvt_scalef32_pk_f32_fp4 v[8:9], v187, 1.0
	v_cvt_scalef32_pk_f32_fp4 v[10:11], v187, 1.0 op_sel:[1,0,0]
	v_cvt_scalef32_pk_f32_fp4 v[12:13], v187, 1.0 op_sel:[0,1,0]
	v_cvt_scalef32_pk_f32_fp4 v[14:15], v187, 1.0 op_sel:[1,1,0]
	v_readlane_b32 s54, v90, 63
	s_lshl_b32 s56, s54, 9
	s_add_u32 s56, s64, s56
	s_addc_u32 s57, s65, 0
	global_load_dwordx2 v[186:187], v227, s[56:57]
	v_pk_fma_f32 v[130:131], v[0:1], s[0:1], v[130:131] op_sel_hi:[1,0,1]
	v_pk_fma_f32 v[138:139], v[2:3], s[0:1], v[138:139] op_sel_hi:[1,0,1]
	v_pk_fma_f32 v[140:141], v[4:5], s[0:1], v[140:141] op_sel_hi:[1,0,1]
	v_pk_fma_f32 v[142:143], v[6:7], s[0:1], v[142:143] op_sel_hi:[1,0,1]
	v_pk_fma_f32 v[128:129], v[8:9], s[0:1], v[128:129] op_sel_hi:[1,0,1]
	v_pk_fma_f32 v[132:133], v[10:11], s[0:1], v[132:133] op_sel_hi:[1,0,1]
	v_pk_fma_f32 v[134:135], v[12:13], s[0:1], v[134:135] op_sel_hi:[1,0,1]
	v_pk_fma_f32 v[136:137], v[14:15], s[0:1], v[136:137] op_sel_hi:[1,0,1]
	v_readlane_b32 s0, v167, 48
	s_waitcnt vmcnt(15)
; __device__ void peer_gather_phase(const Params& P, int l, bool do_store) {
;     ...
; #pragma unroll
;       for (int j = 0; j < 8; ++j) {
;         const float a = __builtin_bit_cast(float, __builtin_amdgcn_readlane(__builtin_bit_cast(int, avec), kb + j));
;         const f32x2 aa = f32x2{a, a};
;         y[0] += aa * __builtin_amdgcn_cvt_scalef32_pk_f32_fp4(v8[j].x, 1.0f, 0); y[1] += aa * __builtin_amdgcn_cvt_scalef32_pk_f32_fp4(v8[j].x, 1.0f, 1);
;         y[2] += aa * __builtin_amdgcn_cvt_scalef32_pk_f32_fp4(v8[j].x, 1.0f, 2); y[3] += aa * __builtin_amdgcn_cvt_scalef32_pk_f32_fp4(v8[j].x, 1.0f, 3);
;         y[4] += aa * __builtin_amdgcn_cvt_scalef32_pk_f32_fp4(v8[j].y, 1.0f, 0); y[5] += aa * __builtin_amdgcn_cvt_scalef32_pk_f32_fp4(v8[j].y, 1.0f, 1);
;         y[6] += aa * __builtin_amdgcn_cvt_scalef32_pk_f32_fp4(v8[j].y, 1.0f, 2); y[7] += aa * __builtin_amdgcn_cvt_scalef32_pk_f32_fp4(v8[j].y, 1.0f, 3);
;       }
	v_cvt_scalef32_pk_f32_fp4 v[0:1], v144, 1.0
	v_cvt_scalef32_pk_f32_fp4 v[2:3], v144, 1.0 op_sel:[1,0,0]
	v_cvt_scalef32_pk_f32_fp4 v[4:5], v144, 1.0 op_sel:[0,1,0]
	v_cvt_scalef32_pk_f32_fp4 v[6:7], v144, 1.0 op_sel:[1,1,0]
	v_cvt_scalef32_pk_f32_fp4 v[8:9], v145, 1.0
	v_cvt_scalef32_pk_f32_fp4 v[10:11], v145, 1.0 op_sel:[1,0,0]
	v_cvt_scalef32_pk_f32_fp4 v[12:13], v145, 1.0 op_sel:[0,1,0]
	v_cvt_scalef32_pk_f32_fp4 v[14:15], v145, 1.0 op_sel:[1,1,0]
	v_pk_fma_f32 v[130:131], v[0:1], s[0:1], v[130:131] op_sel_hi:[1,0,1]
	v_pk_fma_f32 v[138:139], v[2:3], s[0:1], v[138:139] op_sel_hi:[1,0,1]
	v_pk_fma_f32 v[140:141], v[4:5], s[0:1], v[140:141] op_sel_hi:[1,0,1]
	v_pk_fma_f32 v[142:143], v[6:7], s[0:1], v[142:143] op_sel_hi:[1,0,1]
	v_pk_fma_f32 v[128:129], v[8:9], s[0:1], v[128:129] op_sel_hi:[1,0,1]
	v_pk_fma_f32 v[132:133], v[10:11], s[0:1], v[132:133] op_sel_hi:[1,0,1]
	v_pk_fma_f32 v[134:135], v[12:13], s[0:1], v[134:135] op_sel_hi:[1,0,1]
	v_pk_fma_f32 v[136:137], v[14:15], s[0:1], v[136:137] op_sel_hi:[1,0,1]
	v_readlane_b32 s0, v167, 49
	s_waitcnt vmcnt(14)
	v_cvt_scalef32_pk_f32_fp4 v[0:1], v146, 1.0
	v_cvt_scalef32_pk_f32_fp4 v[2:3], v146, 1.0 op_sel:[1,0,0]
	v_cvt_scalef32_pk_f32_fp4 v[4:5], v146, 1.0 op_sel:[0,1,0]
	v_cvt_scalef32_pk_f32_fp4 v[6:7], v146, 1.0 op_sel:[1,1,0]
	v_cvt_scalef32_pk_f32_fp4 v[8:9], v147, 1.0
	v_cvt_scalef32_pk_f32_fp4 v[10:11], v147, 1.0 op_sel:[1,0,0]
	v_cvt_scalef32_pk_f32_fp4 v[12:13], v147, 1.0 op_sel:[0,1,0]
	v_cvt_scalef32_pk_f32_fp4 v[14:15], v147, 1.0 op_sel:[1,1,0]
	v_pk_fma_f32 v[130:131], v[0:1], s[0:1], v[130:131] op_sel_hi:[1,0,1]
	v_pk_fma_f32 v[138:139], v[2:3], s[0:1], v[138:139] op_sel_hi:[1,0,1]
	v_pk_fma_f32 v[140:141], v[4:5], s[0:1], v[140:141] op_sel_hi:[1,0,1]
	v_pk_fma_f32 v[142:143], v[6:7], s[0:1], v[142:143] op_sel_hi:[1,0,1]
	v_pk_fma_f32 v[128:129], v[8:9], s[0:1], v[128:129] op_sel_hi:[1,0,1]
	v_pk_fma_f32 v[132:133], v[10:11], s[0:1], v[132:133] op_sel_hi:[1,0,1]
	v_pk_fma_f32 v[134:135], v[12:13], s[0:1], v[134:135] op_sel_hi:[1,0,1]
	v_pk_fma_f32 v[136:137], v[14:15], s[0:1], v[136:137] op_sel_hi:[1,0,1]
	v_readlane_b32 s0, v167, 50
	s_waitcnt vmcnt(13)
	v_cvt_scalef32_pk_f32_fp4 v[0:1], v148, 1.0
	v_cvt_scalef32_pk_f32_fp4 v[2:3], v148, 1.0 op_sel:[1,0,0]
	v_cvt_scalef32_pk_f32_fp4 v[4:5], v148, 1.0 op_sel:[0,1,0]
	v_cvt_scalef32_pk_f32_fp4 v[6:7], v148, 1.0 op_sel:[1,1,0]
	v_cvt_scalef32_pk_f32_fp4 v[8:9], v149, 1.0
	v_cvt_scalef32_pk_f32_fp4 v[10:11], v149, 1.0 op_sel:[1,0,0]
	v_cvt_scalef32_pk_f32_fp4 v[12:13], v149, 1.0 op_sel:[0,1,0]
	v_cvt_scalef32_pk_f32_fp4 v[14:15], v149, 1.0 op_sel:[1,1,0]
	v_pk_fma_f32 v[130:131], v[0:1], s[0:1], v[130:131] op_sel_hi:[1,0,1]
	v_pk_fma_f32 v[138:139], v[2:3], s[0:1], v[138:139] op_sel_hi:[1,0,1]
	v_pk_fma_f32 v[140:141], v[4:5], s[0:1], v[140:141] op_sel_hi:[1,0,1]
	v_pk_fma_f32 v[142:143], v[6:7], s[0:1], v[142:143] op_sel_hi:[1,0,1]
	v_pk_fma_f32 v[128:129], v[8:9], s[0:1], v[128:129] op_sel_hi:[1,0,1]
	v_pk_fma_f32 v[132:133], v[10:11], s[0:1], v[132:133] op_sel_hi:[1,0,1]
	v_pk_fma_f32 v[134:135], v[12:13], s[0:1], v[134:135] op_sel_hi:[1,0,1]
	v_pk_fma_f32 v[136:137], v[14:15], s[0:1], v[136:137] op_sel_hi:[1,0,1]
	v_readlane_b32 s0, v167, 51
	s_waitcnt vmcnt(12)
	v_cvt_scalef32_pk_f32_fp4 v[0:1], v150, 1.0
	v_cvt_scalef32_pk_f32_fp4 v[2:3], v150, 1.0 op_sel:[1,0,0]
	v_cvt_scalef32_pk_f32_fp4 v[4:5], v150, 1.0 op_sel:[0,1,0]
	v_cvt_scalef32_pk_f32_fp4 v[6:7], v150, 1.0 op_sel:[1,1,0]
	v_cvt_scalef32_pk_f32_fp4 v[8:9], v151, 1.0
	v_cvt_scalef32_pk_f32_fp4 v[10:11], v151, 1.0 op_sel:[1,0,0]
	v_cvt_scalef32_pk_f32_fp4 v[12:13], v151, 1.0 op_sel:[0,1,0]
	v_cvt_scalef32_pk_f32_fp4 v[14:15], v151, 1.0 op_sel:[1,1,0]
	v_pk_fma_f32 v[130:131], v[0:1], s[0:1], v[130:131] op_sel_hi:[1,0,1]
	v_pk_fma_f32 v[138:139], v[2:3], s[0:1], v[138:139] op_sel_hi:[1,0,1]
	v_pk_fma_f32 v[140:141], v[4:5], s[0:1], v[140:141] op_sel_hi:[1,0,1]
	v_pk_fma_f32 v[142:143], v[6:7], s[0:1], v[142:143] op_sel_hi:[1,0,1]
	v_pk_fma_f32 v[128:129], v[8:9], s[0:1], v[128:129] op_sel_hi:[1,0,1]
	v_pk_fma_f32 v[132:133], v[10:11], s[0:1], v[132:133] op_sel_hi:[1,0,1]
	v_pk_fma_f32 v[134:135], v[12:13], s[0:1], v[134:135] op_sel_hi:[1,0,1]
	v_pk_fma_f32 v[136:137], v[14:15], s[0:1], v[136:137] op_sel_hi:[1,0,1]
	v_readlane_b32 s0, v167, 52
	s_waitcnt vmcnt(11)
	v_cvt_scalef32_pk_f32_fp4 v[0:1], v152, 1.0
	v_cvt_scalef32_pk_f32_fp4 v[2:3], v152, 1.0 op_sel:[1,0,0]
	v_cvt_scalef32_pk_f32_fp4 v[4:5], v152, 1.0 op_sel:[0,1,0]
	v_cvt_scalef32_pk_f32_fp4 v[6:7], v152, 1.0 op_sel:[1,1,0]
	v_cvt_scalef32_pk_f32_fp4 v[8:9], v153, 1.0
	v_cvt_scalef32_pk_f32_fp4 v[10:11], v153, 1.0 op_sel:[1,0,0]
	v_cvt_scalef32_pk_f32_fp4 v[12:13], v153, 1.0 op_sel:[0,1,0]
	v_cvt_scalef32_pk_f32_fp4 v[14:15], v153, 1.0 op_sel:[1,1,0]
	v_pk_fma_f32 v[130:131], v[0:1], s[0:1], v[130:131] op_sel_hi:[1,0,1]
	v_pk_fma_f32 v[138:139], v[2:3], s[0:1], v[138:139] op_sel_hi:[1,0,1]
	v_pk_fma_f32 v[140:141], v[4:5], s[0:1], v[140:141] op_sel_hi:[1,0,1]
	v_pk_fma_f32 v[142:143], v[6:7], s[0:1], v[142:143] op_sel_hi:[1,0,1]
	v_pk_fma_f32 v[128:129], v[8:9], s[0:1], v[128:129] op_sel_hi:[1,0,1]
	v_pk_fma_f32 v[132:133], v[10:11], s[0:1], v[132:133] op_sel_hi:[1,0,1]
	v_pk_fma_f32 v[134:135], v[12:13], s[0:1], v[134:135] op_sel_hi:[1,0,1]
	v_pk_fma_f32 v[136:137], v[14:15], s[0:1], v[136:137] op_sel_hi:[1,0,1]
	v_readlane_b32 s0, v167, 53
	s_waitcnt vmcnt(10)
; __device__ void peer_gather_phase(const Params& P, int l, bool do_store) {
;     ...
; #pragma unroll
;       for (int j = 0; j < 8; ++j) {
;         const float a = __builtin_bit_cast(float, __builtin_amdgcn_readlane(__builtin_bit_cast(int, avec), kb + j));
;         const f32x2 aa = f32x2{a, a};
;         y[0] += aa * __builtin_amdgcn_cvt_scalef32_pk_f32_fp4(v8[j].x, 1.0f, 0); y[1] += aa * __builtin_amdgcn_cvt_scalef32_pk_f32_fp4(v8[j].x, 1.0f, 1);
;         y[2] += aa * __builtin_amdgcn_cvt_scalef32_pk_f32_fp4(v8[j].x, 1.0f, 2); y[3] += aa * __builtin_amdgcn_cvt_scalef32_pk_f32_fp4(v8[j].x, 1.0f, 3);
;         y[4] += aa * __builtin_amdgcn_cvt_scalef32_pk_f32_fp4(v8[j].y, 1.0f, 0); y[5] += aa * __builtin_amdgcn_cvt_scalef32_pk_f32_fp4(v8[j].y, 1.0f, 1);
;         y[6] += aa * __builtin_amdgcn_cvt_scalef32_pk_f32_fp4(v8[j].y, 1.0f, 2); y[7] += aa * __builtin_amdgcn_cvt_scalef32_pk_f32_fp4(v8[j].y, 1.0f, 3);
;       }
	v_cvt_scalef32_pk_f32_fp4 v[0:1], v154, 1.0
	v_cvt_scalef32_pk_f32_fp4 v[2:3], v154, 1.0 op_sel:[1,0,0]
	v_cvt_scalef32_pk_f32_fp4 v[4:5], v154, 1.0 op_sel:[0,1,0]
	v_cvt_scalef32_pk_f32_fp4 v[6:7], v154, 1.0 op_sel:[1,1,0]
	v_cvt_scalef32_pk_f32_fp4 v[8:9], v155, 1.0
	v_cvt_scalef32_pk_f32_fp4 v[10:11], v155, 1.0 op_sel:[1,0,0]
	v_cvt_scalef32_pk_f32_fp4 v[12:13], v155, 1.0 op_sel:[0,1,0]
	v_cvt_scalef32_pk_f32_fp4 v[14:15], v155, 1.0 op_sel:[1,1,0]
	v_pk_fma_f32 v[130:131], v[0:1], s[0:1], v[130:131] op_sel_hi:[1,0,1]
	v_pk_fma_f32 v[138:139], v[2:3], s[0:1], v[138:139] op_sel_hi:[1,0,1]
	v_pk_fma_f32 v[140:141], v[4:5], s[0:1], v[140:141] op_sel_hi:[1,0,1]
	v_pk_fma_f32 v[142:143], v[6:7], s[0:1], v[142:143] op_sel_hi:[1,0,1]
	v_pk_fma_f32 v[128:129], v[8:9], s[0:1], v[128:129] op_sel_hi:[1,0,1]
	v_pk_fma_f32 v[132:133], v[10:11], s[0:1], v[132:133] op_sel_hi:[1,0,1]
	v_pk_fma_f32 v[134:135], v[12:13], s[0:1], v[134:135] op_sel_hi:[1,0,1]
	v_pk_fma_f32 v[136:137], v[14:15], s[0:1], v[136:137] op_sel_hi:[1,0,1]
	v_readlane_b32 s0, v167, 54
	s_waitcnt vmcnt(9)
	v_cvt_scalef32_pk_f32_fp4 v[0:1], v156, 1.0
	v_cvt_scalef32_pk_f32_fp4 v[2:3], v156, 1.0 op_sel:[1,0,0]
	v_cvt_scalef32_pk_f32_fp4 v[4:5], v156, 1.0 op_sel:[0,1,0]
	v_cvt_scalef32_pk_f32_fp4 v[6:7], v156, 1.0 op_sel:[1,1,0]
	v_cvt_scalef32_pk_f32_fp4 v[8:9], v157, 1.0
	v_cvt_scalef32_pk_f32_fp4 v[10:11], v157, 1.0 op_sel:[1,0,0]
	v_cvt_scalef32_pk_f32_fp4 v[12:13], v157, 1.0 op_sel:[0,1,0]
	v_cvt_scalef32_pk_f32_fp4 v[14:15], v157, 1.0 op_sel:[1,1,0]
	v_pk_fma_f32 v[130:131], v[0:1], s[0:1], v[130:131] op_sel_hi:[1,0,1]
	v_pk_fma_f32 v[138:139], v[2:3], s[0:1], v[138:139] op_sel_hi:[1,0,1]
	v_pk_fma_f32 v[140:141], v[4:5], s[0:1], v[140:141] op_sel_hi:[1,0,1]
	v_pk_fma_f32 v[142:143], v[6:7], s[0:1], v[142:143] op_sel_hi:[1,0,1]
	v_pk_fma_f32 v[128:129], v[8:9], s[0:1], v[128:129] op_sel_hi:[1,0,1]
	v_pk_fma_f32 v[132:133], v[10:11], s[0:1], v[132:133] op_sel_hi:[1,0,1]
	v_pk_fma_f32 v[134:135], v[12:13], s[0:1], v[134:135] op_sel_hi:[1,0,1]
	v_pk_fma_f32 v[136:137], v[14:15], s[0:1], v[136:137] op_sel_hi:[1,0,1]
	v_readlane_b32 s0, v167, 55
	s_waitcnt vmcnt(8)
	v_cvt_scalef32_pk_f32_fp4 v[0:1], v158, 1.0
	v_cvt_scalef32_pk_f32_fp4 v[2:3], v158, 1.0 op_sel:[1,0,0]
	v_cvt_scalef32_pk_f32_fp4 v[4:5], v158, 1.0 op_sel:[0,1,0]
	v_cvt_scalef32_pk_f32_fp4 v[6:7], v158, 1.0 op_sel:[1,1,0]
	v_cvt_scalef32_pk_f32_fp4 v[8:9], v159, 1.0
	v_cvt_scalef32_pk_f32_fp4 v[10:11], v159, 1.0 op_sel:[1,0,0]
	v_cvt_scalef32_pk_f32_fp4 v[12:13], v159, 1.0 op_sel:[0,1,0]
	v_cvt_scalef32_pk_f32_fp4 v[14:15], v159, 1.0 op_sel:[1,1,0]
	v_pk_fma_f32 v[130:131], v[0:1], s[0:1], v[130:131] op_sel_hi:[1,0,1]
	v_pk_fma_f32 v[138:139], v[2:3], s[0:1], v[138:139] op_sel_hi:[1,0,1]
	v_pk_fma_f32 v[140:141], v[4:5], s[0:1], v[140:141] op_sel_hi:[1,0,1]
	v_pk_fma_f32 v[142:143], v[6:7], s[0:1], v[142:143] op_sel_hi:[1,0,1]
	v_pk_fma_f32 v[128:129], v[8:9], s[0:1], v[128:129] op_sel_hi:[1,0,1]
	v_pk_fma_f32 v[132:133], v[10:11], s[0:1], v[132:133] op_sel_hi:[1,0,1]
	v_pk_fma_f32 v[134:135], v[12:13], s[0:1], v[134:135] op_sel_hi:[1,0,1]
	v_pk_fma_f32 v[136:137], v[14:15], s[0:1], v[136:137] op_sel_hi:[1,0,1]
	v_readlane_b32 s0, v167, 56
	s_waitcnt vmcnt(7)
	v_cvt_scalef32_pk_f32_fp4 v[0:1], v168, 1.0
	v_cvt_scalef32_pk_f32_fp4 v[2:3], v168, 1.0 op_sel:[1,0,0]
	v_cvt_scalef32_pk_f32_fp4 v[4:5], v168, 1.0 op_sel:[0,1,0]
	v_cvt_scalef32_pk_f32_fp4 v[6:7], v168, 1.0 op_sel:[1,1,0]
	v_cvt_scalef32_pk_f32_fp4 v[8:9], v169, 1.0
	v_cvt_scalef32_pk_f32_fp4 v[10:11], v169, 1.0 op_sel:[1,0,0]
	v_cvt_scalef32_pk_f32_fp4 v[12:13], v169, 1.0 op_sel:[0,1,0]
	v_cvt_scalef32_pk_f32_fp4 v[14:15], v169, 1.0 op_sel:[1,1,0]
	v_pk_fma_f32 v[130:131], v[0:1], s[0:1], v[130:131] op_sel_hi:[1,0,1]
	v_pk_fma_f32 v[138:139], v[2:3], s[0:1], v[138:139] op_sel_hi:[1,0,1]
	v_pk_fma_f32 v[140:141], v[4:5], s[0:1], v[140:141] op_sel_hi:[1,0,1]
	v_pk_fma_f32 v[142:143], v[6:7], s[0:1], v[142:143] op_sel_hi:[1,0,1]
	v_pk_fma_f32 v[128:129], v[8:9], s[0:1], v[128:129] op_sel_hi:[1,0,1]
	v_pk_fma_f32 v[132:133], v[10:11], s[0:1], v[132:133] op_sel_hi:[1,0,1]
	v_pk_fma_f32 v[134:135], v[12:13], s[0:1], v[134:135] op_sel_hi:[1,0,1]
	v_pk_fma_f32 v[136:137], v[14:15], s[0:1], v[136:137] op_sel_hi:[1,0,1]
	v_readlane_b32 s0, v167, 57
	s_waitcnt vmcnt(6)
	v_cvt_scalef32_pk_f32_fp4 v[0:1], v170, 1.0
	v_cvt_scalef32_pk_f32_fp4 v[2:3], v170, 1.0 op_sel:[1,0,0]
	v_cvt_scalef32_pk_f32_fp4 v[4:5], v170, 1.0 op_sel:[0,1,0]
	v_cvt_scalef32_pk_f32_fp4 v[6:7], v170, 1.0 op_sel:[1,1,0]
	v_cvt_scalef32_pk_f32_fp4 v[8:9], v171, 1.0
	v_cvt_scalef32_pk_f32_fp4 v[10:11], v171, 1.0 op_sel:[1,0,0]
	v_cvt_scalef32_pk_f32_fp4 v[12:13], v171, 1.0 op_sel:[0,1,0]
	v_cvt_scalef32_pk_f32_fp4 v[14:15], v171, 1.0 op_sel:[1,1,0]
	v_pk_fma_f32 v[130:131], v[0:1], s[0:1], v[130:131] op_sel_hi:[1,0,1]
	v_pk_fma_f32 v[138:139], v[2:3], s[0:1], v[138:139] op_sel_hi:[1,0,1]
	v_pk_fma_f32 v[140:141], v[4:5], s[0:1], v[140:141] op_sel_hi:[1,0,1]
	v_pk_fma_f32 v[142:143], v[6:7], s[0:1], v[142:143] op_sel_hi:[1,0,1]
	v_pk_fma_f32 v[128:129], v[8:9], s[0:1], v[128:129] op_sel_hi:[1,0,1]
	v_pk_fma_f32 v[132:133], v[10:11], s[0:1], v[132:133] op_sel_hi:[1,0,1]
	v_pk_fma_f32 v[134:135], v[12:13], s[0:1], v[134:135] op_sel_hi:[1,0,1]
	v_pk_fma_f32 v[136:137], v[14:15], s[0:1], v[136:137] op_sel_hi:[1,0,1]
	v_readlane_b32 s0, v167, 58
	s_waitcnt vmcnt(5)
; __device__ void peer_gather_phase(const Params& P, int l, bool do_store) {
;     ...
; #pragma unroll
;       for (int j = 0; j < 8; ++j) {
;         const float a = __builtin_bit_cast(float, __builtin_amdgcn_readlane(__builtin_bit_cast(int, avec), kb + j));
;         const f32x2 aa = f32x2{a, a};
;         y[0] += aa * __builtin_amdgcn_cvt_scalef32_pk_f32_fp4(v8[j].x, 1.0f, 0); y[1] += aa * __builtin_amdgcn_cvt_scalef32_pk_f32_fp4(v8[j].x, 1.0f, 1);
;         y[2] += aa * __builtin_amdgcn_cvt_scalef32_pk_f32_fp4(v8[j].x, 1.0f, 2); y[3] += aa * __builtin_amdgcn_cvt_scalef32_pk_f32_fp4(v8[j].x, 1.0f, 3);
;         y[4] += aa * __builtin_amdgcn_cvt_scalef32_pk_f32_fp4(v8[j].y, 1.0f, 0); y[5] += aa * __builtin_amdgcn_cvt_scalef32_pk_f32_fp4(v8[j].y, 1.0f, 1);
;         y[6] += aa * __builtin_amdgcn_cvt_scalef32_pk_f32_fp4(v8[j].y, 1.0f, 2); y[7] += aa * __builtin_amdgcn_cvt_scalef32_pk_f32_fp4(v8[j].y, 1.0f, 3);
;       }
	v_cvt_scalef32_pk_f32_fp4 v[0:1], v172, 1.0
	v_cvt_scalef32_pk_f32_fp4 v[2:3], v172, 1.0 op_sel:[1,0,0]
	v_cvt_scalef32_pk_f32_fp4 v[4:5], v172, 1.0 op_sel:[0,1,0]
	v_cvt_scalef32_pk_f32_fp4 v[6:7], v172, 1.0 op_sel:[1,1,0]
	v_cvt_scalef32_pk_f32_fp4 v[8:9], v173, 1.0
	v_cvt_scalef32_pk_f32_fp4 v[10:11], v173, 1.0 op_sel:[1,0,0]
	v_cvt_scalef32_pk_f32_fp4 v[12:13], v173, 1.0 op_sel:[0,1,0]
	v_cvt_scalef32_pk_f32_fp4 v[14:15], v173, 1.0 op_sel:[1,1,0]
	v_pk_fma_f32 v[130:131], v[0:1], s[0:1], v[130:131] op_sel_hi:[1,0,1]
	v_pk_fma_f32 v[138:139], v[2:3], s[0:1], v[138:139] op_sel_hi:[1,0,1]
	v_pk_fma_f32 v[140:141], v[4:5], s[0:1], v[140:141] op_sel_hi:[1,0,1]
	v_pk_fma_f32 v[142:143], v[6:7], s[0:1], v[142:143] op_sel_hi:[1,0,1]
	v_pk_fma_f32 v[128:129], v[8:9], s[0:1], v[128:129] op_sel_hi:[1,0,1]
	v_pk_fma_f32 v[132:133], v[10:11], s[0:1], v[132:133] op_sel_hi:[1,0,1]
	v_pk_fma_f32 v[134:135], v[12:13], s[0:1], v[134:135] op_sel_hi:[1,0,1]
	v_pk_fma_f32 v[136:137], v[14:15], s[0:1], v[136:137] op_sel_hi:[1,0,1]
	v_readlane_b32 s0, v167, 59
	s_waitcnt vmcnt(4)
	v_cvt_scalef32_pk_f32_fp4 v[0:1], v174, 1.0
	v_cvt_scalef32_pk_f32_fp4 v[2:3], v174, 1.0 op_sel:[1,0,0]
	v_cvt_scalef32_pk_f32_fp4 v[4:5], v174, 1.0 op_sel:[0,1,0]
	v_cvt_scalef32_pk_f32_fp4 v[6:7], v174, 1.0 op_sel:[1,1,0]
	v_cvt_scalef32_pk_f32_fp4 v[8:9], v175, 1.0
	v_cvt_scalef32_pk_f32_fp4 v[10:11], v175, 1.0 op_sel:[1,0,0]
	v_cvt_scalef32_pk_f32_fp4 v[12:13], v175, 1.0 op_sel:[0,1,0]
	v_cvt_scalef32_pk_f32_fp4 v[14:15], v175, 1.0 op_sel:[1,1,0]
	v_pk_fma_f32 v[130:131], v[0:1], s[0:1], v[130:131] op_sel_hi:[1,0,1]
	v_pk_fma_f32 v[138:139], v[2:3], s[0:1], v[138:139] op_sel_hi:[1,0,1]
	v_pk_fma_f32 v[140:141], v[4:5], s[0:1], v[140:141] op_sel_hi:[1,0,1]
	v_pk_fma_f32 v[142:143], v[6:7], s[0:1], v[142:143] op_sel_hi:[1,0,1]
	v_pk_fma_f32 v[128:129], v[8:9], s[0:1], v[128:129] op_sel_hi:[1,0,1]
	v_pk_fma_f32 v[132:133], v[10:11], s[0:1], v[132:133] op_sel_hi:[1,0,1]
	v_pk_fma_f32 v[134:135], v[12:13], s[0:1], v[134:135] op_sel_hi:[1,0,1]
	v_pk_fma_f32 v[136:137], v[14:15], s[0:1], v[136:137] op_sel_hi:[1,0,1]
	v_readlane_b32 s0, v167, 60
	s_waitcnt vmcnt(3)
	v_cvt_scalef32_pk_f32_fp4 v[0:1], v180, 1.0
	v_cvt_scalef32_pk_f32_fp4 v[2:3], v180, 1.0 op_sel:[1,0,0]
	v_cvt_scalef32_pk_f32_fp4 v[4:5], v180, 1.0 op_sel:[0,1,0]
	v_cvt_scalef32_pk_f32_fp4 v[6:7], v180, 1.0 op_sel:[1,1,0]
	v_cvt_scalef32_pk_f32_fp4 v[8:9], v181, 1.0
	v_cvt_scalef32_pk_f32_fp4 v[10:11], v181, 1.0 op_sel:[1,0,0]
	v_cvt_scalef32_pk_f32_fp4 v[12:13], v181, 1.0 op_sel:[0,1,0]
	v_cvt_scalef32_pk_f32_fp4 v[14:15], v181, 1.0 op_sel:[1,1,0]
	v_pk_fma_f32 v[130:131], v[0:1], s[0:1], v[130:131] op_sel_hi:[1,0,1]
	v_pk_fma_f32 v[138:139], v[2:3], s[0:1], v[138:139] op_sel_hi:[1,0,1]
	v_pk_fma_f32 v[140:141], v[4:5], s[0:1], v[140:141] op_sel_hi:[1,0,1]
	v_pk_fma_f32 v[142:143], v[6:7], s[0:1], v[142:143] op_sel_hi:[1,0,1]
	v_pk_fma_f32 v[128:129], v[8:9], s[0:1], v[128:129] op_sel_hi:[1,0,1]
	v_pk_fma_f32 v[132:133], v[10:11], s[0:1], v[132:133] op_sel_hi:[1,0,1]
	v_pk_fma_f32 v[134:135], v[12:13], s[0:1], v[134:135] op_sel_hi:[1,0,1]
	v_pk_fma_f32 v[136:137], v[14:15], s[0:1], v[136:137] op_sel_hi:[1,0,1]
	v_readlane_b32 s0, v167, 61
	s_waitcnt vmcnt(2)
	v_cvt_scalef32_pk_f32_fp4 v[0:1], v182, 1.0
	v_cvt_scalef32_pk_f32_fp4 v[2:3], v182, 1.0 op_sel:[1,0,0]
	v_cvt_scalef32_pk_f32_fp4 v[4:5], v182, 1.0 op_sel:[0,1,0]
	v_cvt_scalef32_pk_f32_fp4 v[6:7], v182, 1.0 op_sel:[1,1,0]
	v_cvt_scalef32_pk_f32_fp4 v[8:9], v183, 1.0
	v_cvt_scalef32_pk_f32_fp4 v[10:11], v183, 1.0 op_sel:[1,0,0]
	v_cvt_scalef32_pk_f32_fp4 v[12:13], v183, 1.0 op_sel:[0,1,0]
	v_cvt_scalef32_pk_f32_fp4 v[14:15], v183, 1.0 op_sel:[1,1,0]
	v_pk_fma_f32 v[130:131], v[0:1], s[0:1], v[130:131] op_sel_hi:[1,0,1]
	v_pk_fma_f32 v[138:139], v[2:3], s[0:1], v[138:139] op_sel_hi:[1,0,1]
	v_pk_fma_f32 v[140:141], v[4:5], s[0:1], v[140:141] op_sel_hi:[1,0,1]
	v_pk_fma_f32 v[142:143], v[6:7], s[0:1], v[142:143] op_sel_hi:[1,0,1]
	v_pk_fma_f32 v[128:129], v[8:9], s[0:1], v[128:129] op_sel_hi:[1,0,1]
	v_pk_fma_f32 v[132:133], v[10:11], s[0:1], v[132:133] op_sel_hi:[1,0,1]
	v_pk_fma_f32 v[134:135], v[12:13], s[0:1], v[134:135] op_sel_hi:[1,0,1]
	v_pk_fma_f32 v[136:137], v[14:15], s[0:1], v[136:137] op_sel_hi:[1,0,1]
	v_readlane_b32 s0, v167, 62
	s_waitcnt vmcnt(1)
	v_cvt_scalef32_pk_f32_fp4 v[0:1], v184, 1.0
	v_cvt_scalef32_pk_f32_fp4 v[2:3], v184, 1.0 op_sel:[1,0,0]
	v_cvt_scalef32_pk_f32_fp4 v[4:5], v184, 1.0 op_sel:[0,1,0]
	v_cvt_scalef32_pk_f32_fp4 v[6:7], v184, 1.0 op_sel:[1,1,0]
	v_cvt_scalef32_pk_f32_fp4 v[8:9], v185, 1.0
	v_cvt_scalef32_pk_f32_fp4 v[10:11], v185, 1.0 op_sel:[1,0,0]
	v_cvt_scalef32_pk_f32_fp4 v[12:13], v185, 1.0 op_sel:[0,1,0]
	v_cvt_scalef32_pk_f32_fp4 v[14:15], v185, 1.0 op_sel:[1,1,0]
	v_pk_fma_f32 v[130:131], v[0:1], s[0:1], v[130:131] op_sel_hi:[1,0,1]
	v_pk_fma_f32 v[138:139], v[2:3], s[0:1], v[138:139] op_sel_hi:[1,0,1]
	v_pk_fma_f32 v[140:141], v[4:5], s[0:1], v[140:141] op_sel_hi:[1,0,1]
	v_pk_fma_f32 v[142:143], v[6:7], s[0:1], v[142:143] op_sel_hi:[1,0,1]
	v_pk_fma_f32 v[128:129], v[8:9], s[0:1], v[128:129] op_sel_hi:[1,0,1]
	v_pk_fma_f32 v[132:133], v[10:11], s[0:1], v[132:133] op_sel_hi:[1,0,1]
	v_pk_fma_f32 v[134:135], v[12:13], s[0:1], v[134:135] op_sel_hi:[1,0,1]
	v_pk_fma_f32 v[136:137], v[14:15], s[0:1], v[136:137] op_sel_hi:[1,0,1]
	v_readlane_b32 s0, v167, 63
	s_waitcnt vmcnt(0)
; __device__ void peer_gather_phase(const Params& P, int l, bool do_store) {
;     ...
;       for (int j = 0; j < 8; ++j) {
;         const float a = __builtin_bit_cast(float, __builtin_amdgcn_readlane(__builtin_bit_cast(int, avec), kb + j));
;         const f32x2 aa = f32x2{a, a};
;         y[0] += aa * __builtin_amdgcn_cvt_scalef32_pk_f32_fp4(v8[j].x, 1.0f, 0); y[1] += aa * __builtin_amdgcn_cvt_scalef32_pk_f32_fp4(v8[j].x, 1.0f, 1);
;         y[2] += aa * __builtin_amdgcn_cvt_scalef32_pk_f32_fp4(v8[j].x, 1.0f, 2); y[3] += aa * __builtin_amdgcn_cvt_scalef32_pk_f32_fp4(v8[j].x, 1.0f, 3);
;         y[4] += aa * __builtin_amdgcn_cvt_scalef32_pk_f32_fp4(v8[j].y, 1.0f, 0); y[5] += aa * __builtin_amdgcn_cvt_scalef32_pk_f32_fp4(v8[j].y, 1.0f, 1);
;         y[6] += aa * __builtin_amdgcn_cvt_scalef32_pk_f32_fp4(v8[j].y, 1.0f, 2); y[7] += aa * __builtin_amdgcn_cvt_scalef32_pk_f32_fp4(v8[j].y, 1.0f, 3);
;       }
;     ...
;     float* xfp = P.out + (size_t)t * 1024 + lane * 16;
;     float pre[16];
; #pragma unroll
;     for (int k2 = 0; k2 < 8; ++k2) {
;       pre[2 * k2 + 0] = ALPHA_C * xf[k2].x + y[k2].x;
;       pre[2 * k2 + 1] = ALPHA_C * xf[k2].y + y[k2].y;
;     }
;     float sm = 0.f;
; #pragma unroll
;     for (int k = 0; k < 16; ++k) sm += pre[k];
;     const float mean = wave_sum(sm) * (1.f / 1024.f);
;     float vs = 0.f;
; #pragma unroll
;     for (int k = 0; k < 16; ++k) { const float dd = pre[k] - mean; vs += dd * dd; }
;     const float rstd = rsqrtf(wave_sum(vs) * (1.f / 1024.f) + EPS_C);
;     const float* g2 = P.ln2_g + l * 1024 + lane * 16;
;     const float* b2 = P.ln2_b + l * 1024 + lane * 16;
;     float o[16];
; #pragma unroll
;     for (int k4 = 0; k4 < 4; ++k4) {
;       const float4 gg = *(const float4*)(g2 + 4 * k4), bb = *(const float4*)(b2 + 4 * k4);
;       o[4 * k4 + 0] = (pre[4 * k4 + 0] - mean) * rstd * gg.x + bb.x; o[4 * k4 + 1] = (pre[4 * k4 + 1] - mean) * rstd * gg.y + bb.y;
;       o[4 * k4 + 2] = (pre[4 * k4 + 2] - mean) * rstd * gg.z + bb.z; o[4 * k4 + 3] = (pre[4 * k4 + 3] - mean) * rstd * gg.w + bb.w;
;       float4 ov; ov.x = o[4 * k4]; ov.y = o[4 * k4 + 1]; ov.z = o[4 * k4 + 2]; ov.w = o[4 * k4 + 3];
;       if (do_store && l == 1) *(float4*)(xfp + 4 * k4) = ov;
;     }
;     bf16_t* xbo = P.XB + (size_t)t * 1024 + lane * 16;
;     if (do_store && l == 0) {
;       *(bf16x8*)(xbo) = pack8(o);
	v_cvt_scalef32_pk_f32_fp4 v[0:1], v186, 1.0
	v_cvt_scalef32_pk_f32_fp4 v[2:3], v186, 1.0 op_sel:[1,0,0]
	v_cvt_scalef32_pk_f32_fp4 v[4:5], v186, 1.0 op_sel:[0,1,0]
	v_cvt_scalef32_pk_f32_fp4 v[6:7], v186, 1.0 op_sel:[1,1,0]
	v_cvt_scalef32_pk_f32_fp4 v[8:9], v187, 1.0
	v_cvt_scalef32_pk_f32_fp4 v[10:11], v187, 1.0 op_sel:[1,0,0]
	v_cvt_scalef32_pk_f32_fp4 v[12:13], v187, 1.0 op_sel:[0,1,0]
	v_cvt_scalef32_pk_f32_fp4 v[14:15], v187, 1.0 op_sel:[1,1,0]
	v_pk_fma_f32 v[130:131], v[0:1], s[0:1], v[130:131] op_sel_hi:[1,0,1]
	v_pk_fma_f32 v[138:139], v[2:3], s[0:1], v[138:139] op_sel_hi:[1,0,1]
	v_pk_fma_f32 v[140:141], v[4:5], s[0:1], v[140:141] op_sel_hi:[1,0,1]
	v_pk_fma_f32 v[142:143], v[6:7], s[0:1], v[142:143] op_sel_hi:[1,0,1]
	v_pk_fma_f32 v[128:129], v[8:9], s[0:1], v[128:129] op_sel_hi:[1,0,1]
	v_pk_fma_f32 v[132:133], v[10:11], s[0:1], v[132:133] op_sel_hi:[1,0,1]
	v_pk_fma_f32 v[134:135], v[12:13], s[0:1], v[134:135] op_sel_hi:[1,0,1]
	v_pk_fma_f32 v[136:137], v[14:15], s[0:1], v[136:137] op_sel_hi:[1,0,1]
	v_lshlrev_b32_e32 v0, 16, v70
	v_lshlrev_b32_e32 v2, 16, v69
	v_and_b32_e32 v3, 0xffff0000, v69
	v_and_b32_e32 v1, 0xffff0000, v70
	s_mov_b32 s0, 0x3fb504f3
	v_pk_fma_f32 v[16:17], v[0:1], s[0:1], v[140:141] op_sel_hi:[1,0,1]
	v_pk_fma_f32 v[18:19], v[2:3], s[0:1], v[138:139] op_sel_hi:[1,0,1]
	global_load_dwordx4 v[0:3], v[82:83], off
	global_load_dwordx4 v[20:23], v[84:85], off
	global_load_dwordx4 v[44:47], v[82:83], off offset:16
	global_load_dwordx4 v[48:51], v[84:85], off offset:16
	global_load_dwordx4 v[52:55], v[82:83], off offset:32
	global_load_dwordx4 v[228:231], v[84:85], off offset:32
	global_load_dwordx4 v[232:235], v[82:83], off offset:48
	global_load_dwordx4 v[236:239], v[84:85], off offset:48
	v_lshlrev_b32_e32 v4, 16, v68
	v_and_b32_e32 v5, 0xffff0000, v68
	v_pk_fma_f32 v[4:5], v[4:5], s[0:1], v[130:131] op_sel_hi:[1,0,1]
	v_lshlrev_b32_e32 v10, 16, v71
	v_add_f32_e32 v24, 0, v4
	v_add_f32_e32 v24, v5, v24
	v_add_f32_e32 v24, v18, v24
	v_add_f32_e32 v24, v19, v24
	v_and_b32_e32 v11, 0xffff0000, v71
	v_add_f32_e32 v24, v16, v24
	v_pk_fma_f32 v[10:11], v[10:11], s[0:1], v[142:143] op_sel_hi:[1,0,1]
	v_add_f32_e32 v24, v17, v24
	v_lshlrev_b32_e32 v6, 16, v64
	v_lshlrev_b32_e32 v8, 16, v66
	v_lshlrev_b32_e32 v12, 16, v65
	v_lshlrev_b32_e32 v14, 16, v67
	v_and_b32_e32 v7, 0xffff0000, v64
	v_and_b32_e32 v13, 0xffff0000, v65
	v_and_b32_e32 v9, 0xffff0000, v66
	v_and_b32_e32 v15, 0xffff0000, v67
	v_add_f32_e32 v24, v10, v24
	v_add_f32_e32 v26, v11, v24
	v_pk_fma_f32 v[24:25], v[14:15], s[0:1], v[136:137] op_sel_hi:[1,0,1]
	v_pk_fma_f32 v[14:15], v[8:9], s[0:1], v[134:135] op_sel_hi:[1,0,1]
	v_pk_fma_f32 v[8:9], v[12:13], s[0:1], v[132:133] op_sel_hi:[1,0,1]
	v_pk_fma_f32 v[12:13], v[6:7], s[0:1], v[128:129] op_sel_hi:[1,0,1]
	v_mov_b32_e32 v7, v177
	v_add_f32_e32 v6, v12, v26
	v_add_f32_e32 v6, v13, v6
	v_add_f32_e32 v6, v8, v6
	v_add_f32_e32 v6, v9, v6
	v_add_f32_e32 v6, v14, v6
	v_add_f32_e32 v6, v15, v6
	v_add_f32_e32 v6, v24, v6
	v_add_f32_e32 v6, v25, v6
	s_nop 1
	v_add_f32_dpp v6, v6, v6 row_shr:1 row_mask:0xf bank_mask:0xf bound_ctrl:1
	s_nop 1
	v_add_f32_dpp v6, v6, v6 row_shr:2 row_mask:0xf bank_mask:0xf bound_ctrl:1
	s_nop 1
	v_add_f32_dpp v6, v6, v6 row_shr:4 row_mask:0xf bank_mask:0xf bound_ctrl:1
	s_nop 1
	v_add_f32_dpp v6, v6, v6 row_shr:8 row_mask:0xf bank_mask:0xf bound_ctrl:1
	s_nop 1
	v_mov_b32_dpp v7, v6 row_bcast:15 row_mask:0xa bank_mask:0xf
	v_add_f32_e32 v6, v6, v7
	v_mov_b32_e32 v7, v177
	s_nop 1
	v_mov_b32_dpp v7, v6 row_bcast:31 row_mask:0xc bank_mask:0xf
	v_add_f32_e32 v6, v6, v7
	s_nop 0
	v_readlane_b32 s0, v6, 63
	s_nop 1
	v_mul_f32_e32 v26, s0, v210
	v_pk_add_f32 v[28:29], v[4:5], v[26:27] op_sel_hi:[1,0] neg_lo:[0,1] neg_hi:[0,1]
	v_pk_add_f32 v[32:33], v[18:19], v[26:27] op_sel_hi:[1,0] neg_lo:[0,1] neg_hi:[0,1]
	v_pk_mul_f32 v[30:31], v[28:29], v[28:29]
	v_pk_mul_f32 v[18:19], v[32:33], v[32:33]
	v_pk_add_f32 v[4:5], v[16:17], v[26:27] op_sel_hi:[1,0] neg_lo:[0,1] neg_hi:[0,1]
	v_pk_add_f32 v[6:7], v[10:11], v[26:27] op_sel_hi:[1,0] neg_lo:[0,1] neg_hi:[0,1]
	v_pk_add_f32 v[10:11], v[12:13], v[26:27] op_sel_hi:[1,0] neg_lo:[0,1] neg_hi:[0,1]
	v_pk_add_f32 v[8:9], v[8:9], v[26:27] op_sel_hi:[1,0] neg_lo:[0,1] neg_hi:[0,1]
	v_pk_add_f32 v[14:15], v[14:15], v[26:27] op_sel_hi:[1,0] neg_lo:[0,1] neg_hi:[0,1]
	v_pk_add_f32 v[12:13], v[24:25], v[26:27] op_sel_hi:[1,0] neg_lo:[0,1] neg_hi:[0,1]
	v_add_f32_e32 v26, v30, v31
	v_add_f32_e32 v18, v18, v26
	v_pk_mul_f32 v[16:17], v[4:5], v[4:5]
	v_add_f32_e32 v18, v19, v18
	v_add_f32_e32 v16, v16, v18
	v_pk_mul_f32 v[34:35], v[6:7], v[6:7]
	v_add_f32_e32 v16, v17, v16
	v_add_f32_e32 v16, v34, v16
	v_pk_mul_f32 v[36:37], v[10:11], v[10:11]
	v_add_f32_e32 v16, v35, v16
	v_add_f32_e32 v16, v36, v16
	v_pk_mul_f32 v[38:39], v[8:9], v[8:9]
	v_add_f32_e32 v16, v37, v16
	v_add_f32_e32 v16, v38, v16
	v_pk_mul_f32 v[40:41], v[14:15], v[14:15]
	v_add_f32_e32 v16, v39, v16
	v_add_f32_e32 v16, v40, v16
	v_pk_mul_f32 v[24:25], v[12:13], v[12:13]
	v_add_f32_e32 v16, v41, v16
	v_add_f32_e32 v16, v24, v16
	v_add_f32_e32 v16, v25, v16
	v_mov_b32_e32 v17, v177
	s_nop 0
	v_add_f32_dpp v16, v16, v16 row_shr:1 row_mask:0xf bank_mask:0xf bound_ctrl:1
	s_nop 1
	v_add_f32_dpp v16, v16, v16 row_shr:2 row_mask:0xf bank_mask:0xf bound_ctrl:1
	s_nop 1
	v_add_f32_dpp v16, v16, v16 row_shr:4 row_mask:0xf bank_mask:0xf bound_ctrl:1
	s_nop 1
	v_add_f32_dpp v16, v16, v16 row_shr:8 row_mask:0xf bank_mask:0xf bound_ctrl:1
	s_nop 1
	v_mov_b32_dpp v17, v16 row_bcast:15 row_mask:0xa bank_mask:0xf
	v_add_f32_e32 v16, v16, v17
	v_mov_b32_e32 v17, v177
	s_nop 1
	v_mov_b32_dpp v17, v16 row_bcast:31 row_mask:0xc bank_mask:0xf
	v_add_f32_e32 v16, v16, v17
	s_nop 0
	v_readlane_b32 s0, v16, 63
	s_nop 1
	v_fma_f32 v16, s0, v210, v203
	s_mov_b32 s0, 0x800000
	v_mul_f32_e32 v17, 0x4b800000, v16
	v_cmp_gt_f32_e32 vcc, s0, v16
	s_nop 1
	v_cndmask_b32_e32 v16, v16, v17, vcc
	v_rsq_f32_e32 v18, v16
	v_lshl_add_u64 v[16:17], v[94:95], 2, v[80:81]
	v_mul_f32_e32 v19, 0x45800000, v18
	v_cndmask_b32_e32 v18, v18, v19, vcc
	v_pk_mul_f32 v[24:25], v[28:29], v[18:19] op_sel_hi:[1,0]
	s_and_b64 vcc, exec, s[38:39]
	s_waitcnt vmcnt(0)
	v_pk_fma_f32 v[0:1], v[0:1], v[24:25], v[20:21]
	v_pk_mul_f32 v[20:21], v[32:33], v[18:19] op_sel_hi:[1,0]
	s_nop 0
	v_pk_fma_f32 v[2:3], v[2:3], v[20:21], v[22:23]
	s_cbranch_vccz .LBB0_25
	global_store_dwordx4 v[16:17], v[0:3], off
